# sample-state streaming loop rewritten by hand: global loads in a 16-deep ring with counted vmcnt instead of one serialised flat load per iteration
# speedup vs baseline: 1.0414x; 1.0414x over previous
.LBB0_835:
	s_or_b64 exec, exec, s[48:49]
	v_lshlrev_b32_e32 v0, 2, v36
	v_and_b32_e32 v156, 0x1fc, v0
	v_ashrrev_i32_e32 v0, 31, v38
	v_lshrrev_b32_e32 v0, 30, v0
	v_add_u32_e32 v0, v38, v0
	v_ashrrev_i32_e32 v0, 2, v0
	v_ashrrev_i32_e32 v1, 31, v0
	v_or_b32_e32 v2, s30, v156
	v_lshlrev_b64 v[0:1], 14, v[0:1]
	v_lshlrev_b32_e32 v32, 3, v2
	v_lshl_add_u64 v[90:91], s[26:27], 0, v[0:1]
	s_mov_b64 s[48:49], 0x4000
	v_lshl_add_u64 v[0:1], v[90:91], 0, v[32:33]
	v_lshl_add_u64 v[92:93], v[90:91], 0, s[48:49]
	s_waitcnt lgkmcnt(0)
	s_barrier
	flat_load_dwordx4 v[26:29], v[0:1]
	flat_load_dwordx4 v[116:119], v[0:1] offset:16
	v_lshl_add_u64 v[0:1], v[92:93], 0, v[32:33]
	flat_load_dwordx4 v[124:127], v[0:1]
	flat_load_dwordx4 v[132:135], v[0:1] offset:16
	v_ashrrev_i32_e32 v94, 7, v36
	v_ashrrev_i32_e32 v95, 31, v94
	v_and_b32_e32 v25, 0x7f, v36
	v_lshlrev_b64 v[30:31], 11, v[94:95]
	v_mov_b32_e32 v0, 0
	v_lshl_or_b32 v30, v25, 4, v30
	v_mov_b32_e32 v87, v86
	v_mov_b32_e32 v96, v86
	v_mov_b32_e32 v97, v86
	s_mov_b64 s[48:49], 0
	v_lshl_add_u32 v32, v94, 5, 0
	v_mov_b32_e32 v1, v0
	v_mov_b32_e32 v2, v0
	v_mov_b32_e32 v3, v0
	v_mov_b32_e32 v4, v0
	v_mov_b32_e32 v5, v0
	v_mov_b32_e32 v6, v0
	v_mov_b32_e32 v7, v0
	v_mov_b32_e32 v8, v0
	v_mov_b32_e32 v9, v0
	v_mov_b32_e32 v10, v0
	v_mov_b32_e32 v11, v0
	v_mov_b32_e32 v12, v0
	v_mov_b32_e32 v13, v0
	v_mov_b32_e32 v14, v0
	v_mov_b32_e32 v15, v0
	v_mov_b32_e32 v16, v0
	v_mov_b32_e32 v17, v0
	v_mov_b32_e32 v18, v0
	v_mov_b32_e32 v19, v0
	v_mov_b32_e32 v20, v0
	v_mov_b32_e32 v21, v0
	v_mov_b32_e32 v22, v0
	v_mov_b32_e32 v23, v0
	v_mov_b32_e32 v24, v0
	v_lshl_add_u64 v[98:99], s[42:43], 0, v[30:31]
	v_lshl_add_u64 v[100:101], s[12:13], 0, v[30:31]
	v_mov_b32_e32 v25, v0
	v_mov_b32_e32 v30, v0
	v_mov_b32_e32 v31, v0
	s_waitcnt vmcnt(0) lgkmcnt(0)
	v_lshlrev_b32_e32 v102, 16, v26
	v_and_b32_e32 v104, 0xffff0000, v26
	v_lshlrev_b32_e32 v106, 16, v27
	v_and_b32_e32 v108, 0xffff0000, v27
	v_lshlrev_b32_e32 v103, 16, v28
	v_and_b32_e32 v105, 0xffff0000, v28
	v_lshlrev_b32_e32 v107, 16, v29
	v_and_b32_e32 v109, 0xffff0000, v29
	v_lshlrev_b32_e32 v110, 16, v116
	v_and_b32_e32 v112, 0xffff0000, v116
	v_lshlrev_b32_e32 v114, 16, v117
	v_and_b32_e32 v116, 0xffff0000, v117
	v_lshlrev_b32_e32 v111, 16, v118
	v_and_b32_e32 v113, 0xffff0000, v118
	v_lshlrev_b32_e32 v115, 16, v119
	v_and_b32_e32 v117, 0xffff0000, v119
	v_lshlrev_b32_e32 v118, 16, v124
	v_and_b32_e32 v120, 0xffff0000, v124
	v_lshlrev_b32_e32 v122, 16, v125
	v_and_b32_e32 v124, 0xffff0000, v125
	v_lshlrev_b32_e32 v119, 16, v126
	v_and_b32_e32 v121, 0xffff0000, v126
	v_lshlrev_b32_e32 v123, 16, v127
	v_and_b32_e32 v125, 0xffff0000, v127
	v_lshlrev_b32_e32 v126, 16, v132
	v_and_b32_e32 v128, 0xffff0000, v132
	v_lshlrev_b32_e32 v130, 16, v133
	v_and_b32_e32 v132, 0xffff0000, v133
	v_lshlrev_b32_e32 v127, 16, v134
	v_and_b32_e32 v129, 0xffff0000, v134
	v_lshlrev_b32_e32 v131, 16, v135
	v_and_b32_e32 v133, 0xffff0000, v135
	v_mov_b32_e32 v26, v0
	v_mov_b32_e32 v27, v0
	v_mov_b32_e32 v28, v0
	v_mov_b32_e32 v29, v0
	v_subrev_u32_e32 v246, s12, v100
	s_mov_b32 s98, s12
	s_mov_b32 s99, s13
	s_add_u32 s100, s42, 0x6950000
	s_addc_u32 s101, s43, 0
	global_load_dwordx4 v[134:137], v246, s[98:99] nt
	s_add_u32 s98, s98, 0x2000
	s_addc_u32 s99, s99, 0
	global_load_dwordx4 v[138:141], v246, s[98:99] nt
	s_add_u32 s98, s98, 0x2000
	s_addc_u32 s99, s99, 0
	global_load_dwordx4 v[142:145], v246, s[98:99] nt
	s_add_u32 s98, s98, 0x2000
	s_addc_u32 s99, s99, 0
	global_load_dwordx4 v[158:161], v246, s[98:99] nt
	s_add_u32 s98, s98, 0x2000
	s_addc_u32 s99, s99, 0
	global_load_dwordx4 v[162:165], v246, s[98:99] nt
	s_add_u32 s98, s98, 0x2000
	s_addc_u32 s99, s99, 0
	global_load_dwordx4 v[166:169], v246, s[98:99] nt
	s_add_u32 s98, s98, 0x2000
	s_addc_u32 s99, s99, 0
	global_load_dwordx4 v[170:173], v246, s[98:99] nt
	s_add_u32 s98, s98, 0x2000
	s_addc_u32 s99, s99, 0
	global_load_dwordx4 v[174:177], v246, s[98:99] nt
	s_add_u32 s98, s98, 0x2000
	s_addc_u32 s99, s99, 0
	global_load_dwordx4 v[178:181], v246, s[98:99] nt
	s_add_u32 s98, s98, 0x2000
	s_addc_u32 s99, s99, 0
	global_load_dwordx4 v[182:185], v246, s[98:99] nt
	s_add_u32 s98, s98, 0x2000
	s_addc_u32 s99, s99, 0
	global_load_dwordx4 v[186:189], v246, s[98:99] nt
	s_add_u32 s98, s98, 0x2000
	s_addc_u32 s99, s99, 0
	global_load_dwordx4 v[190:193], v246, s[98:99] nt
	s_add_u32 s98, s98, 0x2000
	s_addc_u32 s99, s99, 0
	global_load_dwordx4 v[194:197], v246, s[98:99] nt
	s_add_u32 s98, s98, 0x2000
	s_addc_u32 s99, s99, 0
	global_load_dwordx4 v[210:213], v246, s[98:99] nt
	s_add_u32 s98, s98, 0x2000
	s_addc_u32 s99, s99, 0
	global_load_dwordx4 v[214:217], v246, s[98:99] nt
	s_add_u32 s98, s98, 0x2000
	s_addc_u32 s99, s99, 0
	global_load_dwordx4 v[218:221], v246, s[98:99] nt
	s_add_u32 s98, s98, 0x2000
	s_addc_u32 s99, s99, 0
	ds_read_b128 v[222:225], v32
	ds_read_b128 v[226:229], v32 offset:16
	ds_read_b128 v[230:233], v32 offset:16384
	ds_read_b128 v[234:237], v32 offset:16400
	s_mov_b32 vcc_lo, 0
	s_waitcnt vmcnt(15)
	s_waitcnt lgkmcnt(2)
	v_pk_fma_f32 v[0:1], v[134:135], v[222:223], v[0:1] op_sel_hi:[1,0,1]
	v_pk_fma_f32 v[2:3], v[136:137], v[222:223], v[2:3] op_sel_hi:[1,0,1]
	v_pk_fma_f32 v[4:5], v[134:135], v[222:223], v[4:5] op_sel:[0,1,0]
	v_pk_fma_f32 v[6:7], v[136:137], v[222:223], v[6:7] op_sel:[0,1,0]
	v_pk_fma_f32 v[8:9], v[134:135], v[224:225], v[8:9] op_sel_hi:[1,0,1]
	v_pk_fma_f32 v[10:11], v[136:137], v[224:225], v[10:11] op_sel_hi:[1,0,1]
	v_pk_fma_f32 v[12:13], v[134:135], v[224:225], v[12:13] op_sel:[0,1,0]
	v_pk_fma_f32 v[14:15], v[136:137], v[224:225], v[14:15] op_sel:[0,1,0]
	v_pk_fma_f32 v[16:17], v[134:135], v[226:227], v[16:17] op_sel_hi:[1,0,1]
	v_pk_fma_f32 v[18:19], v[136:137], v[226:227], v[18:19] op_sel_hi:[1,0,1]
	v_pk_fma_f32 v[20:21], v[134:135], v[226:227], v[20:21] op_sel:[0,1,0]
	v_pk_fma_f32 v[22:23], v[136:137], v[226:227], v[22:23] op_sel:[0,1,0]
	v_pk_fma_f32 v[24:25], v[134:135], v[228:229], v[24:25] op_sel_hi:[1,0,1]
	v_pk_fma_f32 v[26:27], v[136:137], v[228:229], v[26:27] op_sel_hi:[1,0,1]
	v_pk_fma_f32 v[28:29], v[134:135], v[228:229], v[28:29] op_sel:[0,1,0]
	v_pk_fma_f32 v[30:31], v[136:137], v[228:229], v[30:31] op_sel:[0,1,0]
	ds_read_b128 v[222:225], v32 offset:128
	ds_read_b128 v[226:229], v32 offset:144
	s_waitcnt lgkmcnt(2)
	v_pk_mul_f32 v[238:239], v[230:231], v[102:103] op_sel_hi:[0,1]
	v_pk_mul_f32 v[240:241], v[230:231], v[110:111] op_sel_hi:[0,1]
	v_pk_fma_f32 v[238:239], v[86:87], v[134:135], v[238:239]
	v_pk_fma_f32 v[240:241], v[86:87], v[136:137], v[240:241]
	v_pk_fma_f32 v[238:239], v[234:235], v[118:119], v[238:239] op_sel_hi:[0,1,1]
	v_pk_fma_f32 v[240:241], v[234:235], v[126:127], v[240:241] op_sel_hi:[0,1,1]
	v_pk_fma_f32 v[238:239], v[230:231], v[104:105], v[238:239] op_sel:[1,0,0]
	v_pk_fma_f32 v[240:241], v[230:231], v[112:113], v[240:241] op_sel:[1,0,0]
	v_pk_fma_f32 v[238:239], v[234:235], v[120:121], v[238:239] op_sel:[1,0,0]
	v_pk_fma_f32 v[240:241], v[234:235], v[128:129], v[240:241] op_sel:[1,0,0]
	v_pk_fma_f32 v[238:239], v[232:233], v[106:107], v[238:239] op_sel_hi:[0,1,1]
	v_pk_fma_f32 v[240:241], v[232:233], v[114:115], v[240:241] op_sel_hi:[0,1,1]
	v_pk_fma_f32 v[238:239], v[236:237], v[122:123], v[238:239] op_sel_hi:[0,1,1]
	v_pk_fma_f32 v[240:241], v[236:237], v[130:131], v[240:241] op_sel_hi:[0,1,1]
	v_pk_fma_f32 v[238:239], v[232:233], v[108:109], v[238:239] op_sel:[1,0,0]
	v_pk_fma_f32 v[240:241], v[232:233], v[116:117], v[240:241] op_sel:[1,0,0]
	v_pk_fma_f32 v[238:239], v[236:237], v[124:125], v[238:239] op_sel:[1,0,0]
	v_pk_fma_f32 v[240:241], v[236:237], v[132:133], v[240:241] op_sel:[1,0,0]
	ds_read_b128 v[230:233], v32 offset:16512
	ds_read_b128 v[234:237], v32 offset:16528
	global_store_dwordx4 v246, v[238:241], s[100:101] nt
	global_load_dwordx4 v[134:137], v246, s[98:99] nt
	s_add_u32 s100, s100, 0x2000
	s_addc_u32 s101, s101, 0
	s_add_u32 s98, s98, 0x2000
	s_addc_u32 s99, s99, 0
	s_waitcnt vmcnt(16)
	s_waitcnt lgkmcnt(2)
	v_pk_fma_f32 v[0:1], v[138:139], v[222:223], v[0:1] op_sel_hi:[1,0,1]
	v_pk_fma_f32 v[2:3], v[140:141], v[222:223], v[2:3] op_sel_hi:[1,0,1]
	v_pk_fma_f32 v[4:5], v[138:139], v[222:223], v[4:5] op_sel:[0,1,0]
	v_pk_fma_f32 v[6:7], v[140:141], v[222:223], v[6:7] op_sel:[0,1,0]
	v_pk_fma_f32 v[8:9], v[138:139], v[224:225], v[8:9] op_sel_hi:[1,0,1]
	v_pk_fma_f32 v[10:11], v[140:141], v[224:225], v[10:11] op_sel_hi:[1,0,1]
	v_pk_fma_f32 v[12:13], v[138:139], v[224:225], v[12:13] op_sel:[0,1,0]
	v_pk_fma_f32 v[14:15], v[140:141], v[224:225], v[14:15] op_sel:[0,1,0]
	v_pk_fma_f32 v[16:17], v[138:139], v[226:227], v[16:17] op_sel_hi:[1,0,1]
	v_pk_fma_f32 v[18:19], v[140:141], v[226:227], v[18:19] op_sel_hi:[1,0,1]
	v_pk_fma_f32 v[20:21], v[138:139], v[226:227], v[20:21] op_sel:[0,1,0]
	v_pk_fma_f32 v[22:23], v[140:141], v[226:227], v[22:23] op_sel:[0,1,0]
	v_pk_fma_f32 v[24:25], v[138:139], v[228:229], v[24:25] op_sel_hi:[1,0,1]
	v_pk_fma_f32 v[26:27], v[140:141], v[228:229], v[26:27] op_sel_hi:[1,0,1]
	v_pk_fma_f32 v[28:29], v[138:139], v[228:229], v[28:29] op_sel:[0,1,0]
	v_pk_fma_f32 v[30:31], v[140:141], v[228:229], v[30:31] op_sel:[0,1,0]
	ds_read_b128 v[222:225], v32 offset:256
	ds_read_b128 v[226:229], v32 offset:272
	s_waitcnt lgkmcnt(2)
	v_pk_mul_f32 v[242:243], v[230:231], v[102:103] op_sel_hi:[0,1]
	v_pk_mul_f32 v[244:245], v[230:231], v[110:111] op_sel_hi:[0,1]
	v_pk_fma_f32 v[242:243], v[86:87], v[138:139], v[242:243]
	v_pk_fma_f32 v[244:245], v[86:87], v[140:141], v[244:245]
	v_pk_fma_f32 v[242:243], v[234:235], v[118:119], v[242:243] op_sel_hi:[0,1,1]
	v_pk_fma_f32 v[244:245], v[234:235], v[126:127], v[244:245] op_sel_hi:[0,1,1]
	v_pk_fma_f32 v[242:243], v[230:231], v[104:105], v[242:243] op_sel:[1,0,0]
	v_pk_fma_f32 v[244:245], v[230:231], v[112:113], v[244:245] op_sel:[1,0,0]
	v_pk_fma_f32 v[242:243], v[234:235], v[120:121], v[242:243] op_sel:[1,0,0]
	v_pk_fma_f32 v[244:245], v[234:235], v[128:129], v[244:245] op_sel:[1,0,0]
	v_pk_fma_f32 v[242:243], v[232:233], v[106:107], v[242:243] op_sel_hi:[0,1,1]
	v_pk_fma_f32 v[244:245], v[232:233], v[114:115], v[244:245] op_sel_hi:[0,1,1]
	v_pk_fma_f32 v[242:243], v[236:237], v[122:123], v[242:243] op_sel_hi:[0,1,1]
	v_pk_fma_f32 v[244:245], v[236:237], v[130:131], v[244:245] op_sel_hi:[0,1,1]
	v_pk_fma_f32 v[242:243], v[232:233], v[108:109], v[242:243] op_sel:[1,0,0]
	v_pk_fma_f32 v[244:245], v[232:233], v[116:117], v[244:245] op_sel:[1,0,0]
	v_pk_fma_f32 v[242:243], v[236:237], v[124:125], v[242:243] op_sel:[1,0,0]
	v_pk_fma_f32 v[244:245], v[236:237], v[132:133], v[244:245] op_sel:[1,0,0]
	ds_read_b128 v[230:233], v32 offset:16640
	ds_read_b128 v[234:237], v32 offset:16656
	global_store_dwordx4 v246, v[242:245], s[100:101] nt
	global_load_dwordx4 v[138:141], v246, s[98:99] nt
	s_add_u32 s100, s100, 0x2000
	s_addc_u32 s101, s101, 0
	s_add_u32 s98, s98, 0x2000
	s_addc_u32 s99, s99, 0
	s_waitcnt vmcnt(17)
	s_waitcnt lgkmcnt(2)
	v_pk_fma_f32 v[0:1], v[142:143], v[222:223], v[0:1] op_sel_hi:[1,0,1]
	v_pk_fma_f32 v[2:3], v[144:145], v[222:223], v[2:3] op_sel_hi:[1,0,1]
	v_pk_fma_f32 v[4:5], v[142:143], v[222:223], v[4:5] op_sel:[0,1,0]
	v_pk_fma_f32 v[6:7], v[144:145], v[222:223], v[6:7] op_sel:[0,1,0]
	v_pk_fma_f32 v[8:9], v[142:143], v[224:225], v[8:9] op_sel_hi:[1,0,1]
	v_pk_fma_f32 v[10:11], v[144:145], v[224:225], v[10:11] op_sel_hi:[1,0,1]
	v_pk_fma_f32 v[12:13], v[142:143], v[224:225], v[12:13] op_sel:[0,1,0]
	v_pk_fma_f32 v[14:15], v[144:145], v[224:225], v[14:15] op_sel:[0,1,0]
	v_pk_fma_f32 v[16:17], v[142:143], v[226:227], v[16:17] op_sel_hi:[1,0,1]
	v_pk_fma_f32 v[18:19], v[144:145], v[226:227], v[18:19] op_sel_hi:[1,0,1]
	v_pk_fma_f32 v[20:21], v[142:143], v[226:227], v[20:21] op_sel:[0,1,0]
	v_pk_fma_f32 v[22:23], v[144:145], v[226:227], v[22:23] op_sel:[0,1,0]
	v_pk_fma_f32 v[24:25], v[142:143], v[228:229], v[24:25] op_sel_hi:[1,0,1]
	v_pk_fma_f32 v[26:27], v[144:145], v[228:229], v[26:27] op_sel_hi:[1,0,1]
	v_pk_fma_f32 v[28:29], v[142:143], v[228:229], v[28:29] op_sel:[0,1,0]
	v_pk_fma_f32 v[30:31], v[144:145], v[228:229], v[30:31] op_sel:[0,1,0]
	ds_read_b128 v[222:225], v32 offset:384
	ds_read_b128 v[226:229], v32 offset:400
	s_waitcnt lgkmcnt(2)
	v_pk_mul_f32 v[238:239], v[230:231], v[102:103] op_sel_hi:[0,1]
	v_pk_mul_f32 v[240:241], v[230:231], v[110:111] op_sel_hi:[0,1]
	v_pk_fma_f32 v[238:239], v[86:87], v[142:143], v[238:239]
	v_pk_fma_f32 v[240:241], v[86:87], v[144:145], v[240:241]
	v_pk_fma_f32 v[238:239], v[234:235], v[118:119], v[238:239] op_sel_hi:[0,1,1]
	v_pk_fma_f32 v[240:241], v[234:235], v[126:127], v[240:241] op_sel_hi:[0,1,1]
	v_pk_fma_f32 v[238:239], v[230:231], v[104:105], v[238:239] op_sel:[1,0,0]
	v_pk_fma_f32 v[240:241], v[230:231], v[112:113], v[240:241] op_sel:[1,0,0]
	v_pk_fma_f32 v[238:239], v[234:235], v[120:121], v[238:239] op_sel:[1,0,0]
	v_pk_fma_f32 v[240:241], v[234:235], v[128:129], v[240:241] op_sel:[1,0,0]
	v_pk_fma_f32 v[238:239], v[232:233], v[106:107], v[238:239] op_sel_hi:[0,1,1]
	v_pk_fma_f32 v[240:241], v[232:233], v[114:115], v[240:241] op_sel_hi:[0,1,1]
	v_pk_fma_f32 v[238:239], v[236:237], v[122:123], v[238:239] op_sel_hi:[0,1,1]
	v_pk_fma_f32 v[240:241], v[236:237], v[130:131], v[240:241] op_sel_hi:[0,1,1]
	v_pk_fma_f32 v[238:239], v[232:233], v[108:109], v[238:239] op_sel:[1,0,0]
	v_pk_fma_f32 v[240:241], v[232:233], v[116:117], v[240:241] op_sel:[1,0,0]
	v_pk_fma_f32 v[238:239], v[236:237], v[124:125], v[238:239] op_sel:[1,0,0]
	v_pk_fma_f32 v[240:241], v[236:237], v[132:133], v[240:241] op_sel:[1,0,0]
	ds_read_b128 v[230:233], v32 offset:16768
	ds_read_b128 v[234:237], v32 offset:16784
	global_store_dwordx4 v246, v[238:241], s[100:101] nt
	global_load_dwordx4 v[142:145], v246, s[98:99] nt
	s_add_u32 s100, s100, 0x2000
	s_addc_u32 s101, s101, 0
	s_add_u32 s98, s98, 0x2000
	s_addc_u32 s99, s99, 0
	s_waitcnt vmcnt(18)
	s_waitcnt lgkmcnt(2)
	v_pk_fma_f32 v[0:1], v[158:159], v[222:223], v[0:1] op_sel_hi:[1,0,1]
	v_pk_fma_f32 v[2:3], v[160:161], v[222:223], v[2:3] op_sel_hi:[1,0,1]
	v_pk_fma_f32 v[4:5], v[158:159], v[222:223], v[4:5] op_sel:[0,1,0]
	v_pk_fma_f32 v[6:7], v[160:161], v[222:223], v[6:7] op_sel:[0,1,0]
	v_pk_fma_f32 v[8:9], v[158:159], v[224:225], v[8:9] op_sel_hi:[1,0,1]
	v_pk_fma_f32 v[10:11], v[160:161], v[224:225], v[10:11] op_sel_hi:[1,0,1]
	v_pk_fma_f32 v[12:13], v[158:159], v[224:225], v[12:13] op_sel:[0,1,0]
	v_pk_fma_f32 v[14:15], v[160:161], v[224:225], v[14:15] op_sel:[0,1,0]
	v_pk_fma_f32 v[16:17], v[158:159], v[226:227], v[16:17] op_sel_hi:[1,0,1]
	v_pk_fma_f32 v[18:19], v[160:161], v[226:227], v[18:19] op_sel_hi:[1,0,1]
	v_pk_fma_f32 v[20:21], v[158:159], v[226:227], v[20:21] op_sel:[0,1,0]
	v_pk_fma_f32 v[22:23], v[160:161], v[226:227], v[22:23] op_sel:[0,1,0]
	v_pk_fma_f32 v[24:25], v[158:159], v[228:229], v[24:25] op_sel_hi:[1,0,1]
	v_pk_fma_f32 v[26:27], v[160:161], v[228:229], v[26:27] op_sel_hi:[1,0,1]
	v_pk_fma_f32 v[28:29], v[158:159], v[228:229], v[28:29] op_sel:[0,1,0]
	v_pk_fma_f32 v[30:31], v[160:161], v[228:229], v[30:31] op_sel:[0,1,0]
	ds_read_b128 v[222:225], v32 offset:512
	ds_read_b128 v[226:229], v32 offset:528
	s_waitcnt lgkmcnt(2)
	v_pk_mul_f32 v[242:243], v[230:231], v[102:103] op_sel_hi:[0,1]
	v_pk_mul_f32 v[244:245], v[230:231], v[110:111] op_sel_hi:[0,1]
	v_pk_fma_f32 v[242:243], v[86:87], v[158:159], v[242:243]
	v_pk_fma_f32 v[244:245], v[86:87], v[160:161], v[244:245]
	v_pk_fma_f32 v[242:243], v[234:235], v[118:119], v[242:243] op_sel_hi:[0,1,1]
	v_pk_fma_f32 v[244:245], v[234:235], v[126:127], v[244:245] op_sel_hi:[0,1,1]
	v_pk_fma_f32 v[242:243], v[230:231], v[104:105], v[242:243] op_sel:[1,0,0]
	v_pk_fma_f32 v[244:245], v[230:231], v[112:113], v[244:245] op_sel:[1,0,0]
	v_pk_fma_f32 v[242:243], v[234:235], v[120:121], v[242:243] op_sel:[1,0,0]
	v_pk_fma_f32 v[244:245], v[234:235], v[128:129], v[244:245] op_sel:[1,0,0]
	v_pk_fma_f32 v[242:243], v[232:233], v[106:107], v[242:243] op_sel_hi:[0,1,1]
	v_pk_fma_f32 v[244:245], v[232:233], v[114:115], v[244:245] op_sel_hi:[0,1,1]
	v_pk_fma_f32 v[242:243], v[236:237], v[122:123], v[242:243] op_sel_hi:[0,1,1]
	v_pk_fma_f32 v[244:245], v[236:237], v[130:131], v[244:245] op_sel_hi:[0,1,1]
	v_pk_fma_f32 v[242:243], v[232:233], v[108:109], v[242:243] op_sel:[1,0,0]
	v_pk_fma_f32 v[244:245], v[232:233], v[116:117], v[244:245] op_sel:[1,0,0]
	v_pk_fma_f32 v[242:243], v[236:237], v[124:125], v[242:243] op_sel:[1,0,0]
	v_pk_fma_f32 v[244:245], v[236:237], v[132:133], v[244:245] op_sel:[1,0,0]
	ds_read_b128 v[230:233], v32 offset:16896
	ds_read_b128 v[234:237], v32 offset:16912
	global_store_dwordx4 v246, v[242:245], s[100:101] nt
	global_load_dwordx4 v[158:161], v246, s[98:99] nt
	s_add_u32 s100, s100, 0x2000
	s_addc_u32 s101, s101, 0
	s_add_u32 s98, s98, 0x2000
	s_addc_u32 s99, s99, 0
	s_waitcnt vmcnt(19)
	s_waitcnt lgkmcnt(2)
	v_pk_fma_f32 v[0:1], v[162:163], v[222:223], v[0:1] op_sel_hi:[1,0,1]
	v_pk_fma_f32 v[2:3], v[164:165], v[222:223], v[2:3] op_sel_hi:[1,0,1]
	v_pk_fma_f32 v[4:5], v[162:163], v[222:223], v[4:5] op_sel:[0,1,0]
	v_pk_fma_f32 v[6:7], v[164:165], v[222:223], v[6:7] op_sel:[0,1,0]
	v_pk_fma_f32 v[8:9], v[162:163], v[224:225], v[8:9] op_sel_hi:[1,0,1]
	v_pk_fma_f32 v[10:11], v[164:165], v[224:225], v[10:11] op_sel_hi:[1,0,1]
	v_pk_fma_f32 v[12:13], v[162:163], v[224:225], v[12:13] op_sel:[0,1,0]
	v_pk_fma_f32 v[14:15], v[164:165], v[224:225], v[14:15] op_sel:[0,1,0]
	v_pk_fma_f32 v[16:17], v[162:163], v[226:227], v[16:17] op_sel_hi:[1,0,1]
	v_pk_fma_f32 v[18:19], v[164:165], v[226:227], v[18:19] op_sel_hi:[1,0,1]
	v_pk_fma_f32 v[20:21], v[162:163], v[226:227], v[20:21] op_sel:[0,1,0]
	v_pk_fma_f32 v[22:23], v[164:165], v[226:227], v[22:23] op_sel:[0,1,0]
	v_pk_fma_f32 v[24:25], v[162:163], v[228:229], v[24:25] op_sel_hi:[1,0,1]
	v_pk_fma_f32 v[26:27], v[164:165], v[228:229], v[26:27] op_sel_hi:[1,0,1]
	v_pk_fma_f32 v[28:29], v[162:163], v[228:229], v[28:29] op_sel:[0,1,0]
	v_pk_fma_f32 v[30:31], v[164:165], v[228:229], v[30:31] op_sel:[0,1,0]
	ds_read_b128 v[222:225], v32 offset:640
	ds_read_b128 v[226:229], v32 offset:656
	s_waitcnt lgkmcnt(2)
	v_pk_mul_f32 v[238:239], v[230:231], v[102:103] op_sel_hi:[0,1]
	v_pk_mul_f32 v[240:241], v[230:231], v[110:111] op_sel_hi:[0,1]
	v_pk_fma_f32 v[238:239], v[86:87], v[162:163], v[238:239]
	v_pk_fma_f32 v[240:241], v[86:87], v[164:165], v[240:241]
	v_pk_fma_f32 v[238:239], v[234:235], v[118:119], v[238:239] op_sel_hi:[0,1,1]
	v_pk_fma_f32 v[240:241], v[234:235], v[126:127], v[240:241] op_sel_hi:[0,1,1]
	v_pk_fma_f32 v[238:239], v[230:231], v[104:105], v[238:239] op_sel:[1,0,0]
	v_pk_fma_f32 v[240:241], v[230:231], v[112:113], v[240:241] op_sel:[1,0,0]
	v_pk_fma_f32 v[238:239], v[234:235], v[120:121], v[238:239] op_sel:[1,0,0]
	v_pk_fma_f32 v[240:241], v[234:235], v[128:129], v[240:241] op_sel:[1,0,0]
	v_pk_fma_f32 v[238:239], v[232:233], v[106:107], v[238:239] op_sel_hi:[0,1,1]
	v_pk_fma_f32 v[240:241], v[232:233], v[114:115], v[240:241] op_sel_hi:[0,1,1]
	v_pk_fma_f32 v[238:239], v[236:237], v[122:123], v[238:239] op_sel_hi:[0,1,1]
	v_pk_fma_f32 v[240:241], v[236:237], v[130:131], v[240:241] op_sel_hi:[0,1,1]
	v_pk_fma_f32 v[238:239], v[232:233], v[108:109], v[238:239] op_sel:[1,0,0]
	v_pk_fma_f32 v[240:241], v[232:233], v[116:117], v[240:241] op_sel:[1,0,0]
	v_pk_fma_f32 v[238:239], v[236:237], v[124:125], v[238:239] op_sel:[1,0,0]
	v_pk_fma_f32 v[240:241], v[236:237], v[132:133], v[240:241] op_sel:[1,0,0]
	ds_read_b128 v[230:233], v32 offset:17024
	ds_read_b128 v[234:237], v32 offset:17040
	global_store_dwordx4 v246, v[238:241], s[100:101] nt
	global_load_dwordx4 v[162:165], v246, s[98:99] nt
	s_add_u32 s100, s100, 0x2000
	s_addc_u32 s101, s101, 0
	s_add_u32 s98, s98, 0x2000
	s_addc_u32 s99, s99, 0
	s_waitcnt vmcnt(20)
	s_waitcnt lgkmcnt(2)
	v_pk_fma_f32 v[0:1], v[166:167], v[222:223], v[0:1] op_sel_hi:[1,0,1]
	v_pk_fma_f32 v[2:3], v[168:169], v[222:223], v[2:3] op_sel_hi:[1,0,1]
	v_pk_fma_f32 v[4:5], v[166:167], v[222:223], v[4:5] op_sel:[0,1,0]
	v_pk_fma_f32 v[6:7], v[168:169], v[222:223], v[6:7] op_sel:[0,1,0]
	v_pk_fma_f32 v[8:9], v[166:167], v[224:225], v[8:9] op_sel_hi:[1,0,1]
	v_pk_fma_f32 v[10:11], v[168:169], v[224:225], v[10:11] op_sel_hi:[1,0,1]
	v_pk_fma_f32 v[12:13], v[166:167], v[224:225], v[12:13] op_sel:[0,1,0]
	v_pk_fma_f32 v[14:15], v[168:169], v[224:225], v[14:15] op_sel:[0,1,0]
	v_pk_fma_f32 v[16:17], v[166:167], v[226:227], v[16:17] op_sel_hi:[1,0,1]
	v_pk_fma_f32 v[18:19], v[168:169], v[226:227], v[18:19] op_sel_hi:[1,0,1]
	v_pk_fma_f32 v[20:21], v[166:167], v[226:227], v[20:21] op_sel:[0,1,0]
	v_pk_fma_f32 v[22:23], v[168:169], v[226:227], v[22:23] op_sel:[0,1,0]
	v_pk_fma_f32 v[24:25], v[166:167], v[228:229], v[24:25] op_sel_hi:[1,0,1]
	v_pk_fma_f32 v[26:27], v[168:169], v[228:229], v[26:27] op_sel_hi:[1,0,1]
	v_pk_fma_f32 v[28:29], v[166:167], v[228:229], v[28:29] op_sel:[0,1,0]
	v_pk_fma_f32 v[30:31], v[168:169], v[228:229], v[30:31] op_sel:[0,1,0]
	ds_read_b128 v[222:225], v32 offset:768
	ds_read_b128 v[226:229], v32 offset:784
	s_waitcnt lgkmcnt(2)
	v_pk_mul_f32 v[242:243], v[230:231], v[102:103] op_sel_hi:[0,1]
	v_pk_mul_f32 v[244:245], v[230:231], v[110:111] op_sel_hi:[0,1]
	v_pk_fma_f32 v[242:243], v[86:87], v[166:167], v[242:243]
	v_pk_fma_f32 v[244:245], v[86:87], v[168:169], v[244:245]
	v_pk_fma_f32 v[242:243], v[234:235], v[118:119], v[242:243] op_sel_hi:[0,1,1]
	v_pk_fma_f32 v[244:245], v[234:235], v[126:127], v[244:245] op_sel_hi:[0,1,1]
	v_pk_fma_f32 v[242:243], v[230:231], v[104:105], v[242:243] op_sel:[1,0,0]
	v_pk_fma_f32 v[244:245], v[230:231], v[112:113], v[244:245] op_sel:[1,0,0]
	v_pk_fma_f32 v[242:243], v[234:235], v[120:121], v[242:243] op_sel:[1,0,0]
	v_pk_fma_f32 v[244:245], v[234:235], v[128:129], v[244:245] op_sel:[1,0,0]
	v_pk_fma_f32 v[242:243], v[232:233], v[106:107], v[242:243] op_sel_hi:[0,1,1]
	v_pk_fma_f32 v[244:245], v[232:233], v[114:115], v[244:245] op_sel_hi:[0,1,1]
	v_pk_fma_f32 v[242:243], v[236:237], v[122:123], v[242:243] op_sel_hi:[0,1,1]
	v_pk_fma_f32 v[244:245], v[236:237], v[130:131], v[244:245] op_sel_hi:[0,1,1]
	v_pk_fma_f32 v[242:243], v[232:233], v[108:109], v[242:243] op_sel:[1,0,0]
	v_pk_fma_f32 v[244:245], v[232:233], v[116:117], v[244:245] op_sel:[1,0,0]
	v_pk_fma_f32 v[242:243], v[236:237], v[124:125], v[242:243] op_sel:[1,0,0]
	v_pk_fma_f32 v[244:245], v[236:237], v[132:133], v[244:245] op_sel:[1,0,0]
	ds_read_b128 v[230:233], v32 offset:17152
	ds_read_b128 v[234:237], v32 offset:17168
	global_store_dwordx4 v246, v[242:245], s[100:101] nt
	global_load_dwordx4 v[166:169], v246, s[98:99] nt
	s_add_u32 s100, s100, 0x2000
	s_addc_u32 s101, s101, 0
	s_add_u32 s98, s98, 0x2000
	s_addc_u32 s99, s99, 0
	s_waitcnt vmcnt(21)
	s_waitcnt lgkmcnt(2)
	v_pk_fma_f32 v[0:1], v[170:171], v[222:223], v[0:1] op_sel_hi:[1,0,1]
	v_pk_fma_f32 v[2:3], v[172:173], v[222:223], v[2:3] op_sel_hi:[1,0,1]
	v_pk_fma_f32 v[4:5], v[170:171], v[222:223], v[4:5] op_sel:[0,1,0]
	v_pk_fma_f32 v[6:7], v[172:173], v[222:223], v[6:7] op_sel:[0,1,0]
	v_pk_fma_f32 v[8:9], v[170:171], v[224:225], v[8:9] op_sel_hi:[1,0,1]
	v_pk_fma_f32 v[10:11], v[172:173], v[224:225], v[10:11] op_sel_hi:[1,0,1]
	v_pk_fma_f32 v[12:13], v[170:171], v[224:225], v[12:13] op_sel:[0,1,0]
	v_pk_fma_f32 v[14:15], v[172:173], v[224:225], v[14:15] op_sel:[0,1,0]
	v_pk_fma_f32 v[16:17], v[170:171], v[226:227], v[16:17] op_sel_hi:[1,0,1]
	v_pk_fma_f32 v[18:19], v[172:173], v[226:227], v[18:19] op_sel_hi:[1,0,1]
	v_pk_fma_f32 v[20:21], v[170:171], v[226:227], v[20:21] op_sel:[0,1,0]
	v_pk_fma_f32 v[22:23], v[172:173], v[226:227], v[22:23] op_sel:[0,1,0]
	v_pk_fma_f32 v[24:25], v[170:171], v[228:229], v[24:25] op_sel_hi:[1,0,1]
	v_pk_fma_f32 v[26:27], v[172:173], v[228:229], v[26:27] op_sel_hi:[1,0,1]
	v_pk_fma_f32 v[28:29], v[170:171], v[228:229], v[28:29] op_sel:[0,1,0]
	v_pk_fma_f32 v[30:31], v[172:173], v[228:229], v[30:31] op_sel:[0,1,0]
	ds_read_b128 v[222:225], v32 offset:896
	ds_read_b128 v[226:229], v32 offset:912
	s_waitcnt lgkmcnt(2)
	v_pk_mul_f32 v[238:239], v[230:231], v[102:103] op_sel_hi:[0,1]
	v_pk_mul_f32 v[240:241], v[230:231], v[110:111] op_sel_hi:[0,1]
	v_pk_fma_f32 v[238:239], v[86:87], v[170:171], v[238:239]
	v_pk_fma_f32 v[240:241], v[86:87], v[172:173], v[240:241]
	v_pk_fma_f32 v[238:239], v[234:235], v[118:119], v[238:239] op_sel_hi:[0,1,1]
	v_pk_fma_f32 v[240:241], v[234:235], v[126:127], v[240:241] op_sel_hi:[0,1,1]
	v_pk_fma_f32 v[238:239], v[230:231], v[104:105], v[238:239] op_sel:[1,0,0]
	v_pk_fma_f32 v[240:241], v[230:231], v[112:113], v[240:241] op_sel:[1,0,0]
	v_pk_fma_f32 v[238:239], v[234:235], v[120:121], v[238:239] op_sel:[1,0,0]
	v_pk_fma_f32 v[240:241], v[234:235], v[128:129], v[240:241] op_sel:[1,0,0]
	v_pk_fma_f32 v[238:239], v[232:233], v[106:107], v[238:239] op_sel_hi:[0,1,1]
	v_pk_fma_f32 v[240:241], v[232:233], v[114:115], v[240:241] op_sel_hi:[0,1,1]
	v_pk_fma_f32 v[238:239], v[236:237], v[122:123], v[238:239] op_sel_hi:[0,1,1]
	v_pk_fma_f32 v[240:241], v[236:237], v[130:131], v[240:241] op_sel_hi:[0,1,1]
	v_pk_fma_f32 v[238:239], v[232:233], v[108:109], v[238:239] op_sel:[1,0,0]
	v_pk_fma_f32 v[240:241], v[232:233], v[116:117], v[240:241] op_sel:[1,0,0]
	v_pk_fma_f32 v[238:239], v[236:237], v[124:125], v[238:239] op_sel:[1,0,0]
	v_pk_fma_f32 v[240:241], v[236:237], v[132:133], v[240:241] op_sel:[1,0,0]
	ds_read_b128 v[230:233], v32 offset:17280
	ds_read_b128 v[234:237], v32 offset:17296
	global_store_dwordx4 v246, v[238:241], s[100:101] nt
	global_load_dwordx4 v[170:173], v246, s[98:99] nt
	s_add_u32 s100, s100, 0x2000
	s_addc_u32 s101, s101, 0
	s_add_u32 s98, s98, 0x2000
	s_addc_u32 s99, s99, 0
	s_waitcnt vmcnt(22)
	s_waitcnt lgkmcnt(2)
	v_pk_fma_f32 v[0:1], v[174:175], v[222:223], v[0:1] op_sel_hi:[1,0,1]
	v_pk_fma_f32 v[2:3], v[176:177], v[222:223], v[2:3] op_sel_hi:[1,0,1]
	v_pk_fma_f32 v[4:5], v[174:175], v[222:223], v[4:5] op_sel:[0,1,0]
	v_pk_fma_f32 v[6:7], v[176:177], v[222:223], v[6:7] op_sel:[0,1,0]
	v_pk_fma_f32 v[8:9], v[174:175], v[224:225], v[8:9] op_sel_hi:[1,0,1]
	v_pk_fma_f32 v[10:11], v[176:177], v[224:225], v[10:11] op_sel_hi:[1,0,1]
	v_pk_fma_f32 v[12:13], v[174:175], v[224:225], v[12:13] op_sel:[0,1,0]
	v_pk_fma_f32 v[14:15], v[176:177], v[224:225], v[14:15] op_sel:[0,1,0]
	v_pk_fma_f32 v[16:17], v[174:175], v[226:227], v[16:17] op_sel_hi:[1,0,1]
	v_pk_fma_f32 v[18:19], v[176:177], v[226:227], v[18:19] op_sel_hi:[1,0,1]
	v_pk_fma_f32 v[20:21], v[174:175], v[226:227], v[20:21] op_sel:[0,1,0]
	v_pk_fma_f32 v[22:23], v[176:177], v[226:227], v[22:23] op_sel:[0,1,0]
	v_pk_fma_f32 v[24:25], v[174:175], v[228:229], v[24:25] op_sel_hi:[1,0,1]
	v_pk_fma_f32 v[26:27], v[176:177], v[228:229], v[26:27] op_sel_hi:[1,0,1]
	v_pk_fma_f32 v[28:29], v[174:175], v[228:229], v[28:29] op_sel:[0,1,0]
	v_pk_fma_f32 v[30:31], v[176:177], v[228:229], v[30:31] op_sel:[0,1,0]
	ds_read_b128 v[222:225], v32 offset:1024
	ds_read_b128 v[226:229], v32 offset:1040
	s_waitcnt lgkmcnt(2)
	v_pk_mul_f32 v[242:243], v[230:231], v[102:103] op_sel_hi:[0,1]
	v_pk_mul_f32 v[244:245], v[230:231], v[110:111] op_sel_hi:[0,1]
	v_pk_fma_f32 v[242:243], v[86:87], v[174:175], v[242:243]
	v_pk_fma_f32 v[244:245], v[86:87], v[176:177], v[244:245]
	v_pk_fma_f32 v[242:243], v[234:235], v[118:119], v[242:243] op_sel_hi:[0,1,1]
	v_pk_fma_f32 v[244:245], v[234:235], v[126:127], v[244:245] op_sel_hi:[0,1,1]
	v_pk_fma_f32 v[242:243], v[230:231], v[104:105], v[242:243] op_sel:[1,0,0]
	v_pk_fma_f32 v[244:245], v[230:231], v[112:113], v[244:245] op_sel:[1,0,0]
	v_pk_fma_f32 v[242:243], v[234:235], v[120:121], v[242:243] op_sel:[1,0,0]
	v_pk_fma_f32 v[244:245], v[234:235], v[128:129], v[244:245] op_sel:[1,0,0]
	v_pk_fma_f32 v[242:243], v[232:233], v[106:107], v[242:243] op_sel_hi:[0,1,1]
	v_pk_fma_f32 v[244:245], v[232:233], v[114:115], v[244:245] op_sel_hi:[0,1,1]
	v_pk_fma_f32 v[242:243], v[236:237], v[122:123], v[242:243] op_sel_hi:[0,1,1]
	v_pk_fma_f32 v[244:245], v[236:237], v[130:131], v[244:245] op_sel_hi:[0,1,1]
	v_pk_fma_f32 v[242:243], v[232:233], v[108:109], v[242:243] op_sel:[1,0,0]
	v_pk_fma_f32 v[244:245], v[232:233], v[116:117], v[244:245] op_sel:[1,0,0]
	v_pk_fma_f32 v[242:243], v[236:237], v[124:125], v[242:243] op_sel:[1,0,0]
	v_pk_fma_f32 v[244:245], v[236:237], v[132:133], v[244:245] op_sel:[1,0,0]
	ds_read_b128 v[230:233], v32 offset:17408
	ds_read_b128 v[234:237], v32 offset:17424
	global_store_dwordx4 v246, v[242:245], s[100:101] nt
	global_load_dwordx4 v[174:177], v246, s[98:99] nt
	s_add_u32 s100, s100, 0x2000
	s_addc_u32 s101, s101, 0
	s_add_u32 s98, s98, 0x2000
	s_addc_u32 s99, s99, 0
	s_waitcnt vmcnt(23)
	s_waitcnt lgkmcnt(2)
	v_pk_fma_f32 v[0:1], v[178:179], v[222:223], v[0:1] op_sel_hi:[1,0,1]
	v_pk_fma_f32 v[2:3], v[180:181], v[222:223], v[2:3] op_sel_hi:[1,0,1]
	v_pk_fma_f32 v[4:5], v[178:179], v[222:223], v[4:5] op_sel:[0,1,0]
	v_pk_fma_f32 v[6:7], v[180:181], v[222:223], v[6:7] op_sel:[0,1,0]
	v_pk_fma_f32 v[8:9], v[178:179], v[224:225], v[8:9] op_sel_hi:[1,0,1]
	v_pk_fma_f32 v[10:11], v[180:181], v[224:225], v[10:11] op_sel_hi:[1,0,1]
	v_pk_fma_f32 v[12:13], v[178:179], v[224:225], v[12:13] op_sel:[0,1,0]
	v_pk_fma_f32 v[14:15], v[180:181], v[224:225], v[14:15] op_sel:[0,1,0]
	v_pk_fma_f32 v[16:17], v[178:179], v[226:227], v[16:17] op_sel_hi:[1,0,1]
	v_pk_fma_f32 v[18:19], v[180:181], v[226:227], v[18:19] op_sel_hi:[1,0,1]
	v_pk_fma_f32 v[20:21], v[178:179], v[226:227], v[20:21] op_sel:[0,1,0]
	v_pk_fma_f32 v[22:23], v[180:181], v[226:227], v[22:23] op_sel:[0,1,0]
	v_pk_fma_f32 v[24:25], v[178:179], v[228:229], v[24:25] op_sel_hi:[1,0,1]
	v_pk_fma_f32 v[26:27], v[180:181], v[228:229], v[26:27] op_sel_hi:[1,0,1]
	v_pk_fma_f32 v[28:29], v[178:179], v[228:229], v[28:29] op_sel:[0,1,0]
	v_pk_fma_f32 v[30:31], v[180:181], v[228:229], v[30:31] op_sel:[0,1,0]
	ds_read_b128 v[222:225], v32 offset:1152
	ds_read_b128 v[226:229], v32 offset:1168
	s_waitcnt lgkmcnt(2)
	v_pk_mul_f32 v[238:239], v[230:231], v[102:103] op_sel_hi:[0,1]
	v_pk_mul_f32 v[240:241], v[230:231], v[110:111] op_sel_hi:[0,1]
	v_pk_fma_f32 v[238:239], v[86:87], v[178:179], v[238:239]
	v_pk_fma_f32 v[240:241], v[86:87], v[180:181], v[240:241]
	v_pk_fma_f32 v[238:239], v[234:235], v[118:119], v[238:239] op_sel_hi:[0,1,1]
	v_pk_fma_f32 v[240:241], v[234:235], v[126:127], v[240:241] op_sel_hi:[0,1,1]
	v_pk_fma_f32 v[238:239], v[230:231], v[104:105], v[238:239] op_sel:[1,0,0]
	v_pk_fma_f32 v[240:241], v[230:231], v[112:113], v[240:241] op_sel:[1,0,0]
	v_pk_fma_f32 v[238:239], v[234:235], v[120:121], v[238:239] op_sel:[1,0,0]
	v_pk_fma_f32 v[240:241], v[234:235], v[128:129], v[240:241] op_sel:[1,0,0]
	v_pk_fma_f32 v[238:239], v[232:233], v[106:107], v[238:239] op_sel_hi:[0,1,1]
	v_pk_fma_f32 v[240:241], v[232:233], v[114:115], v[240:241] op_sel_hi:[0,1,1]
	v_pk_fma_f32 v[238:239], v[236:237], v[122:123], v[238:239] op_sel_hi:[0,1,1]
	v_pk_fma_f32 v[240:241], v[236:237], v[130:131], v[240:241] op_sel_hi:[0,1,1]
	v_pk_fma_f32 v[238:239], v[232:233], v[108:109], v[238:239] op_sel:[1,0,0]
	v_pk_fma_f32 v[240:241], v[232:233], v[116:117], v[240:241] op_sel:[1,0,0]
	v_pk_fma_f32 v[238:239], v[236:237], v[124:125], v[238:239] op_sel:[1,0,0]
	v_pk_fma_f32 v[240:241], v[236:237], v[132:133], v[240:241] op_sel:[1,0,0]
	ds_read_b128 v[230:233], v32 offset:17536
	ds_read_b128 v[234:237], v32 offset:17552
	global_store_dwordx4 v246, v[238:241], s[100:101] nt
	global_load_dwordx4 v[178:181], v246, s[98:99] nt
	s_add_u32 s100, s100, 0x2000
	s_addc_u32 s101, s101, 0
	s_add_u32 s98, s98, 0x2000
	s_addc_u32 s99, s99, 0
	s_waitcnt vmcnt(24)
	s_waitcnt lgkmcnt(2)
	v_pk_fma_f32 v[0:1], v[182:183], v[222:223], v[0:1] op_sel_hi:[1,0,1]
	v_pk_fma_f32 v[2:3], v[184:185], v[222:223], v[2:3] op_sel_hi:[1,0,1]
	v_pk_fma_f32 v[4:5], v[182:183], v[222:223], v[4:5] op_sel:[0,1,0]
	v_pk_fma_f32 v[6:7], v[184:185], v[222:223], v[6:7] op_sel:[0,1,0]
	v_pk_fma_f32 v[8:9], v[182:183], v[224:225], v[8:9] op_sel_hi:[1,0,1]
	v_pk_fma_f32 v[10:11], v[184:185], v[224:225], v[10:11] op_sel_hi:[1,0,1]
	v_pk_fma_f32 v[12:13], v[182:183], v[224:225], v[12:13] op_sel:[0,1,0]
	v_pk_fma_f32 v[14:15], v[184:185], v[224:225], v[14:15] op_sel:[0,1,0]
	v_pk_fma_f32 v[16:17], v[182:183], v[226:227], v[16:17] op_sel_hi:[1,0,1]
	v_pk_fma_f32 v[18:19], v[184:185], v[226:227], v[18:19] op_sel_hi:[1,0,1]
	v_pk_fma_f32 v[20:21], v[182:183], v[226:227], v[20:21] op_sel:[0,1,0]
	v_pk_fma_f32 v[22:23], v[184:185], v[226:227], v[22:23] op_sel:[0,1,0]
	v_pk_fma_f32 v[24:25], v[182:183], v[228:229], v[24:25] op_sel_hi:[1,0,1]
	v_pk_fma_f32 v[26:27], v[184:185], v[228:229], v[26:27] op_sel_hi:[1,0,1]
	v_pk_fma_f32 v[28:29], v[182:183], v[228:229], v[28:29] op_sel:[0,1,0]
	v_pk_fma_f32 v[30:31], v[184:185], v[228:229], v[30:31] op_sel:[0,1,0]
	ds_read_b128 v[222:225], v32 offset:1280
	ds_read_b128 v[226:229], v32 offset:1296
	s_waitcnt lgkmcnt(2)
	v_pk_mul_f32 v[242:243], v[230:231], v[102:103] op_sel_hi:[0,1]
	v_pk_mul_f32 v[244:245], v[230:231], v[110:111] op_sel_hi:[0,1]
	v_pk_fma_f32 v[242:243], v[86:87], v[182:183], v[242:243]
	v_pk_fma_f32 v[244:245], v[86:87], v[184:185], v[244:245]
	v_pk_fma_f32 v[242:243], v[234:235], v[118:119], v[242:243] op_sel_hi:[0,1,1]
	v_pk_fma_f32 v[244:245], v[234:235], v[126:127], v[244:245] op_sel_hi:[0,1,1]
	v_pk_fma_f32 v[242:243], v[230:231], v[104:105], v[242:243] op_sel:[1,0,0]
	v_pk_fma_f32 v[244:245], v[230:231], v[112:113], v[244:245] op_sel:[1,0,0]
	v_pk_fma_f32 v[242:243], v[234:235], v[120:121], v[242:243] op_sel:[1,0,0]
	v_pk_fma_f32 v[244:245], v[234:235], v[128:129], v[244:245] op_sel:[1,0,0]
	v_pk_fma_f32 v[242:243], v[232:233], v[106:107], v[242:243] op_sel_hi:[0,1,1]
	v_pk_fma_f32 v[244:245], v[232:233], v[114:115], v[244:245] op_sel_hi:[0,1,1]
	v_pk_fma_f32 v[242:243], v[236:237], v[122:123], v[242:243] op_sel_hi:[0,1,1]
	v_pk_fma_f32 v[244:245], v[236:237], v[130:131], v[244:245] op_sel_hi:[0,1,1]
	v_pk_fma_f32 v[242:243], v[232:233], v[108:109], v[242:243] op_sel:[1,0,0]
	v_pk_fma_f32 v[244:245], v[232:233], v[116:117], v[244:245] op_sel:[1,0,0]
	v_pk_fma_f32 v[242:243], v[236:237], v[124:125], v[242:243] op_sel:[1,0,0]
	v_pk_fma_f32 v[244:245], v[236:237], v[132:133], v[244:245] op_sel:[1,0,0]
	ds_read_b128 v[230:233], v32 offset:17664
	ds_read_b128 v[234:237], v32 offset:17680
	global_store_dwordx4 v246, v[242:245], s[100:101] nt
	global_load_dwordx4 v[182:185], v246, s[98:99] nt
	s_add_u32 s100, s100, 0x2000
	s_addc_u32 s101, s101, 0
	s_add_u32 s98, s98, 0x2000
	s_addc_u32 s99, s99, 0
	s_waitcnt vmcnt(25)
	s_waitcnt lgkmcnt(2)
	v_pk_fma_f32 v[0:1], v[186:187], v[222:223], v[0:1] op_sel_hi:[1,0,1]
	v_pk_fma_f32 v[2:3], v[188:189], v[222:223], v[2:3] op_sel_hi:[1,0,1]
	v_pk_fma_f32 v[4:5], v[186:187], v[222:223], v[4:5] op_sel:[0,1,0]
	v_pk_fma_f32 v[6:7], v[188:189], v[222:223], v[6:7] op_sel:[0,1,0]
	v_pk_fma_f32 v[8:9], v[186:187], v[224:225], v[8:9] op_sel_hi:[1,0,1]
	v_pk_fma_f32 v[10:11], v[188:189], v[224:225], v[10:11] op_sel_hi:[1,0,1]
	v_pk_fma_f32 v[12:13], v[186:187], v[224:225], v[12:13] op_sel:[0,1,0]
	v_pk_fma_f32 v[14:15], v[188:189], v[224:225], v[14:15] op_sel:[0,1,0]
	v_pk_fma_f32 v[16:17], v[186:187], v[226:227], v[16:17] op_sel_hi:[1,0,1]
	v_pk_fma_f32 v[18:19], v[188:189], v[226:227], v[18:19] op_sel_hi:[1,0,1]
	v_pk_fma_f32 v[20:21], v[186:187], v[226:227], v[20:21] op_sel:[0,1,0]
	v_pk_fma_f32 v[22:23], v[188:189], v[226:227], v[22:23] op_sel:[0,1,0]
	v_pk_fma_f32 v[24:25], v[186:187], v[228:229], v[24:25] op_sel_hi:[1,0,1]
	v_pk_fma_f32 v[26:27], v[188:189], v[228:229], v[26:27] op_sel_hi:[1,0,1]
	v_pk_fma_f32 v[28:29], v[186:187], v[228:229], v[28:29] op_sel:[0,1,0]
	v_pk_fma_f32 v[30:31], v[188:189], v[228:229], v[30:31] op_sel:[0,1,0]
	ds_read_b128 v[222:225], v32 offset:1408
	ds_read_b128 v[226:229], v32 offset:1424
	s_waitcnt lgkmcnt(2)
	v_pk_mul_f32 v[238:239], v[230:231], v[102:103] op_sel_hi:[0,1]
	v_pk_mul_f32 v[240:241], v[230:231], v[110:111] op_sel_hi:[0,1]
	v_pk_fma_f32 v[238:239], v[86:87], v[186:187], v[238:239]
	v_pk_fma_f32 v[240:241], v[86:87], v[188:189], v[240:241]
	v_pk_fma_f32 v[238:239], v[234:235], v[118:119], v[238:239] op_sel_hi:[0,1,1]
	v_pk_fma_f32 v[240:241], v[234:235], v[126:127], v[240:241] op_sel_hi:[0,1,1]
	v_pk_fma_f32 v[238:239], v[230:231], v[104:105], v[238:239] op_sel:[1,0,0]
	v_pk_fma_f32 v[240:241], v[230:231], v[112:113], v[240:241] op_sel:[1,0,0]
	v_pk_fma_f32 v[238:239], v[234:235], v[120:121], v[238:239] op_sel:[1,0,0]
	v_pk_fma_f32 v[240:241], v[234:235], v[128:129], v[240:241] op_sel:[1,0,0]
	v_pk_fma_f32 v[238:239], v[232:233], v[106:107], v[238:239] op_sel_hi:[0,1,1]
	v_pk_fma_f32 v[240:241], v[232:233], v[114:115], v[240:241] op_sel_hi:[0,1,1]
	v_pk_fma_f32 v[238:239], v[236:237], v[122:123], v[238:239] op_sel_hi:[0,1,1]
	v_pk_fma_f32 v[240:241], v[236:237], v[130:131], v[240:241] op_sel_hi:[0,1,1]
	v_pk_fma_f32 v[238:239], v[232:233], v[108:109], v[238:239] op_sel:[1,0,0]
	v_pk_fma_f32 v[240:241], v[232:233], v[116:117], v[240:241] op_sel:[1,0,0]
	v_pk_fma_f32 v[238:239], v[236:237], v[124:125], v[238:239] op_sel:[1,0,0]
	v_pk_fma_f32 v[240:241], v[236:237], v[132:133], v[240:241] op_sel:[1,0,0]
	ds_read_b128 v[230:233], v32 offset:17792
	ds_read_b128 v[234:237], v32 offset:17808
	global_store_dwordx4 v246, v[238:241], s[100:101] nt
	global_load_dwordx4 v[186:189], v246, s[98:99] nt
	s_add_u32 s100, s100, 0x2000
	s_addc_u32 s101, s101, 0
	s_add_u32 s98, s98, 0x2000
	s_addc_u32 s99, s99, 0
	s_waitcnt vmcnt(26)
	s_waitcnt lgkmcnt(2)
	v_pk_fma_f32 v[0:1], v[190:191], v[222:223], v[0:1] op_sel_hi:[1,0,1]
	v_pk_fma_f32 v[2:3], v[192:193], v[222:223], v[2:3] op_sel_hi:[1,0,1]
	v_pk_fma_f32 v[4:5], v[190:191], v[222:223], v[4:5] op_sel:[0,1,0]
	v_pk_fma_f32 v[6:7], v[192:193], v[222:223], v[6:7] op_sel:[0,1,0]
	v_pk_fma_f32 v[8:9], v[190:191], v[224:225], v[8:9] op_sel_hi:[1,0,1]
	v_pk_fma_f32 v[10:11], v[192:193], v[224:225], v[10:11] op_sel_hi:[1,0,1]
	v_pk_fma_f32 v[12:13], v[190:191], v[224:225], v[12:13] op_sel:[0,1,0]
	v_pk_fma_f32 v[14:15], v[192:193], v[224:225], v[14:15] op_sel:[0,1,0]
	v_pk_fma_f32 v[16:17], v[190:191], v[226:227], v[16:17] op_sel_hi:[1,0,1]
	v_pk_fma_f32 v[18:19], v[192:193], v[226:227], v[18:19] op_sel_hi:[1,0,1]
	v_pk_fma_f32 v[20:21], v[190:191], v[226:227], v[20:21] op_sel:[0,1,0]
	v_pk_fma_f32 v[22:23], v[192:193], v[226:227], v[22:23] op_sel:[0,1,0]
	v_pk_fma_f32 v[24:25], v[190:191], v[228:229], v[24:25] op_sel_hi:[1,0,1]
	v_pk_fma_f32 v[26:27], v[192:193], v[228:229], v[26:27] op_sel_hi:[1,0,1]
	v_pk_fma_f32 v[28:29], v[190:191], v[228:229], v[28:29] op_sel:[0,1,0]
	v_pk_fma_f32 v[30:31], v[192:193], v[228:229], v[30:31] op_sel:[0,1,0]
	ds_read_b128 v[222:225], v32 offset:1536
	ds_read_b128 v[226:229], v32 offset:1552
	s_waitcnt lgkmcnt(2)
	v_pk_mul_f32 v[242:243], v[230:231], v[102:103] op_sel_hi:[0,1]
	v_pk_mul_f32 v[244:245], v[230:231], v[110:111] op_sel_hi:[0,1]
	v_pk_fma_f32 v[242:243], v[86:87], v[190:191], v[242:243]
	v_pk_fma_f32 v[244:245], v[86:87], v[192:193], v[244:245]
	v_pk_fma_f32 v[242:243], v[234:235], v[118:119], v[242:243] op_sel_hi:[0,1,1]
	v_pk_fma_f32 v[244:245], v[234:235], v[126:127], v[244:245] op_sel_hi:[0,1,1]
	v_pk_fma_f32 v[242:243], v[230:231], v[104:105], v[242:243] op_sel:[1,0,0]
	v_pk_fma_f32 v[244:245], v[230:231], v[112:113], v[244:245] op_sel:[1,0,0]
	v_pk_fma_f32 v[242:243], v[234:235], v[120:121], v[242:243] op_sel:[1,0,0]
	v_pk_fma_f32 v[244:245], v[234:235], v[128:129], v[244:245] op_sel:[1,0,0]
	v_pk_fma_f32 v[242:243], v[232:233], v[106:107], v[242:243] op_sel_hi:[0,1,1]
	v_pk_fma_f32 v[244:245], v[232:233], v[114:115], v[244:245] op_sel_hi:[0,1,1]
	v_pk_fma_f32 v[242:243], v[236:237], v[122:123], v[242:243] op_sel_hi:[0,1,1]
	v_pk_fma_f32 v[244:245], v[236:237], v[130:131], v[244:245] op_sel_hi:[0,1,1]
	v_pk_fma_f32 v[242:243], v[232:233], v[108:109], v[242:243] op_sel:[1,0,0]
	v_pk_fma_f32 v[244:245], v[232:233], v[116:117], v[244:245] op_sel:[1,0,0]
	v_pk_fma_f32 v[242:243], v[236:237], v[124:125], v[242:243] op_sel:[1,0,0]
	v_pk_fma_f32 v[244:245], v[236:237], v[132:133], v[244:245] op_sel:[1,0,0]
	ds_read_b128 v[230:233], v32 offset:17920
	ds_read_b128 v[234:237], v32 offset:17936
	global_store_dwordx4 v246, v[242:245], s[100:101] nt
	global_load_dwordx4 v[190:193], v246, s[98:99] nt
	s_add_u32 s100, s100, 0x2000
	s_addc_u32 s101, s101, 0
	s_add_u32 s98, s98, 0x2000
	s_addc_u32 s99, s99, 0
	s_waitcnt vmcnt(27)
	s_waitcnt lgkmcnt(2)
	v_pk_fma_f32 v[0:1], v[194:195], v[222:223], v[0:1] op_sel_hi:[1,0,1]
	v_pk_fma_f32 v[2:3], v[196:197], v[222:223], v[2:3] op_sel_hi:[1,0,1]
	v_pk_fma_f32 v[4:5], v[194:195], v[222:223], v[4:5] op_sel:[0,1,0]
	v_pk_fma_f32 v[6:7], v[196:197], v[222:223], v[6:7] op_sel:[0,1,0]
	v_pk_fma_f32 v[8:9], v[194:195], v[224:225], v[8:9] op_sel_hi:[1,0,1]
	v_pk_fma_f32 v[10:11], v[196:197], v[224:225], v[10:11] op_sel_hi:[1,0,1]
	v_pk_fma_f32 v[12:13], v[194:195], v[224:225], v[12:13] op_sel:[0,1,0]
	v_pk_fma_f32 v[14:15], v[196:197], v[224:225], v[14:15] op_sel:[0,1,0]
	v_pk_fma_f32 v[16:17], v[194:195], v[226:227], v[16:17] op_sel_hi:[1,0,1]
	v_pk_fma_f32 v[18:19], v[196:197], v[226:227], v[18:19] op_sel_hi:[1,0,1]
	v_pk_fma_f32 v[20:21], v[194:195], v[226:227], v[20:21] op_sel:[0,1,0]
	v_pk_fma_f32 v[22:23], v[196:197], v[226:227], v[22:23] op_sel:[0,1,0]
	v_pk_fma_f32 v[24:25], v[194:195], v[228:229], v[24:25] op_sel_hi:[1,0,1]
	v_pk_fma_f32 v[26:27], v[196:197], v[228:229], v[26:27] op_sel_hi:[1,0,1]
	v_pk_fma_f32 v[28:29], v[194:195], v[228:229], v[28:29] op_sel:[0,1,0]
	v_pk_fma_f32 v[30:31], v[196:197], v[228:229], v[30:31] op_sel:[0,1,0]
	ds_read_b128 v[222:225], v32 offset:1664
	ds_read_b128 v[226:229], v32 offset:1680
	s_waitcnt lgkmcnt(2)
	v_pk_mul_f32 v[238:239], v[230:231], v[102:103] op_sel_hi:[0,1]
	v_pk_mul_f32 v[240:241], v[230:231], v[110:111] op_sel_hi:[0,1]
	v_pk_fma_f32 v[238:239], v[86:87], v[194:195], v[238:239]
	v_pk_fma_f32 v[240:241], v[86:87], v[196:197], v[240:241]
	v_pk_fma_f32 v[238:239], v[234:235], v[118:119], v[238:239] op_sel_hi:[0,1,1]
	v_pk_fma_f32 v[240:241], v[234:235], v[126:127], v[240:241] op_sel_hi:[0,1,1]
	v_pk_fma_f32 v[238:239], v[230:231], v[104:105], v[238:239] op_sel:[1,0,0]
	v_pk_fma_f32 v[240:241], v[230:231], v[112:113], v[240:241] op_sel:[1,0,0]
	v_pk_fma_f32 v[238:239], v[234:235], v[120:121], v[238:239] op_sel:[1,0,0]
	v_pk_fma_f32 v[240:241], v[234:235], v[128:129], v[240:241] op_sel:[1,0,0]
	v_pk_fma_f32 v[238:239], v[232:233], v[106:107], v[238:239] op_sel_hi:[0,1,1]
	v_pk_fma_f32 v[240:241], v[232:233], v[114:115], v[240:241] op_sel_hi:[0,1,1]
	v_pk_fma_f32 v[238:239], v[236:237], v[122:123], v[238:239] op_sel_hi:[0,1,1]
	v_pk_fma_f32 v[240:241], v[236:237], v[130:131], v[240:241] op_sel_hi:[0,1,1]
	v_pk_fma_f32 v[238:239], v[232:233], v[108:109], v[238:239] op_sel:[1,0,0]
	v_pk_fma_f32 v[240:241], v[232:233], v[116:117], v[240:241] op_sel:[1,0,0]
	v_pk_fma_f32 v[238:239], v[236:237], v[124:125], v[238:239] op_sel:[1,0,0]
	v_pk_fma_f32 v[240:241], v[236:237], v[132:133], v[240:241] op_sel:[1,0,0]
	ds_read_b128 v[230:233], v32 offset:18048
	ds_read_b128 v[234:237], v32 offset:18064
	global_store_dwordx4 v246, v[238:241], s[100:101] nt
	global_load_dwordx4 v[194:197], v246, s[98:99] nt
	s_add_u32 s100, s100, 0x2000
	s_addc_u32 s101, s101, 0
	s_add_u32 s98, s98, 0x2000
	s_addc_u32 s99, s99, 0
	s_waitcnt vmcnt(28)
	s_waitcnt lgkmcnt(2)
	v_pk_fma_f32 v[0:1], v[210:211], v[222:223], v[0:1] op_sel_hi:[1,0,1]
	v_pk_fma_f32 v[2:3], v[212:213], v[222:223], v[2:3] op_sel_hi:[1,0,1]
	v_pk_fma_f32 v[4:5], v[210:211], v[222:223], v[4:5] op_sel:[0,1,0]
	v_pk_fma_f32 v[6:7], v[212:213], v[222:223], v[6:7] op_sel:[0,1,0]
	v_pk_fma_f32 v[8:9], v[210:211], v[224:225], v[8:9] op_sel_hi:[1,0,1]
	v_pk_fma_f32 v[10:11], v[212:213], v[224:225], v[10:11] op_sel_hi:[1,0,1]
	v_pk_fma_f32 v[12:13], v[210:211], v[224:225], v[12:13] op_sel:[0,1,0]
	v_pk_fma_f32 v[14:15], v[212:213], v[224:225], v[14:15] op_sel:[0,1,0]
	v_pk_fma_f32 v[16:17], v[210:211], v[226:227], v[16:17] op_sel_hi:[1,0,1]
	v_pk_fma_f32 v[18:19], v[212:213], v[226:227], v[18:19] op_sel_hi:[1,0,1]
	v_pk_fma_f32 v[20:21], v[210:211], v[226:227], v[20:21] op_sel:[0,1,0]
	v_pk_fma_f32 v[22:23], v[212:213], v[226:227], v[22:23] op_sel:[0,1,0]
	v_pk_fma_f32 v[24:25], v[210:211], v[228:229], v[24:25] op_sel_hi:[1,0,1]
	v_pk_fma_f32 v[26:27], v[212:213], v[228:229], v[26:27] op_sel_hi:[1,0,1]
	v_pk_fma_f32 v[28:29], v[210:211], v[228:229], v[28:29] op_sel:[0,1,0]
	v_pk_fma_f32 v[30:31], v[212:213], v[228:229], v[30:31] op_sel:[0,1,0]
	ds_read_b128 v[222:225], v32 offset:1792
	ds_read_b128 v[226:229], v32 offset:1808
	s_waitcnt lgkmcnt(2)
	v_pk_mul_f32 v[242:243], v[230:231], v[102:103] op_sel_hi:[0,1]
	v_pk_mul_f32 v[244:245], v[230:231], v[110:111] op_sel_hi:[0,1]
	v_pk_fma_f32 v[242:243], v[86:87], v[210:211], v[242:243]
	v_pk_fma_f32 v[244:245], v[86:87], v[212:213], v[244:245]
	v_pk_fma_f32 v[242:243], v[234:235], v[118:119], v[242:243] op_sel_hi:[0,1,1]
	v_pk_fma_f32 v[244:245], v[234:235], v[126:127], v[244:245] op_sel_hi:[0,1,1]
	v_pk_fma_f32 v[242:243], v[230:231], v[104:105], v[242:243] op_sel:[1,0,0]
	v_pk_fma_f32 v[244:245], v[230:231], v[112:113], v[244:245] op_sel:[1,0,0]
	v_pk_fma_f32 v[242:243], v[234:235], v[120:121], v[242:243] op_sel:[1,0,0]
	v_pk_fma_f32 v[244:245], v[234:235], v[128:129], v[244:245] op_sel:[1,0,0]
	v_pk_fma_f32 v[242:243], v[232:233], v[106:107], v[242:243] op_sel_hi:[0,1,1]
	v_pk_fma_f32 v[244:245], v[232:233], v[114:115], v[244:245] op_sel_hi:[0,1,1]
	v_pk_fma_f32 v[242:243], v[236:237], v[122:123], v[242:243] op_sel_hi:[0,1,1]
	v_pk_fma_f32 v[244:245], v[236:237], v[130:131], v[244:245] op_sel_hi:[0,1,1]
	v_pk_fma_f32 v[242:243], v[232:233], v[108:109], v[242:243] op_sel:[1,0,0]
	v_pk_fma_f32 v[244:245], v[232:233], v[116:117], v[244:245] op_sel:[1,0,0]
	v_pk_fma_f32 v[242:243], v[236:237], v[124:125], v[242:243] op_sel:[1,0,0]
	v_pk_fma_f32 v[244:245], v[236:237], v[132:133], v[244:245] op_sel:[1,0,0]
	ds_read_b128 v[230:233], v32 offset:18176
	ds_read_b128 v[234:237], v32 offset:18192
	global_store_dwordx4 v246, v[242:245], s[100:101] nt
	global_load_dwordx4 v[210:213], v246, s[98:99] nt
	s_add_u32 s100, s100, 0x2000
	s_addc_u32 s101, s101, 0
	s_add_u32 s98, s98, 0x2000
	s_addc_u32 s99, s99, 0
	s_waitcnt vmcnt(29)
	s_waitcnt lgkmcnt(2)
	v_pk_fma_f32 v[0:1], v[214:215], v[222:223], v[0:1] op_sel_hi:[1,0,1]
	v_pk_fma_f32 v[2:3], v[216:217], v[222:223], v[2:3] op_sel_hi:[1,0,1]
	v_pk_fma_f32 v[4:5], v[214:215], v[222:223], v[4:5] op_sel:[0,1,0]
	v_pk_fma_f32 v[6:7], v[216:217], v[222:223], v[6:7] op_sel:[0,1,0]
	v_pk_fma_f32 v[8:9], v[214:215], v[224:225], v[8:9] op_sel_hi:[1,0,1]
	v_pk_fma_f32 v[10:11], v[216:217], v[224:225], v[10:11] op_sel_hi:[1,0,1]
	v_pk_fma_f32 v[12:13], v[214:215], v[224:225], v[12:13] op_sel:[0,1,0]
	v_pk_fma_f32 v[14:15], v[216:217], v[224:225], v[14:15] op_sel:[0,1,0]
	v_pk_fma_f32 v[16:17], v[214:215], v[226:227], v[16:17] op_sel_hi:[1,0,1]
	v_pk_fma_f32 v[18:19], v[216:217], v[226:227], v[18:19] op_sel_hi:[1,0,1]
	v_pk_fma_f32 v[20:21], v[214:215], v[226:227], v[20:21] op_sel:[0,1,0]
	v_pk_fma_f32 v[22:23], v[216:217], v[226:227], v[22:23] op_sel:[0,1,0]
	v_pk_fma_f32 v[24:25], v[214:215], v[228:229], v[24:25] op_sel_hi:[1,0,1]
	v_pk_fma_f32 v[26:27], v[216:217], v[228:229], v[26:27] op_sel_hi:[1,0,1]
	v_pk_fma_f32 v[28:29], v[214:215], v[228:229], v[28:29] op_sel:[0,1,0]
	v_pk_fma_f32 v[30:31], v[216:217], v[228:229], v[30:31] op_sel:[0,1,0]
	ds_read_b128 v[222:225], v32 offset:1920
	ds_read_b128 v[226:229], v32 offset:1936
	s_waitcnt lgkmcnt(2)
	v_pk_mul_f32 v[238:239], v[230:231], v[102:103] op_sel_hi:[0,1]
	v_pk_mul_f32 v[240:241], v[230:231], v[110:111] op_sel_hi:[0,1]
	v_pk_fma_f32 v[238:239], v[86:87], v[214:215], v[238:239]
	v_pk_fma_f32 v[240:241], v[86:87], v[216:217], v[240:241]
	v_pk_fma_f32 v[238:239], v[234:235], v[118:119], v[238:239] op_sel_hi:[0,1,1]
	v_pk_fma_f32 v[240:241], v[234:235], v[126:127], v[240:241] op_sel_hi:[0,1,1]
	v_pk_fma_f32 v[238:239], v[230:231], v[104:105], v[238:239] op_sel:[1,0,0]
	v_pk_fma_f32 v[240:241], v[230:231], v[112:113], v[240:241] op_sel:[1,0,0]
	v_pk_fma_f32 v[238:239], v[234:235], v[120:121], v[238:239] op_sel:[1,0,0]
	v_pk_fma_f32 v[240:241], v[234:235], v[128:129], v[240:241] op_sel:[1,0,0]
	v_pk_fma_f32 v[238:239], v[232:233], v[106:107], v[238:239] op_sel_hi:[0,1,1]
	v_pk_fma_f32 v[240:241], v[232:233], v[114:115], v[240:241] op_sel_hi:[0,1,1]
	v_pk_fma_f32 v[238:239], v[236:237], v[122:123], v[238:239] op_sel_hi:[0,1,1]
	v_pk_fma_f32 v[240:241], v[236:237], v[130:131], v[240:241] op_sel_hi:[0,1,1]
	v_pk_fma_f32 v[238:239], v[232:233], v[108:109], v[238:239] op_sel:[1,0,0]
	v_pk_fma_f32 v[240:241], v[232:233], v[116:117], v[240:241] op_sel:[1,0,0]
	v_pk_fma_f32 v[238:239], v[236:237], v[124:125], v[238:239] op_sel:[1,0,0]
	v_pk_fma_f32 v[240:241], v[236:237], v[132:133], v[240:241] op_sel:[1,0,0]
	ds_read_b128 v[230:233], v32 offset:18304
	ds_read_b128 v[234:237], v32 offset:18320
	global_store_dwordx4 v246, v[238:241], s[100:101] nt
	global_load_dwordx4 v[214:217], v246, s[98:99] nt
	s_add_u32 s100, s100, 0x2000
	s_addc_u32 s101, s101, 0
	s_add_u32 s98, s98, 0x2000
	s_addc_u32 s99, s99, 0
	s_waitcnt vmcnt(30)
	s_waitcnt lgkmcnt(2)
	v_pk_fma_f32 v[0:1], v[218:219], v[222:223], v[0:1] op_sel_hi:[1,0,1]
	v_pk_fma_f32 v[2:3], v[220:221], v[222:223], v[2:3] op_sel_hi:[1,0,1]
	v_pk_fma_f32 v[4:5], v[218:219], v[222:223], v[4:5] op_sel:[0,1,0]
	v_pk_fma_f32 v[6:7], v[220:221], v[222:223], v[6:7] op_sel:[0,1,0]
	v_pk_fma_f32 v[8:9], v[218:219], v[224:225], v[8:9] op_sel_hi:[1,0,1]
	v_pk_fma_f32 v[10:11], v[220:221], v[224:225], v[10:11] op_sel_hi:[1,0,1]
	v_pk_fma_f32 v[12:13], v[218:219], v[224:225], v[12:13] op_sel:[0,1,0]
	v_pk_fma_f32 v[14:15], v[220:221], v[224:225], v[14:15] op_sel:[0,1,0]
	v_pk_fma_f32 v[16:17], v[218:219], v[226:227], v[16:17] op_sel_hi:[1,0,1]
	v_pk_fma_f32 v[18:19], v[220:221], v[226:227], v[18:19] op_sel_hi:[1,0,1]
	v_pk_fma_f32 v[20:21], v[218:219], v[226:227], v[20:21] op_sel:[0,1,0]
	v_pk_fma_f32 v[22:23], v[220:221], v[226:227], v[22:23] op_sel:[0,1,0]
	v_pk_fma_f32 v[24:25], v[218:219], v[228:229], v[24:25] op_sel_hi:[1,0,1]
	v_pk_fma_f32 v[26:27], v[220:221], v[228:229], v[26:27] op_sel_hi:[1,0,1]
	v_pk_fma_f32 v[28:29], v[218:219], v[228:229], v[28:29] op_sel:[0,1,0]
	v_pk_fma_f32 v[30:31], v[220:221], v[228:229], v[30:31] op_sel:[0,1,0]
	ds_read_b128 v[222:225], v32 offset:2048
	ds_read_b128 v[226:229], v32 offset:2064
	s_waitcnt lgkmcnt(2)
	v_pk_mul_f32 v[242:243], v[230:231], v[102:103] op_sel_hi:[0,1]
	v_pk_mul_f32 v[244:245], v[230:231], v[110:111] op_sel_hi:[0,1]
	v_pk_fma_f32 v[242:243], v[86:87], v[218:219], v[242:243]
	v_pk_fma_f32 v[244:245], v[86:87], v[220:221], v[244:245]
	v_pk_fma_f32 v[242:243], v[234:235], v[118:119], v[242:243] op_sel_hi:[0,1,1]
	v_pk_fma_f32 v[244:245], v[234:235], v[126:127], v[244:245] op_sel_hi:[0,1,1]
	v_pk_fma_f32 v[242:243], v[230:231], v[104:105], v[242:243] op_sel:[1,0,0]
	v_pk_fma_f32 v[244:245], v[230:231], v[112:113], v[244:245] op_sel:[1,0,0]
	v_pk_fma_f32 v[242:243], v[234:235], v[120:121], v[242:243] op_sel:[1,0,0]
	v_pk_fma_f32 v[244:245], v[234:235], v[128:129], v[244:245] op_sel:[1,0,0]
	v_pk_fma_f32 v[242:243], v[232:233], v[106:107], v[242:243] op_sel_hi:[0,1,1]
	v_pk_fma_f32 v[244:245], v[232:233], v[114:115], v[244:245] op_sel_hi:[0,1,1]
	v_pk_fma_f32 v[242:243], v[236:237], v[122:123], v[242:243] op_sel_hi:[0,1,1]
	v_pk_fma_f32 v[244:245], v[236:237], v[130:131], v[244:245] op_sel_hi:[0,1,1]
	v_pk_fma_f32 v[242:243], v[232:233], v[108:109], v[242:243] op_sel:[1,0,0]
	v_pk_fma_f32 v[244:245], v[232:233], v[116:117], v[244:245] op_sel:[1,0,0]
	v_pk_fma_f32 v[242:243], v[236:237], v[124:125], v[242:243] op_sel:[1,0,0]
	v_pk_fma_f32 v[244:245], v[236:237], v[132:133], v[244:245] op_sel:[1,0,0]
	ds_read_b128 v[230:233], v32 offset:18432
	ds_read_b128 v[234:237], v32 offset:18448
	global_store_dwordx4 v246, v[242:245], s[100:101] nt
	global_load_dwordx4 v[218:221], v246, s[98:99] nt
	s_add_u32 s100, s100, 0x2000
	s_addc_u32 s101, s101, 0
	s_add_u32 s98, s98, 0x2000
	s_addc_u32 s99, s99, 0
	v_add_u32_e32 v32, 0x800, v32
.Lsstream_a_loop:
	s_waitcnt vmcnt(30)
	s_waitcnt lgkmcnt(2)
	v_pk_fma_f32 v[0:1], v[134:135], v[222:223], v[0:1] op_sel_hi:[1,0,1]
	v_pk_fma_f32 v[2:3], v[136:137], v[222:223], v[2:3] op_sel_hi:[1,0,1]
	v_pk_fma_f32 v[4:5], v[134:135], v[222:223], v[4:5] op_sel:[0,1,0]
	v_pk_fma_f32 v[6:7], v[136:137], v[222:223], v[6:7] op_sel:[0,1,0]
	v_pk_fma_f32 v[8:9], v[134:135], v[224:225], v[8:9] op_sel_hi:[1,0,1]
	v_pk_fma_f32 v[10:11], v[136:137], v[224:225], v[10:11] op_sel_hi:[1,0,1]
	v_pk_fma_f32 v[12:13], v[134:135], v[224:225], v[12:13] op_sel:[0,1,0]
	v_pk_fma_f32 v[14:15], v[136:137], v[224:225], v[14:15] op_sel:[0,1,0]
	v_pk_fma_f32 v[16:17], v[134:135], v[226:227], v[16:17] op_sel_hi:[1,0,1]
	v_pk_fma_f32 v[18:19], v[136:137], v[226:227], v[18:19] op_sel_hi:[1,0,1]
	v_pk_fma_f32 v[20:21], v[134:135], v[226:227], v[20:21] op_sel:[0,1,0]
	v_pk_fma_f32 v[22:23], v[136:137], v[226:227], v[22:23] op_sel:[0,1,0]
	v_pk_fma_f32 v[24:25], v[134:135], v[228:229], v[24:25] op_sel_hi:[1,0,1]
	v_pk_fma_f32 v[26:27], v[136:137], v[228:229], v[26:27] op_sel_hi:[1,0,1]
	v_pk_fma_f32 v[28:29], v[134:135], v[228:229], v[28:29] op_sel:[0,1,0]
	v_pk_fma_f32 v[30:31], v[136:137], v[228:229], v[30:31] op_sel:[0,1,0]
	ds_read_b128 v[222:225], v32 offset:128
	ds_read_b128 v[226:229], v32 offset:144
	s_waitcnt lgkmcnt(2)
	v_pk_mul_f32 v[238:239], v[230:231], v[102:103] op_sel_hi:[0,1]
	v_pk_mul_f32 v[240:241], v[230:231], v[110:111] op_sel_hi:[0,1]
	v_pk_fma_f32 v[238:239], v[86:87], v[134:135], v[238:239]
	v_pk_fma_f32 v[240:241], v[86:87], v[136:137], v[240:241]
	v_pk_fma_f32 v[238:239], v[234:235], v[118:119], v[238:239] op_sel_hi:[0,1,1]
	v_pk_fma_f32 v[240:241], v[234:235], v[126:127], v[240:241] op_sel_hi:[0,1,1]
	v_pk_fma_f32 v[238:239], v[230:231], v[104:105], v[238:239] op_sel:[1,0,0]
	v_pk_fma_f32 v[240:241], v[230:231], v[112:113], v[240:241] op_sel:[1,0,0]
	v_pk_fma_f32 v[238:239], v[234:235], v[120:121], v[238:239] op_sel:[1,0,0]
	v_pk_fma_f32 v[240:241], v[234:235], v[128:129], v[240:241] op_sel:[1,0,0]
	v_pk_fma_f32 v[238:239], v[232:233], v[106:107], v[238:239] op_sel_hi:[0,1,1]
	v_pk_fma_f32 v[240:241], v[232:233], v[114:115], v[240:241] op_sel_hi:[0,1,1]
	v_pk_fma_f32 v[238:239], v[236:237], v[122:123], v[238:239] op_sel_hi:[0,1,1]
	v_pk_fma_f32 v[240:241], v[236:237], v[130:131], v[240:241] op_sel_hi:[0,1,1]
	v_pk_fma_f32 v[238:239], v[232:233], v[108:109], v[238:239] op_sel:[1,0,0]
	v_pk_fma_f32 v[240:241], v[232:233], v[116:117], v[240:241] op_sel:[1,0,0]
	v_pk_fma_f32 v[238:239], v[236:237], v[124:125], v[238:239] op_sel:[1,0,0]
	v_pk_fma_f32 v[240:241], v[236:237], v[132:133], v[240:241] op_sel:[1,0,0]
	ds_read_b128 v[230:233], v32 offset:16512
	ds_read_b128 v[234:237], v32 offset:16528
	global_store_dwordx4 v246, v[238:241], s[100:101] nt
	global_load_dwordx4 v[134:137], v246, s[98:99] nt
	s_add_u32 s100, s100, 0x2000
	s_addc_u32 s101, s101, 0
	s_add_u32 s98, s98, 0x2000
	s_addc_u32 s99, s99, 0
	s_waitcnt vmcnt(30)
	s_waitcnt lgkmcnt(2)
	v_pk_fma_f32 v[0:1], v[138:139], v[222:223], v[0:1] op_sel_hi:[1,0,1]
	v_pk_fma_f32 v[2:3], v[140:141], v[222:223], v[2:3] op_sel_hi:[1,0,1]
	v_pk_fma_f32 v[4:5], v[138:139], v[222:223], v[4:5] op_sel:[0,1,0]
	v_pk_fma_f32 v[6:7], v[140:141], v[222:223], v[6:7] op_sel:[0,1,0]
	v_pk_fma_f32 v[8:9], v[138:139], v[224:225], v[8:9] op_sel_hi:[1,0,1]
	v_pk_fma_f32 v[10:11], v[140:141], v[224:225], v[10:11] op_sel_hi:[1,0,1]
	v_pk_fma_f32 v[12:13], v[138:139], v[224:225], v[12:13] op_sel:[0,1,0]
	v_pk_fma_f32 v[14:15], v[140:141], v[224:225], v[14:15] op_sel:[0,1,0]
	v_pk_fma_f32 v[16:17], v[138:139], v[226:227], v[16:17] op_sel_hi:[1,0,1]
	v_pk_fma_f32 v[18:19], v[140:141], v[226:227], v[18:19] op_sel_hi:[1,0,1]
	v_pk_fma_f32 v[20:21], v[138:139], v[226:227], v[20:21] op_sel:[0,1,0]
	v_pk_fma_f32 v[22:23], v[140:141], v[226:227], v[22:23] op_sel:[0,1,0]
	v_pk_fma_f32 v[24:25], v[138:139], v[228:229], v[24:25] op_sel_hi:[1,0,1]
	v_pk_fma_f32 v[26:27], v[140:141], v[228:229], v[26:27] op_sel_hi:[1,0,1]
	v_pk_fma_f32 v[28:29], v[138:139], v[228:229], v[28:29] op_sel:[0,1,0]
	v_pk_fma_f32 v[30:31], v[140:141], v[228:229], v[30:31] op_sel:[0,1,0]
	ds_read_b128 v[222:225], v32 offset:256
	ds_read_b128 v[226:229], v32 offset:272
	s_waitcnt lgkmcnt(2)
	v_pk_mul_f32 v[242:243], v[230:231], v[102:103] op_sel_hi:[0,1]
	v_pk_mul_f32 v[244:245], v[230:231], v[110:111] op_sel_hi:[0,1]
	v_pk_fma_f32 v[242:243], v[86:87], v[138:139], v[242:243]
	v_pk_fma_f32 v[244:245], v[86:87], v[140:141], v[244:245]
	v_pk_fma_f32 v[242:243], v[234:235], v[118:119], v[242:243] op_sel_hi:[0,1,1]
	v_pk_fma_f32 v[244:245], v[234:235], v[126:127], v[244:245] op_sel_hi:[0,1,1]
	v_pk_fma_f32 v[242:243], v[230:231], v[104:105], v[242:243] op_sel:[1,0,0]
	v_pk_fma_f32 v[244:245], v[230:231], v[112:113], v[244:245] op_sel:[1,0,0]
	v_pk_fma_f32 v[242:243], v[234:235], v[120:121], v[242:243] op_sel:[1,0,0]
	v_pk_fma_f32 v[244:245], v[234:235], v[128:129], v[244:245] op_sel:[1,0,0]
	v_pk_fma_f32 v[242:243], v[232:233], v[106:107], v[242:243] op_sel_hi:[0,1,1]
	v_pk_fma_f32 v[244:245], v[232:233], v[114:115], v[244:245] op_sel_hi:[0,1,1]
	v_pk_fma_f32 v[242:243], v[236:237], v[122:123], v[242:243] op_sel_hi:[0,1,1]
	v_pk_fma_f32 v[244:245], v[236:237], v[130:131], v[244:245] op_sel_hi:[0,1,1]
	v_pk_fma_f32 v[242:243], v[232:233], v[108:109], v[242:243] op_sel:[1,0,0]
	v_pk_fma_f32 v[244:245], v[232:233], v[116:117], v[244:245] op_sel:[1,0,0]
	v_pk_fma_f32 v[242:243], v[236:237], v[124:125], v[242:243] op_sel:[1,0,0]
	v_pk_fma_f32 v[244:245], v[236:237], v[132:133], v[244:245] op_sel:[1,0,0]
	ds_read_b128 v[230:233], v32 offset:16640
	ds_read_b128 v[234:237], v32 offset:16656
	global_store_dwordx4 v246, v[242:245], s[100:101] nt
	global_load_dwordx4 v[138:141], v246, s[98:99] nt
	s_add_u32 s100, s100, 0x2000
	s_addc_u32 s101, s101, 0
	s_add_u32 s98, s98, 0x2000
	s_addc_u32 s99, s99, 0
	s_waitcnt vmcnt(30)
	s_waitcnt lgkmcnt(2)
	v_pk_fma_f32 v[0:1], v[142:143], v[222:223], v[0:1] op_sel_hi:[1,0,1]
	v_pk_fma_f32 v[2:3], v[144:145], v[222:223], v[2:3] op_sel_hi:[1,0,1]
	v_pk_fma_f32 v[4:5], v[142:143], v[222:223], v[4:5] op_sel:[0,1,0]
	v_pk_fma_f32 v[6:7], v[144:145], v[222:223], v[6:7] op_sel:[0,1,0]
	v_pk_fma_f32 v[8:9], v[142:143], v[224:225], v[8:9] op_sel_hi:[1,0,1]
	v_pk_fma_f32 v[10:11], v[144:145], v[224:225], v[10:11] op_sel_hi:[1,0,1]
	v_pk_fma_f32 v[12:13], v[142:143], v[224:225], v[12:13] op_sel:[0,1,0]
	v_pk_fma_f32 v[14:15], v[144:145], v[224:225], v[14:15] op_sel:[0,1,0]
	v_pk_fma_f32 v[16:17], v[142:143], v[226:227], v[16:17] op_sel_hi:[1,0,1]
	v_pk_fma_f32 v[18:19], v[144:145], v[226:227], v[18:19] op_sel_hi:[1,0,1]
	v_pk_fma_f32 v[20:21], v[142:143], v[226:227], v[20:21] op_sel:[0,1,0]
	v_pk_fma_f32 v[22:23], v[144:145], v[226:227], v[22:23] op_sel:[0,1,0]
	v_pk_fma_f32 v[24:25], v[142:143], v[228:229], v[24:25] op_sel_hi:[1,0,1]
	v_pk_fma_f32 v[26:27], v[144:145], v[228:229], v[26:27] op_sel_hi:[1,0,1]
	v_pk_fma_f32 v[28:29], v[142:143], v[228:229], v[28:29] op_sel:[0,1,0]
	v_pk_fma_f32 v[30:31], v[144:145], v[228:229], v[30:31] op_sel:[0,1,0]
	ds_read_b128 v[222:225], v32 offset:384
	ds_read_b128 v[226:229], v32 offset:400
	s_waitcnt lgkmcnt(2)
	v_pk_mul_f32 v[238:239], v[230:231], v[102:103] op_sel_hi:[0,1]
	v_pk_mul_f32 v[240:241], v[230:231], v[110:111] op_sel_hi:[0,1]
	v_pk_fma_f32 v[238:239], v[86:87], v[142:143], v[238:239]
	v_pk_fma_f32 v[240:241], v[86:87], v[144:145], v[240:241]
	v_pk_fma_f32 v[238:239], v[234:235], v[118:119], v[238:239] op_sel_hi:[0,1,1]
	v_pk_fma_f32 v[240:241], v[234:235], v[126:127], v[240:241] op_sel_hi:[0,1,1]
	v_pk_fma_f32 v[238:239], v[230:231], v[104:105], v[238:239] op_sel:[1,0,0]
	v_pk_fma_f32 v[240:241], v[230:231], v[112:113], v[240:241] op_sel:[1,0,0]
	v_pk_fma_f32 v[238:239], v[234:235], v[120:121], v[238:239] op_sel:[1,0,0]
	v_pk_fma_f32 v[240:241], v[234:235], v[128:129], v[240:241] op_sel:[1,0,0]
	v_pk_fma_f32 v[238:239], v[232:233], v[106:107], v[238:239] op_sel_hi:[0,1,1]
	v_pk_fma_f32 v[240:241], v[232:233], v[114:115], v[240:241] op_sel_hi:[0,1,1]
	v_pk_fma_f32 v[238:239], v[236:237], v[122:123], v[238:239] op_sel_hi:[0,1,1]
	v_pk_fma_f32 v[240:241], v[236:237], v[130:131], v[240:241] op_sel_hi:[0,1,1]
	v_pk_fma_f32 v[238:239], v[232:233], v[108:109], v[238:239] op_sel:[1,0,0]
	v_pk_fma_f32 v[240:241], v[232:233], v[116:117], v[240:241] op_sel:[1,0,0]
	v_pk_fma_f32 v[238:239], v[236:237], v[124:125], v[238:239] op_sel:[1,0,0]
	v_pk_fma_f32 v[240:241], v[236:237], v[132:133], v[240:241] op_sel:[1,0,0]
	ds_read_b128 v[230:233], v32 offset:16768
	ds_read_b128 v[234:237], v32 offset:16784
	global_store_dwordx4 v246, v[238:241], s[100:101] nt
	global_load_dwordx4 v[142:145], v246, s[98:99] nt
	s_add_u32 s100, s100, 0x2000
	s_addc_u32 s101, s101, 0
	s_add_u32 s98, s98, 0x2000
	s_addc_u32 s99, s99, 0
	s_waitcnt vmcnt(30)
	s_waitcnt lgkmcnt(2)
	v_pk_fma_f32 v[0:1], v[158:159], v[222:223], v[0:1] op_sel_hi:[1,0,1]
	v_pk_fma_f32 v[2:3], v[160:161], v[222:223], v[2:3] op_sel_hi:[1,0,1]
	v_pk_fma_f32 v[4:5], v[158:159], v[222:223], v[4:5] op_sel:[0,1,0]
	v_pk_fma_f32 v[6:7], v[160:161], v[222:223], v[6:7] op_sel:[0,1,0]
	v_pk_fma_f32 v[8:9], v[158:159], v[224:225], v[8:9] op_sel_hi:[1,0,1]
	v_pk_fma_f32 v[10:11], v[160:161], v[224:225], v[10:11] op_sel_hi:[1,0,1]
	v_pk_fma_f32 v[12:13], v[158:159], v[224:225], v[12:13] op_sel:[0,1,0]
	v_pk_fma_f32 v[14:15], v[160:161], v[224:225], v[14:15] op_sel:[0,1,0]
	v_pk_fma_f32 v[16:17], v[158:159], v[226:227], v[16:17] op_sel_hi:[1,0,1]
	v_pk_fma_f32 v[18:19], v[160:161], v[226:227], v[18:19] op_sel_hi:[1,0,1]
	v_pk_fma_f32 v[20:21], v[158:159], v[226:227], v[20:21] op_sel:[0,1,0]
	v_pk_fma_f32 v[22:23], v[160:161], v[226:227], v[22:23] op_sel:[0,1,0]
	v_pk_fma_f32 v[24:25], v[158:159], v[228:229], v[24:25] op_sel_hi:[1,0,1]
	v_pk_fma_f32 v[26:27], v[160:161], v[228:229], v[26:27] op_sel_hi:[1,0,1]
	v_pk_fma_f32 v[28:29], v[158:159], v[228:229], v[28:29] op_sel:[0,1,0]
	v_pk_fma_f32 v[30:31], v[160:161], v[228:229], v[30:31] op_sel:[0,1,0]
	ds_read_b128 v[222:225], v32 offset:512
	ds_read_b128 v[226:229], v32 offset:528
	s_waitcnt lgkmcnt(2)
	v_pk_mul_f32 v[242:243], v[230:231], v[102:103] op_sel_hi:[0,1]
	v_pk_mul_f32 v[244:245], v[230:231], v[110:111] op_sel_hi:[0,1]
	v_pk_fma_f32 v[242:243], v[86:87], v[158:159], v[242:243]
	v_pk_fma_f32 v[244:245], v[86:87], v[160:161], v[244:245]
	v_pk_fma_f32 v[242:243], v[234:235], v[118:119], v[242:243] op_sel_hi:[0,1,1]
	v_pk_fma_f32 v[244:245], v[234:235], v[126:127], v[244:245] op_sel_hi:[0,1,1]
	v_pk_fma_f32 v[242:243], v[230:231], v[104:105], v[242:243] op_sel:[1,0,0]
	v_pk_fma_f32 v[244:245], v[230:231], v[112:113], v[244:245] op_sel:[1,0,0]
	v_pk_fma_f32 v[242:243], v[234:235], v[120:121], v[242:243] op_sel:[1,0,0]
	v_pk_fma_f32 v[244:245], v[234:235], v[128:129], v[244:245] op_sel:[1,0,0]
	v_pk_fma_f32 v[242:243], v[232:233], v[106:107], v[242:243] op_sel_hi:[0,1,1]
	v_pk_fma_f32 v[244:245], v[232:233], v[114:115], v[244:245] op_sel_hi:[0,1,1]
	v_pk_fma_f32 v[242:243], v[236:237], v[122:123], v[242:243] op_sel_hi:[0,1,1]
	v_pk_fma_f32 v[244:245], v[236:237], v[130:131], v[244:245] op_sel_hi:[0,1,1]
	v_pk_fma_f32 v[242:243], v[232:233], v[108:109], v[242:243] op_sel:[1,0,0]
	v_pk_fma_f32 v[244:245], v[232:233], v[116:117], v[244:245] op_sel:[1,0,0]
	v_pk_fma_f32 v[242:243], v[236:237], v[124:125], v[242:243] op_sel:[1,0,0]
	v_pk_fma_f32 v[244:245], v[236:237], v[132:133], v[244:245] op_sel:[1,0,0]
	ds_read_b128 v[230:233], v32 offset:16896
	ds_read_b128 v[234:237], v32 offset:16912
	global_store_dwordx4 v246, v[242:245], s[100:101] nt
	global_load_dwordx4 v[158:161], v246, s[98:99] nt
	s_add_u32 s100, s100, 0x2000
	s_addc_u32 s101, s101, 0
	s_add_u32 s98, s98, 0x2000
	s_addc_u32 s99, s99, 0
	s_waitcnt vmcnt(30)
	s_waitcnt lgkmcnt(2)
	v_pk_fma_f32 v[0:1], v[162:163], v[222:223], v[0:1] op_sel_hi:[1,0,1]
	v_pk_fma_f32 v[2:3], v[164:165], v[222:223], v[2:3] op_sel_hi:[1,0,1]
	v_pk_fma_f32 v[4:5], v[162:163], v[222:223], v[4:5] op_sel:[0,1,0]
	v_pk_fma_f32 v[6:7], v[164:165], v[222:223], v[6:7] op_sel:[0,1,0]
	v_pk_fma_f32 v[8:9], v[162:163], v[224:225], v[8:9] op_sel_hi:[1,0,1]
	v_pk_fma_f32 v[10:11], v[164:165], v[224:225], v[10:11] op_sel_hi:[1,0,1]
	v_pk_fma_f32 v[12:13], v[162:163], v[224:225], v[12:13] op_sel:[0,1,0]
	v_pk_fma_f32 v[14:15], v[164:165], v[224:225], v[14:15] op_sel:[0,1,0]
	v_pk_fma_f32 v[16:17], v[162:163], v[226:227], v[16:17] op_sel_hi:[1,0,1]
	v_pk_fma_f32 v[18:19], v[164:165], v[226:227], v[18:19] op_sel_hi:[1,0,1]
	v_pk_fma_f32 v[20:21], v[162:163], v[226:227], v[20:21] op_sel:[0,1,0]
	v_pk_fma_f32 v[22:23], v[164:165], v[226:227], v[22:23] op_sel:[0,1,0]
	v_pk_fma_f32 v[24:25], v[162:163], v[228:229], v[24:25] op_sel_hi:[1,0,1]
	v_pk_fma_f32 v[26:27], v[164:165], v[228:229], v[26:27] op_sel_hi:[1,0,1]
	v_pk_fma_f32 v[28:29], v[162:163], v[228:229], v[28:29] op_sel:[0,1,0]
	v_pk_fma_f32 v[30:31], v[164:165], v[228:229], v[30:31] op_sel:[0,1,0]
	ds_read_b128 v[222:225], v32 offset:640
	ds_read_b128 v[226:229], v32 offset:656
	s_waitcnt lgkmcnt(2)
	v_pk_mul_f32 v[238:239], v[230:231], v[102:103] op_sel_hi:[0,1]
	v_pk_mul_f32 v[240:241], v[230:231], v[110:111] op_sel_hi:[0,1]
	v_pk_fma_f32 v[238:239], v[86:87], v[162:163], v[238:239]
	v_pk_fma_f32 v[240:241], v[86:87], v[164:165], v[240:241]
	v_pk_fma_f32 v[238:239], v[234:235], v[118:119], v[238:239] op_sel_hi:[0,1,1]
	v_pk_fma_f32 v[240:241], v[234:235], v[126:127], v[240:241] op_sel_hi:[0,1,1]
	v_pk_fma_f32 v[238:239], v[230:231], v[104:105], v[238:239] op_sel:[1,0,0]
	v_pk_fma_f32 v[240:241], v[230:231], v[112:113], v[240:241] op_sel:[1,0,0]
	v_pk_fma_f32 v[238:239], v[234:235], v[120:121], v[238:239] op_sel:[1,0,0]
	v_pk_fma_f32 v[240:241], v[234:235], v[128:129], v[240:241] op_sel:[1,0,0]
	v_pk_fma_f32 v[238:239], v[232:233], v[106:107], v[238:239] op_sel_hi:[0,1,1]
	v_pk_fma_f32 v[240:241], v[232:233], v[114:115], v[240:241] op_sel_hi:[0,1,1]
	v_pk_fma_f32 v[238:239], v[236:237], v[122:123], v[238:239] op_sel_hi:[0,1,1]
	v_pk_fma_f32 v[240:241], v[236:237], v[130:131], v[240:241] op_sel_hi:[0,1,1]
	v_pk_fma_f32 v[238:239], v[232:233], v[108:109], v[238:239] op_sel:[1,0,0]
	v_pk_fma_f32 v[240:241], v[232:233], v[116:117], v[240:241] op_sel:[1,0,0]
	v_pk_fma_f32 v[238:239], v[236:237], v[124:125], v[238:239] op_sel:[1,0,0]
	v_pk_fma_f32 v[240:241], v[236:237], v[132:133], v[240:241] op_sel:[1,0,0]
	ds_read_b128 v[230:233], v32 offset:17024
	ds_read_b128 v[234:237], v32 offset:17040
	global_store_dwordx4 v246, v[238:241], s[100:101] nt
	global_load_dwordx4 v[162:165], v246, s[98:99] nt
	s_add_u32 s100, s100, 0x2000
	s_addc_u32 s101, s101, 0
	s_add_u32 s98, s98, 0x2000
	s_addc_u32 s99, s99, 0
	s_waitcnt vmcnt(30)
	s_waitcnt lgkmcnt(2)
	v_pk_fma_f32 v[0:1], v[166:167], v[222:223], v[0:1] op_sel_hi:[1,0,1]
	v_pk_fma_f32 v[2:3], v[168:169], v[222:223], v[2:3] op_sel_hi:[1,0,1]
	v_pk_fma_f32 v[4:5], v[166:167], v[222:223], v[4:5] op_sel:[0,1,0]
	v_pk_fma_f32 v[6:7], v[168:169], v[222:223], v[6:7] op_sel:[0,1,0]
	v_pk_fma_f32 v[8:9], v[166:167], v[224:225], v[8:9] op_sel_hi:[1,0,1]
	v_pk_fma_f32 v[10:11], v[168:169], v[224:225], v[10:11] op_sel_hi:[1,0,1]
	v_pk_fma_f32 v[12:13], v[166:167], v[224:225], v[12:13] op_sel:[0,1,0]
	v_pk_fma_f32 v[14:15], v[168:169], v[224:225], v[14:15] op_sel:[0,1,0]
	v_pk_fma_f32 v[16:17], v[166:167], v[226:227], v[16:17] op_sel_hi:[1,0,1]
	v_pk_fma_f32 v[18:19], v[168:169], v[226:227], v[18:19] op_sel_hi:[1,0,1]
	v_pk_fma_f32 v[20:21], v[166:167], v[226:227], v[20:21] op_sel:[0,1,0]
	v_pk_fma_f32 v[22:23], v[168:169], v[226:227], v[22:23] op_sel:[0,1,0]
	v_pk_fma_f32 v[24:25], v[166:167], v[228:229], v[24:25] op_sel_hi:[1,0,1]
	v_pk_fma_f32 v[26:27], v[168:169], v[228:229], v[26:27] op_sel_hi:[1,0,1]
	v_pk_fma_f32 v[28:29], v[166:167], v[228:229], v[28:29] op_sel:[0,1,0]
	v_pk_fma_f32 v[30:31], v[168:169], v[228:229], v[30:31] op_sel:[0,1,0]
	ds_read_b128 v[222:225], v32 offset:768
	ds_read_b128 v[226:229], v32 offset:784
	s_waitcnt lgkmcnt(2)
	v_pk_mul_f32 v[242:243], v[230:231], v[102:103] op_sel_hi:[0,1]
	v_pk_mul_f32 v[244:245], v[230:231], v[110:111] op_sel_hi:[0,1]
	v_pk_fma_f32 v[242:243], v[86:87], v[166:167], v[242:243]
	v_pk_fma_f32 v[244:245], v[86:87], v[168:169], v[244:245]
	v_pk_fma_f32 v[242:243], v[234:235], v[118:119], v[242:243] op_sel_hi:[0,1,1]
	v_pk_fma_f32 v[244:245], v[234:235], v[126:127], v[244:245] op_sel_hi:[0,1,1]
	v_pk_fma_f32 v[242:243], v[230:231], v[104:105], v[242:243] op_sel:[1,0,0]
	v_pk_fma_f32 v[244:245], v[230:231], v[112:113], v[244:245] op_sel:[1,0,0]
	v_pk_fma_f32 v[242:243], v[234:235], v[120:121], v[242:243] op_sel:[1,0,0]
	v_pk_fma_f32 v[244:245], v[234:235], v[128:129], v[244:245] op_sel:[1,0,0]
	v_pk_fma_f32 v[242:243], v[232:233], v[106:107], v[242:243] op_sel_hi:[0,1,1]
	v_pk_fma_f32 v[244:245], v[232:233], v[114:115], v[244:245] op_sel_hi:[0,1,1]
	v_pk_fma_f32 v[242:243], v[236:237], v[122:123], v[242:243] op_sel_hi:[0,1,1]
	v_pk_fma_f32 v[244:245], v[236:237], v[130:131], v[244:245] op_sel_hi:[0,1,1]
	v_pk_fma_f32 v[242:243], v[232:233], v[108:109], v[242:243] op_sel:[1,0,0]
	v_pk_fma_f32 v[244:245], v[232:233], v[116:117], v[244:245] op_sel:[1,0,0]
	v_pk_fma_f32 v[242:243], v[236:237], v[124:125], v[242:243] op_sel:[1,0,0]
	v_pk_fma_f32 v[244:245], v[236:237], v[132:133], v[244:245] op_sel:[1,0,0]
	ds_read_b128 v[230:233], v32 offset:17152
	ds_read_b128 v[234:237], v32 offset:17168
	global_store_dwordx4 v246, v[242:245], s[100:101] nt
	global_load_dwordx4 v[166:169], v246, s[98:99] nt
	s_add_u32 s100, s100, 0x2000
	s_addc_u32 s101, s101, 0
	s_add_u32 s98, s98, 0x2000
	s_addc_u32 s99, s99, 0
	s_waitcnt vmcnt(30)
	s_waitcnt lgkmcnt(2)
	v_pk_fma_f32 v[0:1], v[170:171], v[222:223], v[0:1] op_sel_hi:[1,0,1]
	v_pk_fma_f32 v[2:3], v[172:173], v[222:223], v[2:3] op_sel_hi:[1,0,1]
	v_pk_fma_f32 v[4:5], v[170:171], v[222:223], v[4:5] op_sel:[0,1,0]
	v_pk_fma_f32 v[6:7], v[172:173], v[222:223], v[6:7] op_sel:[0,1,0]
	v_pk_fma_f32 v[8:9], v[170:171], v[224:225], v[8:9] op_sel_hi:[1,0,1]
	v_pk_fma_f32 v[10:11], v[172:173], v[224:225], v[10:11] op_sel_hi:[1,0,1]
	v_pk_fma_f32 v[12:13], v[170:171], v[224:225], v[12:13] op_sel:[0,1,0]
	v_pk_fma_f32 v[14:15], v[172:173], v[224:225], v[14:15] op_sel:[0,1,0]
	v_pk_fma_f32 v[16:17], v[170:171], v[226:227], v[16:17] op_sel_hi:[1,0,1]
	v_pk_fma_f32 v[18:19], v[172:173], v[226:227], v[18:19] op_sel_hi:[1,0,1]
	v_pk_fma_f32 v[20:21], v[170:171], v[226:227], v[20:21] op_sel:[0,1,0]
	v_pk_fma_f32 v[22:23], v[172:173], v[226:227], v[22:23] op_sel:[0,1,0]
	v_pk_fma_f32 v[24:25], v[170:171], v[228:229], v[24:25] op_sel_hi:[1,0,1]
	v_pk_fma_f32 v[26:27], v[172:173], v[228:229], v[26:27] op_sel_hi:[1,0,1]
	v_pk_fma_f32 v[28:29], v[170:171], v[228:229], v[28:29] op_sel:[0,1,0]
	v_pk_fma_f32 v[30:31], v[172:173], v[228:229], v[30:31] op_sel:[0,1,0]
	ds_read_b128 v[222:225], v32 offset:896
	ds_read_b128 v[226:229], v32 offset:912
	s_waitcnt lgkmcnt(2)
	v_pk_mul_f32 v[238:239], v[230:231], v[102:103] op_sel_hi:[0,1]
	v_pk_mul_f32 v[240:241], v[230:231], v[110:111] op_sel_hi:[0,1]
	v_pk_fma_f32 v[238:239], v[86:87], v[170:171], v[238:239]
	v_pk_fma_f32 v[240:241], v[86:87], v[172:173], v[240:241]
	v_pk_fma_f32 v[238:239], v[234:235], v[118:119], v[238:239] op_sel_hi:[0,1,1]
	v_pk_fma_f32 v[240:241], v[234:235], v[126:127], v[240:241] op_sel_hi:[0,1,1]
	v_pk_fma_f32 v[238:239], v[230:231], v[104:105], v[238:239] op_sel:[1,0,0]
	v_pk_fma_f32 v[240:241], v[230:231], v[112:113], v[240:241] op_sel:[1,0,0]
	v_pk_fma_f32 v[238:239], v[234:235], v[120:121], v[238:239] op_sel:[1,0,0]
	v_pk_fma_f32 v[240:241], v[234:235], v[128:129], v[240:241] op_sel:[1,0,0]
	v_pk_fma_f32 v[238:239], v[232:233], v[106:107], v[238:239] op_sel_hi:[0,1,1]
	v_pk_fma_f32 v[240:241], v[232:233], v[114:115], v[240:241] op_sel_hi:[0,1,1]
	v_pk_fma_f32 v[238:239], v[236:237], v[122:123], v[238:239] op_sel_hi:[0,1,1]
	v_pk_fma_f32 v[240:241], v[236:237], v[130:131], v[240:241] op_sel_hi:[0,1,1]
	v_pk_fma_f32 v[238:239], v[232:233], v[108:109], v[238:239] op_sel:[1,0,0]
	v_pk_fma_f32 v[240:241], v[232:233], v[116:117], v[240:241] op_sel:[1,0,0]
	v_pk_fma_f32 v[238:239], v[236:237], v[124:125], v[238:239] op_sel:[1,0,0]
	v_pk_fma_f32 v[240:241], v[236:237], v[132:133], v[240:241] op_sel:[1,0,0]
	ds_read_b128 v[230:233], v32 offset:17280
	ds_read_b128 v[234:237], v32 offset:17296
	global_store_dwordx4 v246, v[238:241], s[100:101] nt
	global_load_dwordx4 v[170:173], v246, s[98:99] nt
	s_add_u32 s100, s100, 0x2000
	s_addc_u32 s101, s101, 0
	s_add_u32 s98, s98, 0x2000
	s_addc_u32 s99, s99, 0
	s_waitcnt vmcnt(30)
	s_waitcnt lgkmcnt(2)
	v_pk_fma_f32 v[0:1], v[174:175], v[222:223], v[0:1] op_sel_hi:[1,0,1]
	v_pk_fma_f32 v[2:3], v[176:177], v[222:223], v[2:3] op_sel_hi:[1,0,1]
	v_pk_fma_f32 v[4:5], v[174:175], v[222:223], v[4:5] op_sel:[0,1,0]
	v_pk_fma_f32 v[6:7], v[176:177], v[222:223], v[6:7] op_sel:[0,1,0]
	v_pk_fma_f32 v[8:9], v[174:175], v[224:225], v[8:9] op_sel_hi:[1,0,1]
	v_pk_fma_f32 v[10:11], v[176:177], v[224:225], v[10:11] op_sel_hi:[1,0,1]
	v_pk_fma_f32 v[12:13], v[174:175], v[224:225], v[12:13] op_sel:[0,1,0]
	v_pk_fma_f32 v[14:15], v[176:177], v[224:225], v[14:15] op_sel:[0,1,0]
	v_pk_fma_f32 v[16:17], v[174:175], v[226:227], v[16:17] op_sel_hi:[1,0,1]
	v_pk_fma_f32 v[18:19], v[176:177], v[226:227], v[18:19] op_sel_hi:[1,0,1]
	v_pk_fma_f32 v[20:21], v[174:175], v[226:227], v[20:21] op_sel:[0,1,0]
	v_pk_fma_f32 v[22:23], v[176:177], v[226:227], v[22:23] op_sel:[0,1,0]
	v_pk_fma_f32 v[24:25], v[174:175], v[228:229], v[24:25] op_sel_hi:[1,0,1]
	v_pk_fma_f32 v[26:27], v[176:177], v[228:229], v[26:27] op_sel_hi:[1,0,1]
	v_pk_fma_f32 v[28:29], v[174:175], v[228:229], v[28:29] op_sel:[0,1,0]
	v_pk_fma_f32 v[30:31], v[176:177], v[228:229], v[30:31] op_sel:[0,1,0]
	ds_read_b128 v[222:225], v32 offset:1024
	ds_read_b128 v[226:229], v32 offset:1040
	s_waitcnt lgkmcnt(2)
	v_pk_mul_f32 v[242:243], v[230:231], v[102:103] op_sel_hi:[0,1]
	v_pk_mul_f32 v[244:245], v[230:231], v[110:111] op_sel_hi:[0,1]
	v_pk_fma_f32 v[242:243], v[86:87], v[174:175], v[242:243]
	v_pk_fma_f32 v[244:245], v[86:87], v[176:177], v[244:245]
	v_pk_fma_f32 v[242:243], v[234:235], v[118:119], v[242:243] op_sel_hi:[0,1,1]
	v_pk_fma_f32 v[244:245], v[234:235], v[126:127], v[244:245] op_sel_hi:[0,1,1]
	v_pk_fma_f32 v[242:243], v[230:231], v[104:105], v[242:243] op_sel:[1,0,0]
	v_pk_fma_f32 v[244:245], v[230:231], v[112:113], v[244:245] op_sel:[1,0,0]
	v_pk_fma_f32 v[242:243], v[234:235], v[120:121], v[242:243] op_sel:[1,0,0]
	v_pk_fma_f32 v[244:245], v[234:235], v[128:129], v[244:245] op_sel:[1,0,0]
	v_pk_fma_f32 v[242:243], v[232:233], v[106:107], v[242:243] op_sel_hi:[0,1,1]
	v_pk_fma_f32 v[244:245], v[232:233], v[114:115], v[244:245] op_sel_hi:[0,1,1]
	v_pk_fma_f32 v[242:243], v[236:237], v[122:123], v[242:243] op_sel_hi:[0,1,1]
	v_pk_fma_f32 v[244:245], v[236:237], v[130:131], v[244:245] op_sel_hi:[0,1,1]
	v_pk_fma_f32 v[242:243], v[232:233], v[108:109], v[242:243] op_sel:[1,0,0]
	v_pk_fma_f32 v[244:245], v[232:233], v[116:117], v[244:245] op_sel:[1,0,0]
	v_pk_fma_f32 v[242:243], v[236:237], v[124:125], v[242:243] op_sel:[1,0,0]
	v_pk_fma_f32 v[244:245], v[236:237], v[132:133], v[244:245] op_sel:[1,0,0]
	ds_read_b128 v[230:233], v32 offset:17408
	ds_read_b128 v[234:237], v32 offset:17424
	global_store_dwordx4 v246, v[242:245], s[100:101] nt
	global_load_dwordx4 v[174:177], v246, s[98:99] nt
	s_add_u32 s100, s100, 0x2000
	s_addc_u32 s101, s101, 0
	s_add_u32 s98, s98, 0x2000
	s_addc_u32 s99, s99, 0
	s_waitcnt vmcnt(30)
	s_waitcnt lgkmcnt(2)
	v_pk_fma_f32 v[0:1], v[178:179], v[222:223], v[0:1] op_sel_hi:[1,0,1]
	v_pk_fma_f32 v[2:3], v[180:181], v[222:223], v[2:3] op_sel_hi:[1,0,1]
	v_pk_fma_f32 v[4:5], v[178:179], v[222:223], v[4:5] op_sel:[0,1,0]
	v_pk_fma_f32 v[6:7], v[180:181], v[222:223], v[6:7] op_sel:[0,1,0]
	v_pk_fma_f32 v[8:9], v[178:179], v[224:225], v[8:9] op_sel_hi:[1,0,1]
	v_pk_fma_f32 v[10:11], v[180:181], v[224:225], v[10:11] op_sel_hi:[1,0,1]
	v_pk_fma_f32 v[12:13], v[178:179], v[224:225], v[12:13] op_sel:[0,1,0]
	v_pk_fma_f32 v[14:15], v[180:181], v[224:225], v[14:15] op_sel:[0,1,0]
	v_pk_fma_f32 v[16:17], v[178:179], v[226:227], v[16:17] op_sel_hi:[1,0,1]
	v_pk_fma_f32 v[18:19], v[180:181], v[226:227], v[18:19] op_sel_hi:[1,0,1]
	v_pk_fma_f32 v[20:21], v[178:179], v[226:227], v[20:21] op_sel:[0,1,0]
	v_pk_fma_f32 v[22:23], v[180:181], v[226:227], v[22:23] op_sel:[0,1,0]
	v_pk_fma_f32 v[24:25], v[178:179], v[228:229], v[24:25] op_sel_hi:[1,0,1]
	v_pk_fma_f32 v[26:27], v[180:181], v[228:229], v[26:27] op_sel_hi:[1,0,1]
	v_pk_fma_f32 v[28:29], v[178:179], v[228:229], v[28:29] op_sel:[0,1,0]
	v_pk_fma_f32 v[30:31], v[180:181], v[228:229], v[30:31] op_sel:[0,1,0]
	ds_read_b128 v[222:225], v32 offset:1152
	ds_read_b128 v[226:229], v32 offset:1168
	s_waitcnt lgkmcnt(2)
	v_pk_mul_f32 v[238:239], v[230:231], v[102:103] op_sel_hi:[0,1]
	v_pk_mul_f32 v[240:241], v[230:231], v[110:111] op_sel_hi:[0,1]
	v_pk_fma_f32 v[238:239], v[86:87], v[178:179], v[238:239]
	v_pk_fma_f32 v[240:241], v[86:87], v[180:181], v[240:241]
	v_pk_fma_f32 v[238:239], v[234:235], v[118:119], v[238:239] op_sel_hi:[0,1,1]
	v_pk_fma_f32 v[240:241], v[234:235], v[126:127], v[240:241] op_sel_hi:[0,1,1]
	v_pk_fma_f32 v[238:239], v[230:231], v[104:105], v[238:239] op_sel:[1,0,0]
	v_pk_fma_f32 v[240:241], v[230:231], v[112:113], v[240:241] op_sel:[1,0,0]
	v_pk_fma_f32 v[238:239], v[234:235], v[120:121], v[238:239] op_sel:[1,0,0]
	v_pk_fma_f32 v[240:241], v[234:235], v[128:129], v[240:241] op_sel:[1,0,0]
	v_pk_fma_f32 v[238:239], v[232:233], v[106:107], v[238:239] op_sel_hi:[0,1,1]
	v_pk_fma_f32 v[240:241], v[232:233], v[114:115], v[240:241] op_sel_hi:[0,1,1]
	v_pk_fma_f32 v[238:239], v[236:237], v[122:123], v[238:239] op_sel_hi:[0,1,1]
	v_pk_fma_f32 v[240:241], v[236:237], v[130:131], v[240:241] op_sel_hi:[0,1,1]
	v_pk_fma_f32 v[238:239], v[232:233], v[108:109], v[238:239] op_sel:[1,0,0]
	v_pk_fma_f32 v[240:241], v[232:233], v[116:117], v[240:241] op_sel:[1,0,0]
	v_pk_fma_f32 v[238:239], v[236:237], v[124:125], v[238:239] op_sel:[1,0,0]
	v_pk_fma_f32 v[240:241], v[236:237], v[132:133], v[240:241] op_sel:[1,0,0]
	ds_read_b128 v[230:233], v32 offset:17536
	ds_read_b128 v[234:237], v32 offset:17552
	global_store_dwordx4 v246, v[238:241], s[100:101] nt
	global_load_dwordx4 v[178:181], v246, s[98:99] nt
	s_add_u32 s100, s100, 0x2000
	s_addc_u32 s101, s101, 0
	s_add_u32 s98, s98, 0x2000
	s_addc_u32 s99, s99, 0
	s_waitcnt vmcnt(30)
	s_waitcnt lgkmcnt(2)
	v_pk_fma_f32 v[0:1], v[182:183], v[222:223], v[0:1] op_sel_hi:[1,0,1]
	v_pk_fma_f32 v[2:3], v[184:185], v[222:223], v[2:3] op_sel_hi:[1,0,1]
	v_pk_fma_f32 v[4:5], v[182:183], v[222:223], v[4:5] op_sel:[0,1,0]
	v_pk_fma_f32 v[6:7], v[184:185], v[222:223], v[6:7] op_sel:[0,1,0]
	v_pk_fma_f32 v[8:9], v[182:183], v[224:225], v[8:9] op_sel_hi:[1,0,1]
	v_pk_fma_f32 v[10:11], v[184:185], v[224:225], v[10:11] op_sel_hi:[1,0,1]
	v_pk_fma_f32 v[12:13], v[182:183], v[224:225], v[12:13] op_sel:[0,1,0]
	v_pk_fma_f32 v[14:15], v[184:185], v[224:225], v[14:15] op_sel:[0,1,0]
	v_pk_fma_f32 v[16:17], v[182:183], v[226:227], v[16:17] op_sel_hi:[1,0,1]
	v_pk_fma_f32 v[18:19], v[184:185], v[226:227], v[18:19] op_sel_hi:[1,0,1]
	v_pk_fma_f32 v[20:21], v[182:183], v[226:227], v[20:21] op_sel:[0,1,0]
	v_pk_fma_f32 v[22:23], v[184:185], v[226:227], v[22:23] op_sel:[0,1,0]
	v_pk_fma_f32 v[24:25], v[182:183], v[228:229], v[24:25] op_sel_hi:[1,0,1]
	v_pk_fma_f32 v[26:27], v[184:185], v[228:229], v[26:27] op_sel_hi:[1,0,1]
	v_pk_fma_f32 v[28:29], v[182:183], v[228:229], v[28:29] op_sel:[0,1,0]
	v_pk_fma_f32 v[30:31], v[184:185], v[228:229], v[30:31] op_sel:[0,1,0]
	ds_read_b128 v[222:225], v32 offset:1280
	ds_read_b128 v[226:229], v32 offset:1296
	s_waitcnt lgkmcnt(2)
	v_pk_mul_f32 v[242:243], v[230:231], v[102:103] op_sel_hi:[0,1]
	v_pk_mul_f32 v[244:245], v[230:231], v[110:111] op_sel_hi:[0,1]
	v_pk_fma_f32 v[242:243], v[86:87], v[182:183], v[242:243]
	v_pk_fma_f32 v[244:245], v[86:87], v[184:185], v[244:245]
	v_pk_fma_f32 v[242:243], v[234:235], v[118:119], v[242:243] op_sel_hi:[0,1,1]
	v_pk_fma_f32 v[244:245], v[234:235], v[126:127], v[244:245] op_sel_hi:[0,1,1]
	v_pk_fma_f32 v[242:243], v[230:231], v[104:105], v[242:243] op_sel:[1,0,0]
	v_pk_fma_f32 v[244:245], v[230:231], v[112:113], v[244:245] op_sel:[1,0,0]
	v_pk_fma_f32 v[242:243], v[234:235], v[120:121], v[242:243] op_sel:[1,0,0]
	v_pk_fma_f32 v[244:245], v[234:235], v[128:129], v[244:245] op_sel:[1,0,0]
	v_pk_fma_f32 v[242:243], v[232:233], v[106:107], v[242:243] op_sel_hi:[0,1,1]
	v_pk_fma_f32 v[244:245], v[232:233], v[114:115], v[244:245] op_sel_hi:[0,1,1]
	v_pk_fma_f32 v[242:243], v[236:237], v[122:123], v[242:243] op_sel_hi:[0,1,1]
	v_pk_fma_f32 v[244:245], v[236:237], v[130:131], v[244:245] op_sel_hi:[0,1,1]
	v_pk_fma_f32 v[242:243], v[232:233], v[108:109], v[242:243] op_sel:[1,0,0]
	v_pk_fma_f32 v[244:245], v[232:233], v[116:117], v[244:245] op_sel:[1,0,0]
	v_pk_fma_f32 v[242:243], v[236:237], v[124:125], v[242:243] op_sel:[1,0,0]
	v_pk_fma_f32 v[244:245], v[236:237], v[132:133], v[244:245] op_sel:[1,0,0]
	ds_read_b128 v[230:233], v32 offset:17664
	ds_read_b128 v[234:237], v32 offset:17680
	global_store_dwordx4 v246, v[242:245], s[100:101] nt
	global_load_dwordx4 v[182:185], v246, s[98:99] nt
	s_add_u32 s100, s100, 0x2000
	s_addc_u32 s101, s101, 0
	s_add_u32 s98, s98, 0x2000
	s_addc_u32 s99, s99, 0
	s_waitcnt vmcnt(30)
	s_waitcnt lgkmcnt(2)
	v_pk_fma_f32 v[0:1], v[186:187], v[222:223], v[0:1] op_sel_hi:[1,0,1]
	v_pk_fma_f32 v[2:3], v[188:189], v[222:223], v[2:3] op_sel_hi:[1,0,1]
	v_pk_fma_f32 v[4:5], v[186:187], v[222:223], v[4:5] op_sel:[0,1,0]
	v_pk_fma_f32 v[6:7], v[188:189], v[222:223], v[6:7] op_sel:[0,1,0]
	v_pk_fma_f32 v[8:9], v[186:187], v[224:225], v[8:9] op_sel_hi:[1,0,1]
	v_pk_fma_f32 v[10:11], v[188:189], v[224:225], v[10:11] op_sel_hi:[1,0,1]
	v_pk_fma_f32 v[12:13], v[186:187], v[224:225], v[12:13] op_sel:[0,1,0]
	v_pk_fma_f32 v[14:15], v[188:189], v[224:225], v[14:15] op_sel:[0,1,0]
	v_pk_fma_f32 v[16:17], v[186:187], v[226:227], v[16:17] op_sel_hi:[1,0,1]
	v_pk_fma_f32 v[18:19], v[188:189], v[226:227], v[18:19] op_sel_hi:[1,0,1]
	v_pk_fma_f32 v[20:21], v[186:187], v[226:227], v[20:21] op_sel:[0,1,0]
	v_pk_fma_f32 v[22:23], v[188:189], v[226:227], v[22:23] op_sel:[0,1,0]
	v_pk_fma_f32 v[24:25], v[186:187], v[228:229], v[24:25] op_sel_hi:[1,0,1]
	v_pk_fma_f32 v[26:27], v[188:189], v[228:229], v[26:27] op_sel_hi:[1,0,1]
	v_pk_fma_f32 v[28:29], v[186:187], v[228:229], v[28:29] op_sel:[0,1,0]
	v_pk_fma_f32 v[30:31], v[188:189], v[228:229], v[30:31] op_sel:[0,1,0]
	ds_read_b128 v[222:225], v32 offset:1408
	ds_read_b128 v[226:229], v32 offset:1424
	s_waitcnt lgkmcnt(2)
	v_pk_mul_f32 v[238:239], v[230:231], v[102:103] op_sel_hi:[0,1]
	v_pk_mul_f32 v[240:241], v[230:231], v[110:111] op_sel_hi:[0,1]
	v_pk_fma_f32 v[238:239], v[86:87], v[186:187], v[238:239]
	v_pk_fma_f32 v[240:241], v[86:87], v[188:189], v[240:241]
	v_pk_fma_f32 v[238:239], v[234:235], v[118:119], v[238:239] op_sel_hi:[0,1,1]
	v_pk_fma_f32 v[240:241], v[234:235], v[126:127], v[240:241] op_sel_hi:[0,1,1]
	v_pk_fma_f32 v[238:239], v[230:231], v[104:105], v[238:239] op_sel:[1,0,0]
	v_pk_fma_f32 v[240:241], v[230:231], v[112:113], v[240:241] op_sel:[1,0,0]
	v_pk_fma_f32 v[238:239], v[234:235], v[120:121], v[238:239] op_sel:[1,0,0]
	v_pk_fma_f32 v[240:241], v[234:235], v[128:129], v[240:241] op_sel:[1,0,0]
	v_pk_fma_f32 v[238:239], v[232:233], v[106:107], v[238:239] op_sel_hi:[0,1,1]
	v_pk_fma_f32 v[240:241], v[232:233], v[114:115], v[240:241] op_sel_hi:[0,1,1]
	v_pk_fma_f32 v[238:239], v[236:237], v[122:123], v[238:239] op_sel_hi:[0,1,1]
	v_pk_fma_f32 v[240:241], v[236:237], v[130:131], v[240:241] op_sel_hi:[0,1,1]
	v_pk_fma_f32 v[238:239], v[232:233], v[108:109], v[238:239] op_sel:[1,0,0]
	v_pk_fma_f32 v[240:241], v[232:233], v[116:117], v[240:241] op_sel:[1,0,0]
	v_pk_fma_f32 v[238:239], v[236:237], v[124:125], v[238:239] op_sel:[1,0,0]
	v_pk_fma_f32 v[240:241], v[236:237], v[132:133], v[240:241] op_sel:[1,0,0]
	ds_read_b128 v[230:233], v32 offset:17792
	ds_read_b128 v[234:237], v32 offset:17808
	global_store_dwordx4 v246, v[238:241], s[100:101] nt
	global_load_dwordx4 v[186:189], v246, s[98:99] nt
	s_add_u32 s100, s100, 0x2000
	s_addc_u32 s101, s101, 0
	s_add_u32 s98, s98, 0x2000
	s_addc_u32 s99, s99, 0
	s_waitcnt vmcnt(30)
	s_waitcnt lgkmcnt(2)
	v_pk_fma_f32 v[0:1], v[190:191], v[222:223], v[0:1] op_sel_hi:[1,0,1]
	v_pk_fma_f32 v[2:3], v[192:193], v[222:223], v[2:3] op_sel_hi:[1,0,1]
	v_pk_fma_f32 v[4:5], v[190:191], v[222:223], v[4:5] op_sel:[0,1,0]
	v_pk_fma_f32 v[6:7], v[192:193], v[222:223], v[6:7] op_sel:[0,1,0]
	v_pk_fma_f32 v[8:9], v[190:191], v[224:225], v[8:9] op_sel_hi:[1,0,1]
	v_pk_fma_f32 v[10:11], v[192:193], v[224:225], v[10:11] op_sel_hi:[1,0,1]
	v_pk_fma_f32 v[12:13], v[190:191], v[224:225], v[12:13] op_sel:[0,1,0]
	v_pk_fma_f32 v[14:15], v[192:193], v[224:225], v[14:15] op_sel:[0,1,0]
	v_pk_fma_f32 v[16:17], v[190:191], v[226:227], v[16:17] op_sel_hi:[1,0,1]
	v_pk_fma_f32 v[18:19], v[192:193], v[226:227], v[18:19] op_sel_hi:[1,0,1]
	v_pk_fma_f32 v[20:21], v[190:191], v[226:227], v[20:21] op_sel:[0,1,0]
	v_pk_fma_f32 v[22:23], v[192:193], v[226:227], v[22:23] op_sel:[0,1,0]
	v_pk_fma_f32 v[24:25], v[190:191], v[228:229], v[24:25] op_sel_hi:[1,0,1]
	v_pk_fma_f32 v[26:27], v[192:193], v[228:229], v[26:27] op_sel_hi:[1,0,1]
	v_pk_fma_f32 v[28:29], v[190:191], v[228:229], v[28:29] op_sel:[0,1,0]
	v_pk_fma_f32 v[30:31], v[192:193], v[228:229], v[30:31] op_sel:[0,1,0]
	ds_read_b128 v[222:225], v32 offset:1536
	ds_read_b128 v[226:229], v32 offset:1552
	s_waitcnt lgkmcnt(2)
	v_pk_mul_f32 v[242:243], v[230:231], v[102:103] op_sel_hi:[0,1]
	v_pk_mul_f32 v[244:245], v[230:231], v[110:111] op_sel_hi:[0,1]
	v_pk_fma_f32 v[242:243], v[86:87], v[190:191], v[242:243]
	v_pk_fma_f32 v[244:245], v[86:87], v[192:193], v[244:245]
	v_pk_fma_f32 v[242:243], v[234:235], v[118:119], v[242:243] op_sel_hi:[0,1,1]
	v_pk_fma_f32 v[244:245], v[234:235], v[126:127], v[244:245] op_sel_hi:[0,1,1]
	v_pk_fma_f32 v[242:243], v[230:231], v[104:105], v[242:243] op_sel:[1,0,0]
	v_pk_fma_f32 v[244:245], v[230:231], v[112:113], v[244:245] op_sel:[1,0,0]
	v_pk_fma_f32 v[242:243], v[234:235], v[120:121], v[242:243] op_sel:[1,0,0]
	v_pk_fma_f32 v[244:245], v[234:235], v[128:129], v[244:245] op_sel:[1,0,0]
	v_pk_fma_f32 v[242:243], v[232:233], v[106:107], v[242:243] op_sel_hi:[0,1,1]
	v_pk_fma_f32 v[244:245], v[232:233], v[114:115], v[244:245] op_sel_hi:[0,1,1]
	v_pk_fma_f32 v[242:243], v[236:237], v[122:123], v[242:243] op_sel_hi:[0,1,1]
	v_pk_fma_f32 v[244:245], v[236:237], v[130:131], v[244:245] op_sel_hi:[0,1,1]
	v_pk_fma_f32 v[242:243], v[232:233], v[108:109], v[242:243] op_sel:[1,0,0]
	v_pk_fma_f32 v[244:245], v[232:233], v[116:117], v[244:245] op_sel:[1,0,0]
	v_pk_fma_f32 v[242:243], v[236:237], v[124:125], v[242:243] op_sel:[1,0,0]
	v_pk_fma_f32 v[244:245], v[236:237], v[132:133], v[244:245] op_sel:[1,0,0]
	ds_read_b128 v[230:233], v32 offset:17920
	ds_read_b128 v[234:237], v32 offset:17936
	global_store_dwordx4 v246, v[242:245], s[100:101] nt
	global_load_dwordx4 v[190:193], v246, s[98:99] nt
	s_add_u32 s100, s100, 0x2000
	s_addc_u32 s101, s101, 0
	s_add_u32 s98, s98, 0x2000
	s_addc_u32 s99, s99, 0
	s_waitcnt vmcnt(30)
	s_waitcnt lgkmcnt(2)
	v_pk_fma_f32 v[0:1], v[194:195], v[222:223], v[0:1] op_sel_hi:[1,0,1]
	v_pk_fma_f32 v[2:3], v[196:197], v[222:223], v[2:3] op_sel_hi:[1,0,1]
	v_pk_fma_f32 v[4:5], v[194:195], v[222:223], v[4:5] op_sel:[0,1,0]
	v_pk_fma_f32 v[6:7], v[196:197], v[222:223], v[6:7] op_sel:[0,1,0]
	v_pk_fma_f32 v[8:9], v[194:195], v[224:225], v[8:9] op_sel_hi:[1,0,1]
	v_pk_fma_f32 v[10:11], v[196:197], v[224:225], v[10:11] op_sel_hi:[1,0,1]
	v_pk_fma_f32 v[12:13], v[194:195], v[224:225], v[12:13] op_sel:[0,1,0]
	v_pk_fma_f32 v[14:15], v[196:197], v[224:225], v[14:15] op_sel:[0,1,0]
	v_pk_fma_f32 v[16:17], v[194:195], v[226:227], v[16:17] op_sel_hi:[1,0,1]
	v_pk_fma_f32 v[18:19], v[196:197], v[226:227], v[18:19] op_sel_hi:[1,0,1]
	v_pk_fma_f32 v[20:21], v[194:195], v[226:227], v[20:21] op_sel:[0,1,0]
	v_pk_fma_f32 v[22:23], v[196:197], v[226:227], v[22:23] op_sel:[0,1,0]
	v_pk_fma_f32 v[24:25], v[194:195], v[228:229], v[24:25] op_sel_hi:[1,0,1]
	v_pk_fma_f32 v[26:27], v[196:197], v[228:229], v[26:27] op_sel_hi:[1,0,1]
	v_pk_fma_f32 v[28:29], v[194:195], v[228:229], v[28:29] op_sel:[0,1,0]
	v_pk_fma_f32 v[30:31], v[196:197], v[228:229], v[30:31] op_sel:[0,1,0]
	ds_read_b128 v[222:225], v32 offset:1664
	ds_read_b128 v[226:229], v32 offset:1680
	s_waitcnt lgkmcnt(2)
	v_pk_mul_f32 v[238:239], v[230:231], v[102:103] op_sel_hi:[0,1]
	v_pk_mul_f32 v[240:241], v[230:231], v[110:111] op_sel_hi:[0,1]
	v_pk_fma_f32 v[238:239], v[86:87], v[194:195], v[238:239]
	v_pk_fma_f32 v[240:241], v[86:87], v[196:197], v[240:241]
	v_pk_fma_f32 v[238:239], v[234:235], v[118:119], v[238:239] op_sel_hi:[0,1,1]
	v_pk_fma_f32 v[240:241], v[234:235], v[126:127], v[240:241] op_sel_hi:[0,1,1]
	v_pk_fma_f32 v[238:239], v[230:231], v[104:105], v[238:239] op_sel:[1,0,0]
	v_pk_fma_f32 v[240:241], v[230:231], v[112:113], v[240:241] op_sel:[1,0,0]
	v_pk_fma_f32 v[238:239], v[234:235], v[120:121], v[238:239] op_sel:[1,0,0]
	v_pk_fma_f32 v[240:241], v[234:235], v[128:129], v[240:241] op_sel:[1,0,0]
	v_pk_fma_f32 v[238:239], v[232:233], v[106:107], v[238:239] op_sel_hi:[0,1,1]
	v_pk_fma_f32 v[240:241], v[232:233], v[114:115], v[240:241] op_sel_hi:[0,1,1]
	v_pk_fma_f32 v[238:239], v[236:237], v[122:123], v[238:239] op_sel_hi:[0,1,1]
	v_pk_fma_f32 v[240:241], v[236:237], v[130:131], v[240:241] op_sel_hi:[0,1,1]
	v_pk_fma_f32 v[238:239], v[232:233], v[108:109], v[238:239] op_sel:[1,0,0]
	v_pk_fma_f32 v[240:241], v[232:233], v[116:117], v[240:241] op_sel:[1,0,0]
	v_pk_fma_f32 v[238:239], v[236:237], v[124:125], v[238:239] op_sel:[1,0,0]
	v_pk_fma_f32 v[240:241], v[236:237], v[132:133], v[240:241] op_sel:[1,0,0]
	ds_read_b128 v[230:233], v32 offset:18048
	ds_read_b128 v[234:237], v32 offset:18064
	global_store_dwordx4 v246, v[238:241], s[100:101] nt
	global_load_dwordx4 v[194:197], v246, s[98:99] nt
	s_add_u32 s100, s100, 0x2000
	s_addc_u32 s101, s101, 0
	s_add_u32 s98, s98, 0x2000
	s_addc_u32 s99, s99, 0
	s_waitcnt vmcnt(30)
	s_waitcnt lgkmcnt(2)
	v_pk_fma_f32 v[0:1], v[210:211], v[222:223], v[0:1] op_sel_hi:[1,0,1]
	v_pk_fma_f32 v[2:3], v[212:213], v[222:223], v[2:3] op_sel_hi:[1,0,1]
	v_pk_fma_f32 v[4:5], v[210:211], v[222:223], v[4:5] op_sel:[0,1,0]
	v_pk_fma_f32 v[6:7], v[212:213], v[222:223], v[6:7] op_sel:[0,1,0]
	v_pk_fma_f32 v[8:9], v[210:211], v[224:225], v[8:9] op_sel_hi:[1,0,1]
	v_pk_fma_f32 v[10:11], v[212:213], v[224:225], v[10:11] op_sel_hi:[1,0,1]
	v_pk_fma_f32 v[12:13], v[210:211], v[224:225], v[12:13] op_sel:[0,1,0]
	v_pk_fma_f32 v[14:15], v[212:213], v[224:225], v[14:15] op_sel:[0,1,0]
	v_pk_fma_f32 v[16:17], v[210:211], v[226:227], v[16:17] op_sel_hi:[1,0,1]
	v_pk_fma_f32 v[18:19], v[212:213], v[226:227], v[18:19] op_sel_hi:[1,0,1]
	v_pk_fma_f32 v[20:21], v[210:211], v[226:227], v[20:21] op_sel:[0,1,0]
	v_pk_fma_f32 v[22:23], v[212:213], v[226:227], v[22:23] op_sel:[0,1,0]
	v_pk_fma_f32 v[24:25], v[210:211], v[228:229], v[24:25] op_sel_hi:[1,0,1]
	v_pk_fma_f32 v[26:27], v[212:213], v[228:229], v[26:27] op_sel_hi:[1,0,1]
	v_pk_fma_f32 v[28:29], v[210:211], v[228:229], v[28:29] op_sel:[0,1,0]
	v_pk_fma_f32 v[30:31], v[212:213], v[228:229], v[30:31] op_sel:[0,1,0]
	ds_read_b128 v[222:225], v32 offset:1792
	ds_read_b128 v[226:229], v32 offset:1808
	s_waitcnt lgkmcnt(2)
	v_pk_mul_f32 v[242:243], v[230:231], v[102:103] op_sel_hi:[0,1]
	v_pk_mul_f32 v[244:245], v[230:231], v[110:111] op_sel_hi:[0,1]
	v_pk_fma_f32 v[242:243], v[86:87], v[210:211], v[242:243]
	v_pk_fma_f32 v[244:245], v[86:87], v[212:213], v[244:245]
	v_pk_fma_f32 v[242:243], v[234:235], v[118:119], v[242:243] op_sel_hi:[0,1,1]
	v_pk_fma_f32 v[244:245], v[234:235], v[126:127], v[244:245] op_sel_hi:[0,1,1]
	v_pk_fma_f32 v[242:243], v[230:231], v[104:105], v[242:243] op_sel:[1,0,0]
	v_pk_fma_f32 v[244:245], v[230:231], v[112:113], v[244:245] op_sel:[1,0,0]
	v_pk_fma_f32 v[242:243], v[234:235], v[120:121], v[242:243] op_sel:[1,0,0]
	v_pk_fma_f32 v[244:245], v[234:235], v[128:129], v[244:245] op_sel:[1,0,0]
	v_pk_fma_f32 v[242:243], v[232:233], v[106:107], v[242:243] op_sel_hi:[0,1,1]
	v_pk_fma_f32 v[244:245], v[232:233], v[114:115], v[244:245] op_sel_hi:[0,1,1]
	v_pk_fma_f32 v[242:243], v[236:237], v[122:123], v[242:243] op_sel_hi:[0,1,1]
	v_pk_fma_f32 v[244:245], v[236:237], v[130:131], v[244:245] op_sel_hi:[0,1,1]
	v_pk_fma_f32 v[242:243], v[232:233], v[108:109], v[242:243] op_sel:[1,0,0]
	v_pk_fma_f32 v[244:245], v[232:233], v[116:117], v[244:245] op_sel:[1,0,0]
	v_pk_fma_f32 v[242:243], v[236:237], v[124:125], v[242:243] op_sel:[1,0,0]
	v_pk_fma_f32 v[244:245], v[236:237], v[132:133], v[244:245] op_sel:[1,0,0]
	ds_read_b128 v[230:233], v32 offset:18176
	ds_read_b128 v[234:237], v32 offset:18192
	global_store_dwordx4 v246, v[242:245], s[100:101] nt
	global_load_dwordx4 v[210:213], v246, s[98:99] nt
	s_add_u32 s100, s100, 0x2000
	s_addc_u32 s101, s101, 0
	s_add_u32 s98, s98, 0x2000
	s_addc_u32 s99, s99, 0
	s_waitcnt vmcnt(30)
	s_waitcnt lgkmcnt(2)
	v_pk_fma_f32 v[0:1], v[214:215], v[222:223], v[0:1] op_sel_hi:[1,0,1]
	v_pk_fma_f32 v[2:3], v[216:217], v[222:223], v[2:3] op_sel_hi:[1,0,1]
	v_pk_fma_f32 v[4:5], v[214:215], v[222:223], v[4:5] op_sel:[0,1,0]
	v_pk_fma_f32 v[6:7], v[216:217], v[222:223], v[6:7] op_sel:[0,1,0]
	v_pk_fma_f32 v[8:9], v[214:215], v[224:225], v[8:9] op_sel_hi:[1,0,1]
	v_pk_fma_f32 v[10:11], v[216:217], v[224:225], v[10:11] op_sel_hi:[1,0,1]
	v_pk_fma_f32 v[12:13], v[214:215], v[224:225], v[12:13] op_sel:[0,1,0]
	v_pk_fma_f32 v[14:15], v[216:217], v[224:225], v[14:15] op_sel:[0,1,0]
	v_pk_fma_f32 v[16:17], v[214:215], v[226:227], v[16:17] op_sel_hi:[1,0,1]
	v_pk_fma_f32 v[18:19], v[216:217], v[226:227], v[18:19] op_sel_hi:[1,0,1]
	v_pk_fma_f32 v[20:21], v[214:215], v[226:227], v[20:21] op_sel:[0,1,0]
	v_pk_fma_f32 v[22:23], v[216:217], v[226:227], v[22:23] op_sel:[0,1,0]
	v_pk_fma_f32 v[24:25], v[214:215], v[228:229], v[24:25] op_sel_hi:[1,0,1]
	v_pk_fma_f32 v[26:27], v[216:217], v[228:229], v[26:27] op_sel_hi:[1,0,1]
	v_pk_fma_f32 v[28:29], v[214:215], v[228:229], v[28:29] op_sel:[0,1,0]
	v_pk_fma_f32 v[30:31], v[216:217], v[228:229], v[30:31] op_sel:[0,1,0]
	ds_read_b128 v[222:225], v32 offset:1920
	ds_read_b128 v[226:229], v32 offset:1936
	s_waitcnt lgkmcnt(2)
	v_pk_mul_f32 v[238:239], v[230:231], v[102:103] op_sel_hi:[0,1]
	v_pk_mul_f32 v[240:241], v[230:231], v[110:111] op_sel_hi:[0,1]
	v_pk_fma_f32 v[238:239], v[86:87], v[214:215], v[238:239]
	v_pk_fma_f32 v[240:241], v[86:87], v[216:217], v[240:241]
	v_pk_fma_f32 v[238:239], v[234:235], v[118:119], v[238:239] op_sel_hi:[0,1,1]
	v_pk_fma_f32 v[240:241], v[234:235], v[126:127], v[240:241] op_sel_hi:[0,1,1]
	v_pk_fma_f32 v[238:239], v[230:231], v[104:105], v[238:239] op_sel:[1,0,0]
	v_pk_fma_f32 v[240:241], v[230:231], v[112:113], v[240:241] op_sel:[1,0,0]
	v_pk_fma_f32 v[238:239], v[234:235], v[120:121], v[238:239] op_sel:[1,0,0]
	v_pk_fma_f32 v[240:241], v[234:235], v[128:129], v[240:241] op_sel:[1,0,0]
	v_pk_fma_f32 v[238:239], v[232:233], v[106:107], v[238:239] op_sel_hi:[0,1,1]
	v_pk_fma_f32 v[240:241], v[232:233], v[114:115], v[240:241] op_sel_hi:[0,1,1]
	v_pk_fma_f32 v[238:239], v[236:237], v[122:123], v[238:239] op_sel_hi:[0,1,1]
	v_pk_fma_f32 v[240:241], v[236:237], v[130:131], v[240:241] op_sel_hi:[0,1,1]
	v_pk_fma_f32 v[238:239], v[232:233], v[108:109], v[238:239] op_sel:[1,0,0]
	v_pk_fma_f32 v[240:241], v[232:233], v[116:117], v[240:241] op_sel:[1,0,0]
	v_pk_fma_f32 v[238:239], v[236:237], v[124:125], v[238:239] op_sel:[1,0,0]
	v_pk_fma_f32 v[240:241], v[236:237], v[132:133], v[240:241] op_sel:[1,0,0]
	ds_read_b128 v[230:233], v32 offset:18304
	ds_read_b128 v[234:237], v32 offset:18320
	global_store_dwordx4 v246, v[238:241], s[100:101] nt
	global_load_dwordx4 v[214:217], v246, s[98:99] nt
	s_add_u32 s100, s100, 0x2000
	s_addc_u32 s101, s101, 0
	s_add_u32 s98, s98, 0x2000
	s_addc_u32 s99, s99, 0
	s_waitcnt vmcnt(30)
	s_waitcnt lgkmcnt(2)
	v_pk_fma_f32 v[0:1], v[218:219], v[222:223], v[0:1] op_sel_hi:[1,0,1]
	v_pk_fma_f32 v[2:3], v[220:221], v[222:223], v[2:3] op_sel_hi:[1,0,1]
	v_pk_fma_f32 v[4:5], v[218:219], v[222:223], v[4:5] op_sel:[0,1,0]
	v_pk_fma_f32 v[6:7], v[220:221], v[222:223], v[6:7] op_sel:[0,1,0]
	v_pk_fma_f32 v[8:9], v[218:219], v[224:225], v[8:9] op_sel_hi:[1,0,1]
	v_pk_fma_f32 v[10:11], v[220:221], v[224:225], v[10:11] op_sel_hi:[1,0,1]
	v_pk_fma_f32 v[12:13], v[218:219], v[224:225], v[12:13] op_sel:[0,1,0]
	v_pk_fma_f32 v[14:15], v[220:221], v[224:225], v[14:15] op_sel:[0,1,0]
	v_pk_fma_f32 v[16:17], v[218:219], v[226:227], v[16:17] op_sel_hi:[1,0,1]
	v_pk_fma_f32 v[18:19], v[220:221], v[226:227], v[18:19] op_sel_hi:[1,0,1]
	v_pk_fma_f32 v[20:21], v[218:219], v[226:227], v[20:21] op_sel:[0,1,0]
	v_pk_fma_f32 v[22:23], v[220:221], v[226:227], v[22:23] op_sel:[0,1,0]
	v_pk_fma_f32 v[24:25], v[218:219], v[228:229], v[24:25] op_sel_hi:[1,0,1]
	v_pk_fma_f32 v[26:27], v[220:221], v[228:229], v[26:27] op_sel_hi:[1,0,1]
	v_pk_fma_f32 v[28:29], v[218:219], v[228:229], v[28:29] op_sel:[0,1,0]
	v_pk_fma_f32 v[30:31], v[220:221], v[228:229], v[30:31] op_sel:[0,1,0]
	ds_read_b128 v[222:225], v32 offset:2048
	ds_read_b128 v[226:229], v32 offset:2064
	s_waitcnt lgkmcnt(2)
	v_pk_mul_f32 v[242:243], v[230:231], v[102:103] op_sel_hi:[0,1]
	v_pk_mul_f32 v[244:245], v[230:231], v[110:111] op_sel_hi:[0,1]
	v_pk_fma_f32 v[242:243], v[86:87], v[218:219], v[242:243]
	v_pk_fma_f32 v[244:245], v[86:87], v[220:221], v[244:245]
	v_pk_fma_f32 v[242:243], v[234:235], v[118:119], v[242:243] op_sel_hi:[0,1,1]
	v_pk_fma_f32 v[244:245], v[234:235], v[126:127], v[244:245] op_sel_hi:[0,1,1]
	v_pk_fma_f32 v[242:243], v[230:231], v[104:105], v[242:243] op_sel:[1,0,0]
	v_pk_fma_f32 v[244:245], v[230:231], v[112:113], v[244:245] op_sel:[1,0,0]
	v_pk_fma_f32 v[242:243], v[234:235], v[120:121], v[242:243] op_sel:[1,0,0]
	v_pk_fma_f32 v[244:245], v[234:235], v[128:129], v[244:245] op_sel:[1,0,0]
	v_pk_fma_f32 v[242:243], v[232:233], v[106:107], v[242:243] op_sel_hi:[0,1,1]
	v_pk_fma_f32 v[244:245], v[232:233], v[114:115], v[244:245] op_sel_hi:[0,1,1]
	v_pk_fma_f32 v[242:243], v[236:237], v[122:123], v[242:243] op_sel_hi:[0,1,1]
	v_pk_fma_f32 v[244:245], v[236:237], v[130:131], v[244:245] op_sel_hi:[0,1,1]
	v_pk_fma_f32 v[242:243], v[232:233], v[108:109], v[242:243] op_sel:[1,0,0]
	v_pk_fma_f32 v[244:245], v[232:233], v[116:117], v[244:245] op_sel:[1,0,0]
	v_pk_fma_f32 v[242:243], v[236:237], v[124:125], v[242:243] op_sel:[1,0,0]
	v_pk_fma_f32 v[244:245], v[236:237], v[132:133], v[244:245] op_sel:[1,0,0]
	ds_read_b128 v[230:233], v32 offset:18432
	ds_read_b128 v[234:237], v32 offset:18448
	global_store_dwordx4 v246, v[242:245], s[100:101] nt
	global_load_dwordx4 v[218:221], v246, s[98:99] nt
	s_add_u32 s100, s100, 0x2000
	s_addc_u32 s101, s101, 0
	s_add_u32 s98, s98, 0x2000
	s_addc_u32 s99, s99, 0
	v_add_u32_e32 v32, 0x800, v32
	s_add_u32 vcc_lo, vcc_lo, 1
	s_cmp_lt_u32 vcc_lo, 6
	s_cbranch_scc1 .Lsstream_a_loop
	s_waitcnt vmcnt(30)
	s_waitcnt lgkmcnt(2)
	v_pk_fma_f32 v[0:1], v[134:135], v[222:223], v[0:1] op_sel_hi:[1,0,1]
	v_pk_fma_f32 v[2:3], v[136:137], v[222:223], v[2:3] op_sel_hi:[1,0,1]
	v_pk_fma_f32 v[4:5], v[134:135], v[222:223], v[4:5] op_sel:[0,1,0]
	v_pk_fma_f32 v[6:7], v[136:137], v[222:223], v[6:7] op_sel:[0,1,0]
	v_pk_fma_f32 v[8:9], v[134:135], v[224:225], v[8:9] op_sel_hi:[1,0,1]
	v_pk_fma_f32 v[10:11], v[136:137], v[224:225], v[10:11] op_sel_hi:[1,0,1]
	v_pk_fma_f32 v[12:13], v[134:135], v[224:225], v[12:13] op_sel:[0,1,0]
	v_pk_fma_f32 v[14:15], v[136:137], v[224:225], v[14:15] op_sel:[0,1,0]
	v_pk_fma_f32 v[16:17], v[134:135], v[226:227], v[16:17] op_sel_hi:[1,0,1]
	v_pk_fma_f32 v[18:19], v[136:137], v[226:227], v[18:19] op_sel_hi:[1,0,1]
	v_pk_fma_f32 v[20:21], v[134:135], v[226:227], v[20:21] op_sel:[0,1,0]
	v_pk_fma_f32 v[22:23], v[136:137], v[226:227], v[22:23] op_sel:[0,1,0]
	v_pk_fma_f32 v[24:25], v[134:135], v[228:229], v[24:25] op_sel_hi:[1,0,1]
	v_pk_fma_f32 v[26:27], v[136:137], v[228:229], v[26:27] op_sel_hi:[1,0,1]
	v_pk_fma_f32 v[28:29], v[134:135], v[228:229], v[28:29] op_sel:[0,1,0]
	v_pk_fma_f32 v[30:31], v[136:137], v[228:229], v[30:31] op_sel:[0,1,0]
	ds_read_b128 v[222:225], v32 offset:128
	ds_read_b128 v[226:229], v32 offset:144
	s_waitcnt lgkmcnt(2)
	v_pk_mul_f32 v[238:239], v[230:231], v[102:103] op_sel_hi:[0,1]
	v_pk_mul_f32 v[240:241], v[230:231], v[110:111] op_sel_hi:[0,1]
	v_pk_fma_f32 v[238:239], v[86:87], v[134:135], v[238:239]
	v_pk_fma_f32 v[240:241], v[86:87], v[136:137], v[240:241]
	v_pk_fma_f32 v[238:239], v[234:235], v[118:119], v[238:239] op_sel_hi:[0,1,1]
	v_pk_fma_f32 v[240:241], v[234:235], v[126:127], v[240:241] op_sel_hi:[0,1,1]
	v_pk_fma_f32 v[238:239], v[230:231], v[104:105], v[238:239] op_sel:[1,0,0]
	v_pk_fma_f32 v[240:241], v[230:231], v[112:113], v[240:241] op_sel:[1,0,0]
	v_pk_fma_f32 v[238:239], v[234:235], v[120:121], v[238:239] op_sel:[1,0,0]
	v_pk_fma_f32 v[240:241], v[234:235], v[128:129], v[240:241] op_sel:[1,0,0]
	v_pk_fma_f32 v[238:239], v[232:233], v[106:107], v[238:239] op_sel_hi:[0,1,1]
	v_pk_fma_f32 v[240:241], v[232:233], v[114:115], v[240:241] op_sel_hi:[0,1,1]
	v_pk_fma_f32 v[238:239], v[236:237], v[122:123], v[238:239] op_sel_hi:[0,1,1]
	v_pk_fma_f32 v[240:241], v[236:237], v[130:131], v[240:241] op_sel_hi:[0,1,1]
	v_pk_fma_f32 v[238:239], v[232:233], v[108:109], v[238:239] op_sel:[1,0,0]
	v_pk_fma_f32 v[240:241], v[232:233], v[116:117], v[240:241] op_sel:[1,0,0]
	v_pk_fma_f32 v[238:239], v[236:237], v[124:125], v[238:239] op_sel:[1,0,0]
	v_pk_fma_f32 v[240:241], v[236:237], v[132:133], v[240:241] op_sel:[1,0,0]
	ds_read_b128 v[230:233], v32 offset:16512
	ds_read_b128 v[234:237], v32 offset:16528
	global_store_dwordx4 v246, v[238:241], s[100:101] nt
	s_add_u32 s100, s100, 0x2000
	s_addc_u32 s101, s101, 0
	s_waitcnt vmcnt(29)
	s_waitcnt lgkmcnt(2)
	v_pk_fma_f32 v[0:1], v[138:139], v[222:223], v[0:1] op_sel_hi:[1,0,1]
	v_pk_fma_f32 v[2:3], v[140:141], v[222:223], v[2:3] op_sel_hi:[1,0,1]
	v_pk_fma_f32 v[4:5], v[138:139], v[222:223], v[4:5] op_sel:[0,1,0]
	v_pk_fma_f32 v[6:7], v[140:141], v[222:223], v[6:7] op_sel:[0,1,0]
	v_pk_fma_f32 v[8:9], v[138:139], v[224:225], v[8:9] op_sel_hi:[1,0,1]
	v_pk_fma_f32 v[10:11], v[140:141], v[224:225], v[10:11] op_sel_hi:[1,0,1]
	v_pk_fma_f32 v[12:13], v[138:139], v[224:225], v[12:13] op_sel:[0,1,0]
	v_pk_fma_f32 v[14:15], v[140:141], v[224:225], v[14:15] op_sel:[0,1,0]
	v_pk_fma_f32 v[16:17], v[138:139], v[226:227], v[16:17] op_sel_hi:[1,0,1]
	v_pk_fma_f32 v[18:19], v[140:141], v[226:227], v[18:19] op_sel_hi:[1,0,1]
	v_pk_fma_f32 v[20:21], v[138:139], v[226:227], v[20:21] op_sel:[0,1,0]
	v_pk_fma_f32 v[22:23], v[140:141], v[226:227], v[22:23] op_sel:[0,1,0]
	v_pk_fma_f32 v[24:25], v[138:139], v[228:229], v[24:25] op_sel_hi:[1,0,1]
	v_pk_fma_f32 v[26:27], v[140:141], v[228:229], v[26:27] op_sel_hi:[1,0,1]
	v_pk_fma_f32 v[28:29], v[138:139], v[228:229], v[28:29] op_sel:[0,1,0]
	v_pk_fma_f32 v[30:31], v[140:141], v[228:229], v[30:31] op_sel:[0,1,0]
	ds_read_b128 v[222:225], v32 offset:256
	ds_read_b128 v[226:229], v32 offset:272
	s_waitcnt lgkmcnt(2)
	v_pk_mul_f32 v[242:243], v[230:231], v[102:103] op_sel_hi:[0,1]
	v_pk_mul_f32 v[244:245], v[230:231], v[110:111] op_sel_hi:[0,1]
	v_pk_fma_f32 v[242:243], v[86:87], v[138:139], v[242:243]
	v_pk_fma_f32 v[244:245], v[86:87], v[140:141], v[244:245]
	v_pk_fma_f32 v[242:243], v[234:235], v[118:119], v[242:243] op_sel_hi:[0,1,1]
	v_pk_fma_f32 v[244:245], v[234:235], v[126:127], v[244:245] op_sel_hi:[0,1,1]
	v_pk_fma_f32 v[242:243], v[230:231], v[104:105], v[242:243] op_sel:[1,0,0]
	v_pk_fma_f32 v[244:245], v[230:231], v[112:113], v[244:245] op_sel:[1,0,0]
	v_pk_fma_f32 v[242:243], v[234:235], v[120:121], v[242:243] op_sel:[1,0,0]
	v_pk_fma_f32 v[244:245], v[234:235], v[128:129], v[244:245] op_sel:[1,0,0]
	v_pk_fma_f32 v[242:243], v[232:233], v[106:107], v[242:243] op_sel_hi:[0,1,1]
	v_pk_fma_f32 v[244:245], v[232:233], v[114:115], v[244:245] op_sel_hi:[0,1,1]
	v_pk_fma_f32 v[242:243], v[236:237], v[122:123], v[242:243] op_sel_hi:[0,1,1]
	v_pk_fma_f32 v[244:245], v[236:237], v[130:131], v[244:245] op_sel_hi:[0,1,1]
	v_pk_fma_f32 v[242:243], v[232:233], v[108:109], v[242:243] op_sel:[1,0,0]
	v_pk_fma_f32 v[244:245], v[232:233], v[116:117], v[244:245] op_sel:[1,0,0]
	v_pk_fma_f32 v[242:243], v[236:237], v[124:125], v[242:243] op_sel:[1,0,0]
	v_pk_fma_f32 v[244:245], v[236:237], v[132:133], v[244:245] op_sel:[1,0,0]
	ds_read_b128 v[230:233], v32 offset:16640
	ds_read_b128 v[234:237], v32 offset:16656
	global_store_dwordx4 v246, v[242:245], s[100:101] nt
	s_add_u32 s100, s100, 0x2000
	s_addc_u32 s101, s101, 0
	s_waitcnt vmcnt(28)
	s_waitcnt lgkmcnt(2)
	v_pk_fma_f32 v[0:1], v[142:143], v[222:223], v[0:1] op_sel_hi:[1,0,1]
	v_pk_fma_f32 v[2:3], v[144:145], v[222:223], v[2:3] op_sel_hi:[1,0,1]
	v_pk_fma_f32 v[4:5], v[142:143], v[222:223], v[4:5] op_sel:[0,1,0]
	v_pk_fma_f32 v[6:7], v[144:145], v[222:223], v[6:7] op_sel:[0,1,0]
	v_pk_fma_f32 v[8:9], v[142:143], v[224:225], v[8:9] op_sel_hi:[1,0,1]
	v_pk_fma_f32 v[10:11], v[144:145], v[224:225], v[10:11] op_sel_hi:[1,0,1]
	v_pk_fma_f32 v[12:13], v[142:143], v[224:225], v[12:13] op_sel:[0,1,0]
	v_pk_fma_f32 v[14:15], v[144:145], v[224:225], v[14:15] op_sel:[0,1,0]
	v_pk_fma_f32 v[16:17], v[142:143], v[226:227], v[16:17] op_sel_hi:[1,0,1]
	v_pk_fma_f32 v[18:19], v[144:145], v[226:227], v[18:19] op_sel_hi:[1,0,1]
	v_pk_fma_f32 v[20:21], v[142:143], v[226:227], v[20:21] op_sel:[0,1,0]
	v_pk_fma_f32 v[22:23], v[144:145], v[226:227], v[22:23] op_sel:[0,1,0]
	v_pk_fma_f32 v[24:25], v[142:143], v[228:229], v[24:25] op_sel_hi:[1,0,1]
	v_pk_fma_f32 v[26:27], v[144:145], v[228:229], v[26:27] op_sel_hi:[1,0,1]
	v_pk_fma_f32 v[28:29], v[142:143], v[228:229], v[28:29] op_sel:[0,1,0]
	v_pk_fma_f32 v[30:31], v[144:145], v[228:229], v[30:31] op_sel:[0,1,0]
	ds_read_b128 v[222:225], v32 offset:384
	ds_read_b128 v[226:229], v32 offset:400
	s_waitcnt lgkmcnt(2)
	v_pk_mul_f32 v[238:239], v[230:231], v[102:103] op_sel_hi:[0,1]
	v_pk_mul_f32 v[240:241], v[230:231], v[110:111] op_sel_hi:[0,1]
	v_pk_fma_f32 v[238:239], v[86:87], v[142:143], v[238:239]
	v_pk_fma_f32 v[240:241], v[86:87], v[144:145], v[240:241]
	v_pk_fma_f32 v[238:239], v[234:235], v[118:119], v[238:239] op_sel_hi:[0,1,1]
	v_pk_fma_f32 v[240:241], v[234:235], v[126:127], v[240:241] op_sel_hi:[0,1,1]
	v_pk_fma_f32 v[238:239], v[230:231], v[104:105], v[238:239] op_sel:[1,0,0]
	v_pk_fma_f32 v[240:241], v[230:231], v[112:113], v[240:241] op_sel:[1,0,0]
	v_pk_fma_f32 v[238:239], v[234:235], v[120:121], v[238:239] op_sel:[1,0,0]
	v_pk_fma_f32 v[240:241], v[234:235], v[128:129], v[240:241] op_sel:[1,0,0]
	v_pk_fma_f32 v[238:239], v[232:233], v[106:107], v[238:239] op_sel_hi:[0,1,1]
	v_pk_fma_f32 v[240:241], v[232:233], v[114:115], v[240:241] op_sel_hi:[0,1,1]
	v_pk_fma_f32 v[238:239], v[236:237], v[122:123], v[238:239] op_sel_hi:[0,1,1]
	v_pk_fma_f32 v[240:241], v[236:237], v[130:131], v[240:241] op_sel_hi:[0,1,1]
	v_pk_fma_f32 v[238:239], v[232:233], v[108:109], v[238:239] op_sel:[1,0,0]
	v_pk_fma_f32 v[240:241], v[232:233], v[116:117], v[240:241] op_sel:[1,0,0]
	v_pk_fma_f32 v[238:239], v[236:237], v[124:125], v[238:239] op_sel:[1,0,0]
	v_pk_fma_f32 v[240:241], v[236:237], v[132:133], v[240:241] op_sel:[1,0,0]
	ds_read_b128 v[230:233], v32 offset:16768
	ds_read_b128 v[234:237], v32 offset:16784
	global_store_dwordx4 v246, v[238:241], s[100:101] nt
	s_add_u32 s100, s100, 0x2000
	s_addc_u32 s101, s101, 0
	s_waitcnt vmcnt(27)
	s_waitcnt lgkmcnt(2)
	v_pk_fma_f32 v[0:1], v[158:159], v[222:223], v[0:1] op_sel_hi:[1,0,1]
	v_pk_fma_f32 v[2:3], v[160:161], v[222:223], v[2:3] op_sel_hi:[1,0,1]
	v_pk_fma_f32 v[4:5], v[158:159], v[222:223], v[4:5] op_sel:[0,1,0]
	v_pk_fma_f32 v[6:7], v[160:161], v[222:223], v[6:7] op_sel:[0,1,0]
	v_pk_fma_f32 v[8:9], v[158:159], v[224:225], v[8:9] op_sel_hi:[1,0,1]
	v_pk_fma_f32 v[10:11], v[160:161], v[224:225], v[10:11] op_sel_hi:[1,0,1]
	v_pk_fma_f32 v[12:13], v[158:159], v[224:225], v[12:13] op_sel:[0,1,0]
	v_pk_fma_f32 v[14:15], v[160:161], v[224:225], v[14:15] op_sel:[0,1,0]
	v_pk_fma_f32 v[16:17], v[158:159], v[226:227], v[16:17] op_sel_hi:[1,0,1]
	v_pk_fma_f32 v[18:19], v[160:161], v[226:227], v[18:19] op_sel_hi:[1,0,1]
	v_pk_fma_f32 v[20:21], v[158:159], v[226:227], v[20:21] op_sel:[0,1,0]
	v_pk_fma_f32 v[22:23], v[160:161], v[226:227], v[22:23] op_sel:[0,1,0]
	v_pk_fma_f32 v[24:25], v[158:159], v[228:229], v[24:25] op_sel_hi:[1,0,1]
	v_pk_fma_f32 v[26:27], v[160:161], v[228:229], v[26:27] op_sel_hi:[1,0,1]
	v_pk_fma_f32 v[28:29], v[158:159], v[228:229], v[28:29] op_sel:[0,1,0]
	v_pk_fma_f32 v[30:31], v[160:161], v[228:229], v[30:31] op_sel:[0,1,0]
	ds_read_b128 v[222:225], v32 offset:512
	ds_read_b128 v[226:229], v32 offset:528
	s_waitcnt lgkmcnt(2)
	v_pk_mul_f32 v[242:243], v[230:231], v[102:103] op_sel_hi:[0,1]
	v_pk_mul_f32 v[244:245], v[230:231], v[110:111] op_sel_hi:[0,1]
	v_pk_fma_f32 v[242:243], v[86:87], v[158:159], v[242:243]
	v_pk_fma_f32 v[244:245], v[86:87], v[160:161], v[244:245]
	v_pk_fma_f32 v[242:243], v[234:235], v[118:119], v[242:243] op_sel_hi:[0,1,1]
	v_pk_fma_f32 v[244:245], v[234:235], v[126:127], v[244:245] op_sel_hi:[0,1,1]
	v_pk_fma_f32 v[242:243], v[230:231], v[104:105], v[242:243] op_sel:[1,0,0]
	v_pk_fma_f32 v[244:245], v[230:231], v[112:113], v[244:245] op_sel:[1,0,0]
	v_pk_fma_f32 v[242:243], v[234:235], v[120:121], v[242:243] op_sel:[1,0,0]
	v_pk_fma_f32 v[244:245], v[234:235], v[128:129], v[244:245] op_sel:[1,0,0]
	v_pk_fma_f32 v[242:243], v[232:233], v[106:107], v[242:243] op_sel_hi:[0,1,1]
	v_pk_fma_f32 v[244:245], v[232:233], v[114:115], v[244:245] op_sel_hi:[0,1,1]
	v_pk_fma_f32 v[242:243], v[236:237], v[122:123], v[242:243] op_sel_hi:[0,1,1]
	v_pk_fma_f32 v[244:245], v[236:237], v[130:131], v[244:245] op_sel_hi:[0,1,1]
	v_pk_fma_f32 v[242:243], v[232:233], v[108:109], v[242:243] op_sel:[1,0,0]
	v_pk_fma_f32 v[244:245], v[232:233], v[116:117], v[244:245] op_sel:[1,0,0]
	v_pk_fma_f32 v[242:243], v[236:237], v[124:125], v[242:243] op_sel:[1,0,0]
	v_pk_fma_f32 v[244:245], v[236:237], v[132:133], v[244:245] op_sel:[1,0,0]
	ds_read_b128 v[230:233], v32 offset:16896
	ds_read_b128 v[234:237], v32 offset:16912
	global_store_dwordx4 v246, v[242:245], s[100:101] nt
	s_add_u32 s100, s100, 0x2000
	s_addc_u32 s101, s101, 0
	s_waitcnt vmcnt(26)
	s_waitcnt lgkmcnt(2)
	v_pk_fma_f32 v[0:1], v[162:163], v[222:223], v[0:1] op_sel_hi:[1,0,1]
	v_pk_fma_f32 v[2:3], v[164:165], v[222:223], v[2:3] op_sel_hi:[1,0,1]
	v_pk_fma_f32 v[4:5], v[162:163], v[222:223], v[4:5] op_sel:[0,1,0]
	v_pk_fma_f32 v[6:7], v[164:165], v[222:223], v[6:7] op_sel:[0,1,0]
	v_pk_fma_f32 v[8:9], v[162:163], v[224:225], v[8:9] op_sel_hi:[1,0,1]
	v_pk_fma_f32 v[10:11], v[164:165], v[224:225], v[10:11] op_sel_hi:[1,0,1]
	v_pk_fma_f32 v[12:13], v[162:163], v[224:225], v[12:13] op_sel:[0,1,0]
	v_pk_fma_f32 v[14:15], v[164:165], v[224:225], v[14:15] op_sel:[0,1,0]
	v_pk_fma_f32 v[16:17], v[162:163], v[226:227], v[16:17] op_sel_hi:[1,0,1]
	v_pk_fma_f32 v[18:19], v[164:165], v[226:227], v[18:19] op_sel_hi:[1,0,1]
	v_pk_fma_f32 v[20:21], v[162:163], v[226:227], v[20:21] op_sel:[0,1,0]
	v_pk_fma_f32 v[22:23], v[164:165], v[226:227], v[22:23] op_sel:[0,1,0]
	v_pk_fma_f32 v[24:25], v[162:163], v[228:229], v[24:25] op_sel_hi:[1,0,1]
	v_pk_fma_f32 v[26:27], v[164:165], v[228:229], v[26:27] op_sel_hi:[1,0,1]
	v_pk_fma_f32 v[28:29], v[162:163], v[228:229], v[28:29] op_sel:[0,1,0]
	v_pk_fma_f32 v[30:31], v[164:165], v[228:229], v[30:31] op_sel:[0,1,0]
	ds_read_b128 v[222:225], v32 offset:640
	ds_read_b128 v[226:229], v32 offset:656
	s_waitcnt lgkmcnt(2)
	v_pk_mul_f32 v[238:239], v[230:231], v[102:103] op_sel_hi:[0,1]
	v_pk_mul_f32 v[240:241], v[230:231], v[110:111] op_sel_hi:[0,1]
	v_pk_fma_f32 v[238:239], v[86:87], v[162:163], v[238:239]
	v_pk_fma_f32 v[240:241], v[86:87], v[164:165], v[240:241]
	v_pk_fma_f32 v[238:239], v[234:235], v[118:119], v[238:239] op_sel_hi:[0,1,1]
	v_pk_fma_f32 v[240:241], v[234:235], v[126:127], v[240:241] op_sel_hi:[0,1,1]
	v_pk_fma_f32 v[238:239], v[230:231], v[104:105], v[238:239] op_sel:[1,0,0]
	v_pk_fma_f32 v[240:241], v[230:231], v[112:113], v[240:241] op_sel:[1,0,0]
	v_pk_fma_f32 v[238:239], v[234:235], v[120:121], v[238:239] op_sel:[1,0,0]
	v_pk_fma_f32 v[240:241], v[234:235], v[128:129], v[240:241] op_sel:[1,0,0]
	v_pk_fma_f32 v[238:239], v[232:233], v[106:107], v[238:239] op_sel_hi:[0,1,1]
	v_pk_fma_f32 v[240:241], v[232:233], v[114:115], v[240:241] op_sel_hi:[0,1,1]
	v_pk_fma_f32 v[238:239], v[236:237], v[122:123], v[238:239] op_sel_hi:[0,1,1]
	v_pk_fma_f32 v[240:241], v[236:237], v[130:131], v[240:241] op_sel_hi:[0,1,1]
	v_pk_fma_f32 v[238:239], v[232:233], v[108:109], v[238:239] op_sel:[1,0,0]
	v_pk_fma_f32 v[240:241], v[232:233], v[116:117], v[240:241] op_sel:[1,0,0]
	v_pk_fma_f32 v[238:239], v[236:237], v[124:125], v[238:239] op_sel:[1,0,0]
	v_pk_fma_f32 v[240:241], v[236:237], v[132:133], v[240:241] op_sel:[1,0,0]
	ds_read_b128 v[230:233], v32 offset:17024
	ds_read_b128 v[234:237], v32 offset:17040
	global_store_dwordx4 v246, v[238:241], s[100:101] nt
	s_add_u32 s100, s100, 0x2000
	s_addc_u32 s101, s101, 0
	s_waitcnt vmcnt(25)
	s_waitcnt lgkmcnt(2)
	v_pk_fma_f32 v[0:1], v[166:167], v[222:223], v[0:1] op_sel_hi:[1,0,1]
	v_pk_fma_f32 v[2:3], v[168:169], v[222:223], v[2:3] op_sel_hi:[1,0,1]
	v_pk_fma_f32 v[4:5], v[166:167], v[222:223], v[4:5] op_sel:[0,1,0]
	v_pk_fma_f32 v[6:7], v[168:169], v[222:223], v[6:7] op_sel:[0,1,0]
	v_pk_fma_f32 v[8:9], v[166:167], v[224:225], v[8:9] op_sel_hi:[1,0,1]
	v_pk_fma_f32 v[10:11], v[168:169], v[224:225], v[10:11] op_sel_hi:[1,0,1]
	v_pk_fma_f32 v[12:13], v[166:167], v[224:225], v[12:13] op_sel:[0,1,0]
	v_pk_fma_f32 v[14:15], v[168:169], v[224:225], v[14:15] op_sel:[0,1,0]
	v_pk_fma_f32 v[16:17], v[166:167], v[226:227], v[16:17] op_sel_hi:[1,0,1]
	v_pk_fma_f32 v[18:19], v[168:169], v[226:227], v[18:19] op_sel_hi:[1,0,1]
	v_pk_fma_f32 v[20:21], v[166:167], v[226:227], v[20:21] op_sel:[0,1,0]
	v_pk_fma_f32 v[22:23], v[168:169], v[226:227], v[22:23] op_sel:[0,1,0]
	v_pk_fma_f32 v[24:25], v[166:167], v[228:229], v[24:25] op_sel_hi:[1,0,1]
	v_pk_fma_f32 v[26:27], v[168:169], v[228:229], v[26:27] op_sel_hi:[1,0,1]
	v_pk_fma_f32 v[28:29], v[166:167], v[228:229], v[28:29] op_sel:[0,1,0]
	v_pk_fma_f32 v[30:31], v[168:169], v[228:229], v[30:31] op_sel:[0,1,0]
	ds_read_b128 v[222:225], v32 offset:768
	ds_read_b128 v[226:229], v32 offset:784
	s_waitcnt lgkmcnt(2)
	v_pk_mul_f32 v[242:243], v[230:231], v[102:103] op_sel_hi:[0,1]
	v_pk_mul_f32 v[244:245], v[230:231], v[110:111] op_sel_hi:[0,1]
	v_pk_fma_f32 v[242:243], v[86:87], v[166:167], v[242:243]
	v_pk_fma_f32 v[244:245], v[86:87], v[168:169], v[244:245]
	v_pk_fma_f32 v[242:243], v[234:235], v[118:119], v[242:243] op_sel_hi:[0,1,1]
	v_pk_fma_f32 v[244:245], v[234:235], v[126:127], v[244:245] op_sel_hi:[0,1,1]
	v_pk_fma_f32 v[242:243], v[230:231], v[104:105], v[242:243] op_sel:[1,0,0]
	v_pk_fma_f32 v[244:245], v[230:231], v[112:113], v[244:245] op_sel:[1,0,0]
	v_pk_fma_f32 v[242:243], v[234:235], v[120:121], v[242:243] op_sel:[1,0,0]
	v_pk_fma_f32 v[244:245], v[234:235], v[128:129], v[244:245] op_sel:[1,0,0]
	v_pk_fma_f32 v[242:243], v[232:233], v[106:107], v[242:243] op_sel_hi:[0,1,1]
	v_pk_fma_f32 v[244:245], v[232:233], v[114:115], v[244:245] op_sel_hi:[0,1,1]
	v_pk_fma_f32 v[242:243], v[236:237], v[122:123], v[242:243] op_sel_hi:[0,1,1]
	v_pk_fma_f32 v[244:245], v[236:237], v[130:131], v[244:245] op_sel_hi:[0,1,1]
	v_pk_fma_f32 v[242:243], v[232:233], v[108:109], v[242:243] op_sel:[1,0,0]
	v_pk_fma_f32 v[244:245], v[232:233], v[116:117], v[244:245] op_sel:[1,0,0]
	v_pk_fma_f32 v[242:243], v[236:237], v[124:125], v[242:243] op_sel:[1,0,0]
	v_pk_fma_f32 v[244:245], v[236:237], v[132:133], v[244:245] op_sel:[1,0,0]
	ds_read_b128 v[230:233], v32 offset:17152
	ds_read_b128 v[234:237], v32 offset:17168
	global_store_dwordx4 v246, v[242:245], s[100:101] nt
	s_add_u32 s100, s100, 0x2000
	s_addc_u32 s101, s101, 0
	s_waitcnt vmcnt(24)
	s_waitcnt lgkmcnt(2)
	v_pk_fma_f32 v[0:1], v[170:171], v[222:223], v[0:1] op_sel_hi:[1,0,1]
	v_pk_fma_f32 v[2:3], v[172:173], v[222:223], v[2:3] op_sel_hi:[1,0,1]
	v_pk_fma_f32 v[4:5], v[170:171], v[222:223], v[4:5] op_sel:[0,1,0]
	v_pk_fma_f32 v[6:7], v[172:173], v[222:223], v[6:7] op_sel:[0,1,0]
	v_pk_fma_f32 v[8:9], v[170:171], v[224:225], v[8:9] op_sel_hi:[1,0,1]
	v_pk_fma_f32 v[10:11], v[172:173], v[224:225], v[10:11] op_sel_hi:[1,0,1]
	v_pk_fma_f32 v[12:13], v[170:171], v[224:225], v[12:13] op_sel:[0,1,0]
	v_pk_fma_f32 v[14:15], v[172:173], v[224:225], v[14:15] op_sel:[0,1,0]
	v_pk_fma_f32 v[16:17], v[170:171], v[226:227], v[16:17] op_sel_hi:[1,0,1]
	v_pk_fma_f32 v[18:19], v[172:173], v[226:227], v[18:19] op_sel_hi:[1,0,1]
	v_pk_fma_f32 v[20:21], v[170:171], v[226:227], v[20:21] op_sel:[0,1,0]
	v_pk_fma_f32 v[22:23], v[172:173], v[226:227], v[22:23] op_sel:[0,1,0]
	v_pk_fma_f32 v[24:25], v[170:171], v[228:229], v[24:25] op_sel_hi:[1,0,1]
	v_pk_fma_f32 v[26:27], v[172:173], v[228:229], v[26:27] op_sel_hi:[1,0,1]
	v_pk_fma_f32 v[28:29], v[170:171], v[228:229], v[28:29] op_sel:[0,1,0]
	v_pk_fma_f32 v[30:31], v[172:173], v[228:229], v[30:31] op_sel:[0,1,0]
	ds_read_b128 v[222:225], v32 offset:896
	ds_read_b128 v[226:229], v32 offset:912
	s_waitcnt lgkmcnt(2)
	v_pk_mul_f32 v[238:239], v[230:231], v[102:103] op_sel_hi:[0,1]
	v_pk_mul_f32 v[240:241], v[230:231], v[110:111] op_sel_hi:[0,1]
	v_pk_fma_f32 v[238:239], v[86:87], v[170:171], v[238:239]
	v_pk_fma_f32 v[240:241], v[86:87], v[172:173], v[240:241]
	v_pk_fma_f32 v[238:239], v[234:235], v[118:119], v[238:239] op_sel_hi:[0,1,1]
	v_pk_fma_f32 v[240:241], v[234:235], v[126:127], v[240:241] op_sel_hi:[0,1,1]
	v_pk_fma_f32 v[238:239], v[230:231], v[104:105], v[238:239] op_sel:[1,0,0]
	v_pk_fma_f32 v[240:241], v[230:231], v[112:113], v[240:241] op_sel:[1,0,0]
	v_pk_fma_f32 v[238:239], v[234:235], v[120:121], v[238:239] op_sel:[1,0,0]
	v_pk_fma_f32 v[240:241], v[234:235], v[128:129], v[240:241] op_sel:[1,0,0]
	v_pk_fma_f32 v[238:239], v[232:233], v[106:107], v[238:239] op_sel_hi:[0,1,1]
	v_pk_fma_f32 v[240:241], v[232:233], v[114:115], v[240:241] op_sel_hi:[0,1,1]
	v_pk_fma_f32 v[238:239], v[236:237], v[122:123], v[238:239] op_sel_hi:[0,1,1]
	v_pk_fma_f32 v[240:241], v[236:237], v[130:131], v[240:241] op_sel_hi:[0,1,1]
	v_pk_fma_f32 v[238:239], v[232:233], v[108:109], v[238:239] op_sel:[1,0,0]
	v_pk_fma_f32 v[240:241], v[232:233], v[116:117], v[240:241] op_sel:[1,0,0]
	v_pk_fma_f32 v[238:239], v[236:237], v[124:125], v[238:239] op_sel:[1,0,0]
	v_pk_fma_f32 v[240:241], v[236:237], v[132:133], v[240:241] op_sel:[1,0,0]
	ds_read_b128 v[230:233], v32 offset:17280
	ds_read_b128 v[234:237], v32 offset:17296
	global_store_dwordx4 v246, v[238:241], s[100:101] nt
	s_add_u32 s100, s100, 0x2000
	s_addc_u32 s101, s101, 0
	s_waitcnt vmcnt(23)
	s_waitcnt lgkmcnt(2)
	v_pk_fma_f32 v[0:1], v[174:175], v[222:223], v[0:1] op_sel_hi:[1,0,1]
	v_pk_fma_f32 v[2:3], v[176:177], v[222:223], v[2:3] op_sel_hi:[1,0,1]
	v_pk_fma_f32 v[4:5], v[174:175], v[222:223], v[4:5] op_sel:[0,1,0]
	v_pk_fma_f32 v[6:7], v[176:177], v[222:223], v[6:7] op_sel:[0,1,0]
	v_pk_fma_f32 v[8:9], v[174:175], v[224:225], v[8:9] op_sel_hi:[1,0,1]
	v_pk_fma_f32 v[10:11], v[176:177], v[224:225], v[10:11] op_sel_hi:[1,0,1]
	v_pk_fma_f32 v[12:13], v[174:175], v[224:225], v[12:13] op_sel:[0,1,0]
	v_pk_fma_f32 v[14:15], v[176:177], v[224:225], v[14:15] op_sel:[0,1,0]
	v_pk_fma_f32 v[16:17], v[174:175], v[226:227], v[16:17] op_sel_hi:[1,0,1]
	v_pk_fma_f32 v[18:19], v[176:177], v[226:227], v[18:19] op_sel_hi:[1,0,1]
	v_pk_fma_f32 v[20:21], v[174:175], v[226:227], v[20:21] op_sel:[0,1,0]
	v_pk_fma_f32 v[22:23], v[176:177], v[226:227], v[22:23] op_sel:[0,1,0]
	v_pk_fma_f32 v[24:25], v[174:175], v[228:229], v[24:25] op_sel_hi:[1,0,1]
	v_pk_fma_f32 v[26:27], v[176:177], v[228:229], v[26:27] op_sel_hi:[1,0,1]
	v_pk_fma_f32 v[28:29], v[174:175], v[228:229], v[28:29] op_sel:[0,1,0]
	v_pk_fma_f32 v[30:31], v[176:177], v[228:229], v[30:31] op_sel:[0,1,0]
	ds_read_b128 v[222:225], v32 offset:1024
	ds_read_b128 v[226:229], v32 offset:1040
	s_waitcnt lgkmcnt(2)
	v_pk_mul_f32 v[242:243], v[230:231], v[102:103] op_sel_hi:[0,1]
	v_pk_mul_f32 v[244:245], v[230:231], v[110:111] op_sel_hi:[0,1]
	v_pk_fma_f32 v[242:243], v[86:87], v[174:175], v[242:243]
	v_pk_fma_f32 v[244:245], v[86:87], v[176:177], v[244:245]
	v_pk_fma_f32 v[242:243], v[234:235], v[118:119], v[242:243] op_sel_hi:[0,1,1]
	v_pk_fma_f32 v[244:245], v[234:235], v[126:127], v[244:245] op_sel_hi:[0,1,1]
	v_pk_fma_f32 v[242:243], v[230:231], v[104:105], v[242:243] op_sel:[1,0,0]
	v_pk_fma_f32 v[244:245], v[230:231], v[112:113], v[244:245] op_sel:[1,0,0]
	v_pk_fma_f32 v[242:243], v[234:235], v[120:121], v[242:243] op_sel:[1,0,0]
	v_pk_fma_f32 v[244:245], v[234:235], v[128:129], v[244:245] op_sel:[1,0,0]
	v_pk_fma_f32 v[242:243], v[232:233], v[106:107], v[242:243] op_sel_hi:[0,1,1]
	v_pk_fma_f32 v[244:245], v[232:233], v[114:115], v[244:245] op_sel_hi:[0,1,1]
	v_pk_fma_f32 v[242:243], v[236:237], v[122:123], v[242:243] op_sel_hi:[0,1,1]
	v_pk_fma_f32 v[244:245], v[236:237], v[130:131], v[244:245] op_sel_hi:[0,1,1]
	v_pk_fma_f32 v[242:243], v[232:233], v[108:109], v[242:243] op_sel:[1,0,0]
	v_pk_fma_f32 v[244:245], v[232:233], v[116:117], v[244:245] op_sel:[1,0,0]
	v_pk_fma_f32 v[242:243], v[236:237], v[124:125], v[242:243] op_sel:[1,0,0]
	v_pk_fma_f32 v[244:245], v[236:237], v[132:133], v[244:245] op_sel:[1,0,0]
	ds_read_b128 v[230:233], v32 offset:17408
	ds_read_b128 v[234:237], v32 offset:17424
	global_store_dwordx4 v246, v[242:245], s[100:101] nt
	s_add_u32 s100, s100, 0x2000
	s_addc_u32 s101, s101, 0
	s_waitcnt vmcnt(22)
	s_waitcnt lgkmcnt(2)
	v_pk_fma_f32 v[0:1], v[178:179], v[222:223], v[0:1] op_sel_hi:[1,0,1]
	v_pk_fma_f32 v[2:3], v[180:181], v[222:223], v[2:3] op_sel_hi:[1,0,1]
	v_pk_fma_f32 v[4:5], v[178:179], v[222:223], v[4:5] op_sel:[0,1,0]
	v_pk_fma_f32 v[6:7], v[180:181], v[222:223], v[6:7] op_sel:[0,1,0]
	v_pk_fma_f32 v[8:9], v[178:179], v[224:225], v[8:9] op_sel_hi:[1,0,1]
	v_pk_fma_f32 v[10:11], v[180:181], v[224:225], v[10:11] op_sel_hi:[1,0,1]
	v_pk_fma_f32 v[12:13], v[178:179], v[224:225], v[12:13] op_sel:[0,1,0]
	v_pk_fma_f32 v[14:15], v[180:181], v[224:225], v[14:15] op_sel:[0,1,0]
	v_pk_fma_f32 v[16:17], v[178:179], v[226:227], v[16:17] op_sel_hi:[1,0,1]
	v_pk_fma_f32 v[18:19], v[180:181], v[226:227], v[18:19] op_sel_hi:[1,0,1]
	v_pk_fma_f32 v[20:21], v[178:179], v[226:227], v[20:21] op_sel:[0,1,0]
	v_pk_fma_f32 v[22:23], v[180:181], v[226:227], v[22:23] op_sel:[0,1,0]
	v_pk_fma_f32 v[24:25], v[178:179], v[228:229], v[24:25] op_sel_hi:[1,0,1]
	v_pk_fma_f32 v[26:27], v[180:181], v[228:229], v[26:27] op_sel_hi:[1,0,1]
	v_pk_fma_f32 v[28:29], v[178:179], v[228:229], v[28:29] op_sel:[0,1,0]
	v_pk_fma_f32 v[30:31], v[180:181], v[228:229], v[30:31] op_sel:[0,1,0]
	ds_read_b128 v[222:225], v32 offset:1152
	ds_read_b128 v[226:229], v32 offset:1168
	s_waitcnt lgkmcnt(2)
	v_pk_mul_f32 v[238:239], v[230:231], v[102:103] op_sel_hi:[0,1]
	v_pk_mul_f32 v[240:241], v[230:231], v[110:111] op_sel_hi:[0,1]
	v_pk_fma_f32 v[238:239], v[86:87], v[178:179], v[238:239]
	v_pk_fma_f32 v[240:241], v[86:87], v[180:181], v[240:241]
	v_pk_fma_f32 v[238:239], v[234:235], v[118:119], v[238:239] op_sel_hi:[0,1,1]
	v_pk_fma_f32 v[240:241], v[234:235], v[126:127], v[240:241] op_sel_hi:[0,1,1]
	v_pk_fma_f32 v[238:239], v[230:231], v[104:105], v[238:239] op_sel:[1,0,0]
	v_pk_fma_f32 v[240:241], v[230:231], v[112:113], v[240:241] op_sel:[1,0,0]
	v_pk_fma_f32 v[238:239], v[234:235], v[120:121], v[238:239] op_sel:[1,0,0]
	v_pk_fma_f32 v[240:241], v[234:235], v[128:129], v[240:241] op_sel:[1,0,0]
	v_pk_fma_f32 v[238:239], v[232:233], v[106:107], v[238:239] op_sel_hi:[0,1,1]
	v_pk_fma_f32 v[240:241], v[232:233], v[114:115], v[240:241] op_sel_hi:[0,1,1]
	v_pk_fma_f32 v[238:239], v[236:237], v[122:123], v[238:239] op_sel_hi:[0,1,1]
	v_pk_fma_f32 v[240:241], v[236:237], v[130:131], v[240:241] op_sel_hi:[0,1,1]
	v_pk_fma_f32 v[238:239], v[232:233], v[108:109], v[238:239] op_sel:[1,0,0]
	v_pk_fma_f32 v[240:241], v[232:233], v[116:117], v[240:241] op_sel:[1,0,0]
	v_pk_fma_f32 v[238:239], v[236:237], v[124:125], v[238:239] op_sel:[1,0,0]
	v_pk_fma_f32 v[240:241], v[236:237], v[132:133], v[240:241] op_sel:[1,0,0]
	ds_read_b128 v[230:233], v32 offset:17536
	ds_read_b128 v[234:237], v32 offset:17552
	global_store_dwordx4 v246, v[238:241], s[100:101] nt
	s_add_u32 s100, s100, 0x2000
	s_addc_u32 s101, s101, 0
	s_waitcnt vmcnt(21)
	s_waitcnt lgkmcnt(2)
	v_pk_fma_f32 v[0:1], v[182:183], v[222:223], v[0:1] op_sel_hi:[1,0,1]
	v_pk_fma_f32 v[2:3], v[184:185], v[222:223], v[2:3] op_sel_hi:[1,0,1]
	v_pk_fma_f32 v[4:5], v[182:183], v[222:223], v[4:5] op_sel:[0,1,0]
	v_pk_fma_f32 v[6:7], v[184:185], v[222:223], v[6:7] op_sel:[0,1,0]
	v_pk_fma_f32 v[8:9], v[182:183], v[224:225], v[8:9] op_sel_hi:[1,0,1]
	v_pk_fma_f32 v[10:11], v[184:185], v[224:225], v[10:11] op_sel_hi:[1,0,1]
	v_pk_fma_f32 v[12:13], v[182:183], v[224:225], v[12:13] op_sel:[0,1,0]
	v_pk_fma_f32 v[14:15], v[184:185], v[224:225], v[14:15] op_sel:[0,1,0]
	v_pk_fma_f32 v[16:17], v[182:183], v[226:227], v[16:17] op_sel_hi:[1,0,1]
	v_pk_fma_f32 v[18:19], v[184:185], v[226:227], v[18:19] op_sel_hi:[1,0,1]
	v_pk_fma_f32 v[20:21], v[182:183], v[226:227], v[20:21] op_sel:[0,1,0]
	v_pk_fma_f32 v[22:23], v[184:185], v[226:227], v[22:23] op_sel:[0,1,0]
	v_pk_fma_f32 v[24:25], v[182:183], v[228:229], v[24:25] op_sel_hi:[1,0,1]
	v_pk_fma_f32 v[26:27], v[184:185], v[228:229], v[26:27] op_sel_hi:[1,0,1]
	v_pk_fma_f32 v[28:29], v[182:183], v[228:229], v[28:29] op_sel:[0,1,0]
	v_pk_fma_f32 v[30:31], v[184:185], v[228:229], v[30:31] op_sel:[0,1,0]
	ds_read_b128 v[222:225], v32 offset:1280
	ds_read_b128 v[226:229], v32 offset:1296
	s_waitcnt lgkmcnt(2)
	v_pk_mul_f32 v[242:243], v[230:231], v[102:103] op_sel_hi:[0,1]
	v_pk_mul_f32 v[244:245], v[230:231], v[110:111] op_sel_hi:[0,1]
	v_pk_fma_f32 v[242:243], v[86:87], v[182:183], v[242:243]
	v_pk_fma_f32 v[244:245], v[86:87], v[184:185], v[244:245]
	v_pk_fma_f32 v[242:243], v[234:235], v[118:119], v[242:243] op_sel_hi:[0,1,1]
	v_pk_fma_f32 v[244:245], v[234:235], v[126:127], v[244:245] op_sel_hi:[0,1,1]
	v_pk_fma_f32 v[242:243], v[230:231], v[104:105], v[242:243] op_sel:[1,0,0]
	v_pk_fma_f32 v[244:245], v[230:231], v[112:113], v[244:245] op_sel:[1,0,0]
	v_pk_fma_f32 v[242:243], v[234:235], v[120:121], v[242:243] op_sel:[1,0,0]
	v_pk_fma_f32 v[244:245], v[234:235], v[128:129], v[244:245] op_sel:[1,0,0]
	v_pk_fma_f32 v[242:243], v[232:233], v[106:107], v[242:243] op_sel_hi:[0,1,1]
	v_pk_fma_f32 v[244:245], v[232:233], v[114:115], v[244:245] op_sel_hi:[0,1,1]
	v_pk_fma_f32 v[242:243], v[236:237], v[122:123], v[242:243] op_sel_hi:[0,1,1]
	v_pk_fma_f32 v[244:245], v[236:237], v[130:131], v[244:245] op_sel_hi:[0,1,1]
	v_pk_fma_f32 v[242:243], v[232:233], v[108:109], v[242:243] op_sel:[1,0,0]
	v_pk_fma_f32 v[244:245], v[232:233], v[116:117], v[244:245] op_sel:[1,0,0]
	v_pk_fma_f32 v[242:243], v[236:237], v[124:125], v[242:243] op_sel:[1,0,0]
	v_pk_fma_f32 v[244:245], v[236:237], v[132:133], v[244:245] op_sel:[1,0,0]
	ds_read_b128 v[230:233], v32 offset:17664
	ds_read_b128 v[234:237], v32 offset:17680
	global_store_dwordx4 v246, v[242:245], s[100:101] nt
	s_add_u32 s100, s100, 0x2000
	s_addc_u32 s101, s101, 0
	s_waitcnt vmcnt(20)
	s_waitcnt lgkmcnt(2)
	v_pk_fma_f32 v[0:1], v[186:187], v[222:223], v[0:1] op_sel_hi:[1,0,1]
	v_pk_fma_f32 v[2:3], v[188:189], v[222:223], v[2:3] op_sel_hi:[1,0,1]
	v_pk_fma_f32 v[4:5], v[186:187], v[222:223], v[4:5] op_sel:[0,1,0]
	v_pk_fma_f32 v[6:7], v[188:189], v[222:223], v[6:7] op_sel:[0,1,0]
	v_pk_fma_f32 v[8:9], v[186:187], v[224:225], v[8:9] op_sel_hi:[1,0,1]
	v_pk_fma_f32 v[10:11], v[188:189], v[224:225], v[10:11] op_sel_hi:[1,0,1]
	v_pk_fma_f32 v[12:13], v[186:187], v[224:225], v[12:13] op_sel:[0,1,0]
	v_pk_fma_f32 v[14:15], v[188:189], v[224:225], v[14:15] op_sel:[0,1,0]
	v_pk_fma_f32 v[16:17], v[186:187], v[226:227], v[16:17] op_sel_hi:[1,0,1]
	v_pk_fma_f32 v[18:19], v[188:189], v[226:227], v[18:19] op_sel_hi:[1,0,1]
	v_pk_fma_f32 v[20:21], v[186:187], v[226:227], v[20:21] op_sel:[0,1,0]
	v_pk_fma_f32 v[22:23], v[188:189], v[226:227], v[22:23] op_sel:[0,1,0]
	v_pk_fma_f32 v[24:25], v[186:187], v[228:229], v[24:25] op_sel_hi:[1,0,1]
	v_pk_fma_f32 v[26:27], v[188:189], v[228:229], v[26:27] op_sel_hi:[1,0,1]
	v_pk_fma_f32 v[28:29], v[186:187], v[228:229], v[28:29] op_sel:[0,1,0]
	v_pk_fma_f32 v[30:31], v[188:189], v[228:229], v[30:31] op_sel:[0,1,0]
	ds_read_b128 v[222:225], v32 offset:1408
	ds_read_b128 v[226:229], v32 offset:1424
	s_waitcnt lgkmcnt(2)
	v_pk_mul_f32 v[238:239], v[230:231], v[102:103] op_sel_hi:[0,1]
	v_pk_mul_f32 v[240:241], v[230:231], v[110:111] op_sel_hi:[0,1]
	v_pk_fma_f32 v[238:239], v[86:87], v[186:187], v[238:239]
	v_pk_fma_f32 v[240:241], v[86:87], v[188:189], v[240:241]
	v_pk_fma_f32 v[238:239], v[234:235], v[118:119], v[238:239] op_sel_hi:[0,1,1]
	v_pk_fma_f32 v[240:241], v[234:235], v[126:127], v[240:241] op_sel_hi:[0,1,1]
	v_pk_fma_f32 v[238:239], v[230:231], v[104:105], v[238:239] op_sel:[1,0,0]
	v_pk_fma_f32 v[240:241], v[230:231], v[112:113], v[240:241] op_sel:[1,0,0]
	v_pk_fma_f32 v[238:239], v[234:235], v[120:121], v[238:239] op_sel:[1,0,0]
	v_pk_fma_f32 v[240:241], v[234:235], v[128:129], v[240:241] op_sel:[1,0,0]
	v_pk_fma_f32 v[238:239], v[232:233], v[106:107], v[238:239] op_sel_hi:[0,1,1]
	v_pk_fma_f32 v[240:241], v[232:233], v[114:115], v[240:241] op_sel_hi:[0,1,1]
	v_pk_fma_f32 v[238:239], v[236:237], v[122:123], v[238:239] op_sel_hi:[0,1,1]
	v_pk_fma_f32 v[240:241], v[236:237], v[130:131], v[240:241] op_sel_hi:[0,1,1]
	v_pk_fma_f32 v[238:239], v[232:233], v[108:109], v[238:239] op_sel:[1,0,0]
	v_pk_fma_f32 v[240:241], v[232:233], v[116:117], v[240:241] op_sel:[1,0,0]
	v_pk_fma_f32 v[238:239], v[236:237], v[124:125], v[238:239] op_sel:[1,0,0]
	v_pk_fma_f32 v[240:241], v[236:237], v[132:133], v[240:241] op_sel:[1,0,0]
	ds_read_b128 v[230:233], v32 offset:17792
	ds_read_b128 v[234:237], v32 offset:17808
	global_store_dwordx4 v246, v[238:241], s[100:101] nt
	s_add_u32 s100, s100, 0x2000
	s_addc_u32 s101, s101, 0
	s_waitcnt vmcnt(19)
	s_waitcnt lgkmcnt(2)
	v_pk_fma_f32 v[0:1], v[190:191], v[222:223], v[0:1] op_sel_hi:[1,0,1]
	v_pk_fma_f32 v[2:3], v[192:193], v[222:223], v[2:3] op_sel_hi:[1,0,1]
	v_pk_fma_f32 v[4:5], v[190:191], v[222:223], v[4:5] op_sel:[0,1,0]
	v_pk_fma_f32 v[6:7], v[192:193], v[222:223], v[6:7] op_sel:[0,1,0]
	v_pk_fma_f32 v[8:9], v[190:191], v[224:225], v[8:9] op_sel_hi:[1,0,1]
	v_pk_fma_f32 v[10:11], v[192:193], v[224:225], v[10:11] op_sel_hi:[1,0,1]
	v_pk_fma_f32 v[12:13], v[190:191], v[224:225], v[12:13] op_sel:[0,1,0]
	v_pk_fma_f32 v[14:15], v[192:193], v[224:225], v[14:15] op_sel:[0,1,0]
	v_pk_fma_f32 v[16:17], v[190:191], v[226:227], v[16:17] op_sel_hi:[1,0,1]
	v_pk_fma_f32 v[18:19], v[192:193], v[226:227], v[18:19] op_sel_hi:[1,0,1]
	v_pk_fma_f32 v[20:21], v[190:191], v[226:227], v[20:21] op_sel:[0,1,0]
	v_pk_fma_f32 v[22:23], v[192:193], v[226:227], v[22:23] op_sel:[0,1,0]
	v_pk_fma_f32 v[24:25], v[190:191], v[228:229], v[24:25] op_sel_hi:[1,0,1]
	v_pk_fma_f32 v[26:27], v[192:193], v[228:229], v[26:27] op_sel_hi:[1,0,1]
	v_pk_fma_f32 v[28:29], v[190:191], v[228:229], v[28:29] op_sel:[0,1,0]
	v_pk_fma_f32 v[30:31], v[192:193], v[228:229], v[30:31] op_sel:[0,1,0]
	ds_read_b128 v[222:225], v32 offset:1536
	ds_read_b128 v[226:229], v32 offset:1552
	s_waitcnt lgkmcnt(2)
	v_pk_mul_f32 v[242:243], v[230:231], v[102:103] op_sel_hi:[0,1]
	v_pk_mul_f32 v[244:245], v[230:231], v[110:111] op_sel_hi:[0,1]
	v_pk_fma_f32 v[242:243], v[86:87], v[190:191], v[242:243]
	v_pk_fma_f32 v[244:245], v[86:87], v[192:193], v[244:245]
	v_pk_fma_f32 v[242:243], v[234:235], v[118:119], v[242:243] op_sel_hi:[0,1,1]
	v_pk_fma_f32 v[244:245], v[234:235], v[126:127], v[244:245] op_sel_hi:[0,1,1]
	v_pk_fma_f32 v[242:243], v[230:231], v[104:105], v[242:243] op_sel:[1,0,0]
	v_pk_fma_f32 v[244:245], v[230:231], v[112:113], v[244:245] op_sel:[1,0,0]
	v_pk_fma_f32 v[242:243], v[234:235], v[120:121], v[242:243] op_sel:[1,0,0]
	v_pk_fma_f32 v[244:245], v[234:235], v[128:129], v[244:245] op_sel:[1,0,0]
	v_pk_fma_f32 v[242:243], v[232:233], v[106:107], v[242:243] op_sel_hi:[0,1,1]
	v_pk_fma_f32 v[244:245], v[232:233], v[114:115], v[244:245] op_sel_hi:[0,1,1]
	v_pk_fma_f32 v[242:243], v[236:237], v[122:123], v[242:243] op_sel_hi:[0,1,1]
	v_pk_fma_f32 v[244:245], v[236:237], v[130:131], v[244:245] op_sel_hi:[0,1,1]
	v_pk_fma_f32 v[242:243], v[232:233], v[108:109], v[242:243] op_sel:[1,0,0]
	v_pk_fma_f32 v[244:245], v[232:233], v[116:117], v[244:245] op_sel:[1,0,0]
	v_pk_fma_f32 v[242:243], v[236:237], v[124:125], v[242:243] op_sel:[1,0,0]
	v_pk_fma_f32 v[244:245], v[236:237], v[132:133], v[244:245] op_sel:[1,0,0]
	ds_read_b128 v[230:233], v32 offset:17920
	ds_read_b128 v[234:237], v32 offset:17936
	global_store_dwordx4 v246, v[242:245], s[100:101] nt
	s_add_u32 s100, s100, 0x2000
	s_addc_u32 s101, s101, 0
	s_waitcnt vmcnt(18)
	s_waitcnt lgkmcnt(2)
	v_pk_fma_f32 v[0:1], v[194:195], v[222:223], v[0:1] op_sel_hi:[1,0,1]
	v_pk_fma_f32 v[2:3], v[196:197], v[222:223], v[2:3] op_sel_hi:[1,0,1]
	v_pk_fma_f32 v[4:5], v[194:195], v[222:223], v[4:5] op_sel:[0,1,0]
	v_pk_fma_f32 v[6:7], v[196:197], v[222:223], v[6:7] op_sel:[0,1,0]
	v_pk_fma_f32 v[8:9], v[194:195], v[224:225], v[8:9] op_sel_hi:[1,0,1]
	v_pk_fma_f32 v[10:11], v[196:197], v[224:225], v[10:11] op_sel_hi:[1,0,1]
	v_pk_fma_f32 v[12:13], v[194:195], v[224:225], v[12:13] op_sel:[0,1,0]
	v_pk_fma_f32 v[14:15], v[196:197], v[224:225], v[14:15] op_sel:[0,1,0]
	v_pk_fma_f32 v[16:17], v[194:195], v[226:227], v[16:17] op_sel_hi:[1,0,1]
	v_pk_fma_f32 v[18:19], v[196:197], v[226:227], v[18:19] op_sel_hi:[1,0,1]
	v_pk_fma_f32 v[20:21], v[194:195], v[226:227], v[20:21] op_sel:[0,1,0]
	v_pk_fma_f32 v[22:23], v[196:197], v[226:227], v[22:23] op_sel:[0,1,0]
	v_pk_fma_f32 v[24:25], v[194:195], v[228:229], v[24:25] op_sel_hi:[1,0,1]
	v_pk_fma_f32 v[26:27], v[196:197], v[228:229], v[26:27] op_sel_hi:[1,0,1]
	v_pk_fma_f32 v[28:29], v[194:195], v[228:229], v[28:29] op_sel:[0,1,0]
	v_pk_fma_f32 v[30:31], v[196:197], v[228:229], v[30:31] op_sel:[0,1,0]
	ds_read_b128 v[222:225], v32 offset:1664
	ds_read_b128 v[226:229], v32 offset:1680
	s_waitcnt lgkmcnt(2)
	v_pk_mul_f32 v[238:239], v[230:231], v[102:103] op_sel_hi:[0,1]
	v_pk_mul_f32 v[240:241], v[230:231], v[110:111] op_sel_hi:[0,1]
	v_pk_fma_f32 v[238:239], v[86:87], v[194:195], v[238:239]
	v_pk_fma_f32 v[240:241], v[86:87], v[196:197], v[240:241]
	v_pk_fma_f32 v[238:239], v[234:235], v[118:119], v[238:239] op_sel_hi:[0,1,1]
	v_pk_fma_f32 v[240:241], v[234:235], v[126:127], v[240:241] op_sel_hi:[0,1,1]
	v_pk_fma_f32 v[238:239], v[230:231], v[104:105], v[238:239] op_sel:[1,0,0]
	v_pk_fma_f32 v[240:241], v[230:231], v[112:113], v[240:241] op_sel:[1,0,0]
	v_pk_fma_f32 v[238:239], v[234:235], v[120:121], v[238:239] op_sel:[1,0,0]
	v_pk_fma_f32 v[240:241], v[234:235], v[128:129], v[240:241] op_sel:[1,0,0]
	v_pk_fma_f32 v[238:239], v[232:233], v[106:107], v[238:239] op_sel_hi:[0,1,1]
	v_pk_fma_f32 v[240:241], v[232:233], v[114:115], v[240:241] op_sel_hi:[0,1,1]
	v_pk_fma_f32 v[238:239], v[236:237], v[122:123], v[238:239] op_sel_hi:[0,1,1]
	v_pk_fma_f32 v[240:241], v[236:237], v[130:131], v[240:241] op_sel_hi:[0,1,1]
	v_pk_fma_f32 v[238:239], v[232:233], v[108:109], v[238:239] op_sel:[1,0,0]
	v_pk_fma_f32 v[240:241], v[232:233], v[116:117], v[240:241] op_sel:[1,0,0]
	v_pk_fma_f32 v[238:239], v[236:237], v[124:125], v[238:239] op_sel:[1,0,0]
	v_pk_fma_f32 v[240:241], v[236:237], v[132:133], v[240:241] op_sel:[1,0,0]
	ds_read_b128 v[230:233], v32 offset:18048
	ds_read_b128 v[234:237], v32 offset:18064
	global_store_dwordx4 v246, v[238:241], s[100:101] nt
	s_add_u32 s100, s100, 0x2000
	s_addc_u32 s101, s101, 0
	s_waitcnt vmcnt(17)
	s_waitcnt lgkmcnt(2)
	v_pk_fma_f32 v[0:1], v[210:211], v[222:223], v[0:1] op_sel_hi:[1,0,1]
	v_pk_fma_f32 v[2:3], v[212:213], v[222:223], v[2:3] op_sel_hi:[1,0,1]
	v_pk_fma_f32 v[4:5], v[210:211], v[222:223], v[4:5] op_sel:[0,1,0]
	v_pk_fma_f32 v[6:7], v[212:213], v[222:223], v[6:7] op_sel:[0,1,0]
	v_pk_fma_f32 v[8:9], v[210:211], v[224:225], v[8:9] op_sel_hi:[1,0,1]
	v_pk_fma_f32 v[10:11], v[212:213], v[224:225], v[10:11] op_sel_hi:[1,0,1]
	v_pk_fma_f32 v[12:13], v[210:211], v[224:225], v[12:13] op_sel:[0,1,0]
	v_pk_fma_f32 v[14:15], v[212:213], v[224:225], v[14:15] op_sel:[0,1,0]
	v_pk_fma_f32 v[16:17], v[210:211], v[226:227], v[16:17] op_sel_hi:[1,0,1]
	v_pk_fma_f32 v[18:19], v[212:213], v[226:227], v[18:19] op_sel_hi:[1,0,1]
	v_pk_fma_f32 v[20:21], v[210:211], v[226:227], v[20:21] op_sel:[0,1,0]
	v_pk_fma_f32 v[22:23], v[212:213], v[226:227], v[22:23] op_sel:[0,1,0]
	v_pk_fma_f32 v[24:25], v[210:211], v[228:229], v[24:25] op_sel_hi:[1,0,1]
	v_pk_fma_f32 v[26:27], v[212:213], v[228:229], v[26:27] op_sel_hi:[1,0,1]
	v_pk_fma_f32 v[28:29], v[210:211], v[228:229], v[28:29] op_sel:[0,1,0]
	v_pk_fma_f32 v[30:31], v[212:213], v[228:229], v[30:31] op_sel:[0,1,0]
	ds_read_b128 v[222:225], v32 offset:1792
	ds_read_b128 v[226:229], v32 offset:1808
	s_waitcnt lgkmcnt(2)
	v_pk_mul_f32 v[242:243], v[230:231], v[102:103] op_sel_hi:[0,1]
	v_pk_mul_f32 v[244:245], v[230:231], v[110:111] op_sel_hi:[0,1]
	v_pk_fma_f32 v[242:243], v[86:87], v[210:211], v[242:243]
	v_pk_fma_f32 v[244:245], v[86:87], v[212:213], v[244:245]
	v_pk_fma_f32 v[242:243], v[234:235], v[118:119], v[242:243] op_sel_hi:[0,1,1]
	v_pk_fma_f32 v[244:245], v[234:235], v[126:127], v[244:245] op_sel_hi:[0,1,1]
	v_pk_fma_f32 v[242:243], v[230:231], v[104:105], v[242:243] op_sel:[1,0,0]
	v_pk_fma_f32 v[244:245], v[230:231], v[112:113], v[244:245] op_sel:[1,0,0]
	v_pk_fma_f32 v[242:243], v[234:235], v[120:121], v[242:243] op_sel:[1,0,0]
	v_pk_fma_f32 v[244:245], v[234:235], v[128:129], v[244:245] op_sel:[1,0,0]
	v_pk_fma_f32 v[242:243], v[232:233], v[106:107], v[242:243] op_sel_hi:[0,1,1]
	v_pk_fma_f32 v[244:245], v[232:233], v[114:115], v[244:245] op_sel_hi:[0,1,1]
	v_pk_fma_f32 v[242:243], v[236:237], v[122:123], v[242:243] op_sel_hi:[0,1,1]
	v_pk_fma_f32 v[244:245], v[236:237], v[130:131], v[244:245] op_sel_hi:[0,1,1]
	v_pk_fma_f32 v[242:243], v[232:233], v[108:109], v[242:243] op_sel:[1,0,0]
	v_pk_fma_f32 v[244:245], v[232:233], v[116:117], v[244:245] op_sel:[1,0,0]
	v_pk_fma_f32 v[242:243], v[236:237], v[124:125], v[242:243] op_sel:[1,0,0]
	v_pk_fma_f32 v[244:245], v[236:237], v[132:133], v[244:245] op_sel:[1,0,0]
	ds_read_b128 v[230:233], v32 offset:18176
	ds_read_b128 v[234:237], v32 offset:18192
	global_store_dwordx4 v246, v[242:245], s[100:101] nt
	s_add_u32 s100, s100, 0x2000
	s_addc_u32 s101, s101, 0
	s_waitcnt vmcnt(16)
	s_waitcnt lgkmcnt(2)
	v_pk_fma_f32 v[0:1], v[214:215], v[222:223], v[0:1] op_sel_hi:[1,0,1]
	v_pk_fma_f32 v[2:3], v[216:217], v[222:223], v[2:3] op_sel_hi:[1,0,1]
	v_pk_fma_f32 v[4:5], v[214:215], v[222:223], v[4:5] op_sel:[0,1,0]
	v_pk_fma_f32 v[6:7], v[216:217], v[222:223], v[6:7] op_sel:[0,1,0]
	v_pk_fma_f32 v[8:9], v[214:215], v[224:225], v[8:9] op_sel_hi:[1,0,1]
	v_pk_fma_f32 v[10:11], v[216:217], v[224:225], v[10:11] op_sel_hi:[1,0,1]
	v_pk_fma_f32 v[12:13], v[214:215], v[224:225], v[12:13] op_sel:[0,1,0]
	v_pk_fma_f32 v[14:15], v[216:217], v[224:225], v[14:15] op_sel:[0,1,0]
	v_pk_fma_f32 v[16:17], v[214:215], v[226:227], v[16:17] op_sel_hi:[1,0,1]
	v_pk_fma_f32 v[18:19], v[216:217], v[226:227], v[18:19] op_sel_hi:[1,0,1]
	v_pk_fma_f32 v[20:21], v[214:215], v[226:227], v[20:21] op_sel:[0,1,0]
	v_pk_fma_f32 v[22:23], v[216:217], v[226:227], v[22:23] op_sel:[0,1,0]
	v_pk_fma_f32 v[24:25], v[214:215], v[228:229], v[24:25] op_sel_hi:[1,0,1]
	v_pk_fma_f32 v[26:27], v[216:217], v[228:229], v[26:27] op_sel_hi:[1,0,1]
	v_pk_fma_f32 v[28:29], v[214:215], v[228:229], v[28:29] op_sel:[0,1,0]
	v_pk_fma_f32 v[30:31], v[216:217], v[228:229], v[30:31] op_sel:[0,1,0]
	ds_read_b128 v[222:225], v32 offset:1920
	ds_read_b128 v[226:229], v32 offset:1936
	s_waitcnt lgkmcnt(2)
	v_pk_mul_f32 v[238:239], v[230:231], v[102:103] op_sel_hi:[0,1]
	v_pk_mul_f32 v[240:241], v[230:231], v[110:111] op_sel_hi:[0,1]
	v_pk_fma_f32 v[238:239], v[86:87], v[214:215], v[238:239]
	v_pk_fma_f32 v[240:241], v[86:87], v[216:217], v[240:241]
	v_pk_fma_f32 v[238:239], v[234:235], v[118:119], v[238:239] op_sel_hi:[0,1,1]
	v_pk_fma_f32 v[240:241], v[234:235], v[126:127], v[240:241] op_sel_hi:[0,1,1]
	v_pk_fma_f32 v[238:239], v[230:231], v[104:105], v[238:239] op_sel:[1,0,0]
	v_pk_fma_f32 v[240:241], v[230:231], v[112:113], v[240:241] op_sel:[1,0,0]
	v_pk_fma_f32 v[238:239], v[234:235], v[120:121], v[238:239] op_sel:[1,0,0]
	v_pk_fma_f32 v[240:241], v[234:235], v[128:129], v[240:241] op_sel:[1,0,0]
	v_pk_fma_f32 v[238:239], v[232:233], v[106:107], v[238:239] op_sel_hi:[0,1,1]
	v_pk_fma_f32 v[240:241], v[232:233], v[114:115], v[240:241] op_sel_hi:[0,1,1]
	v_pk_fma_f32 v[238:239], v[236:237], v[122:123], v[238:239] op_sel_hi:[0,1,1]
	v_pk_fma_f32 v[240:241], v[236:237], v[130:131], v[240:241] op_sel_hi:[0,1,1]
	v_pk_fma_f32 v[238:239], v[232:233], v[108:109], v[238:239] op_sel:[1,0,0]
	v_pk_fma_f32 v[240:241], v[232:233], v[116:117], v[240:241] op_sel:[1,0,0]
	v_pk_fma_f32 v[238:239], v[236:237], v[124:125], v[238:239] op_sel:[1,0,0]
	v_pk_fma_f32 v[240:241], v[236:237], v[132:133], v[240:241] op_sel:[1,0,0]
	ds_read_b128 v[230:233], v32 offset:18304
	ds_read_b128 v[234:237], v32 offset:18320
	global_store_dwordx4 v246, v[238:241], s[100:101] nt
	s_add_u32 s100, s100, 0x2000
	s_addc_u32 s101, s101, 0
	s_waitcnt vmcnt(15)
	s_waitcnt lgkmcnt(2)
	v_pk_fma_f32 v[0:1], v[218:219], v[222:223], v[0:1] op_sel_hi:[1,0,1]
	v_pk_fma_f32 v[2:3], v[220:221], v[222:223], v[2:3] op_sel_hi:[1,0,1]
	v_pk_fma_f32 v[4:5], v[218:219], v[222:223], v[4:5] op_sel:[0,1,0]
	v_pk_fma_f32 v[6:7], v[220:221], v[222:223], v[6:7] op_sel:[0,1,0]
	v_pk_fma_f32 v[8:9], v[218:219], v[224:225], v[8:9] op_sel_hi:[1,0,1]
	v_pk_fma_f32 v[10:11], v[220:221], v[224:225], v[10:11] op_sel_hi:[1,0,1]
	v_pk_fma_f32 v[12:13], v[218:219], v[224:225], v[12:13] op_sel:[0,1,0]
	v_pk_fma_f32 v[14:15], v[220:221], v[224:225], v[14:15] op_sel:[0,1,0]
	v_pk_fma_f32 v[16:17], v[218:219], v[226:227], v[16:17] op_sel_hi:[1,0,1]
	v_pk_fma_f32 v[18:19], v[220:221], v[226:227], v[18:19] op_sel_hi:[1,0,1]
	v_pk_fma_f32 v[20:21], v[218:219], v[226:227], v[20:21] op_sel:[0,1,0]
	v_pk_fma_f32 v[22:23], v[220:221], v[226:227], v[22:23] op_sel:[0,1,0]
	v_pk_fma_f32 v[24:25], v[218:219], v[228:229], v[24:25] op_sel_hi:[1,0,1]
	v_pk_fma_f32 v[26:27], v[220:221], v[228:229], v[26:27] op_sel_hi:[1,0,1]
	v_pk_fma_f32 v[28:29], v[218:219], v[228:229], v[28:29] op_sel:[0,1,0]
	v_pk_fma_f32 v[30:31], v[220:221], v[228:229], v[30:31] op_sel:[0,1,0]
	s_waitcnt lgkmcnt(0)
	v_pk_mul_f32 v[242:243], v[230:231], v[102:103] op_sel_hi:[0,1]
	v_pk_mul_f32 v[244:245], v[230:231], v[110:111] op_sel_hi:[0,1]
	v_pk_fma_f32 v[242:243], v[86:87], v[218:219], v[242:243]
	v_pk_fma_f32 v[244:245], v[86:87], v[220:221], v[244:245]
	v_pk_fma_f32 v[242:243], v[234:235], v[118:119], v[242:243] op_sel_hi:[0,1,1]
	v_pk_fma_f32 v[244:245], v[234:235], v[126:127], v[244:245] op_sel_hi:[0,1,1]
	v_pk_fma_f32 v[242:243], v[230:231], v[104:105], v[242:243] op_sel:[1,0,0]
	v_pk_fma_f32 v[244:245], v[230:231], v[112:113], v[244:245] op_sel:[1,0,0]
	v_pk_fma_f32 v[242:243], v[234:235], v[120:121], v[242:243] op_sel:[1,0,0]
	v_pk_fma_f32 v[244:245], v[234:235], v[128:129], v[244:245] op_sel:[1,0,0]
	v_pk_fma_f32 v[242:243], v[232:233], v[106:107], v[242:243] op_sel_hi:[0,1,1]
	v_pk_fma_f32 v[244:245], v[232:233], v[114:115], v[244:245] op_sel_hi:[0,1,1]
	v_pk_fma_f32 v[242:243], v[236:237], v[122:123], v[242:243] op_sel_hi:[0,1,1]
	v_pk_fma_f32 v[244:245], v[236:237], v[130:131], v[244:245] op_sel_hi:[0,1,1]
	v_pk_fma_f32 v[242:243], v[232:233], v[108:109], v[242:243] op_sel:[1,0,0]
	v_pk_fma_f32 v[244:245], v[232:233], v[116:117], v[244:245] op_sel:[1,0,0]
	v_pk_fma_f32 v[242:243], v[236:237], v[124:125], v[242:243] op_sel:[1,0,0]
	v_pk_fma_f32 v[244:245], v[236:237], v[132:133], v[244:245] op_sel:[1,0,0]
	global_store_dwordx4 v246, v[242:245], s[100:101] nt
	s_add_u32 s100, s100, 0x2000
	s_addc_u32 s101, s101, 0
	s_mov_b32 s48, 0x100000
	s_mov_b32 s49, 0
	s_mov_b32 vcc_lo, 0x696e000
	v_lshlrev_b32_e32 v32, 14, v94
	v_lshlrev_b32_e32 v86, 2, v156
	v_add3_u32 v32, 0, v32, v86
	ds_write_b128 v32, v[0:3] offset:32768
	ds_write_b128 v32, v[4:7] offset:34816
	ds_write_b128 v32, v[8:11] offset:36864
	ds_write_b128 v32, v[12:15] offset:38912
	ds_write_b128 v32, v[16:19] offset:40960
	ds_write_b128 v32, v[20:23] offset:43008
	ds_write_b128 v32, v[24:27] offset:45056
	ds_write_b128 v32, v[28:31] offset:47104
	v_lshlrev_b64 v[0:1], 3, v[88:89]
	v_lshl_add_u64 v[2:3], v[90:91], 0, v[0:1]
	s_waitcnt lgkmcnt(0)
	s_barrier
	flat_load_dwordx2 v[2:3], v[2:3]
	v_lshl_add_u64 v[0:1], v[92:93], 0, v[0:1]
	flat_load_dwordx2 v[0:1], v[0:1]
	v_readlane_b32 vcc_lo, v255, 15
	v_readlane_b32 s49, v255, 14
	v_add_f32_e32 v4, v45, v44
	v_mov_b32_e32 v9, vcc_lo
	v_readlane_b32 vcc_lo, v255, 16
	s_add_i32 s48, 0, 0x18800
	v_mov_b32_e32 v8, s49
	v_mov_b32_e32 v18, vcc_lo
	v_readlane_b32 vcc_lo, v255, 17
	s_add_i32 s49, 0, 0x18900
	v_add_u32_e32 v6, 0x10000, v84
	v_mov_b32_e32 v19, vcc_lo
	v_readlane_b32 vcc_lo, v255, 18
	v_add_u32_e32 v7, 0x14000, v84
	v_mul_f32_e32 v4, 0xbfb8aa3b, v4
	v_mov_b32_e32 v20, vcc_lo
	v_readlane_b32 vcc_lo, v255, 19
	v_mov_b32_e32 v10, s48
	v_mov_b32_e32 v24, s49
	v_mov_b32_e32 v21, vcc_lo
	v_readlane_b32 vcc_lo, v255, 20
	v_exp_f32_e32 v25, v4
	s_nop 0
	v_mov_b32_e32 v22, vcc_lo
	v_readlane_b32 vcc_lo, v255, 21
	s_nop 1
	v_mov_b32_e32 v23, vcc_lo
	ds_read2st64_b32 v[4:5], v84 offset0:128 offset1:192
	ds_read_b32 v26, v6
	ds_read_b32 v27, v7
	ds_read_b128 v[10:13], v10
	ds_read_b128 v[14:17], v8
	ds_read_b32 v24, v24
	ds_read_b32 v28, v9
	ds_read_b32 v18, v18
	ds_read_b32 v19, v19
	ds_read_b32 v6, v20
	ds_read_b32 v7, v21
	ds_read_b32 v8, v22
	ds_read_b32 v9, v23
	s_waitcnt lgkmcnt(0)
	v_add_f32_e32 v22, v10, v24
	v_add_f32_e32 v20, v4, v5
	v_add_f32_e32 v23, v11, v28
	v_pk_add_f32 v[4:5], v[14:15], v[6:7]
	v_pk_add_f32 v[6:7], v[16:17], v[8:9]
	v_add_f32_e32 v8, 0, v22
	v_add_f32_e32 v18, v12, v18
	v_add_f32_e32 v8, v8, v23
	v_add_f32_e32 v19, v13, v19
	v_add_f32_e32 v8, v8, v18
	v_add_f32_e32 v8, v8, v19
	v_add_f32_e32 v4, v8, v4
	v_add_f32_e32 v21, v26, v27
	v_add_f32_e32 v4, v4, v5
	v_add_f32_e32 v20, v20, v21
	v_add_f32_e32 v4, v4, v6
	v_add_f32_e32 v4, v4, v7
	v_max_f32_e64 v18, |v4|, v25
	s_waitcnt vmcnt(0)
	v_lshlrev_b32_e32 v9, 16, v2
	v_and_b32_e32 v8, 0xffff0000, v2
	v_lshlrev_b32_e32 v6, 16, v3
	v_and_b32_e32 v7, 0xffff0000, v3
	v_fmac_f32_e32 v20, v10, v9
	v_lshlrev_b32_e32 v2, 16, v0
	v_and_b32_e32 v3, 0xffff0000, v0
	v_lshlrev_b32_e32 v4, 16, v1
	v_and_b32_e32 v5, 0xffff0000, v1
	v_pk_mul_f32 v[0:1], v[12:13], v[6:7]
	v_fmac_f32_e32 v20, v11, v8
	v_add_f32_e32 v0, v20, v0
	v_pk_mul_f32 v[12:13], v[14:15], v[2:3]
	v_add_f32_e32 v0, v0, v1
	v_add_f32_e32 v0, v0, v12
	v_pk_mul_f32 v[14:15], v[16:17], v[4:5]
	v_add_f32_e32 v0, v0, v13
	v_add_f32_e32 v0, v0, v14
	v_add_f32_e32 v0, v0, v15
	v_div_scale_f32 v1, s[48:49], v18, v18, v0
	v_rcp_f32_e32 v10, v1
	v_div_scale_f32 v11, vcc, v0, v18, v0
	v_fma_f32 v12, -v1, v10, 1.0
	v_fmac_f32_e32 v10, v12, v10
	v_mul_f32_e32 v12, v11, v10
	v_fma_f32 v13, -v1, v12, v11
	v_fmac_f32_e32 v12, v13, v10
	v_fma_f32 v1, -v1, v12, v11
	v_div_fmas_f32 v1, v1, v10, v12
	v_div_fixup_f32 v14, v1, v18, v0
	v_mul_f32_e32 v1, v14, v14
	ds_bpermute_b32 v0, v146, v14
	ds_bpermute_b32 v1, v146, v1
	v_bfe_u32 v16, v14, 16, 1
	v_add3_u32 v16, v14, v16, s61
	s_waitcnt lgkmcnt(1)
	v_add_f32_e32 v0, v14, v0
	s_waitcnt lgkmcnt(0)
	v_fmac_f32_e32 v1, v14, v14
	ds_bpermute_b32 v10, v147, v0
	ds_bpermute_b32 v11, v147, v1
	s_waitcnt lgkmcnt(1)
	v_add_f32_e32 v0, v0, v10
	s_waitcnt lgkmcnt(0)
	v_add_f32_e32 v1, v1, v11
	ds_bpermute_b32 v10, v148, v0
	ds_bpermute_b32 v11, v148, v1
	s_waitcnt lgkmcnt(1)
	v_add_f32_e32 v0, v0, v10
	s_waitcnt lgkmcnt(0)
	v_add_f32_e32 v1, v1, v11
	ds_bpermute_b32 v10, v149, v0
	ds_bpermute_b32 v11, v149, v1
	s_waitcnt lgkmcnt(1)
	v_add_f32_e32 v10, v0, v10
	s_waitcnt lgkmcnt(0)
	v_add_f32_e32 v13, v1, v11
	ds_bpermute_b32 v12, v150, v10
	ds_bpermute_b32 v15, v150, v13
	v_lshl_add_u64 v[0:1], v[36:37], 1, s[40:41]
	s_waitcnt lgkmcnt(1)
	v_add_f32_e32 v10, v10, v12
	s_waitcnt lgkmcnt(0)
	v_add_f32_e32 v12, v13, v15
	ds_bpermute_b32 v11, v151, v10
	ds_bpermute_b32 v13, v151, v12
	v_lshlrev_b64 v[14:15], 12, v[38:39]
	v_lshl_add_u64 v[14:15], v[0:1], 0, v[14:15]
	flat_store_short_d16_hi v[14:15], v16
	s_and_saveexec_b64 s[48:49], s[6:7]
	s_cbranch_execz .LBB0_839
	s_waitcnt lgkmcnt(0)
	v_add_f32_e32 v14, v10, v11
	v_lshl_add_u64 v[10:11], s[10:11], 0, v[40:41]
	v_add_f32_e32 v12, v12, v13
	flat_atomic_add_f32 v[10:11], v14
	flat_atomic_add_f32 v[10:11], v12 offset:4

.LBB0_939:
	s_or_b64 exec, exec, s[36:37]
	v_lshlrev_b32_e32 v0, 2, v36
	v_and_b32_e32 v156, 0x1fc, v0
	v_ashrrev_i32_e32 v0, 31, v40
	v_lshrrev_b32_e32 v0, 30, v0
	v_add_u32_e32 v0, v40, v0
	v_ashrrev_i32_e32 v0, 2, v0
	v_ashrrev_i32_e32 v1, 31, v0
	v_or_b32_e32 v2, s28, v156
	v_lshlrev_b64 v[0:1], 14, v[0:1]
	v_lshlrev_b32_e32 v32, 3, v2
	v_lshl_add_u64 v[90:91], s[22:23], 0, v[0:1]
	s_mov_b64 s[36:37], 0x4000
	v_lshl_add_u64 v[0:1], v[90:91], 0, v[32:33]
	v_lshl_add_u64 v[92:93], v[90:91], 0, s[36:37]
	s_waitcnt lgkmcnt(0)
	s_barrier
	flat_load_dwordx4 v[26:29], v[0:1]
	flat_load_dwordx4 v[116:119], v[0:1] offset:16
	v_lshl_add_u64 v[0:1], v[92:93], 0, v[32:33]
	flat_load_dwordx4 v[124:127], v[0:1]
	flat_load_dwordx4 v[132:135], v[0:1] offset:16
	v_ashrrev_i32_e32 v94, 7, v36
	v_ashrrev_i32_e32 v95, 31, v94
	v_and_b32_e32 v25, 0x7f, v36
	v_lshlrev_b64 v[30:31], 11, v[94:95]
	v_mov_b32_e32 v0, 0
	v_lshl_or_b32 v30, v25, 4, v30
	v_mov_b32_e32 v87, v86
	v_mov_b32_e32 v96, v86
	v_mov_b32_e32 v97, v86
	s_mov_b64 s[36:37], 0
	v_lshl_add_u32 v32, v94, 5, 0
	v_mov_b32_e32 v1, v0
	v_mov_b32_e32 v2, v0
	v_mov_b32_e32 v3, v0
	v_mov_b32_e32 v4, v0
	v_mov_b32_e32 v5, v0
	v_mov_b32_e32 v6, v0
	v_mov_b32_e32 v7, v0
	v_mov_b32_e32 v8, v0
	v_mov_b32_e32 v9, v0
	v_mov_b32_e32 v10, v0
	v_mov_b32_e32 v11, v0
	v_mov_b32_e32 v12, v0
	v_mov_b32_e32 v13, v0
	v_mov_b32_e32 v14, v0
	v_mov_b32_e32 v15, v0
	v_mov_b32_e32 v16, v0
	v_mov_b32_e32 v17, v0
	v_mov_b32_e32 v18, v0
	v_mov_b32_e32 v19, v0
	v_mov_b32_e32 v20, v0
	v_mov_b32_e32 v21, v0
	v_mov_b32_e32 v22, v0
	v_mov_b32_e32 v23, v0
	v_mov_b32_e32 v24, v0
	v_lshl_add_u64 v[98:99], s[10:11], 0, v[30:31]
	v_lshl_add_u64 v[100:101], s[12:13], 0, v[30:31]
	v_mov_b32_e32 v25, v0
	v_mov_b32_e32 v30, v0
	v_mov_b32_e32 v31, v0
	s_waitcnt vmcnt(0) lgkmcnt(0)
	v_lshlrev_b32_e32 v102, 16, v26
	v_and_b32_e32 v104, 0xffff0000, v26
	v_lshlrev_b32_e32 v106, 16, v27
	v_and_b32_e32 v108, 0xffff0000, v27
	v_lshlrev_b32_e32 v103, 16, v28
	v_and_b32_e32 v105, 0xffff0000, v28
	v_lshlrev_b32_e32 v107, 16, v29
	v_and_b32_e32 v109, 0xffff0000, v29
	v_lshlrev_b32_e32 v110, 16, v116
	v_and_b32_e32 v112, 0xffff0000, v116
	v_lshlrev_b32_e32 v114, 16, v117
	v_and_b32_e32 v116, 0xffff0000, v117
	v_lshlrev_b32_e32 v111, 16, v118
	v_and_b32_e32 v113, 0xffff0000, v118
	v_lshlrev_b32_e32 v115, 16, v119
	v_and_b32_e32 v117, 0xffff0000, v119
	v_lshlrev_b32_e32 v118, 16, v124
	v_and_b32_e32 v120, 0xffff0000, v124
	v_lshlrev_b32_e32 v122, 16, v125
	v_and_b32_e32 v124, 0xffff0000, v125
	v_lshlrev_b32_e32 v119, 16, v126
	v_and_b32_e32 v121, 0xffff0000, v126
	v_lshlrev_b32_e32 v123, 16, v127
	v_and_b32_e32 v125, 0xffff0000, v127
	v_lshlrev_b32_e32 v126, 16, v132
	v_and_b32_e32 v128, 0xffff0000, v132
	v_lshlrev_b32_e32 v130, 16, v133
	v_and_b32_e32 v132, 0xffff0000, v133
	v_lshlrev_b32_e32 v127, 16, v134
	v_and_b32_e32 v129, 0xffff0000, v134
	v_lshlrev_b32_e32 v131, 16, v135
	v_and_b32_e32 v133, 0xffff0000, v135
	v_mov_b32_e32 v26, v0
	v_mov_b32_e32 v27, v0
	v_mov_b32_e32 v28, v0
	v_mov_b32_e32 v29, v0
	v_subrev_u32_e32 v246, s12, v100
	s_mov_b32 s98, s12
	s_mov_b32 s99, s13
	s_add_u32 s100, s10, 0x6950000
	s_addc_u32 s101, s11, 0
	global_load_dwordx4 v[134:137], v246, s[98:99] nt
	s_add_u32 s98, s98, 0x2000
	s_addc_u32 s99, s99, 0
	global_load_dwordx4 v[138:141], v246, s[98:99] nt
	s_add_u32 s98, s98, 0x2000
	s_addc_u32 s99, s99, 0
	global_load_dwordx4 v[142:145], v246, s[98:99] nt
	s_add_u32 s98, s98, 0x2000
	s_addc_u32 s99, s99, 0
	global_load_dwordx4 v[158:161], v246, s[98:99] nt
	s_add_u32 s98, s98, 0x2000
	s_addc_u32 s99, s99, 0
	global_load_dwordx4 v[162:165], v246, s[98:99] nt
	s_add_u32 s98, s98, 0x2000
	s_addc_u32 s99, s99, 0
	global_load_dwordx4 v[166:169], v246, s[98:99] nt
	s_add_u32 s98, s98, 0x2000
	s_addc_u32 s99, s99, 0
	global_load_dwordx4 v[170:173], v246, s[98:99] nt
	s_add_u32 s98, s98, 0x2000
	s_addc_u32 s99, s99, 0
	global_load_dwordx4 v[174:177], v246, s[98:99] nt
	s_add_u32 s98, s98, 0x2000
	s_addc_u32 s99, s99, 0
	global_load_dwordx4 v[178:181], v246, s[98:99] nt
	s_add_u32 s98, s98, 0x2000
	s_addc_u32 s99, s99, 0
	global_load_dwordx4 v[182:185], v246, s[98:99] nt
	s_add_u32 s98, s98, 0x2000
	s_addc_u32 s99, s99, 0
	global_load_dwordx4 v[186:189], v246, s[98:99] nt
	s_add_u32 s98, s98, 0x2000
	s_addc_u32 s99, s99, 0
	global_load_dwordx4 v[190:193], v246, s[98:99] nt
	s_add_u32 s98, s98, 0x2000
	s_addc_u32 s99, s99, 0
	global_load_dwordx4 v[194:197], v246, s[98:99] nt
	s_add_u32 s98, s98, 0x2000
	s_addc_u32 s99, s99, 0
	global_load_dwordx4 v[210:213], v246, s[98:99] nt
	s_add_u32 s98, s98, 0x2000
	s_addc_u32 s99, s99, 0
	global_load_dwordx4 v[214:217], v246, s[98:99] nt
	s_add_u32 s98, s98, 0x2000
	s_addc_u32 s99, s99, 0
	global_load_dwordx4 v[218:221], v246, s[98:99] nt
	s_add_u32 s98, s98, 0x2000
	s_addc_u32 s99, s99, 0
	ds_read_b128 v[222:225], v32
	ds_read_b128 v[226:229], v32 offset:16
	ds_read_b128 v[230:233], v32 offset:16384
	ds_read_b128 v[234:237], v32 offset:16400
	s_mov_b32 vcc_lo, 0
	s_waitcnt vmcnt(15)
	s_waitcnt lgkmcnt(2)
	v_pk_fma_f32 v[0:1], v[134:135], v[222:223], v[0:1] op_sel_hi:[1,0,1]
	v_pk_fma_f32 v[2:3], v[136:137], v[222:223], v[2:3] op_sel_hi:[1,0,1]
	v_pk_fma_f32 v[4:5], v[134:135], v[222:223], v[4:5] op_sel:[0,1,0]
	v_pk_fma_f32 v[6:7], v[136:137], v[222:223], v[6:7] op_sel:[0,1,0]
	v_pk_fma_f32 v[8:9], v[134:135], v[224:225], v[8:9] op_sel_hi:[1,0,1]
	v_pk_fma_f32 v[10:11], v[136:137], v[224:225], v[10:11] op_sel_hi:[1,0,1]
	v_pk_fma_f32 v[12:13], v[134:135], v[224:225], v[12:13] op_sel:[0,1,0]
	v_pk_fma_f32 v[14:15], v[136:137], v[224:225], v[14:15] op_sel:[0,1,0]
	v_pk_fma_f32 v[16:17], v[134:135], v[226:227], v[16:17] op_sel_hi:[1,0,1]
	v_pk_fma_f32 v[18:19], v[136:137], v[226:227], v[18:19] op_sel_hi:[1,0,1]
	v_pk_fma_f32 v[20:21], v[134:135], v[226:227], v[20:21] op_sel:[0,1,0]
	v_pk_fma_f32 v[22:23], v[136:137], v[226:227], v[22:23] op_sel:[0,1,0]
	v_pk_fma_f32 v[24:25], v[134:135], v[228:229], v[24:25] op_sel_hi:[1,0,1]
	v_pk_fma_f32 v[26:27], v[136:137], v[228:229], v[26:27] op_sel_hi:[1,0,1]
	v_pk_fma_f32 v[28:29], v[134:135], v[228:229], v[28:29] op_sel:[0,1,0]
	v_pk_fma_f32 v[30:31], v[136:137], v[228:229], v[30:31] op_sel:[0,1,0]
	ds_read_b128 v[222:225], v32 offset:128
	ds_read_b128 v[226:229], v32 offset:144
	s_waitcnt lgkmcnt(2)
	v_pk_mul_f32 v[238:239], v[230:231], v[102:103] op_sel_hi:[0,1]
	v_pk_mul_f32 v[240:241], v[230:231], v[110:111] op_sel_hi:[0,1]
	v_pk_fma_f32 v[238:239], v[86:87], v[134:135], v[238:239]
	v_pk_fma_f32 v[240:241], v[86:87], v[136:137], v[240:241]
	v_pk_fma_f32 v[238:239], v[234:235], v[118:119], v[238:239] op_sel_hi:[0,1,1]
	v_pk_fma_f32 v[240:241], v[234:235], v[126:127], v[240:241] op_sel_hi:[0,1,1]
	v_pk_fma_f32 v[238:239], v[230:231], v[104:105], v[238:239] op_sel:[1,0,0]
	v_pk_fma_f32 v[240:241], v[230:231], v[112:113], v[240:241] op_sel:[1,0,0]
	v_pk_fma_f32 v[238:239], v[234:235], v[120:121], v[238:239] op_sel:[1,0,0]
	v_pk_fma_f32 v[240:241], v[234:235], v[128:129], v[240:241] op_sel:[1,0,0]
	v_pk_fma_f32 v[238:239], v[232:233], v[106:107], v[238:239] op_sel_hi:[0,1,1]
	v_pk_fma_f32 v[240:241], v[232:233], v[114:115], v[240:241] op_sel_hi:[0,1,1]
	v_pk_fma_f32 v[238:239], v[236:237], v[122:123], v[238:239] op_sel_hi:[0,1,1]
	v_pk_fma_f32 v[240:241], v[236:237], v[130:131], v[240:241] op_sel_hi:[0,1,1]
	v_pk_fma_f32 v[238:239], v[232:233], v[108:109], v[238:239] op_sel:[1,0,0]
	v_pk_fma_f32 v[240:241], v[232:233], v[116:117], v[240:241] op_sel:[1,0,0]
	v_pk_fma_f32 v[238:239], v[236:237], v[124:125], v[238:239] op_sel:[1,0,0]
	v_pk_fma_f32 v[240:241], v[236:237], v[132:133], v[240:241] op_sel:[1,0,0]
	ds_read_b128 v[230:233], v32 offset:16512
	ds_read_b128 v[234:237], v32 offset:16528
	global_store_dwordx4 v246, v[238:241], s[100:101] nt
	global_load_dwordx4 v[134:137], v246, s[98:99] nt
	s_add_u32 s100, s100, 0x2000
	s_addc_u32 s101, s101, 0
	s_add_u32 s98, s98, 0x2000
	s_addc_u32 s99, s99, 0
	s_waitcnt vmcnt(16)
	s_waitcnt lgkmcnt(2)
	v_pk_fma_f32 v[0:1], v[138:139], v[222:223], v[0:1] op_sel_hi:[1,0,1]
	v_pk_fma_f32 v[2:3], v[140:141], v[222:223], v[2:3] op_sel_hi:[1,0,1]
	v_pk_fma_f32 v[4:5], v[138:139], v[222:223], v[4:5] op_sel:[0,1,0]
	v_pk_fma_f32 v[6:7], v[140:141], v[222:223], v[6:7] op_sel:[0,1,0]
	v_pk_fma_f32 v[8:9], v[138:139], v[224:225], v[8:9] op_sel_hi:[1,0,1]
	v_pk_fma_f32 v[10:11], v[140:141], v[224:225], v[10:11] op_sel_hi:[1,0,1]
	v_pk_fma_f32 v[12:13], v[138:139], v[224:225], v[12:13] op_sel:[0,1,0]
	v_pk_fma_f32 v[14:15], v[140:141], v[224:225], v[14:15] op_sel:[0,1,0]
	v_pk_fma_f32 v[16:17], v[138:139], v[226:227], v[16:17] op_sel_hi:[1,0,1]
	v_pk_fma_f32 v[18:19], v[140:141], v[226:227], v[18:19] op_sel_hi:[1,0,1]
	v_pk_fma_f32 v[20:21], v[138:139], v[226:227], v[20:21] op_sel:[0,1,0]
	v_pk_fma_f32 v[22:23], v[140:141], v[226:227], v[22:23] op_sel:[0,1,0]
	v_pk_fma_f32 v[24:25], v[138:139], v[228:229], v[24:25] op_sel_hi:[1,0,1]
	v_pk_fma_f32 v[26:27], v[140:141], v[228:229], v[26:27] op_sel_hi:[1,0,1]
	v_pk_fma_f32 v[28:29], v[138:139], v[228:229], v[28:29] op_sel:[0,1,0]
	v_pk_fma_f32 v[30:31], v[140:141], v[228:229], v[30:31] op_sel:[0,1,0]
	ds_read_b128 v[222:225], v32 offset:256
	ds_read_b128 v[226:229], v32 offset:272
	s_waitcnt lgkmcnt(2)
	v_pk_mul_f32 v[242:243], v[230:231], v[102:103] op_sel_hi:[0,1]
	v_pk_mul_f32 v[244:245], v[230:231], v[110:111] op_sel_hi:[0,1]
	v_pk_fma_f32 v[242:243], v[86:87], v[138:139], v[242:243]
	v_pk_fma_f32 v[244:245], v[86:87], v[140:141], v[244:245]
	v_pk_fma_f32 v[242:243], v[234:235], v[118:119], v[242:243] op_sel_hi:[0,1,1]
	v_pk_fma_f32 v[244:245], v[234:235], v[126:127], v[244:245] op_sel_hi:[0,1,1]
	v_pk_fma_f32 v[242:243], v[230:231], v[104:105], v[242:243] op_sel:[1,0,0]
	v_pk_fma_f32 v[244:245], v[230:231], v[112:113], v[244:245] op_sel:[1,0,0]
	v_pk_fma_f32 v[242:243], v[234:235], v[120:121], v[242:243] op_sel:[1,0,0]
	v_pk_fma_f32 v[244:245], v[234:235], v[128:129], v[244:245] op_sel:[1,0,0]
	v_pk_fma_f32 v[242:243], v[232:233], v[106:107], v[242:243] op_sel_hi:[0,1,1]
	v_pk_fma_f32 v[244:245], v[232:233], v[114:115], v[244:245] op_sel_hi:[0,1,1]
	v_pk_fma_f32 v[242:243], v[236:237], v[122:123], v[242:243] op_sel_hi:[0,1,1]
	v_pk_fma_f32 v[244:245], v[236:237], v[130:131], v[244:245] op_sel_hi:[0,1,1]
	v_pk_fma_f32 v[242:243], v[232:233], v[108:109], v[242:243] op_sel:[1,0,0]
	v_pk_fma_f32 v[244:245], v[232:233], v[116:117], v[244:245] op_sel:[1,0,0]
	v_pk_fma_f32 v[242:243], v[236:237], v[124:125], v[242:243] op_sel:[1,0,0]
	v_pk_fma_f32 v[244:245], v[236:237], v[132:133], v[244:245] op_sel:[1,0,0]
	ds_read_b128 v[230:233], v32 offset:16640
	ds_read_b128 v[234:237], v32 offset:16656
	global_store_dwordx4 v246, v[242:245], s[100:101] nt
	global_load_dwordx4 v[138:141], v246, s[98:99] nt
	s_add_u32 s100, s100, 0x2000
	s_addc_u32 s101, s101, 0
	s_add_u32 s98, s98, 0x2000
	s_addc_u32 s99, s99, 0
	s_waitcnt vmcnt(17)
	s_waitcnt lgkmcnt(2)
	v_pk_fma_f32 v[0:1], v[142:143], v[222:223], v[0:1] op_sel_hi:[1,0,1]
	v_pk_fma_f32 v[2:3], v[144:145], v[222:223], v[2:3] op_sel_hi:[1,0,1]
	v_pk_fma_f32 v[4:5], v[142:143], v[222:223], v[4:5] op_sel:[0,1,0]
	v_pk_fma_f32 v[6:7], v[144:145], v[222:223], v[6:7] op_sel:[0,1,0]
	v_pk_fma_f32 v[8:9], v[142:143], v[224:225], v[8:9] op_sel_hi:[1,0,1]
	v_pk_fma_f32 v[10:11], v[144:145], v[224:225], v[10:11] op_sel_hi:[1,0,1]
	v_pk_fma_f32 v[12:13], v[142:143], v[224:225], v[12:13] op_sel:[0,1,0]
	v_pk_fma_f32 v[14:15], v[144:145], v[224:225], v[14:15] op_sel:[0,1,0]
	v_pk_fma_f32 v[16:17], v[142:143], v[226:227], v[16:17] op_sel_hi:[1,0,1]
	v_pk_fma_f32 v[18:19], v[144:145], v[226:227], v[18:19] op_sel_hi:[1,0,1]
	v_pk_fma_f32 v[20:21], v[142:143], v[226:227], v[20:21] op_sel:[0,1,0]
	v_pk_fma_f32 v[22:23], v[144:145], v[226:227], v[22:23] op_sel:[0,1,0]
	v_pk_fma_f32 v[24:25], v[142:143], v[228:229], v[24:25] op_sel_hi:[1,0,1]
	v_pk_fma_f32 v[26:27], v[144:145], v[228:229], v[26:27] op_sel_hi:[1,0,1]
	v_pk_fma_f32 v[28:29], v[142:143], v[228:229], v[28:29] op_sel:[0,1,0]
	v_pk_fma_f32 v[30:31], v[144:145], v[228:229], v[30:31] op_sel:[0,1,0]
	ds_read_b128 v[222:225], v32 offset:384
	ds_read_b128 v[226:229], v32 offset:400
	s_waitcnt lgkmcnt(2)
	v_pk_mul_f32 v[238:239], v[230:231], v[102:103] op_sel_hi:[0,1]
	v_pk_mul_f32 v[240:241], v[230:231], v[110:111] op_sel_hi:[0,1]
	v_pk_fma_f32 v[238:239], v[86:87], v[142:143], v[238:239]
	v_pk_fma_f32 v[240:241], v[86:87], v[144:145], v[240:241]
	v_pk_fma_f32 v[238:239], v[234:235], v[118:119], v[238:239] op_sel_hi:[0,1,1]
	v_pk_fma_f32 v[240:241], v[234:235], v[126:127], v[240:241] op_sel_hi:[0,1,1]
	v_pk_fma_f32 v[238:239], v[230:231], v[104:105], v[238:239] op_sel:[1,0,0]
	v_pk_fma_f32 v[240:241], v[230:231], v[112:113], v[240:241] op_sel:[1,0,0]
	v_pk_fma_f32 v[238:239], v[234:235], v[120:121], v[238:239] op_sel:[1,0,0]
	v_pk_fma_f32 v[240:241], v[234:235], v[128:129], v[240:241] op_sel:[1,0,0]
	v_pk_fma_f32 v[238:239], v[232:233], v[106:107], v[238:239] op_sel_hi:[0,1,1]
	v_pk_fma_f32 v[240:241], v[232:233], v[114:115], v[240:241] op_sel_hi:[0,1,1]
	v_pk_fma_f32 v[238:239], v[236:237], v[122:123], v[238:239] op_sel_hi:[0,1,1]
	v_pk_fma_f32 v[240:241], v[236:237], v[130:131], v[240:241] op_sel_hi:[0,1,1]
	v_pk_fma_f32 v[238:239], v[232:233], v[108:109], v[238:239] op_sel:[1,0,0]
	v_pk_fma_f32 v[240:241], v[232:233], v[116:117], v[240:241] op_sel:[1,0,0]
	v_pk_fma_f32 v[238:239], v[236:237], v[124:125], v[238:239] op_sel:[1,0,0]
	v_pk_fma_f32 v[240:241], v[236:237], v[132:133], v[240:241] op_sel:[1,0,0]
	ds_read_b128 v[230:233], v32 offset:16768
	ds_read_b128 v[234:237], v32 offset:16784
	global_store_dwordx4 v246, v[238:241], s[100:101] nt
	global_load_dwordx4 v[142:145], v246, s[98:99] nt
	s_add_u32 s100, s100, 0x2000
	s_addc_u32 s101, s101, 0
	s_add_u32 s98, s98, 0x2000
	s_addc_u32 s99, s99, 0
	s_waitcnt vmcnt(18)
	s_waitcnt lgkmcnt(2)
	v_pk_fma_f32 v[0:1], v[158:159], v[222:223], v[0:1] op_sel_hi:[1,0,1]
	v_pk_fma_f32 v[2:3], v[160:161], v[222:223], v[2:3] op_sel_hi:[1,0,1]
	v_pk_fma_f32 v[4:5], v[158:159], v[222:223], v[4:5] op_sel:[0,1,0]
	v_pk_fma_f32 v[6:7], v[160:161], v[222:223], v[6:7] op_sel:[0,1,0]
	v_pk_fma_f32 v[8:9], v[158:159], v[224:225], v[8:9] op_sel_hi:[1,0,1]
	v_pk_fma_f32 v[10:11], v[160:161], v[224:225], v[10:11] op_sel_hi:[1,0,1]
	v_pk_fma_f32 v[12:13], v[158:159], v[224:225], v[12:13] op_sel:[0,1,0]
	v_pk_fma_f32 v[14:15], v[160:161], v[224:225], v[14:15] op_sel:[0,1,0]
	v_pk_fma_f32 v[16:17], v[158:159], v[226:227], v[16:17] op_sel_hi:[1,0,1]
	v_pk_fma_f32 v[18:19], v[160:161], v[226:227], v[18:19] op_sel_hi:[1,0,1]
	v_pk_fma_f32 v[20:21], v[158:159], v[226:227], v[20:21] op_sel:[0,1,0]
	v_pk_fma_f32 v[22:23], v[160:161], v[226:227], v[22:23] op_sel:[0,1,0]
	v_pk_fma_f32 v[24:25], v[158:159], v[228:229], v[24:25] op_sel_hi:[1,0,1]
	v_pk_fma_f32 v[26:27], v[160:161], v[228:229], v[26:27] op_sel_hi:[1,0,1]
	v_pk_fma_f32 v[28:29], v[158:159], v[228:229], v[28:29] op_sel:[0,1,0]
	v_pk_fma_f32 v[30:31], v[160:161], v[228:229], v[30:31] op_sel:[0,1,0]
	ds_read_b128 v[222:225], v32 offset:512
	ds_read_b128 v[226:229], v32 offset:528
	s_waitcnt lgkmcnt(2)
	v_pk_mul_f32 v[242:243], v[230:231], v[102:103] op_sel_hi:[0,1]
	v_pk_mul_f32 v[244:245], v[230:231], v[110:111] op_sel_hi:[0,1]
	v_pk_fma_f32 v[242:243], v[86:87], v[158:159], v[242:243]
	v_pk_fma_f32 v[244:245], v[86:87], v[160:161], v[244:245]
	v_pk_fma_f32 v[242:243], v[234:235], v[118:119], v[242:243] op_sel_hi:[0,1,1]
	v_pk_fma_f32 v[244:245], v[234:235], v[126:127], v[244:245] op_sel_hi:[0,1,1]
	v_pk_fma_f32 v[242:243], v[230:231], v[104:105], v[242:243] op_sel:[1,0,0]
	v_pk_fma_f32 v[244:245], v[230:231], v[112:113], v[244:245] op_sel:[1,0,0]
	v_pk_fma_f32 v[242:243], v[234:235], v[120:121], v[242:243] op_sel:[1,0,0]
	v_pk_fma_f32 v[244:245], v[234:235], v[128:129], v[244:245] op_sel:[1,0,0]
	v_pk_fma_f32 v[242:243], v[232:233], v[106:107], v[242:243] op_sel_hi:[0,1,1]
	v_pk_fma_f32 v[244:245], v[232:233], v[114:115], v[244:245] op_sel_hi:[0,1,1]
	v_pk_fma_f32 v[242:243], v[236:237], v[122:123], v[242:243] op_sel_hi:[0,1,1]
	v_pk_fma_f32 v[244:245], v[236:237], v[130:131], v[244:245] op_sel_hi:[0,1,1]
	v_pk_fma_f32 v[242:243], v[232:233], v[108:109], v[242:243] op_sel:[1,0,0]
	v_pk_fma_f32 v[244:245], v[232:233], v[116:117], v[244:245] op_sel:[1,0,0]
	v_pk_fma_f32 v[242:243], v[236:237], v[124:125], v[242:243] op_sel:[1,0,0]
	v_pk_fma_f32 v[244:245], v[236:237], v[132:133], v[244:245] op_sel:[1,0,0]
	ds_read_b128 v[230:233], v32 offset:16896
	ds_read_b128 v[234:237], v32 offset:16912
	global_store_dwordx4 v246, v[242:245], s[100:101] nt
	global_load_dwordx4 v[158:161], v246, s[98:99] nt
	s_add_u32 s100, s100, 0x2000
	s_addc_u32 s101, s101, 0
	s_add_u32 s98, s98, 0x2000
	s_addc_u32 s99, s99, 0
	s_waitcnt vmcnt(19)
	s_waitcnt lgkmcnt(2)
	v_pk_fma_f32 v[0:1], v[162:163], v[222:223], v[0:1] op_sel_hi:[1,0,1]
	v_pk_fma_f32 v[2:3], v[164:165], v[222:223], v[2:3] op_sel_hi:[1,0,1]
	v_pk_fma_f32 v[4:5], v[162:163], v[222:223], v[4:5] op_sel:[0,1,0]
	v_pk_fma_f32 v[6:7], v[164:165], v[222:223], v[6:7] op_sel:[0,1,0]
	v_pk_fma_f32 v[8:9], v[162:163], v[224:225], v[8:9] op_sel_hi:[1,0,1]
	v_pk_fma_f32 v[10:11], v[164:165], v[224:225], v[10:11] op_sel_hi:[1,0,1]
	v_pk_fma_f32 v[12:13], v[162:163], v[224:225], v[12:13] op_sel:[0,1,0]
	v_pk_fma_f32 v[14:15], v[164:165], v[224:225], v[14:15] op_sel:[0,1,0]
	v_pk_fma_f32 v[16:17], v[162:163], v[226:227], v[16:17] op_sel_hi:[1,0,1]
	v_pk_fma_f32 v[18:19], v[164:165], v[226:227], v[18:19] op_sel_hi:[1,0,1]
	v_pk_fma_f32 v[20:21], v[162:163], v[226:227], v[20:21] op_sel:[0,1,0]
	v_pk_fma_f32 v[22:23], v[164:165], v[226:227], v[22:23] op_sel:[0,1,0]
	v_pk_fma_f32 v[24:25], v[162:163], v[228:229], v[24:25] op_sel_hi:[1,0,1]
	v_pk_fma_f32 v[26:27], v[164:165], v[228:229], v[26:27] op_sel_hi:[1,0,1]
	v_pk_fma_f32 v[28:29], v[162:163], v[228:229], v[28:29] op_sel:[0,1,0]
	v_pk_fma_f32 v[30:31], v[164:165], v[228:229], v[30:31] op_sel:[0,1,0]
	ds_read_b128 v[222:225], v32 offset:640
	ds_read_b128 v[226:229], v32 offset:656
	s_waitcnt lgkmcnt(2)
	v_pk_mul_f32 v[238:239], v[230:231], v[102:103] op_sel_hi:[0,1]
	v_pk_mul_f32 v[240:241], v[230:231], v[110:111] op_sel_hi:[0,1]
	v_pk_fma_f32 v[238:239], v[86:87], v[162:163], v[238:239]
	v_pk_fma_f32 v[240:241], v[86:87], v[164:165], v[240:241]
	v_pk_fma_f32 v[238:239], v[234:235], v[118:119], v[238:239] op_sel_hi:[0,1,1]
	v_pk_fma_f32 v[240:241], v[234:235], v[126:127], v[240:241] op_sel_hi:[0,1,1]
	v_pk_fma_f32 v[238:239], v[230:231], v[104:105], v[238:239] op_sel:[1,0,0]
	v_pk_fma_f32 v[240:241], v[230:231], v[112:113], v[240:241] op_sel:[1,0,0]
	v_pk_fma_f32 v[238:239], v[234:235], v[120:121], v[238:239] op_sel:[1,0,0]
	v_pk_fma_f32 v[240:241], v[234:235], v[128:129], v[240:241] op_sel:[1,0,0]
	v_pk_fma_f32 v[238:239], v[232:233], v[106:107], v[238:239] op_sel_hi:[0,1,1]
	v_pk_fma_f32 v[240:241], v[232:233], v[114:115], v[240:241] op_sel_hi:[0,1,1]
	v_pk_fma_f32 v[238:239], v[236:237], v[122:123], v[238:239] op_sel_hi:[0,1,1]
	v_pk_fma_f32 v[240:241], v[236:237], v[130:131], v[240:241] op_sel_hi:[0,1,1]
	v_pk_fma_f32 v[238:239], v[232:233], v[108:109], v[238:239] op_sel:[1,0,0]
	v_pk_fma_f32 v[240:241], v[232:233], v[116:117], v[240:241] op_sel:[1,0,0]
	v_pk_fma_f32 v[238:239], v[236:237], v[124:125], v[238:239] op_sel:[1,0,0]
	v_pk_fma_f32 v[240:241], v[236:237], v[132:133], v[240:241] op_sel:[1,0,0]
	ds_read_b128 v[230:233], v32 offset:17024
	ds_read_b128 v[234:237], v32 offset:17040
	global_store_dwordx4 v246, v[238:241], s[100:101] nt
	global_load_dwordx4 v[162:165], v246, s[98:99] nt
	s_add_u32 s100, s100, 0x2000
	s_addc_u32 s101, s101, 0
	s_add_u32 s98, s98, 0x2000
	s_addc_u32 s99, s99, 0
	s_waitcnt vmcnt(20)
	s_waitcnt lgkmcnt(2)
	v_pk_fma_f32 v[0:1], v[166:167], v[222:223], v[0:1] op_sel_hi:[1,0,1]
	v_pk_fma_f32 v[2:3], v[168:169], v[222:223], v[2:3] op_sel_hi:[1,0,1]
	v_pk_fma_f32 v[4:5], v[166:167], v[222:223], v[4:5] op_sel:[0,1,0]
	v_pk_fma_f32 v[6:7], v[168:169], v[222:223], v[6:7] op_sel:[0,1,0]
	v_pk_fma_f32 v[8:9], v[166:167], v[224:225], v[8:9] op_sel_hi:[1,0,1]
	v_pk_fma_f32 v[10:11], v[168:169], v[224:225], v[10:11] op_sel_hi:[1,0,1]
	v_pk_fma_f32 v[12:13], v[166:167], v[224:225], v[12:13] op_sel:[0,1,0]
	v_pk_fma_f32 v[14:15], v[168:169], v[224:225], v[14:15] op_sel:[0,1,0]
	v_pk_fma_f32 v[16:17], v[166:167], v[226:227], v[16:17] op_sel_hi:[1,0,1]
	v_pk_fma_f32 v[18:19], v[168:169], v[226:227], v[18:19] op_sel_hi:[1,0,1]
	v_pk_fma_f32 v[20:21], v[166:167], v[226:227], v[20:21] op_sel:[0,1,0]
	v_pk_fma_f32 v[22:23], v[168:169], v[226:227], v[22:23] op_sel:[0,1,0]
	v_pk_fma_f32 v[24:25], v[166:167], v[228:229], v[24:25] op_sel_hi:[1,0,1]
	v_pk_fma_f32 v[26:27], v[168:169], v[228:229], v[26:27] op_sel_hi:[1,0,1]
	v_pk_fma_f32 v[28:29], v[166:167], v[228:229], v[28:29] op_sel:[0,1,0]
	v_pk_fma_f32 v[30:31], v[168:169], v[228:229], v[30:31] op_sel:[0,1,0]
	ds_read_b128 v[222:225], v32 offset:768
	ds_read_b128 v[226:229], v32 offset:784
	s_waitcnt lgkmcnt(2)
	v_pk_mul_f32 v[242:243], v[230:231], v[102:103] op_sel_hi:[0,1]
	v_pk_mul_f32 v[244:245], v[230:231], v[110:111] op_sel_hi:[0,1]
	v_pk_fma_f32 v[242:243], v[86:87], v[166:167], v[242:243]
	v_pk_fma_f32 v[244:245], v[86:87], v[168:169], v[244:245]
	v_pk_fma_f32 v[242:243], v[234:235], v[118:119], v[242:243] op_sel_hi:[0,1,1]
	v_pk_fma_f32 v[244:245], v[234:235], v[126:127], v[244:245] op_sel_hi:[0,1,1]
	v_pk_fma_f32 v[242:243], v[230:231], v[104:105], v[242:243] op_sel:[1,0,0]
	v_pk_fma_f32 v[244:245], v[230:231], v[112:113], v[244:245] op_sel:[1,0,0]
	v_pk_fma_f32 v[242:243], v[234:235], v[120:121], v[242:243] op_sel:[1,0,0]
	v_pk_fma_f32 v[244:245], v[234:235], v[128:129], v[244:245] op_sel:[1,0,0]
	v_pk_fma_f32 v[242:243], v[232:233], v[106:107], v[242:243] op_sel_hi:[0,1,1]
	v_pk_fma_f32 v[244:245], v[232:233], v[114:115], v[244:245] op_sel_hi:[0,1,1]
	v_pk_fma_f32 v[242:243], v[236:237], v[122:123], v[242:243] op_sel_hi:[0,1,1]
	v_pk_fma_f32 v[244:245], v[236:237], v[130:131], v[244:245] op_sel_hi:[0,1,1]
	v_pk_fma_f32 v[242:243], v[232:233], v[108:109], v[242:243] op_sel:[1,0,0]
	v_pk_fma_f32 v[244:245], v[232:233], v[116:117], v[244:245] op_sel:[1,0,0]
	v_pk_fma_f32 v[242:243], v[236:237], v[124:125], v[242:243] op_sel:[1,0,0]
	v_pk_fma_f32 v[244:245], v[236:237], v[132:133], v[244:245] op_sel:[1,0,0]
	ds_read_b128 v[230:233], v32 offset:17152
	ds_read_b128 v[234:237], v32 offset:17168
	global_store_dwordx4 v246, v[242:245], s[100:101] nt
	global_load_dwordx4 v[166:169], v246, s[98:99] nt
	s_add_u32 s100, s100, 0x2000
	s_addc_u32 s101, s101, 0
	s_add_u32 s98, s98, 0x2000
	s_addc_u32 s99, s99, 0
	s_waitcnt vmcnt(21)
	s_waitcnt lgkmcnt(2)
	v_pk_fma_f32 v[0:1], v[170:171], v[222:223], v[0:1] op_sel_hi:[1,0,1]
	v_pk_fma_f32 v[2:3], v[172:173], v[222:223], v[2:3] op_sel_hi:[1,0,1]
	v_pk_fma_f32 v[4:5], v[170:171], v[222:223], v[4:5] op_sel:[0,1,0]
	v_pk_fma_f32 v[6:7], v[172:173], v[222:223], v[6:7] op_sel:[0,1,0]
	v_pk_fma_f32 v[8:9], v[170:171], v[224:225], v[8:9] op_sel_hi:[1,0,1]
	v_pk_fma_f32 v[10:11], v[172:173], v[224:225], v[10:11] op_sel_hi:[1,0,1]
	v_pk_fma_f32 v[12:13], v[170:171], v[224:225], v[12:13] op_sel:[0,1,0]
	v_pk_fma_f32 v[14:15], v[172:173], v[224:225], v[14:15] op_sel:[0,1,0]
	v_pk_fma_f32 v[16:17], v[170:171], v[226:227], v[16:17] op_sel_hi:[1,0,1]
	v_pk_fma_f32 v[18:19], v[172:173], v[226:227], v[18:19] op_sel_hi:[1,0,1]
	v_pk_fma_f32 v[20:21], v[170:171], v[226:227], v[20:21] op_sel:[0,1,0]
	v_pk_fma_f32 v[22:23], v[172:173], v[226:227], v[22:23] op_sel:[0,1,0]
	v_pk_fma_f32 v[24:25], v[170:171], v[228:229], v[24:25] op_sel_hi:[1,0,1]
	v_pk_fma_f32 v[26:27], v[172:173], v[228:229], v[26:27] op_sel_hi:[1,0,1]
	v_pk_fma_f32 v[28:29], v[170:171], v[228:229], v[28:29] op_sel:[0,1,0]
	v_pk_fma_f32 v[30:31], v[172:173], v[228:229], v[30:31] op_sel:[0,1,0]
	ds_read_b128 v[222:225], v32 offset:896
	ds_read_b128 v[226:229], v32 offset:912
	s_waitcnt lgkmcnt(2)
	v_pk_mul_f32 v[238:239], v[230:231], v[102:103] op_sel_hi:[0,1]
	v_pk_mul_f32 v[240:241], v[230:231], v[110:111] op_sel_hi:[0,1]
	v_pk_fma_f32 v[238:239], v[86:87], v[170:171], v[238:239]
	v_pk_fma_f32 v[240:241], v[86:87], v[172:173], v[240:241]
	v_pk_fma_f32 v[238:239], v[234:235], v[118:119], v[238:239] op_sel_hi:[0,1,1]
	v_pk_fma_f32 v[240:241], v[234:235], v[126:127], v[240:241] op_sel_hi:[0,1,1]
	v_pk_fma_f32 v[238:239], v[230:231], v[104:105], v[238:239] op_sel:[1,0,0]
	v_pk_fma_f32 v[240:241], v[230:231], v[112:113], v[240:241] op_sel:[1,0,0]
	v_pk_fma_f32 v[238:239], v[234:235], v[120:121], v[238:239] op_sel:[1,0,0]
	v_pk_fma_f32 v[240:241], v[234:235], v[128:129], v[240:241] op_sel:[1,0,0]
	v_pk_fma_f32 v[238:239], v[232:233], v[106:107], v[238:239] op_sel_hi:[0,1,1]
	v_pk_fma_f32 v[240:241], v[232:233], v[114:115], v[240:241] op_sel_hi:[0,1,1]
	v_pk_fma_f32 v[238:239], v[236:237], v[122:123], v[238:239] op_sel_hi:[0,1,1]
	v_pk_fma_f32 v[240:241], v[236:237], v[130:131], v[240:241] op_sel_hi:[0,1,1]
	v_pk_fma_f32 v[238:239], v[232:233], v[108:109], v[238:239] op_sel:[1,0,0]
	v_pk_fma_f32 v[240:241], v[232:233], v[116:117], v[240:241] op_sel:[1,0,0]
	v_pk_fma_f32 v[238:239], v[236:237], v[124:125], v[238:239] op_sel:[1,0,0]
	v_pk_fma_f32 v[240:241], v[236:237], v[132:133], v[240:241] op_sel:[1,0,0]
	ds_read_b128 v[230:233], v32 offset:17280
	ds_read_b128 v[234:237], v32 offset:17296
	global_store_dwordx4 v246, v[238:241], s[100:101] nt
	global_load_dwordx4 v[170:173], v246, s[98:99] nt
	s_add_u32 s100, s100, 0x2000
	s_addc_u32 s101, s101, 0
	s_add_u32 s98, s98, 0x2000
	s_addc_u32 s99, s99, 0
	s_waitcnt vmcnt(22)
	s_waitcnt lgkmcnt(2)
	v_pk_fma_f32 v[0:1], v[174:175], v[222:223], v[0:1] op_sel_hi:[1,0,1]
	v_pk_fma_f32 v[2:3], v[176:177], v[222:223], v[2:3] op_sel_hi:[1,0,1]
	v_pk_fma_f32 v[4:5], v[174:175], v[222:223], v[4:5] op_sel:[0,1,0]
	v_pk_fma_f32 v[6:7], v[176:177], v[222:223], v[6:7] op_sel:[0,1,0]
	v_pk_fma_f32 v[8:9], v[174:175], v[224:225], v[8:9] op_sel_hi:[1,0,1]
	v_pk_fma_f32 v[10:11], v[176:177], v[224:225], v[10:11] op_sel_hi:[1,0,1]
	v_pk_fma_f32 v[12:13], v[174:175], v[224:225], v[12:13] op_sel:[0,1,0]
	v_pk_fma_f32 v[14:15], v[176:177], v[224:225], v[14:15] op_sel:[0,1,0]
	v_pk_fma_f32 v[16:17], v[174:175], v[226:227], v[16:17] op_sel_hi:[1,0,1]
	v_pk_fma_f32 v[18:19], v[176:177], v[226:227], v[18:19] op_sel_hi:[1,0,1]
	v_pk_fma_f32 v[20:21], v[174:175], v[226:227], v[20:21] op_sel:[0,1,0]
	v_pk_fma_f32 v[22:23], v[176:177], v[226:227], v[22:23] op_sel:[0,1,0]
	v_pk_fma_f32 v[24:25], v[174:175], v[228:229], v[24:25] op_sel_hi:[1,0,1]
	v_pk_fma_f32 v[26:27], v[176:177], v[228:229], v[26:27] op_sel_hi:[1,0,1]
	v_pk_fma_f32 v[28:29], v[174:175], v[228:229], v[28:29] op_sel:[0,1,0]
	v_pk_fma_f32 v[30:31], v[176:177], v[228:229], v[30:31] op_sel:[0,1,0]
	ds_read_b128 v[222:225], v32 offset:1024
	ds_read_b128 v[226:229], v32 offset:1040
	s_waitcnt lgkmcnt(2)
	v_pk_mul_f32 v[242:243], v[230:231], v[102:103] op_sel_hi:[0,1]
	v_pk_mul_f32 v[244:245], v[230:231], v[110:111] op_sel_hi:[0,1]
	v_pk_fma_f32 v[242:243], v[86:87], v[174:175], v[242:243]
	v_pk_fma_f32 v[244:245], v[86:87], v[176:177], v[244:245]
	v_pk_fma_f32 v[242:243], v[234:235], v[118:119], v[242:243] op_sel_hi:[0,1,1]
	v_pk_fma_f32 v[244:245], v[234:235], v[126:127], v[244:245] op_sel_hi:[0,1,1]
	v_pk_fma_f32 v[242:243], v[230:231], v[104:105], v[242:243] op_sel:[1,0,0]
	v_pk_fma_f32 v[244:245], v[230:231], v[112:113], v[244:245] op_sel:[1,0,0]
	v_pk_fma_f32 v[242:243], v[234:235], v[120:121], v[242:243] op_sel:[1,0,0]
	v_pk_fma_f32 v[244:245], v[234:235], v[128:129], v[244:245] op_sel:[1,0,0]
	v_pk_fma_f32 v[242:243], v[232:233], v[106:107], v[242:243] op_sel_hi:[0,1,1]
	v_pk_fma_f32 v[244:245], v[232:233], v[114:115], v[244:245] op_sel_hi:[0,1,1]
	v_pk_fma_f32 v[242:243], v[236:237], v[122:123], v[242:243] op_sel_hi:[0,1,1]
	v_pk_fma_f32 v[244:245], v[236:237], v[130:131], v[244:245] op_sel_hi:[0,1,1]
	v_pk_fma_f32 v[242:243], v[232:233], v[108:109], v[242:243] op_sel:[1,0,0]
	v_pk_fma_f32 v[244:245], v[232:233], v[116:117], v[244:245] op_sel:[1,0,0]
	v_pk_fma_f32 v[242:243], v[236:237], v[124:125], v[242:243] op_sel:[1,0,0]
	v_pk_fma_f32 v[244:245], v[236:237], v[132:133], v[244:245] op_sel:[1,0,0]
	ds_read_b128 v[230:233], v32 offset:17408
	ds_read_b128 v[234:237], v32 offset:17424
	global_store_dwordx4 v246, v[242:245], s[100:101] nt
	global_load_dwordx4 v[174:177], v246, s[98:99] nt
	s_add_u32 s100, s100, 0x2000
	s_addc_u32 s101, s101, 0
	s_add_u32 s98, s98, 0x2000
	s_addc_u32 s99, s99, 0
	s_waitcnt vmcnt(23)
	s_waitcnt lgkmcnt(2)
	v_pk_fma_f32 v[0:1], v[178:179], v[222:223], v[0:1] op_sel_hi:[1,0,1]
	v_pk_fma_f32 v[2:3], v[180:181], v[222:223], v[2:3] op_sel_hi:[1,0,1]
	v_pk_fma_f32 v[4:5], v[178:179], v[222:223], v[4:5] op_sel:[0,1,0]
	v_pk_fma_f32 v[6:7], v[180:181], v[222:223], v[6:7] op_sel:[0,1,0]
	v_pk_fma_f32 v[8:9], v[178:179], v[224:225], v[8:9] op_sel_hi:[1,0,1]
	v_pk_fma_f32 v[10:11], v[180:181], v[224:225], v[10:11] op_sel_hi:[1,0,1]
	v_pk_fma_f32 v[12:13], v[178:179], v[224:225], v[12:13] op_sel:[0,1,0]
	v_pk_fma_f32 v[14:15], v[180:181], v[224:225], v[14:15] op_sel:[0,1,0]
	v_pk_fma_f32 v[16:17], v[178:179], v[226:227], v[16:17] op_sel_hi:[1,0,1]
	v_pk_fma_f32 v[18:19], v[180:181], v[226:227], v[18:19] op_sel_hi:[1,0,1]
	v_pk_fma_f32 v[20:21], v[178:179], v[226:227], v[20:21] op_sel:[0,1,0]
	v_pk_fma_f32 v[22:23], v[180:181], v[226:227], v[22:23] op_sel:[0,1,0]
	v_pk_fma_f32 v[24:25], v[178:179], v[228:229], v[24:25] op_sel_hi:[1,0,1]
	v_pk_fma_f32 v[26:27], v[180:181], v[228:229], v[26:27] op_sel_hi:[1,0,1]
	v_pk_fma_f32 v[28:29], v[178:179], v[228:229], v[28:29] op_sel:[0,1,0]
	v_pk_fma_f32 v[30:31], v[180:181], v[228:229], v[30:31] op_sel:[0,1,0]
	ds_read_b128 v[222:225], v32 offset:1152
	ds_read_b128 v[226:229], v32 offset:1168
	s_waitcnt lgkmcnt(2)
	v_pk_mul_f32 v[238:239], v[230:231], v[102:103] op_sel_hi:[0,1]
	v_pk_mul_f32 v[240:241], v[230:231], v[110:111] op_sel_hi:[0,1]
	v_pk_fma_f32 v[238:239], v[86:87], v[178:179], v[238:239]
	v_pk_fma_f32 v[240:241], v[86:87], v[180:181], v[240:241]
	v_pk_fma_f32 v[238:239], v[234:235], v[118:119], v[238:239] op_sel_hi:[0,1,1]
	v_pk_fma_f32 v[240:241], v[234:235], v[126:127], v[240:241] op_sel_hi:[0,1,1]
	v_pk_fma_f32 v[238:239], v[230:231], v[104:105], v[238:239] op_sel:[1,0,0]
	v_pk_fma_f32 v[240:241], v[230:231], v[112:113], v[240:241] op_sel:[1,0,0]
	v_pk_fma_f32 v[238:239], v[234:235], v[120:121], v[238:239] op_sel:[1,0,0]
	v_pk_fma_f32 v[240:241], v[234:235], v[128:129], v[240:241] op_sel:[1,0,0]
	v_pk_fma_f32 v[238:239], v[232:233], v[106:107], v[238:239] op_sel_hi:[0,1,1]
	v_pk_fma_f32 v[240:241], v[232:233], v[114:115], v[240:241] op_sel_hi:[0,1,1]
	v_pk_fma_f32 v[238:239], v[236:237], v[122:123], v[238:239] op_sel_hi:[0,1,1]
	v_pk_fma_f32 v[240:241], v[236:237], v[130:131], v[240:241] op_sel_hi:[0,1,1]
	v_pk_fma_f32 v[238:239], v[232:233], v[108:109], v[238:239] op_sel:[1,0,0]
	v_pk_fma_f32 v[240:241], v[232:233], v[116:117], v[240:241] op_sel:[1,0,0]
	v_pk_fma_f32 v[238:239], v[236:237], v[124:125], v[238:239] op_sel:[1,0,0]
	v_pk_fma_f32 v[240:241], v[236:237], v[132:133], v[240:241] op_sel:[1,0,0]
	ds_read_b128 v[230:233], v32 offset:17536
	ds_read_b128 v[234:237], v32 offset:17552
	global_store_dwordx4 v246, v[238:241], s[100:101] nt
	global_load_dwordx4 v[178:181], v246, s[98:99] nt
	s_add_u32 s100, s100, 0x2000
	s_addc_u32 s101, s101, 0
	s_add_u32 s98, s98, 0x2000
	s_addc_u32 s99, s99, 0
	s_waitcnt vmcnt(24)
	s_waitcnt lgkmcnt(2)
	v_pk_fma_f32 v[0:1], v[182:183], v[222:223], v[0:1] op_sel_hi:[1,0,1]
	v_pk_fma_f32 v[2:3], v[184:185], v[222:223], v[2:3] op_sel_hi:[1,0,1]
	v_pk_fma_f32 v[4:5], v[182:183], v[222:223], v[4:5] op_sel:[0,1,0]
	v_pk_fma_f32 v[6:7], v[184:185], v[222:223], v[6:7] op_sel:[0,1,0]
	v_pk_fma_f32 v[8:9], v[182:183], v[224:225], v[8:9] op_sel_hi:[1,0,1]
	v_pk_fma_f32 v[10:11], v[184:185], v[224:225], v[10:11] op_sel_hi:[1,0,1]
	v_pk_fma_f32 v[12:13], v[182:183], v[224:225], v[12:13] op_sel:[0,1,0]
	v_pk_fma_f32 v[14:15], v[184:185], v[224:225], v[14:15] op_sel:[0,1,0]
	v_pk_fma_f32 v[16:17], v[182:183], v[226:227], v[16:17] op_sel_hi:[1,0,1]
	v_pk_fma_f32 v[18:19], v[184:185], v[226:227], v[18:19] op_sel_hi:[1,0,1]
	v_pk_fma_f32 v[20:21], v[182:183], v[226:227], v[20:21] op_sel:[0,1,0]
	v_pk_fma_f32 v[22:23], v[184:185], v[226:227], v[22:23] op_sel:[0,1,0]
	v_pk_fma_f32 v[24:25], v[182:183], v[228:229], v[24:25] op_sel_hi:[1,0,1]
	v_pk_fma_f32 v[26:27], v[184:185], v[228:229], v[26:27] op_sel_hi:[1,0,1]
	v_pk_fma_f32 v[28:29], v[182:183], v[228:229], v[28:29] op_sel:[0,1,0]
	v_pk_fma_f32 v[30:31], v[184:185], v[228:229], v[30:31] op_sel:[0,1,0]
	ds_read_b128 v[222:225], v32 offset:1280
	ds_read_b128 v[226:229], v32 offset:1296
	s_waitcnt lgkmcnt(2)
	v_pk_mul_f32 v[242:243], v[230:231], v[102:103] op_sel_hi:[0,1]
	v_pk_mul_f32 v[244:245], v[230:231], v[110:111] op_sel_hi:[0,1]
	v_pk_fma_f32 v[242:243], v[86:87], v[182:183], v[242:243]
	v_pk_fma_f32 v[244:245], v[86:87], v[184:185], v[244:245]
	v_pk_fma_f32 v[242:243], v[234:235], v[118:119], v[242:243] op_sel_hi:[0,1,1]
	v_pk_fma_f32 v[244:245], v[234:235], v[126:127], v[244:245] op_sel_hi:[0,1,1]
	v_pk_fma_f32 v[242:243], v[230:231], v[104:105], v[242:243] op_sel:[1,0,0]
	v_pk_fma_f32 v[244:245], v[230:231], v[112:113], v[244:245] op_sel:[1,0,0]
	v_pk_fma_f32 v[242:243], v[234:235], v[120:121], v[242:243] op_sel:[1,0,0]
	v_pk_fma_f32 v[244:245], v[234:235], v[128:129], v[244:245] op_sel:[1,0,0]
	v_pk_fma_f32 v[242:243], v[232:233], v[106:107], v[242:243] op_sel_hi:[0,1,1]
	v_pk_fma_f32 v[244:245], v[232:233], v[114:115], v[244:245] op_sel_hi:[0,1,1]
	v_pk_fma_f32 v[242:243], v[236:237], v[122:123], v[242:243] op_sel_hi:[0,1,1]
	v_pk_fma_f32 v[244:245], v[236:237], v[130:131], v[244:245] op_sel_hi:[0,1,1]
	v_pk_fma_f32 v[242:243], v[232:233], v[108:109], v[242:243] op_sel:[1,0,0]
	v_pk_fma_f32 v[244:245], v[232:233], v[116:117], v[244:245] op_sel:[1,0,0]
	v_pk_fma_f32 v[242:243], v[236:237], v[124:125], v[242:243] op_sel:[1,0,0]
	v_pk_fma_f32 v[244:245], v[236:237], v[132:133], v[244:245] op_sel:[1,0,0]
	ds_read_b128 v[230:233], v32 offset:17664
	ds_read_b128 v[234:237], v32 offset:17680
	global_store_dwordx4 v246, v[242:245], s[100:101] nt
	global_load_dwordx4 v[182:185], v246, s[98:99] nt
	s_add_u32 s100, s100, 0x2000
	s_addc_u32 s101, s101, 0
	s_add_u32 s98, s98, 0x2000
	s_addc_u32 s99, s99, 0
	s_waitcnt vmcnt(25)
	s_waitcnt lgkmcnt(2)
	v_pk_fma_f32 v[0:1], v[186:187], v[222:223], v[0:1] op_sel_hi:[1,0,1]
	v_pk_fma_f32 v[2:3], v[188:189], v[222:223], v[2:3] op_sel_hi:[1,0,1]
	v_pk_fma_f32 v[4:5], v[186:187], v[222:223], v[4:5] op_sel:[0,1,0]
	v_pk_fma_f32 v[6:7], v[188:189], v[222:223], v[6:7] op_sel:[0,1,0]
	v_pk_fma_f32 v[8:9], v[186:187], v[224:225], v[8:9] op_sel_hi:[1,0,1]
	v_pk_fma_f32 v[10:11], v[188:189], v[224:225], v[10:11] op_sel_hi:[1,0,1]
	v_pk_fma_f32 v[12:13], v[186:187], v[224:225], v[12:13] op_sel:[0,1,0]
	v_pk_fma_f32 v[14:15], v[188:189], v[224:225], v[14:15] op_sel:[0,1,0]
	v_pk_fma_f32 v[16:17], v[186:187], v[226:227], v[16:17] op_sel_hi:[1,0,1]
	v_pk_fma_f32 v[18:19], v[188:189], v[226:227], v[18:19] op_sel_hi:[1,0,1]
	v_pk_fma_f32 v[20:21], v[186:187], v[226:227], v[20:21] op_sel:[0,1,0]
	v_pk_fma_f32 v[22:23], v[188:189], v[226:227], v[22:23] op_sel:[0,1,0]
	v_pk_fma_f32 v[24:25], v[186:187], v[228:229], v[24:25] op_sel_hi:[1,0,1]
	v_pk_fma_f32 v[26:27], v[188:189], v[228:229], v[26:27] op_sel_hi:[1,0,1]
	v_pk_fma_f32 v[28:29], v[186:187], v[228:229], v[28:29] op_sel:[0,1,0]
	v_pk_fma_f32 v[30:31], v[188:189], v[228:229], v[30:31] op_sel:[0,1,0]
	ds_read_b128 v[222:225], v32 offset:1408
	ds_read_b128 v[226:229], v32 offset:1424
	s_waitcnt lgkmcnt(2)
	v_pk_mul_f32 v[238:239], v[230:231], v[102:103] op_sel_hi:[0,1]
	v_pk_mul_f32 v[240:241], v[230:231], v[110:111] op_sel_hi:[0,1]
	v_pk_fma_f32 v[238:239], v[86:87], v[186:187], v[238:239]
	v_pk_fma_f32 v[240:241], v[86:87], v[188:189], v[240:241]
	v_pk_fma_f32 v[238:239], v[234:235], v[118:119], v[238:239] op_sel_hi:[0,1,1]
	v_pk_fma_f32 v[240:241], v[234:235], v[126:127], v[240:241] op_sel_hi:[0,1,1]
	v_pk_fma_f32 v[238:239], v[230:231], v[104:105], v[238:239] op_sel:[1,0,0]
	v_pk_fma_f32 v[240:241], v[230:231], v[112:113], v[240:241] op_sel:[1,0,0]
	v_pk_fma_f32 v[238:239], v[234:235], v[120:121], v[238:239] op_sel:[1,0,0]
	v_pk_fma_f32 v[240:241], v[234:235], v[128:129], v[240:241] op_sel:[1,0,0]
	v_pk_fma_f32 v[238:239], v[232:233], v[106:107], v[238:239] op_sel_hi:[0,1,1]
	v_pk_fma_f32 v[240:241], v[232:233], v[114:115], v[240:241] op_sel_hi:[0,1,1]
	v_pk_fma_f32 v[238:239], v[236:237], v[122:123], v[238:239] op_sel_hi:[0,1,1]
	v_pk_fma_f32 v[240:241], v[236:237], v[130:131], v[240:241] op_sel_hi:[0,1,1]
	v_pk_fma_f32 v[238:239], v[232:233], v[108:109], v[238:239] op_sel:[1,0,0]
	v_pk_fma_f32 v[240:241], v[232:233], v[116:117], v[240:241] op_sel:[1,0,0]
	v_pk_fma_f32 v[238:239], v[236:237], v[124:125], v[238:239] op_sel:[1,0,0]
	v_pk_fma_f32 v[240:241], v[236:237], v[132:133], v[240:241] op_sel:[1,0,0]
	ds_read_b128 v[230:233], v32 offset:17792
	ds_read_b128 v[234:237], v32 offset:17808
	global_store_dwordx4 v246, v[238:241], s[100:101] nt
	global_load_dwordx4 v[186:189], v246, s[98:99] nt
	s_add_u32 s100, s100, 0x2000
	s_addc_u32 s101, s101, 0
	s_add_u32 s98, s98, 0x2000
	s_addc_u32 s99, s99, 0
	s_waitcnt vmcnt(26)
	s_waitcnt lgkmcnt(2)
	v_pk_fma_f32 v[0:1], v[190:191], v[222:223], v[0:1] op_sel_hi:[1,0,1]
	v_pk_fma_f32 v[2:3], v[192:193], v[222:223], v[2:3] op_sel_hi:[1,0,1]
	v_pk_fma_f32 v[4:5], v[190:191], v[222:223], v[4:5] op_sel:[0,1,0]
	v_pk_fma_f32 v[6:7], v[192:193], v[222:223], v[6:7] op_sel:[0,1,0]
	v_pk_fma_f32 v[8:9], v[190:191], v[224:225], v[8:9] op_sel_hi:[1,0,1]
	v_pk_fma_f32 v[10:11], v[192:193], v[224:225], v[10:11] op_sel_hi:[1,0,1]
	v_pk_fma_f32 v[12:13], v[190:191], v[224:225], v[12:13] op_sel:[0,1,0]
	v_pk_fma_f32 v[14:15], v[192:193], v[224:225], v[14:15] op_sel:[0,1,0]
	v_pk_fma_f32 v[16:17], v[190:191], v[226:227], v[16:17] op_sel_hi:[1,0,1]
	v_pk_fma_f32 v[18:19], v[192:193], v[226:227], v[18:19] op_sel_hi:[1,0,1]
	v_pk_fma_f32 v[20:21], v[190:191], v[226:227], v[20:21] op_sel:[0,1,0]
	v_pk_fma_f32 v[22:23], v[192:193], v[226:227], v[22:23] op_sel:[0,1,0]
	v_pk_fma_f32 v[24:25], v[190:191], v[228:229], v[24:25] op_sel_hi:[1,0,1]
	v_pk_fma_f32 v[26:27], v[192:193], v[228:229], v[26:27] op_sel_hi:[1,0,1]
	v_pk_fma_f32 v[28:29], v[190:191], v[228:229], v[28:29] op_sel:[0,1,0]
	v_pk_fma_f32 v[30:31], v[192:193], v[228:229], v[30:31] op_sel:[0,1,0]
	ds_read_b128 v[222:225], v32 offset:1536
	ds_read_b128 v[226:229], v32 offset:1552
	s_waitcnt lgkmcnt(2)
	v_pk_mul_f32 v[242:243], v[230:231], v[102:103] op_sel_hi:[0,1]
	v_pk_mul_f32 v[244:245], v[230:231], v[110:111] op_sel_hi:[0,1]
	v_pk_fma_f32 v[242:243], v[86:87], v[190:191], v[242:243]
	v_pk_fma_f32 v[244:245], v[86:87], v[192:193], v[244:245]
	v_pk_fma_f32 v[242:243], v[234:235], v[118:119], v[242:243] op_sel_hi:[0,1,1]
	v_pk_fma_f32 v[244:245], v[234:235], v[126:127], v[244:245] op_sel_hi:[0,1,1]
	v_pk_fma_f32 v[242:243], v[230:231], v[104:105], v[242:243] op_sel:[1,0,0]
	v_pk_fma_f32 v[244:245], v[230:231], v[112:113], v[244:245] op_sel:[1,0,0]
	v_pk_fma_f32 v[242:243], v[234:235], v[120:121], v[242:243] op_sel:[1,0,0]
	v_pk_fma_f32 v[244:245], v[234:235], v[128:129], v[244:245] op_sel:[1,0,0]
	v_pk_fma_f32 v[242:243], v[232:233], v[106:107], v[242:243] op_sel_hi:[0,1,1]
	v_pk_fma_f32 v[244:245], v[232:233], v[114:115], v[244:245] op_sel_hi:[0,1,1]
	v_pk_fma_f32 v[242:243], v[236:237], v[122:123], v[242:243] op_sel_hi:[0,1,1]
	v_pk_fma_f32 v[244:245], v[236:237], v[130:131], v[244:245] op_sel_hi:[0,1,1]
	v_pk_fma_f32 v[242:243], v[232:233], v[108:109], v[242:243] op_sel:[1,0,0]
	v_pk_fma_f32 v[244:245], v[232:233], v[116:117], v[244:245] op_sel:[1,0,0]
	v_pk_fma_f32 v[242:243], v[236:237], v[124:125], v[242:243] op_sel:[1,0,0]
	v_pk_fma_f32 v[244:245], v[236:237], v[132:133], v[244:245] op_sel:[1,0,0]
	ds_read_b128 v[230:233], v32 offset:17920
	ds_read_b128 v[234:237], v32 offset:17936
	global_store_dwordx4 v246, v[242:245], s[100:101] nt
	global_load_dwordx4 v[190:193], v246, s[98:99] nt
	s_add_u32 s100, s100, 0x2000
	s_addc_u32 s101, s101, 0
	s_add_u32 s98, s98, 0x2000
	s_addc_u32 s99, s99, 0
	s_waitcnt vmcnt(27)
	s_waitcnt lgkmcnt(2)
	v_pk_fma_f32 v[0:1], v[194:195], v[222:223], v[0:1] op_sel_hi:[1,0,1]
	v_pk_fma_f32 v[2:3], v[196:197], v[222:223], v[2:3] op_sel_hi:[1,0,1]
	v_pk_fma_f32 v[4:5], v[194:195], v[222:223], v[4:5] op_sel:[0,1,0]
	v_pk_fma_f32 v[6:7], v[196:197], v[222:223], v[6:7] op_sel:[0,1,0]
	v_pk_fma_f32 v[8:9], v[194:195], v[224:225], v[8:9] op_sel_hi:[1,0,1]
	v_pk_fma_f32 v[10:11], v[196:197], v[224:225], v[10:11] op_sel_hi:[1,0,1]
	v_pk_fma_f32 v[12:13], v[194:195], v[224:225], v[12:13] op_sel:[0,1,0]
	v_pk_fma_f32 v[14:15], v[196:197], v[224:225], v[14:15] op_sel:[0,1,0]
	v_pk_fma_f32 v[16:17], v[194:195], v[226:227], v[16:17] op_sel_hi:[1,0,1]
	v_pk_fma_f32 v[18:19], v[196:197], v[226:227], v[18:19] op_sel_hi:[1,0,1]
	v_pk_fma_f32 v[20:21], v[194:195], v[226:227], v[20:21] op_sel:[0,1,0]
	v_pk_fma_f32 v[22:23], v[196:197], v[226:227], v[22:23] op_sel:[0,1,0]
	v_pk_fma_f32 v[24:25], v[194:195], v[228:229], v[24:25] op_sel_hi:[1,0,1]
	v_pk_fma_f32 v[26:27], v[196:197], v[228:229], v[26:27] op_sel_hi:[1,0,1]
	v_pk_fma_f32 v[28:29], v[194:195], v[228:229], v[28:29] op_sel:[0,1,0]
	v_pk_fma_f32 v[30:31], v[196:197], v[228:229], v[30:31] op_sel:[0,1,0]
	ds_read_b128 v[222:225], v32 offset:1664
	ds_read_b128 v[226:229], v32 offset:1680
	s_waitcnt lgkmcnt(2)
	v_pk_mul_f32 v[238:239], v[230:231], v[102:103] op_sel_hi:[0,1]
	v_pk_mul_f32 v[240:241], v[230:231], v[110:111] op_sel_hi:[0,1]
	v_pk_fma_f32 v[238:239], v[86:87], v[194:195], v[238:239]
	v_pk_fma_f32 v[240:241], v[86:87], v[196:197], v[240:241]
	v_pk_fma_f32 v[238:239], v[234:235], v[118:119], v[238:239] op_sel_hi:[0,1,1]
	v_pk_fma_f32 v[240:241], v[234:235], v[126:127], v[240:241] op_sel_hi:[0,1,1]
	v_pk_fma_f32 v[238:239], v[230:231], v[104:105], v[238:239] op_sel:[1,0,0]
	v_pk_fma_f32 v[240:241], v[230:231], v[112:113], v[240:241] op_sel:[1,0,0]
	v_pk_fma_f32 v[238:239], v[234:235], v[120:121], v[238:239] op_sel:[1,0,0]
	v_pk_fma_f32 v[240:241], v[234:235], v[128:129], v[240:241] op_sel:[1,0,0]
	v_pk_fma_f32 v[238:239], v[232:233], v[106:107], v[238:239] op_sel_hi:[0,1,1]
	v_pk_fma_f32 v[240:241], v[232:233], v[114:115], v[240:241] op_sel_hi:[0,1,1]
	v_pk_fma_f32 v[238:239], v[236:237], v[122:123], v[238:239] op_sel_hi:[0,1,1]
	v_pk_fma_f32 v[240:241], v[236:237], v[130:131], v[240:241] op_sel_hi:[0,1,1]
	v_pk_fma_f32 v[238:239], v[232:233], v[108:109], v[238:239] op_sel:[1,0,0]
	v_pk_fma_f32 v[240:241], v[232:233], v[116:117], v[240:241] op_sel:[1,0,0]
	v_pk_fma_f32 v[238:239], v[236:237], v[124:125], v[238:239] op_sel:[1,0,0]
	v_pk_fma_f32 v[240:241], v[236:237], v[132:133], v[240:241] op_sel:[1,0,0]
	ds_read_b128 v[230:233], v32 offset:18048
	ds_read_b128 v[234:237], v32 offset:18064
	global_store_dwordx4 v246, v[238:241], s[100:101] nt
	global_load_dwordx4 v[194:197], v246, s[98:99] nt
	s_add_u32 s100, s100, 0x2000
	s_addc_u32 s101, s101, 0
	s_add_u32 s98, s98, 0x2000
	s_addc_u32 s99, s99, 0
	s_waitcnt vmcnt(28)
	s_waitcnt lgkmcnt(2)
	v_pk_fma_f32 v[0:1], v[210:211], v[222:223], v[0:1] op_sel_hi:[1,0,1]
	v_pk_fma_f32 v[2:3], v[212:213], v[222:223], v[2:3] op_sel_hi:[1,0,1]
	v_pk_fma_f32 v[4:5], v[210:211], v[222:223], v[4:5] op_sel:[0,1,0]
	v_pk_fma_f32 v[6:7], v[212:213], v[222:223], v[6:7] op_sel:[0,1,0]
	v_pk_fma_f32 v[8:9], v[210:211], v[224:225], v[8:9] op_sel_hi:[1,0,1]
	v_pk_fma_f32 v[10:11], v[212:213], v[224:225], v[10:11] op_sel_hi:[1,0,1]
	v_pk_fma_f32 v[12:13], v[210:211], v[224:225], v[12:13] op_sel:[0,1,0]
	v_pk_fma_f32 v[14:15], v[212:213], v[224:225], v[14:15] op_sel:[0,1,0]
	v_pk_fma_f32 v[16:17], v[210:211], v[226:227], v[16:17] op_sel_hi:[1,0,1]
	v_pk_fma_f32 v[18:19], v[212:213], v[226:227], v[18:19] op_sel_hi:[1,0,1]
	v_pk_fma_f32 v[20:21], v[210:211], v[226:227], v[20:21] op_sel:[0,1,0]
	v_pk_fma_f32 v[22:23], v[212:213], v[226:227], v[22:23] op_sel:[0,1,0]
	v_pk_fma_f32 v[24:25], v[210:211], v[228:229], v[24:25] op_sel_hi:[1,0,1]
	v_pk_fma_f32 v[26:27], v[212:213], v[228:229], v[26:27] op_sel_hi:[1,0,1]
	v_pk_fma_f32 v[28:29], v[210:211], v[228:229], v[28:29] op_sel:[0,1,0]
	v_pk_fma_f32 v[30:31], v[212:213], v[228:229], v[30:31] op_sel:[0,1,0]
	ds_read_b128 v[222:225], v32 offset:1792
	ds_read_b128 v[226:229], v32 offset:1808
	s_waitcnt lgkmcnt(2)
	v_pk_mul_f32 v[242:243], v[230:231], v[102:103] op_sel_hi:[0,1]
	v_pk_mul_f32 v[244:245], v[230:231], v[110:111] op_sel_hi:[0,1]
	v_pk_fma_f32 v[242:243], v[86:87], v[210:211], v[242:243]
	v_pk_fma_f32 v[244:245], v[86:87], v[212:213], v[244:245]
	v_pk_fma_f32 v[242:243], v[234:235], v[118:119], v[242:243] op_sel_hi:[0,1,1]
	v_pk_fma_f32 v[244:245], v[234:235], v[126:127], v[244:245] op_sel_hi:[0,1,1]
	v_pk_fma_f32 v[242:243], v[230:231], v[104:105], v[242:243] op_sel:[1,0,0]
	v_pk_fma_f32 v[244:245], v[230:231], v[112:113], v[244:245] op_sel:[1,0,0]
	v_pk_fma_f32 v[242:243], v[234:235], v[120:121], v[242:243] op_sel:[1,0,0]
	v_pk_fma_f32 v[244:245], v[234:235], v[128:129], v[244:245] op_sel:[1,0,0]
	v_pk_fma_f32 v[242:243], v[232:233], v[106:107], v[242:243] op_sel_hi:[0,1,1]
	v_pk_fma_f32 v[244:245], v[232:233], v[114:115], v[244:245] op_sel_hi:[0,1,1]
	v_pk_fma_f32 v[242:243], v[236:237], v[122:123], v[242:243] op_sel_hi:[0,1,1]
	v_pk_fma_f32 v[244:245], v[236:237], v[130:131], v[244:245] op_sel_hi:[0,1,1]
	v_pk_fma_f32 v[242:243], v[232:233], v[108:109], v[242:243] op_sel:[1,0,0]
	v_pk_fma_f32 v[244:245], v[232:233], v[116:117], v[244:245] op_sel:[1,0,0]
	v_pk_fma_f32 v[242:243], v[236:237], v[124:125], v[242:243] op_sel:[1,0,0]
	v_pk_fma_f32 v[244:245], v[236:237], v[132:133], v[244:245] op_sel:[1,0,0]
	ds_read_b128 v[230:233], v32 offset:18176
	ds_read_b128 v[234:237], v32 offset:18192
	global_store_dwordx4 v246, v[242:245], s[100:101] nt
	global_load_dwordx4 v[210:213], v246, s[98:99] nt
	s_add_u32 s100, s100, 0x2000
	s_addc_u32 s101, s101, 0
	s_add_u32 s98, s98, 0x2000
	s_addc_u32 s99, s99, 0
	s_waitcnt vmcnt(29)
	s_waitcnt lgkmcnt(2)
	v_pk_fma_f32 v[0:1], v[214:215], v[222:223], v[0:1] op_sel_hi:[1,0,1]
	v_pk_fma_f32 v[2:3], v[216:217], v[222:223], v[2:3] op_sel_hi:[1,0,1]
	v_pk_fma_f32 v[4:5], v[214:215], v[222:223], v[4:5] op_sel:[0,1,0]
	v_pk_fma_f32 v[6:7], v[216:217], v[222:223], v[6:7] op_sel:[0,1,0]
	v_pk_fma_f32 v[8:9], v[214:215], v[224:225], v[8:9] op_sel_hi:[1,0,1]
	v_pk_fma_f32 v[10:11], v[216:217], v[224:225], v[10:11] op_sel_hi:[1,0,1]
	v_pk_fma_f32 v[12:13], v[214:215], v[224:225], v[12:13] op_sel:[0,1,0]
	v_pk_fma_f32 v[14:15], v[216:217], v[224:225], v[14:15] op_sel:[0,1,0]
	v_pk_fma_f32 v[16:17], v[214:215], v[226:227], v[16:17] op_sel_hi:[1,0,1]
	v_pk_fma_f32 v[18:19], v[216:217], v[226:227], v[18:19] op_sel_hi:[1,0,1]
	v_pk_fma_f32 v[20:21], v[214:215], v[226:227], v[20:21] op_sel:[0,1,0]
	v_pk_fma_f32 v[22:23], v[216:217], v[226:227], v[22:23] op_sel:[0,1,0]
	v_pk_fma_f32 v[24:25], v[214:215], v[228:229], v[24:25] op_sel_hi:[1,0,1]
	v_pk_fma_f32 v[26:27], v[216:217], v[228:229], v[26:27] op_sel_hi:[1,0,1]
	v_pk_fma_f32 v[28:29], v[214:215], v[228:229], v[28:29] op_sel:[0,1,0]
	v_pk_fma_f32 v[30:31], v[216:217], v[228:229], v[30:31] op_sel:[0,1,0]
	ds_read_b128 v[222:225], v32 offset:1920
	ds_read_b128 v[226:229], v32 offset:1936
	s_waitcnt lgkmcnt(2)
	v_pk_mul_f32 v[238:239], v[230:231], v[102:103] op_sel_hi:[0,1]
	v_pk_mul_f32 v[240:241], v[230:231], v[110:111] op_sel_hi:[0,1]
	v_pk_fma_f32 v[238:239], v[86:87], v[214:215], v[238:239]
	v_pk_fma_f32 v[240:241], v[86:87], v[216:217], v[240:241]
	v_pk_fma_f32 v[238:239], v[234:235], v[118:119], v[238:239] op_sel_hi:[0,1,1]
	v_pk_fma_f32 v[240:241], v[234:235], v[126:127], v[240:241] op_sel_hi:[0,1,1]
	v_pk_fma_f32 v[238:239], v[230:231], v[104:105], v[238:239] op_sel:[1,0,0]
	v_pk_fma_f32 v[240:241], v[230:231], v[112:113], v[240:241] op_sel:[1,0,0]
	v_pk_fma_f32 v[238:239], v[234:235], v[120:121], v[238:239] op_sel:[1,0,0]
	v_pk_fma_f32 v[240:241], v[234:235], v[128:129], v[240:241] op_sel:[1,0,0]
	v_pk_fma_f32 v[238:239], v[232:233], v[106:107], v[238:239] op_sel_hi:[0,1,1]
	v_pk_fma_f32 v[240:241], v[232:233], v[114:115], v[240:241] op_sel_hi:[0,1,1]
	v_pk_fma_f32 v[238:239], v[236:237], v[122:123], v[238:239] op_sel_hi:[0,1,1]
	v_pk_fma_f32 v[240:241], v[236:237], v[130:131], v[240:241] op_sel_hi:[0,1,1]
	v_pk_fma_f32 v[238:239], v[232:233], v[108:109], v[238:239] op_sel:[1,0,0]
	v_pk_fma_f32 v[240:241], v[232:233], v[116:117], v[240:241] op_sel:[1,0,0]
	v_pk_fma_f32 v[238:239], v[236:237], v[124:125], v[238:239] op_sel:[1,0,0]
	v_pk_fma_f32 v[240:241], v[236:237], v[132:133], v[240:241] op_sel:[1,0,0]
	ds_read_b128 v[230:233], v32 offset:18304
	ds_read_b128 v[234:237], v32 offset:18320
	global_store_dwordx4 v246, v[238:241], s[100:101] nt
	global_load_dwordx4 v[214:217], v246, s[98:99] nt
	s_add_u32 s100, s100, 0x2000
	s_addc_u32 s101, s101, 0
	s_add_u32 s98, s98, 0x2000
	s_addc_u32 s99, s99, 0
	s_waitcnt vmcnt(30)
	s_waitcnt lgkmcnt(2)
	v_pk_fma_f32 v[0:1], v[218:219], v[222:223], v[0:1] op_sel_hi:[1,0,1]
	v_pk_fma_f32 v[2:3], v[220:221], v[222:223], v[2:3] op_sel_hi:[1,0,1]
	v_pk_fma_f32 v[4:5], v[218:219], v[222:223], v[4:5] op_sel:[0,1,0]
	v_pk_fma_f32 v[6:7], v[220:221], v[222:223], v[6:7] op_sel:[0,1,0]
	v_pk_fma_f32 v[8:9], v[218:219], v[224:225], v[8:9] op_sel_hi:[1,0,1]
	v_pk_fma_f32 v[10:11], v[220:221], v[224:225], v[10:11] op_sel_hi:[1,0,1]
	v_pk_fma_f32 v[12:13], v[218:219], v[224:225], v[12:13] op_sel:[0,1,0]
	v_pk_fma_f32 v[14:15], v[220:221], v[224:225], v[14:15] op_sel:[0,1,0]
	v_pk_fma_f32 v[16:17], v[218:219], v[226:227], v[16:17] op_sel_hi:[1,0,1]
	v_pk_fma_f32 v[18:19], v[220:221], v[226:227], v[18:19] op_sel_hi:[1,0,1]
	v_pk_fma_f32 v[20:21], v[218:219], v[226:227], v[20:21] op_sel:[0,1,0]
	v_pk_fma_f32 v[22:23], v[220:221], v[226:227], v[22:23] op_sel:[0,1,0]
	v_pk_fma_f32 v[24:25], v[218:219], v[228:229], v[24:25] op_sel_hi:[1,0,1]
	v_pk_fma_f32 v[26:27], v[220:221], v[228:229], v[26:27] op_sel_hi:[1,0,1]
	v_pk_fma_f32 v[28:29], v[218:219], v[228:229], v[28:29] op_sel:[0,1,0]
	v_pk_fma_f32 v[30:31], v[220:221], v[228:229], v[30:31] op_sel:[0,1,0]
	ds_read_b128 v[222:225], v32 offset:2048
	ds_read_b128 v[226:229], v32 offset:2064
	s_waitcnt lgkmcnt(2)
	v_pk_mul_f32 v[242:243], v[230:231], v[102:103] op_sel_hi:[0,1]
	v_pk_mul_f32 v[244:245], v[230:231], v[110:111] op_sel_hi:[0,1]
	v_pk_fma_f32 v[242:243], v[86:87], v[218:219], v[242:243]
	v_pk_fma_f32 v[244:245], v[86:87], v[220:221], v[244:245]
	v_pk_fma_f32 v[242:243], v[234:235], v[118:119], v[242:243] op_sel_hi:[0,1,1]
	v_pk_fma_f32 v[244:245], v[234:235], v[126:127], v[244:245] op_sel_hi:[0,1,1]
	v_pk_fma_f32 v[242:243], v[230:231], v[104:105], v[242:243] op_sel:[1,0,0]
	v_pk_fma_f32 v[244:245], v[230:231], v[112:113], v[244:245] op_sel:[1,0,0]
	v_pk_fma_f32 v[242:243], v[234:235], v[120:121], v[242:243] op_sel:[1,0,0]
	v_pk_fma_f32 v[244:245], v[234:235], v[128:129], v[244:245] op_sel:[1,0,0]
	v_pk_fma_f32 v[242:243], v[232:233], v[106:107], v[242:243] op_sel_hi:[0,1,1]
	v_pk_fma_f32 v[244:245], v[232:233], v[114:115], v[244:245] op_sel_hi:[0,1,1]
	v_pk_fma_f32 v[242:243], v[236:237], v[122:123], v[242:243] op_sel_hi:[0,1,1]
	v_pk_fma_f32 v[244:245], v[236:237], v[130:131], v[244:245] op_sel_hi:[0,1,1]
	v_pk_fma_f32 v[242:243], v[232:233], v[108:109], v[242:243] op_sel:[1,0,0]
	v_pk_fma_f32 v[244:245], v[232:233], v[116:117], v[244:245] op_sel:[1,0,0]
	v_pk_fma_f32 v[242:243], v[236:237], v[124:125], v[242:243] op_sel:[1,0,0]
	v_pk_fma_f32 v[244:245], v[236:237], v[132:133], v[244:245] op_sel:[1,0,0]
	ds_read_b128 v[230:233], v32 offset:18432
	ds_read_b128 v[234:237], v32 offset:18448
	global_store_dwordx4 v246, v[242:245], s[100:101] nt
	global_load_dwordx4 v[218:221], v246, s[98:99] nt
	s_add_u32 s100, s100, 0x2000
	s_addc_u32 s101, s101, 0
	s_add_u32 s98, s98, 0x2000
	s_addc_u32 s99, s99, 0
	v_add_u32_e32 v32, 0x800, v32
.Lsstream_b_loop:
	s_waitcnt vmcnt(30)
	s_waitcnt lgkmcnt(2)
	v_pk_fma_f32 v[0:1], v[134:135], v[222:223], v[0:1] op_sel_hi:[1,0,1]
	v_pk_fma_f32 v[2:3], v[136:137], v[222:223], v[2:3] op_sel_hi:[1,0,1]
	v_pk_fma_f32 v[4:5], v[134:135], v[222:223], v[4:5] op_sel:[0,1,0]
	v_pk_fma_f32 v[6:7], v[136:137], v[222:223], v[6:7] op_sel:[0,1,0]
	v_pk_fma_f32 v[8:9], v[134:135], v[224:225], v[8:9] op_sel_hi:[1,0,1]
	v_pk_fma_f32 v[10:11], v[136:137], v[224:225], v[10:11] op_sel_hi:[1,0,1]
	v_pk_fma_f32 v[12:13], v[134:135], v[224:225], v[12:13] op_sel:[0,1,0]
	v_pk_fma_f32 v[14:15], v[136:137], v[224:225], v[14:15] op_sel:[0,1,0]
	v_pk_fma_f32 v[16:17], v[134:135], v[226:227], v[16:17] op_sel_hi:[1,0,1]
	v_pk_fma_f32 v[18:19], v[136:137], v[226:227], v[18:19] op_sel_hi:[1,0,1]
	v_pk_fma_f32 v[20:21], v[134:135], v[226:227], v[20:21] op_sel:[0,1,0]
	v_pk_fma_f32 v[22:23], v[136:137], v[226:227], v[22:23] op_sel:[0,1,0]
	v_pk_fma_f32 v[24:25], v[134:135], v[228:229], v[24:25] op_sel_hi:[1,0,1]
	v_pk_fma_f32 v[26:27], v[136:137], v[228:229], v[26:27] op_sel_hi:[1,0,1]
	v_pk_fma_f32 v[28:29], v[134:135], v[228:229], v[28:29] op_sel:[0,1,0]
	v_pk_fma_f32 v[30:31], v[136:137], v[228:229], v[30:31] op_sel:[0,1,0]
	ds_read_b128 v[222:225], v32 offset:128
	ds_read_b128 v[226:229], v32 offset:144
	s_waitcnt lgkmcnt(2)
	v_pk_mul_f32 v[238:239], v[230:231], v[102:103] op_sel_hi:[0,1]
	v_pk_mul_f32 v[240:241], v[230:231], v[110:111] op_sel_hi:[0,1]
	v_pk_fma_f32 v[238:239], v[86:87], v[134:135], v[238:239]
	v_pk_fma_f32 v[240:241], v[86:87], v[136:137], v[240:241]
	v_pk_fma_f32 v[238:239], v[234:235], v[118:119], v[238:239] op_sel_hi:[0,1,1]
	v_pk_fma_f32 v[240:241], v[234:235], v[126:127], v[240:241] op_sel_hi:[0,1,1]
	v_pk_fma_f32 v[238:239], v[230:231], v[104:105], v[238:239] op_sel:[1,0,0]
	v_pk_fma_f32 v[240:241], v[230:231], v[112:113], v[240:241] op_sel:[1,0,0]
	v_pk_fma_f32 v[238:239], v[234:235], v[120:121], v[238:239] op_sel:[1,0,0]
	v_pk_fma_f32 v[240:241], v[234:235], v[128:129], v[240:241] op_sel:[1,0,0]
	v_pk_fma_f32 v[238:239], v[232:233], v[106:107], v[238:239] op_sel_hi:[0,1,1]
	v_pk_fma_f32 v[240:241], v[232:233], v[114:115], v[240:241] op_sel_hi:[0,1,1]
	v_pk_fma_f32 v[238:239], v[236:237], v[122:123], v[238:239] op_sel_hi:[0,1,1]
	v_pk_fma_f32 v[240:241], v[236:237], v[130:131], v[240:241] op_sel_hi:[0,1,1]
	v_pk_fma_f32 v[238:239], v[232:233], v[108:109], v[238:239] op_sel:[1,0,0]
	v_pk_fma_f32 v[240:241], v[232:233], v[116:117], v[240:241] op_sel:[1,0,0]
	v_pk_fma_f32 v[238:239], v[236:237], v[124:125], v[238:239] op_sel:[1,0,0]
	v_pk_fma_f32 v[240:241], v[236:237], v[132:133], v[240:241] op_sel:[1,0,0]
	ds_read_b128 v[230:233], v32 offset:16512
	ds_read_b128 v[234:237], v32 offset:16528
	global_store_dwordx4 v246, v[238:241], s[100:101] nt
	global_load_dwordx4 v[134:137], v246, s[98:99] nt
	s_add_u32 s100, s100, 0x2000
	s_addc_u32 s101, s101, 0
	s_add_u32 s98, s98, 0x2000
	s_addc_u32 s99, s99, 0
	s_waitcnt vmcnt(30)
	s_waitcnt lgkmcnt(2)
	v_pk_fma_f32 v[0:1], v[138:139], v[222:223], v[0:1] op_sel_hi:[1,0,1]
	v_pk_fma_f32 v[2:3], v[140:141], v[222:223], v[2:3] op_sel_hi:[1,0,1]
	v_pk_fma_f32 v[4:5], v[138:139], v[222:223], v[4:5] op_sel:[0,1,0]
	v_pk_fma_f32 v[6:7], v[140:141], v[222:223], v[6:7] op_sel:[0,1,0]
	v_pk_fma_f32 v[8:9], v[138:139], v[224:225], v[8:9] op_sel_hi:[1,0,1]
	v_pk_fma_f32 v[10:11], v[140:141], v[224:225], v[10:11] op_sel_hi:[1,0,1]
	v_pk_fma_f32 v[12:13], v[138:139], v[224:225], v[12:13] op_sel:[0,1,0]
	v_pk_fma_f32 v[14:15], v[140:141], v[224:225], v[14:15] op_sel:[0,1,0]
	v_pk_fma_f32 v[16:17], v[138:139], v[226:227], v[16:17] op_sel_hi:[1,0,1]
	v_pk_fma_f32 v[18:19], v[140:141], v[226:227], v[18:19] op_sel_hi:[1,0,1]
	v_pk_fma_f32 v[20:21], v[138:139], v[226:227], v[20:21] op_sel:[0,1,0]
	v_pk_fma_f32 v[22:23], v[140:141], v[226:227], v[22:23] op_sel:[0,1,0]
	v_pk_fma_f32 v[24:25], v[138:139], v[228:229], v[24:25] op_sel_hi:[1,0,1]
	v_pk_fma_f32 v[26:27], v[140:141], v[228:229], v[26:27] op_sel_hi:[1,0,1]
	v_pk_fma_f32 v[28:29], v[138:139], v[228:229], v[28:29] op_sel:[0,1,0]
	v_pk_fma_f32 v[30:31], v[140:141], v[228:229], v[30:31] op_sel:[0,1,0]
	ds_read_b128 v[222:225], v32 offset:256
	ds_read_b128 v[226:229], v32 offset:272
	s_waitcnt lgkmcnt(2)
	v_pk_mul_f32 v[242:243], v[230:231], v[102:103] op_sel_hi:[0,1]
	v_pk_mul_f32 v[244:245], v[230:231], v[110:111] op_sel_hi:[0,1]
	v_pk_fma_f32 v[242:243], v[86:87], v[138:139], v[242:243]
	v_pk_fma_f32 v[244:245], v[86:87], v[140:141], v[244:245]
	v_pk_fma_f32 v[242:243], v[234:235], v[118:119], v[242:243] op_sel_hi:[0,1,1]
	v_pk_fma_f32 v[244:245], v[234:235], v[126:127], v[244:245] op_sel_hi:[0,1,1]
	v_pk_fma_f32 v[242:243], v[230:231], v[104:105], v[242:243] op_sel:[1,0,0]
	v_pk_fma_f32 v[244:245], v[230:231], v[112:113], v[244:245] op_sel:[1,0,0]
	v_pk_fma_f32 v[242:243], v[234:235], v[120:121], v[242:243] op_sel:[1,0,0]
	v_pk_fma_f32 v[244:245], v[234:235], v[128:129], v[244:245] op_sel:[1,0,0]
	v_pk_fma_f32 v[242:243], v[232:233], v[106:107], v[242:243] op_sel_hi:[0,1,1]
	v_pk_fma_f32 v[244:245], v[232:233], v[114:115], v[244:245] op_sel_hi:[0,1,1]
	v_pk_fma_f32 v[242:243], v[236:237], v[122:123], v[242:243] op_sel_hi:[0,1,1]
	v_pk_fma_f32 v[244:245], v[236:237], v[130:131], v[244:245] op_sel_hi:[0,1,1]
	v_pk_fma_f32 v[242:243], v[232:233], v[108:109], v[242:243] op_sel:[1,0,0]
	v_pk_fma_f32 v[244:245], v[232:233], v[116:117], v[244:245] op_sel:[1,0,0]
	v_pk_fma_f32 v[242:243], v[236:237], v[124:125], v[242:243] op_sel:[1,0,0]
	v_pk_fma_f32 v[244:245], v[236:237], v[132:133], v[244:245] op_sel:[1,0,0]
	ds_read_b128 v[230:233], v32 offset:16640
	ds_read_b128 v[234:237], v32 offset:16656
	global_store_dwordx4 v246, v[242:245], s[100:101] nt
	global_load_dwordx4 v[138:141], v246, s[98:99] nt
	s_add_u32 s100, s100, 0x2000
	s_addc_u32 s101, s101, 0
	s_add_u32 s98, s98, 0x2000
	s_addc_u32 s99, s99, 0
	s_waitcnt vmcnt(30)
	s_waitcnt lgkmcnt(2)
	v_pk_fma_f32 v[0:1], v[142:143], v[222:223], v[0:1] op_sel_hi:[1,0,1]
	v_pk_fma_f32 v[2:3], v[144:145], v[222:223], v[2:3] op_sel_hi:[1,0,1]
	v_pk_fma_f32 v[4:5], v[142:143], v[222:223], v[4:5] op_sel:[0,1,0]
	v_pk_fma_f32 v[6:7], v[144:145], v[222:223], v[6:7] op_sel:[0,1,0]
	v_pk_fma_f32 v[8:9], v[142:143], v[224:225], v[8:9] op_sel_hi:[1,0,1]
	v_pk_fma_f32 v[10:11], v[144:145], v[224:225], v[10:11] op_sel_hi:[1,0,1]
	v_pk_fma_f32 v[12:13], v[142:143], v[224:225], v[12:13] op_sel:[0,1,0]
	v_pk_fma_f32 v[14:15], v[144:145], v[224:225], v[14:15] op_sel:[0,1,0]
	v_pk_fma_f32 v[16:17], v[142:143], v[226:227], v[16:17] op_sel_hi:[1,0,1]
	v_pk_fma_f32 v[18:19], v[144:145], v[226:227], v[18:19] op_sel_hi:[1,0,1]
	v_pk_fma_f32 v[20:21], v[142:143], v[226:227], v[20:21] op_sel:[0,1,0]
	v_pk_fma_f32 v[22:23], v[144:145], v[226:227], v[22:23] op_sel:[0,1,0]
	v_pk_fma_f32 v[24:25], v[142:143], v[228:229], v[24:25] op_sel_hi:[1,0,1]
	v_pk_fma_f32 v[26:27], v[144:145], v[228:229], v[26:27] op_sel_hi:[1,0,1]
	v_pk_fma_f32 v[28:29], v[142:143], v[228:229], v[28:29] op_sel:[0,1,0]
	v_pk_fma_f32 v[30:31], v[144:145], v[228:229], v[30:31] op_sel:[0,1,0]
	ds_read_b128 v[222:225], v32 offset:384
	ds_read_b128 v[226:229], v32 offset:400
	s_waitcnt lgkmcnt(2)
	v_pk_mul_f32 v[238:239], v[230:231], v[102:103] op_sel_hi:[0,1]
	v_pk_mul_f32 v[240:241], v[230:231], v[110:111] op_sel_hi:[0,1]
	v_pk_fma_f32 v[238:239], v[86:87], v[142:143], v[238:239]
	v_pk_fma_f32 v[240:241], v[86:87], v[144:145], v[240:241]
	v_pk_fma_f32 v[238:239], v[234:235], v[118:119], v[238:239] op_sel_hi:[0,1,1]
	v_pk_fma_f32 v[240:241], v[234:235], v[126:127], v[240:241] op_sel_hi:[0,1,1]
	v_pk_fma_f32 v[238:239], v[230:231], v[104:105], v[238:239] op_sel:[1,0,0]
	v_pk_fma_f32 v[240:241], v[230:231], v[112:113], v[240:241] op_sel:[1,0,0]
	v_pk_fma_f32 v[238:239], v[234:235], v[120:121], v[238:239] op_sel:[1,0,0]
	v_pk_fma_f32 v[240:241], v[234:235], v[128:129], v[240:241] op_sel:[1,0,0]
	v_pk_fma_f32 v[238:239], v[232:233], v[106:107], v[238:239] op_sel_hi:[0,1,1]
	v_pk_fma_f32 v[240:241], v[232:233], v[114:115], v[240:241] op_sel_hi:[0,1,1]
	v_pk_fma_f32 v[238:239], v[236:237], v[122:123], v[238:239] op_sel_hi:[0,1,1]
	v_pk_fma_f32 v[240:241], v[236:237], v[130:131], v[240:241] op_sel_hi:[0,1,1]
	v_pk_fma_f32 v[238:239], v[232:233], v[108:109], v[238:239] op_sel:[1,0,0]
	v_pk_fma_f32 v[240:241], v[232:233], v[116:117], v[240:241] op_sel:[1,0,0]
	v_pk_fma_f32 v[238:239], v[236:237], v[124:125], v[238:239] op_sel:[1,0,0]
	v_pk_fma_f32 v[240:241], v[236:237], v[132:133], v[240:241] op_sel:[1,0,0]
	ds_read_b128 v[230:233], v32 offset:16768
	ds_read_b128 v[234:237], v32 offset:16784
	global_store_dwordx4 v246, v[238:241], s[100:101] nt
	global_load_dwordx4 v[142:145], v246, s[98:99] nt
	s_add_u32 s100, s100, 0x2000
	s_addc_u32 s101, s101, 0
	s_add_u32 s98, s98, 0x2000
	s_addc_u32 s99, s99, 0
	s_waitcnt vmcnt(30)
	s_waitcnt lgkmcnt(2)
	v_pk_fma_f32 v[0:1], v[158:159], v[222:223], v[0:1] op_sel_hi:[1,0,1]
	v_pk_fma_f32 v[2:3], v[160:161], v[222:223], v[2:3] op_sel_hi:[1,0,1]
	v_pk_fma_f32 v[4:5], v[158:159], v[222:223], v[4:5] op_sel:[0,1,0]
	v_pk_fma_f32 v[6:7], v[160:161], v[222:223], v[6:7] op_sel:[0,1,0]
	v_pk_fma_f32 v[8:9], v[158:159], v[224:225], v[8:9] op_sel_hi:[1,0,1]
	v_pk_fma_f32 v[10:11], v[160:161], v[224:225], v[10:11] op_sel_hi:[1,0,1]
	v_pk_fma_f32 v[12:13], v[158:159], v[224:225], v[12:13] op_sel:[0,1,0]
	v_pk_fma_f32 v[14:15], v[160:161], v[224:225], v[14:15] op_sel:[0,1,0]
	v_pk_fma_f32 v[16:17], v[158:159], v[226:227], v[16:17] op_sel_hi:[1,0,1]
	v_pk_fma_f32 v[18:19], v[160:161], v[226:227], v[18:19] op_sel_hi:[1,0,1]
	v_pk_fma_f32 v[20:21], v[158:159], v[226:227], v[20:21] op_sel:[0,1,0]
	v_pk_fma_f32 v[22:23], v[160:161], v[226:227], v[22:23] op_sel:[0,1,0]
	v_pk_fma_f32 v[24:25], v[158:159], v[228:229], v[24:25] op_sel_hi:[1,0,1]
	v_pk_fma_f32 v[26:27], v[160:161], v[228:229], v[26:27] op_sel_hi:[1,0,1]
	v_pk_fma_f32 v[28:29], v[158:159], v[228:229], v[28:29] op_sel:[0,1,0]
	v_pk_fma_f32 v[30:31], v[160:161], v[228:229], v[30:31] op_sel:[0,1,0]
	ds_read_b128 v[222:225], v32 offset:512
	ds_read_b128 v[226:229], v32 offset:528
	s_waitcnt lgkmcnt(2)
	v_pk_mul_f32 v[242:243], v[230:231], v[102:103] op_sel_hi:[0,1]
	v_pk_mul_f32 v[244:245], v[230:231], v[110:111] op_sel_hi:[0,1]
	v_pk_fma_f32 v[242:243], v[86:87], v[158:159], v[242:243]
	v_pk_fma_f32 v[244:245], v[86:87], v[160:161], v[244:245]
	v_pk_fma_f32 v[242:243], v[234:235], v[118:119], v[242:243] op_sel_hi:[0,1,1]
	v_pk_fma_f32 v[244:245], v[234:235], v[126:127], v[244:245] op_sel_hi:[0,1,1]
	v_pk_fma_f32 v[242:243], v[230:231], v[104:105], v[242:243] op_sel:[1,0,0]
	v_pk_fma_f32 v[244:245], v[230:231], v[112:113], v[244:245] op_sel:[1,0,0]
	v_pk_fma_f32 v[242:243], v[234:235], v[120:121], v[242:243] op_sel:[1,0,0]
	v_pk_fma_f32 v[244:245], v[234:235], v[128:129], v[244:245] op_sel:[1,0,0]
	v_pk_fma_f32 v[242:243], v[232:233], v[106:107], v[242:243] op_sel_hi:[0,1,1]
	v_pk_fma_f32 v[244:245], v[232:233], v[114:115], v[244:245] op_sel_hi:[0,1,1]
	v_pk_fma_f32 v[242:243], v[236:237], v[122:123], v[242:243] op_sel_hi:[0,1,1]
	v_pk_fma_f32 v[244:245], v[236:237], v[130:131], v[244:245] op_sel_hi:[0,1,1]
	v_pk_fma_f32 v[242:243], v[232:233], v[108:109], v[242:243] op_sel:[1,0,0]
	v_pk_fma_f32 v[244:245], v[232:233], v[116:117], v[244:245] op_sel:[1,0,0]
	v_pk_fma_f32 v[242:243], v[236:237], v[124:125], v[242:243] op_sel:[1,0,0]
	v_pk_fma_f32 v[244:245], v[236:237], v[132:133], v[244:245] op_sel:[1,0,0]
	ds_read_b128 v[230:233], v32 offset:16896
	ds_read_b128 v[234:237], v32 offset:16912
	global_store_dwordx4 v246, v[242:245], s[100:101] nt
	global_load_dwordx4 v[158:161], v246, s[98:99] nt
	s_add_u32 s100, s100, 0x2000
	s_addc_u32 s101, s101, 0
	s_add_u32 s98, s98, 0x2000
	s_addc_u32 s99, s99, 0
	s_waitcnt vmcnt(30)
	s_waitcnt lgkmcnt(2)
	v_pk_fma_f32 v[0:1], v[162:163], v[222:223], v[0:1] op_sel_hi:[1,0,1]
	v_pk_fma_f32 v[2:3], v[164:165], v[222:223], v[2:3] op_sel_hi:[1,0,1]
	v_pk_fma_f32 v[4:5], v[162:163], v[222:223], v[4:5] op_sel:[0,1,0]
	v_pk_fma_f32 v[6:7], v[164:165], v[222:223], v[6:7] op_sel:[0,1,0]
	v_pk_fma_f32 v[8:9], v[162:163], v[224:225], v[8:9] op_sel_hi:[1,0,1]
	v_pk_fma_f32 v[10:11], v[164:165], v[224:225], v[10:11] op_sel_hi:[1,0,1]
	v_pk_fma_f32 v[12:13], v[162:163], v[224:225], v[12:13] op_sel:[0,1,0]
	v_pk_fma_f32 v[14:15], v[164:165], v[224:225], v[14:15] op_sel:[0,1,0]
	v_pk_fma_f32 v[16:17], v[162:163], v[226:227], v[16:17] op_sel_hi:[1,0,1]
	v_pk_fma_f32 v[18:19], v[164:165], v[226:227], v[18:19] op_sel_hi:[1,0,1]
	v_pk_fma_f32 v[20:21], v[162:163], v[226:227], v[20:21] op_sel:[0,1,0]
	v_pk_fma_f32 v[22:23], v[164:165], v[226:227], v[22:23] op_sel:[0,1,0]
	v_pk_fma_f32 v[24:25], v[162:163], v[228:229], v[24:25] op_sel_hi:[1,0,1]
	v_pk_fma_f32 v[26:27], v[164:165], v[228:229], v[26:27] op_sel_hi:[1,0,1]
	v_pk_fma_f32 v[28:29], v[162:163], v[228:229], v[28:29] op_sel:[0,1,0]
	v_pk_fma_f32 v[30:31], v[164:165], v[228:229], v[30:31] op_sel:[0,1,0]
	ds_read_b128 v[222:225], v32 offset:640
	ds_read_b128 v[226:229], v32 offset:656
	s_waitcnt lgkmcnt(2)
	v_pk_mul_f32 v[238:239], v[230:231], v[102:103] op_sel_hi:[0,1]
	v_pk_mul_f32 v[240:241], v[230:231], v[110:111] op_sel_hi:[0,1]
	v_pk_fma_f32 v[238:239], v[86:87], v[162:163], v[238:239]
	v_pk_fma_f32 v[240:241], v[86:87], v[164:165], v[240:241]
	v_pk_fma_f32 v[238:239], v[234:235], v[118:119], v[238:239] op_sel_hi:[0,1,1]
	v_pk_fma_f32 v[240:241], v[234:235], v[126:127], v[240:241] op_sel_hi:[0,1,1]
	v_pk_fma_f32 v[238:239], v[230:231], v[104:105], v[238:239] op_sel:[1,0,0]
	v_pk_fma_f32 v[240:241], v[230:231], v[112:113], v[240:241] op_sel:[1,0,0]
	v_pk_fma_f32 v[238:239], v[234:235], v[120:121], v[238:239] op_sel:[1,0,0]
	v_pk_fma_f32 v[240:241], v[234:235], v[128:129], v[240:241] op_sel:[1,0,0]
	v_pk_fma_f32 v[238:239], v[232:233], v[106:107], v[238:239] op_sel_hi:[0,1,1]
	v_pk_fma_f32 v[240:241], v[232:233], v[114:115], v[240:241] op_sel_hi:[0,1,1]
	v_pk_fma_f32 v[238:239], v[236:237], v[122:123], v[238:239] op_sel_hi:[0,1,1]
	v_pk_fma_f32 v[240:241], v[236:237], v[130:131], v[240:241] op_sel_hi:[0,1,1]
	v_pk_fma_f32 v[238:239], v[232:233], v[108:109], v[238:239] op_sel:[1,0,0]
	v_pk_fma_f32 v[240:241], v[232:233], v[116:117], v[240:241] op_sel:[1,0,0]
	v_pk_fma_f32 v[238:239], v[236:237], v[124:125], v[238:239] op_sel:[1,0,0]
	v_pk_fma_f32 v[240:241], v[236:237], v[132:133], v[240:241] op_sel:[1,0,0]
	ds_read_b128 v[230:233], v32 offset:17024
	ds_read_b128 v[234:237], v32 offset:17040
	global_store_dwordx4 v246, v[238:241], s[100:101] nt
	global_load_dwordx4 v[162:165], v246, s[98:99] nt
	s_add_u32 s100, s100, 0x2000
	s_addc_u32 s101, s101, 0
	s_add_u32 s98, s98, 0x2000
	s_addc_u32 s99, s99, 0
	s_waitcnt vmcnt(30)
	s_waitcnt lgkmcnt(2)
	v_pk_fma_f32 v[0:1], v[166:167], v[222:223], v[0:1] op_sel_hi:[1,0,1]
	v_pk_fma_f32 v[2:3], v[168:169], v[222:223], v[2:3] op_sel_hi:[1,0,1]
	v_pk_fma_f32 v[4:5], v[166:167], v[222:223], v[4:5] op_sel:[0,1,0]
	v_pk_fma_f32 v[6:7], v[168:169], v[222:223], v[6:7] op_sel:[0,1,0]
	v_pk_fma_f32 v[8:9], v[166:167], v[224:225], v[8:9] op_sel_hi:[1,0,1]
	v_pk_fma_f32 v[10:11], v[168:169], v[224:225], v[10:11] op_sel_hi:[1,0,1]
	v_pk_fma_f32 v[12:13], v[166:167], v[224:225], v[12:13] op_sel:[0,1,0]
	v_pk_fma_f32 v[14:15], v[168:169], v[224:225], v[14:15] op_sel:[0,1,0]
	v_pk_fma_f32 v[16:17], v[166:167], v[226:227], v[16:17] op_sel_hi:[1,0,1]
	v_pk_fma_f32 v[18:19], v[168:169], v[226:227], v[18:19] op_sel_hi:[1,0,1]
	v_pk_fma_f32 v[20:21], v[166:167], v[226:227], v[20:21] op_sel:[0,1,0]
	v_pk_fma_f32 v[22:23], v[168:169], v[226:227], v[22:23] op_sel:[0,1,0]
	v_pk_fma_f32 v[24:25], v[166:167], v[228:229], v[24:25] op_sel_hi:[1,0,1]
	v_pk_fma_f32 v[26:27], v[168:169], v[228:229], v[26:27] op_sel_hi:[1,0,1]
	v_pk_fma_f32 v[28:29], v[166:167], v[228:229], v[28:29] op_sel:[0,1,0]
	v_pk_fma_f32 v[30:31], v[168:169], v[228:229], v[30:31] op_sel:[0,1,0]
	ds_read_b128 v[222:225], v32 offset:768
	ds_read_b128 v[226:229], v32 offset:784
	s_waitcnt lgkmcnt(2)
	v_pk_mul_f32 v[242:243], v[230:231], v[102:103] op_sel_hi:[0,1]
	v_pk_mul_f32 v[244:245], v[230:231], v[110:111] op_sel_hi:[0,1]
	v_pk_fma_f32 v[242:243], v[86:87], v[166:167], v[242:243]
	v_pk_fma_f32 v[244:245], v[86:87], v[168:169], v[244:245]
	v_pk_fma_f32 v[242:243], v[234:235], v[118:119], v[242:243] op_sel_hi:[0,1,1]
	v_pk_fma_f32 v[244:245], v[234:235], v[126:127], v[244:245] op_sel_hi:[0,1,1]
	v_pk_fma_f32 v[242:243], v[230:231], v[104:105], v[242:243] op_sel:[1,0,0]
	v_pk_fma_f32 v[244:245], v[230:231], v[112:113], v[244:245] op_sel:[1,0,0]
	v_pk_fma_f32 v[242:243], v[234:235], v[120:121], v[242:243] op_sel:[1,0,0]
	v_pk_fma_f32 v[244:245], v[234:235], v[128:129], v[244:245] op_sel:[1,0,0]
	v_pk_fma_f32 v[242:243], v[232:233], v[106:107], v[242:243] op_sel_hi:[0,1,1]
	v_pk_fma_f32 v[244:245], v[232:233], v[114:115], v[244:245] op_sel_hi:[0,1,1]
	v_pk_fma_f32 v[242:243], v[236:237], v[122:123], v[242:243] op_sel_hi:[0,1,1]
	v_pk_fma_f32 v[244:245], v[236:237], v[130:131], v[244:245] op_sel_hi:[0,1,1]
	v_pk_fma_f32 v[242:243], v[232:233], v[108:109], v[242:243] op_sel:[1,0,0]
	v_pk_fma_f32 v[244:245], v[232:233], v[116:117], v[244:245] op_sel:[1,0,0]
	v_pk_fma_f32 v[242:243], v[236:237], v[124:125], v[242:243] op_sel:[1,0,0]
	v_pk_fma_f32 v[244:245], v[236:237], v[132:133], v[244:245] op_sel:[1,0,0]
	ds_read_b128 v[230:233], v32 offset:17152
	ds_read_b128 v[234:237], v32 offset:17168
	global_store_dwordx4 v246, v[242:245], s[100:101] nt
	global_load_dwordx4 v[166:169], v246, s[98:99] nt
	s_add_u32 s100, s100, 0x2000
	s_addc_u32 s101, s101, 0
	s_add_u32 s98, s98, 0x2000
	s_addc_u32 s99, s99, 0
	s_waitcnt vmcnt(30)
	s_waitcnt lgkmcnt(2)
	v_pk_fma_f32 v[0:1], v[170:171], v[222:223], v[0:1] op_sel_hi:[1,0,1]
	v_pk_fma_f32 v[2:3], v[172:173], v[222:223], v[2:3] op_sel_hi:[1,0,1]
	v_pk_fma_f32 v[4:5], v[170:171], v[222:223], v[4:5] op_sel:[0,1,0]
	v_pk_fma_f32 v[6:7], v[172:173], v[222:223], v[6:7] op_sel:[0,1,0]
	v_pk_fma_f32 v[8:9], v[170:171], v[224:225], v[8:9] op_sel_hi:[1,0,1]
	v_pk_fma_f32 v[10:11], v[172:173], v[224:225], v[10:11] op_sel_hi:[1,0,1]
	v_pk_fma_f32 v[12:13], v[170:171], v[224:225], v[12:13] op_sel:[0,1,0]
	v_pk_fma_f32 v[14:15], v[172:173], v[224:225], v[14:15] op_sel:[0,1,0]
	v_pk_fma_f32 v[16:17], v[170:171], v[226:227], v[16:17] op_sel_hi:[1,0,1]
	v_pk_fma_f32 v[18:19], v[172:173], v[226:227], v[18:19] op_sel_hi:[1,0,1]
	v_pk_fma_f32 v[20:21], v[170:171], v[226:227], v[20:21] op_sel:[0,1,0]
	v_pk_fma_f32 v[22:23], v[172:173], v[226:227], v[22:23] op_sel:[0,1,0]
	v_pk_fma_f32 v[24:25], v[170:171], v[228:229], v[24:25] op_sel_hi:[1,0,1]
	v_pk_fma_f32 v[26:27], v[172:173], v[228:229], v[26:27] op_sel_hi:[1,0,1]
	v_pk_fma_f32 v[28:29], v[170:171], v[228:229], v[28:29] op_sel:[0,1,0]
	v_pk_fma_f32 v[30:31], v[172:173], v[228:229], v[30:31] op_sel:[0,1,0]
	ds_read_b128 v[222:225], v32 offset:896
	ds_read_b128 v[226:229], v32 offset:912
	s_waitcnt lgkmcnt(2)
	v_pk_mul_f32 v[238:239], v[230:231], v[102:103] op_sel_hi:[0,1]
	v_pk_mul_f32 v[240:241], v[230:231], v[110:111] op_sel_hi:[0,1]
	v_pk_fma_f32 v[238:239], v[86:87], v[170:171], v[238:239]
	v_pk_fma_f32 v[240:241], v[86:87], v[172:173], v[240:241]
	v_pk_fma_f32 v[238:239], v[234:235], v[118:119], v[238:239] op_sel_hi:[0,1,1]
	v_pk_fma_f32 v[240:241], v[234:235], v[126:127], v[240:241] op_sel_hi:[0,1,1]
	v_pk_fma_f32 v[238:239], v[230:231], v[104:105], v[238:239] op_sel:[1,0,0]
	v_pk_fma_f32 v[240:241], v[230:231], v[112:113], v[240:241] op_sel:[1,0,0]
	v_pk_fma_f32 v[238:239], v[234:235], v[120:121], v[238:239] op_sel:[1,0,0]
	v_pk_fma_f32 v[240:241], v[234:235], v[128:129], v[240:241] op_sel:[1,0,0]
	v_pk_fma_f32 v[238:239], v[232:233], v[106:107], v[238:239] op_sel_hi:[0,1,1]
	v_pk_fma_f32 v[240:241], v[232:233], v[114:115], v[240:241] op_sel_hi:[0,1,1]
	v_pk_fma_f32 v[238:239], v[236:237], v[122:123], v[238:239] op_sel_hi:[0,1,1]
	v_pk_fma_f32 v[240:241], v[236:237], v[130:131], v[240:241] op_sel_hi:[0,1,1]
	v_pk_fma_f32 v[238:239], v[232:233], v[108:109], v[238:239] op_sel:[1,0,0]
	v_pk_fma_f32 v[240:241], v[232:233], v[116:117], v[240:241] op_sel:[1,0,0]
	v_pk_fma_f32 v[238:239], v[236:237], v[124:125], v[238:239] op_sel:[1,0,0]
	v_pk_fma_f32 v[240:241], v[236:237], v[132:133], v[240:241] op_sel:[1,0,0]
	ds_read_b128 v[230:233], v32 offset:17280
	ds_read_b128 v[234:237], v32 offset:17296
	global_store_dwordx4 v246, v[238:241], s[100:101] nt
	global_load_dwordx4 v[170:173], v246, s[98:99] nt
	s_add_u32 s100, s100, 0x2000
	s_addc_u32 s101, s101, 0
	s_add_u32 s98, s98, 0x2000
	s_addc_u32 s99, s99, 0
	s_waitcnt vmcnt(30)
	s_waitcnt lgkmcnt(2)
	v_pk_fma_f32 v[0:1], v[174:175], v[222:223], v[0:1] op_sel_hi:[1,0,1]
	v_pk_fma_f32 v[2:3], v[176:177], v[222:223], v[2:3] op_sel_hi:[1,0,1]
	v_pk_fma_f32 v[4:5], v[174:175], v[222:223], v[4:5] op_sel:[0,1,0]
	v_pk_fma_f32 v[6:7], v[176:177], v[222:223], v[6:7] op_sel:[0,1,0]
	v_pk_fma_f32 v[8:9], v[174:175], v[224:225], v[8:9] op_sel_hi:[1,0,1]
	v_pk_fma_f32 v[10:11], v[176:177], v[224:225], v[10:11] op_sel_hi:[1,0,1]
	v_pk_fma_f32 v[12:13], v[174:175], v[224:225], v[12:13] op_sel:[0,1,0]
	v_pk_fma_f32 v[14:15], v[176:177], v[224:225], v[14:15] op_sel:[0,1,0]
	v_pk_fma_f32 v[16:17], v[174:175], v[226:227], v[16:17] op_sel_hi:[1,0,1]
	v_pk_fma_f32 v[18:19], v[176:177], v[226:227], v[18:19] op_sel_hi:[1,0,1]
	v_pk_fma_f32 v[20:21], v[174:175], v[226:227], v[20:21] op_sel:[0,1,0]
	v_pk_fma_f32 v[22:23], v[176:177], v[226:227], v[22:23] op_sel:[0,1,0]
	v_pk_fma_f32 v[24:25], v[174:175], v[228:229], v[24:25] op_sel_hi:[1,0,1]
	v_pk_fma_f32 v[26:27], v[176:177], v[228:229], v[26:27] op_sel_hi:[1,0,1]
	v_pk_fma_f32 v[28:29], v[174:175], v[228:229], v[28:29] op_sel:[0,1,0]
	v_pk_fma_f32 v[30:31], v[176:177], v[228:229], v[30:31] op_sel:[0,1,0]
	ds_read_b128 v[222:225], v32 offset:1024
	ds_read_b128 v[226:229], v32 offset:1040
	s_waitcnt lgkmcnt(2)
	v_pk_mul_f32 v[242:243], v[230:231], v[102:103] op_sel_hi:[0,1]
	v_pk_mul_f32 v[244:245], v[230:231], v[110:111] op_sel_hi:[0,1]
	v_pk_fma_f32 v[242:243], v[86:87], v[174:175], v[242:243]
	v_pk_fma_f32 v[244:245], v[86:87], v[176:177], v[244:245]
	v_pk_fma_f32 v[242:243], v[234:235], v[118:119], v[242:243] op_sel_hi:[0,1,1]
	v_pk_fma_f32 v[244:245], v[234:235], v[126:127], v[244:245] op_sel_hi:[0,1,1]
	v_pk_fma_f32 v[242:243], v[230:231], v[104:105], v[242:243] op_sel:[1,0,0]
	v_pk_fma_f32 v[244:245], v[230:231], v[112:113], v[244:245] op_sel:[1,0,0]
	v_pk_fma_f32 v[242:243], v[234:235], v[120:121], v[242:243] op_sel:[1,0,0]
	v_pk_fma_f32 v[244:245], v[234:235], v[128:129], v[244:245] op_sel:[1,0,0]
	v_pk_fma_f32 v[242:243], v[232:233], v[106:107], v[242:243] op_sel_hi:[0,1,1]
	v_pk_fma_f32 v[244:245], v[232:233], v[114:115], v[244:245] op_sel_hi:[0,1,1]
	v_pk_fma_f32 v[242:243], v[236:237], v[122:123], v[242:243] op_sel_hi:[0,1,1]
	v_pk_fma_f32 v[244:245], v[236:237], v[130:131], v[244:245] op_sel_hi:[0,1,1]
	v_pk_fma_f32 v[242:243], v[232:233], v[108:109], v[242:243] op_sel:[1,0,0]
	v_pk_fma_f32 v[244:245], v[232:233], v[116:117], v[244:245] op_sel:[1,0,0]
	v_pk_fma_f32 v[242:243], v[236:237], v[124:125], v[242:243] op_sel:[1,0,0]
	v_pk_fma_f32 v[244:245], v[236:237], v[132:133], v[244:245] op_sel:[1,0,0]
	ds_read_b128 v[230:233], v32 offset:17408
	ds_read_b128 v[234:237], v32 offset:17424
	global_store_dwordx4 v246, v[242:245], s[100:101] nt
	global_load_dwordx4 v[174:177], v246, s[98:99] nt
	s_add_u32 s100, s100, 0x2000
	s_addc_u32 s101, s101, 0
	s_add_u32 s98, s98, 0x2000
	s_addc_u32 s99, s99, 0
	s_waitcnt vmcnt(30)
	s_waitcnt lgkmcnt(2)
	v_pk_fma_f32 v[0:1], v[178:179], v[222:223], v[0:1] op_sel_hi:[1,0,1]
	v_pk_fma_f32 v[2:3], v[180:181], v[222:223], v[2:3] op_sel_hi:[1,0,1]
	v_pk_fma_f32 v[4:5], v[178:179], v[222:223], v[4:5] op_sel:[0,1,0]
	v_pk_fma_f32 v[6:7], v[180:181], v[222:223], v[6:7] op_sel:[0,1,0]
	v_pk_fma_f32 v[8:9], v[178:179], v[224:225], v[8:9] op_sel_hi:[1,0,1]
	v_pk_fma_f32 v[10:11], v[180:181], v[224:225], v[10:11] op_sel_hi:[1,0,1]
	v_pk_fma_f32 v[12:13], v[178:179], v[224:225], v[12:13] op_sel:[0,1,0]
	v_pk_fma_f32 v[14:15], v[180:181], v[224:225], v[14:15] op_sel:[0,1,0]
	v_pk_fma_f32 v[16:17], v[178:179], v[226:227], v[16:17] op_sel_hi:[1,0,1]
	v_pk_fma_f32 v[18:19], v[180:181], v[226:227], v[18:19] op_sel_hi:[1,0,1]
	v_pk_fma_f32 v[20:21], v[178:179], v[226:227], v[20:21] op_sel:[0,1,0]
	v_pk_fma_f32 v[22:23], v[180:181], v[226:227], v[22:23] op_sel:[0,1,0]
	v_pk_fma_f32 v[24:25], v[178:179], v[228:229], v[24:25] op_sel_hi:[1,0,1]
	v_pk_fma_f32 v[26:27], v[180:181], v[228:229], v[26:27] op_sel_hi:[1,0,1]
	v_pk_fma_f32 v[28:29], v[178:179], v[228:229], v[28:29] op_sel:[0,1,0]
	v_pk_fma_f32 v[30:31], v[180:181], v[228:229], v[30:31] op_sel:[0,1,0]
	ds_read_b128 v[222:225], v32 offset:1152
	ds_read_b128 v[226:229], v32 offset:1168
	s_waitcnt lgkmcnt(2)
	v_pk_mul_f32 v[238:239], v[230:231], v[102:103] op_sel_hi:[0,1]
	v_pk_mul_f32 v[240:241], v[230:231], v[110:111] op_sel_hi:[0,1]
	v_pk_fma_f32 v[238:239], v[86:87], v[178:179], v[238:239]
	v_pk_fma_f32 v[240:241], v[86:87], v[180:181], v[240:241]
	v_pk_fma_f32 v[238:239], v[234:235], v[118:119], v[238:239] op_sel_hi:[0,1,1]
	v_pk_fma_f32 v[240:241], v[234:235], v[126:127], v[240:241] op_sel_hi:[0,1,1]
	v_pk_fma_f32 v[238:239], v[230:231], v[104:105], v[238:239] op_sel:[1,0,0]
	v_pk_fma_f32 v[240:241], v[230:231], v[112:113], v[240:241] op_sel:[1,0,0]
	v_pk_fma_f32 v[238:239], v[234:235], v[120:121], v[238:239] op_sel:[1,0,0]
	v_pk_fma_f32 v[240:241], v[234:235], v[128:129], v[240:241] op_sel:[1,0,0]
	v_pk_fma_f32 v[238:239], v[232:233], v[106:107], v[238:239] op_sel_hi:[0,1,1]
	v_pk_fma_f32 v[240:241], v[232:233], v[114:115], v[240:241] op_sel_hi:[0,1,1]
	v_pk_fma_f32 v[238:239], v[236:237], v[122:123], v[238:239] op_sel_hi:[0,1,1]
	v_pk_fma_f32 v[240:241], v[236:237], v[130:131], v[240:241] op_sel_hi:[0,1,1]
	v_pk_fma_f32 v[238:239], v[232:233], v[108:109], v[238:239] op_sel:[1,0,0]
	v_pk_fma_f32 v[240:241], v[232:233], v[116:117], v[240:241] op_sel:[1,0,0]
	v_pk_fma_f32 v[238:239], v[236:237], v[124:125], v[238:239] op_sel:[1,0,0]
	v_pk_fma_f32 v[240:241], v[236:237], v[132:133], v[240:241] op_sel:[1,0,0]
	ds_read_b128 v[230:233], v32 offset:17536
	ds_read_b128 v[234:237], v32 offset:17552
	global_store_dwordx4 v246, v[238:241], s[100:101] nt
	global_load_dwordx4 v[178:181], v246, s[98:99] nt
	s_add_u32 s100, s100, 0x2000
	s_addc_u32 s101, s101, 0
	s_add_u32 s98, s98, 0x2000
	s_addc_u32 s99, s99, 0
	s_waitcnt vmcnt(30)
	s_waitcnt lgkmcnt(2)
	v_pk_fma_f32 v[0:1], v[182:183], v[222:223], v[0:1] op_sel_hi:[1,0,1]
	v_pk_fma_f32 v[2:3], v[184:185], v[222:223], v[2:3] op_sel_hi:[1,0,1]
	v_pk_fma_f32 v[4:5], v[182:183], v[222:223], v[4:5] op_sel:[0,1,0]
	v_pk_fma_f32 v[6:7], v[184:185], v[222:223], v[6:7] op_sel:[0,1,0]
	v_pk_fma_f32 v[8:9], v[182:183], v[224:225], v[8:9] op_sel_hi:[1,0,1]
	v_pk_fma_f32 v[10:11], v[184:185], v[224:225], v[10:11] op_sel_hi:[1,0,1]
	v_pk_fma_f32 v[12:13], v[182:183], v[224:225], v[12:13] op_sel:[0,1,0]
	v_pk_fma_f32 v[14:15], v[184:185], v[224:225], v[14:15] op_sel:[0,1,0]
	v_pk_fma_f32 v[16:17], v[182:183], v[226:227], v[16:17] op_sel_hi:[1,0,1]
	v_pk_fma_f32 v[18:19], v[184:185], v[226:227], v[18:19] op_sel_hi:[1,0,1]
	v_pk_fma_f32 v[20:21], v[182:183], v[226:227], v[20:21] op_sel:[0,1,0]
	v_pk_fma_f32 v[22:23], v[184:185], v[226:227], v[22:23] op_sel:[0,1,0]
	v_pk_fma_f32 v[24:25], v[182:183], v[228:229], v[24:25] op_sel_hi:[1,0,1]
	v_pk_fma_f32 v[26:27], v[184:185], v[228:229], v[26:27] op_sel_hi:[1,0,1]
	v_pk_fma_f32 v[28:29], v[182:183], v[228:229], v[28:29] op_sel:[0,1,0]
	v_pk_fma_f32 v[30:31], v[184:185], v[228:229], v[30:31] op_sel:[0,1,0]
	ds_read_b128 v[222:225], v32 offset:1280
	ds_read_b128 v[226:229], v32 offset:1296
	s_waitcnt lgkmcnt(2)
	v_pk_mul_f32 v[242:243], v[230:231], v[102:103] op_sel_hi:[0,1]
	v_pk_mul_f32 v[244:245], v[230:231], v[110:111] op_sel_hi:[0,1]
	v_pk_fma_f32 v[242:243], v[86:87], v[182:183], v[242:243]
	v_pk_fma_f32 v[244:245], v[86:87], v[184:185], v[244:245]
	v_pk_fma_f32 v[242:243], v[234:235], v[118:119], v[242:243] op_sel_hi:[0,1,1]
	v_pk_fma_f32 v[244:245], v[234:235], v[126:127], v[244:245] op_sel_hi:[0,1,1]
	v_pk_fma_f32 v[242:243], v[230:231], v[104:105], v[242:243] op_sel:[1,0,0]
	v_pk_fma_f32 v[244:245], v[230:231], v[112:113], v[244:245] op_sel:[1,0,0]
	v_pk_fma_f32 v[242:243], v[234:235], v[120:121], v[242:243] op_sel:[1,0,0]
	v_pk_fma_f32 v[244:245], v[234:235], v[128:129], v[244:245] op_sel:[1,0,0]
	v_pk_fma_f32 v[242:243], v[232:233], v[106:107], v[242:243] op_sel_hi:[0,1,1]
	v_pk_fma_f32 v[244:245], v[232:233], v[114:115], v[244:245] op_sel_hi:[0,1,1]
	v_pk_fma_f32 v[242:243], v[236:237], v[122:123], v[242:243] op_sel_hi:[0,1,1]
	v_pk_fma_f32 v[244:245], v[236:237], v[130:131], v[244:245] op_sel_hi:[0,1,1]
	v_pk_fma_f32 v[242:243], v[232:233], v[108:109], v[242:243] op_sel:[1,0,0]
	v_pk_fma_f32 v[244:245], v[232:233], v[116:117], v[244:245] op_sel:[1,0,0]
	v_pk_fma_f32 v[242:243], v[236:237], v[124:125], v[242:243] op_sel:[1,0,0]
	v_pk_fma_f32 v[244:245], v[236:237], v[132:133], v[244:245] op_sel:[1,0,0]
	ds_read_b128 v[230:233], v32 offset:17664
	ds_read_b128 v[234:237], v32 offset:17680
	global_store_dwordx4 v246, v[242:245], s[100:101] nt
	global_load_dwordx4 v[182:185], v246, s[98:99] nt
	s_add_u32 s100, s100, 0x2000
	s_addc_u32 s101, s101, 0
	s_add_u32 s98, s98, 0x2000
	s_addc_u32 s99, s99, 0
	s_waitcnt vmcnt(30)
	s_waitcnt lgkmcnt(2)
	v_pk_fma_f32 v[0:1], v[186:187], v[222:223], v[0:1] op_sel_hi:[1,0,1]
	v_pk_fma_f32 v[2:3], v[188:189], v[222:223], v[2:3] op_sel_hi:[1,0,1]
	v_pk_fma_f32 v[4:5], v[186:187], v[222:223], v[4:5] op_sel:[0,1,0]
	v_pk_fma_f32 v[6:7], v[188:189], v[222:223], v[6:7] op_sel:[0,1,0]
	v_pk_fma_f32 v[8:9], v[186:187], v[224:225], v[8:9] op_sel_hi:[1,0,1]
	v_pk_fma_f32 v[10:11], v[188:189], v[224:225], v[10:11] op_sel_hi:[1,0,1]
	v_pk_fma_f32 v[12:13], v[186:187], v[224:225], v[12:13] op_sel:[0,1,0]
	v_pk_fma_f32 v[14:15], v[188:189], v[224:225], v[14:15] op_sel:[0,1,0]
	v_pk_fma_f32 v[16:17], v[186:187], v[226:227], v[16:17] op_sel_hi:[1,0,1]
	v_pk_fma_f32 v[18:19], v[188:189], v[226:227], v[18:19] op_sel_hi:[1,0,1]
	v_pk_fma_f32 v[20:21], v[186:187], v[226:227], v[20:21] op_sel:[0,1,0]
	v_pk_fma_f32 v[22:23], v[188:189], v[226:227], v[22:23] op_sel:[0,1,0]
	v_pk_fma_f32 v[24:25], v[186:187], v[228:229], v[24:25] op_sel_hi:[1,0,1]
	v_pk_fma_f32 v[26:27], v[188:189], v[228:229], v[26:27] op_sel_hi:[1,0,1]
	v_pk_fma_f32 v[28:29], v[186:187], v[228:229], v[28:29] op_sel:[0,1,0]
	v_pk_fma_f32 v[30:31], v[188:189], v[228:229], v[30:31] op_sel:[0,1,0]
	ds_read_b128 v[222:225], v32 offset:1408
	ds_read_b128 v[226:229], v32 offset:1424
	s_waitcnt lgkmcnt(2)
	v_pk_mul_f32 v[238:239], v[230:231], v[102:103] op_sel_hi:[0,1]
	v_pk_mul_f32 v[240:241], v[230:231], v[110:111] op_sel_hi:[0,1]
	v_pk_fma_f32 v[238:239], v[86:87], v[186:187], v[238:239]
	v_pk_fma_f32 v[240:241], v[86:87], v[188:189], v[240:241]
	v_pk_fma_f32 v[238:239], v[234:235], v[118:119], v[238:239] op_sel_hi:[0,1,1]
	v_pk_fma_f32 v[240:241], v[234:235], v[126:127], v[240:241] op_sel_hi:[0,1,1]
	v_pk_fma_f32 v[238:239], v[230:231], v[104:105], v[238:239] op_sel:[1,0,0]
	v_pk_fma_f32 v[240:241], v[230:231], v[112:113], v[240:241] op_sel:[1,0,0]
	v_pk_fma_f32 v[238:239], v[234:235], v[120:121], v[238:239] op_sel:[1,0,0]
	v_pk_fma_f32 v[240:241], v[234:235], v[128:129], v[240:241] op_sel:[1,0,0]
	v_pk_fma_f32 v[238:239], v[232:233], v[106:107], v[238:239] op_sel_hi:[0,1,1]
	v_pk_fma_f32 v[240:241], v[232:233], v[114:115], v[240:241] op_sel_hi:[0,1,1]
	v_pk_fma_f32 v[238:239], v[236:237], v[122:123], v[238:239] op_sel_hi:[0,1,1]
	v_pk_fma_f32 v[240:241], v[236:237], v[130:131], v[240:241] op_sel_hi:[0,1,1]
	v_pk_fma_f32 v[238:239], v[232:233], v[108:109], v[238:239] op_sel:[1,0,0]
	v_pk_fma_f32 v[240:241], v[232:233], v[116:117], v[240:241] op_sel:[1,0,0]
	v_pk_fma_f32 v[238:239], v[236:237], v[124:125], v[238:239] op_sel:[1,0,0]
	v_pk_fma_f32 v[240:241], v[236:237], v[132:133], v[240:241] op_sel:[1,0,0]
	ds_read_b128 v[230:233], v32 offset:17792
	ds_read_b128 v[234:237], v32 offset:17808
	global_store_dwordx4 v246, v[238:241], s[100:101] nt
	global_load_dwordx4 v[186:189], v246, s[98:99] nt
	s_add_u32 s100, s100, 0x2000
	s_addc_u32 s101, s101, 0
	s_add_u32 s98, s98, 0x2000
	s_addc_u32 s99, s99, 0
	s_waitcnt vmcnt(30)
	s_waitcnt lgkmcnt(2)
	v_pk_fma_f32 v[0:1], v[190:191], v[222:223], v[0:1] op_sel_hi:[1,0,1]
	v_pk_fma_f32 v[2:3], v[192:193], v[222:223], v[2:3] op_sel_hi:[1,0,1]
	v_pk_fma_f32 v[4:5], v[190:191], v[222:223], v[4:5] op_sel:[0,1,0]
	v_pk_fma_f32 v[6:7], v[192:193], v[222:223], v[6:7] op_sel:[0,1,0]
	v_pk_fma_f32 v[8:9], v[190:191], v[224:225], v[8:9] op_sel_hi:[1,0,1]
	v_pk_fma_f32 v[10:11], v[192:193], v[224:225], v[10:11] op_sel_hi:[1,0,1]
	v_pk_fma_f32 v[12:13], v[190:191], v[224:225], v[12:13] op_sel:[0,1,0]
	v_pk_fma_f32 v[14:15], v[192:193], v[224:225], v[14:15] op_sel:[0,1,0]
	v_pk_fma_f32 v[16:17], v[190:191], v[226:227], v[16:17] op_sel_hi:[1,0,1]
	v_pk_fma_f32 v[18:19], v[192:193], v[226:227], v[18:19] op_sel_hi:[1,0,1]
	v_pk_fma_f32 v[20:21], v[190:191], v[226:227], v[20:21] op_sel:[0,1,0]
	v_pk_fma_f32 v[22:23], v[192:193], v[226:227], v[22:23] op_sel:[0,1,0]
	v_pk_fma_f32 v[24:25], v[190:191], v[228:229], v[24:25] op_sel_hi:[1,0,1]
	v_pk_fma_f32 v[26:27], v[192:193], v[228:229], v[26:27] op_sel_hi:[1,0,1]
	v_pk_fma_f32 v[28:29], v[190:191], v[228:229], v[28:29] op_sel:[0,1,0]
	v_pk_fma_f32 v[30:31], v[192:193], v[228:229], v[30:31] op_sel:[0,1,0]
	ds_read_b128 v[222:225], v32 offset:1536
	ds_read_b128 v[226:229], v32 offset:1552
	s_waitcnt lgkmcnt(2)
	v_pk_mul_f32 v[242:243], v[230:231], v[102:103] op_sel_hi:[0,1]
	v_pk_mul_f32 v[244:245], v[230:231], v[110:111] op_sel_hi:[0,1]
	v_pk_fma_f32 v[242:243], v[86:87], v[190:191], v[242:243]
	v_pk_fma_f32 v[244:245], v[86:87], v[192:193], v[244:245]
	v_pk_fma_f32 v[242:243], v[234:235], v[118:119], v[242:243] op_sel_hi:[0,1,1]
	v_pk_fma_f32 v[244:245], v[234:235], v[126:127], v[244:245] op_sel_hi:[0,1,1]
	v_pk_fma_f32 v[242:243], v[230:231], v[104:105], v[242:243] op_sel:[1,0,0]
	v_pk_fma_f32 v[244:245], v[230:231], v[112:113], v[244:245] op_sel:[1,0,0]
	v_pk_fma_f32 v[242:243], v[234:235], v[120:121], v[242:243] op_sel:[1,0,0]
	v_pk_fma_f32 v[244:245], v[234:235], v[128:129], v[244:245] op_sel:[1,0,0]
	v_pk_fma_f32 v[242:243], v[232:233], v[106:107], v[242:243] op_sel_hi:[0,1,1]
	v_pk_fma_f32 v[244:245], v[232:233], v[114:115], v[244:245] op_sel_hi:[0,1,1]
	v_pk_fma_f32 v[242:243], v[236:237], v[122:123], v[242:243] op_sel_hi:[0,1,1]
	v_pk_fma_f32 v[244:245], v[236:237], v[130:131], v[244:245] op_sel_hi:[0,1,1]
	v_pk_fma_f32 v[242:243], v[232:233], v[108:109], v[242:243] op_sel:[1,0,0]
	v_pk_fma_f32 v[244:245], v[232:233], v[116:117], v[244:245] op_sel:[1,0,0]
	v_pk_fma_f32 v[242:243], v[236:237], v[124:125], v[242:243] op_sel:[1,0,0]
	v_pk_fma_f32 v[244:245], v[236:237], v[132:133], v[244:245] op_sel:[1,0,0]
	ds_read_b128 v[230:233], v32 offset:17920
	ds_read_b128 v[234:237], v32 offset:17936
	global_store_dwordx4 v246, v[242:245], s[100:101] nt
	global_load_dwordx4 v[190:193], v246, s[98:99] nt
	s_add_u32 s100, s100, 0x2000
	s_addc_u32 s101, s101, 0
	s_add_u32 s98, s98, 0x2000
	s_addc_u32 s99, s99, 0
	s_waitcnt vmcnt(30)
	s_waitcnt lgkmcnt(2)
	v_pk_fma_f32 v[0:1], v[194:195], v[222:223], v[0:1] op_sel_hi:[1,0,1]
	v_pk_fma_f32 v[2:3], v[196:197], v[222:223], v[2:3] op_sel_hi:[1,0,1]
	v_pk_fma_f32 v[4:5], v[194:195], v[222:223], v[4:5] op_sel:[0,1,0]
	v_pk_fma_f32 v[6:7], v[196:197], v[222:223], v[6:7] op_sel:[0,1,0]
	v_pk_fma_f32 v[8:9], v[194:195], v[224:225], v[8:9] op_sel_hi:[1,0,1]
	v_pk_fma_f32 v[10:11], v[196:197], v[224:225], v[10:11] op_sel_hi:[1,0,1]
	v_pk_fma_f32 v[12:13], v[194:195], v[224:225], v[12:13] op_sel:[0,1,0]
	v_pk_fma_f32 v[14:15], v[196:197], v[224:225], v[14:15] op_sel:[0,1,0]
	v_pk_fma_f32 v[16:17], v[194:195], v[226:227], v[16:17] op_sel_hi:[1,0,1]
	v_pk_fma_f32 v[18:19], v[196:197], v[226:227], v[18:19] op_sel_hi:[1,0,1]
	v_pk_fma_f32 v[20:21], v[194:195], v[226:227], v[20:21] op_sel:[0,1,0]
	v_pk_fma_f32 v[22:23], v[196:197], v[226:227], v[22:23] op_sel:[0,1,0]
	v_pk_fma_f32 v[24:25], v[194:195], v[228:229], v[24:25] op_sel_hi:[1,0,1]
	v_pk_fma_f32 v[26:27], v[196:197], v[228:229], v[26:27] op_sel_hi:[1,0,1]
	v_pk_fma_f32 v[28:29], v[194:195], v[228:229], v[28:29] op_sel:[0,1,0]
	v_pk_fma_f32 v[30:31], v[196:197], v[228:229], v[30:31] op_sel:[0,1,0]
	ds_read_b128 v[222:225], v32 offset:1664
	ds_read_b128 v[226:229], v32 offset:1680
	s_waitcnt lgkmcnt(2)
	v_pk_mul_f32 v[238:239], v[230:231], v[102:103] op_sel_hi:[0,1]
	v_pk_mul_f32 v[240:241], v[230:231], v[110:111] op_sel_hi:[0,1]
	v_pk_fma_f32 v[238:239], v[86:87], v[194:195], v[238:239]
	v_pk_fma_f32 v[240:241], v[86:87], v[196:197], v[240:241]
	v_pk_fma_f32 v[238:239], v[234:235], v[118:119], v[238:239] op_sel_hi:[0,1,1]
	v_pk_fma_f32 v[240:241], v[234:235], v[126:127], v[240:241] op_sel_hi:[0,1,1]
	v_pk_fma_f32 v[238:239], v[230:231], v[104:105], v[238:239] op_sel:[1,0,0]
	v_pk_fma_f32 v[240:241], v[230:231], v[112:113], v[240:241] op_sel:[1,0,0]
	v_pk_fma_f32 v[238:239], v[234:235], v[120:121], v[238:239] op_sel:[1,0,0]
	v_pk_fma_f32 v[240:241], v[234:235], v[128:129], v[240:241] op_sel:[1,0,0]
	v_pk_fma_f32 v[238:239], v[232:233], v[106:107], v[238:239] op_sel_hi:[0,1,1]
	v_pk_fma_f32 v[240:241], v[232:233], v[114:115], v[240:241] op_sel_hi:[0,1,1]
	v_pk_fma_f32 v[238:239], v[236:237], v[122:123], v[238:239] op_sel_hi:[0,1,1]
	v_pk_fma_f32 v[240:241], v[236:237], v[130:131], v[240:241] op_sel_hi:[0,1,1]
	v_pk_fma_f32 v[238:239], v[232:233], v[108:109], v[238:239] op_sel:[1,0,0]
	v_pk_fma_f32 v[240:241], v[232:233], v[116:117], v[240:241] op_sel:[1,0,0]
	v_pk_fma_f32 v[238:239], v[236:237], v[124:125], v[238:239] op_sel:[1,0,0]
	v_pk_fma_f32 v[240:241], v[236:237], v[132:133], v[240:241] op_sel:[1,0,0]
	ds_read_b128 v[230:233], v32 offset:18048
	ds_read_b128 v[234:237], v32 offset:18064
	global_store_dwordx4 v246, v[238:241], s[100:101] nt
	global_load_dwordx4 v[194:197], v246, s[98:99] nt
	s_add_u32 s100, s100, 0x2000
	s_addc_u32 s101, s101, 0
	s_add_u32 s98, s98, 0x2000
	s_addc_u32 s99, s99, 0
	s_waitcnt vmcnt(30)
	s_waitcnt lgkmcnt(2)
	v_pk_fma_f32 v[0:1], v[210:211], v[222:223], v[0:1] op_sel_hi:[1,0,1]
	v_pk_fma_f32 v[2:3], v[212:213], v[222:223], v[2:3] op_sel_hi:[1,0,1]
	v_pk_fma_f32 v[4:5], v[210:211], v[222:223], v[4:5] op_sel:[0,1,0]
	v_pk_fma_f32 v[6:7], v[212:213], v[222:223], v[6:7] op_sel:[0,1,0]
	v_pk_fma_f32 v[8:9], v[210:211], v[224:225], v[8:9] op_sel_hi:[1,0,1]
	v_pk_fma_f32 v[10:11], v[212:213], v[224:225], v[10:11] op_sel_hi:[1,0,1]
	v_pk_fma_f32 v[12:13], v[210:211], v[224:225], v[12:13] op_sel:[0,1,0]
	v_pk_fma_f32 v[14:15], v[212:213], v[224:225], v[14:15] op_sel:[0,1,0]
	v_pk_fma_f32 v[16:17], v[210:211], v[226:227], v[16:17] op_sel_hi:[1,0,1]
	v_pk_fma_f32 v[18:19], v[212:213], v[226:227], v[18:19] op_sel_hi:[1,0,1]
	v_pk_fma_f32 v[20:21], v[210:211], v[226:227], v[20:21] op_sel:[0,1,0]
	v_pk_fma_f32 v[22:23], v[212:213], v[226:227], v[22:23] op_sel:[0,1,0]
	v_pk_fma_f32 v[24:25], v[210:211], v[228:229], v[24:25] op_sel_hi:[1,0,1]
	v_pk_fma_f32 v[26:27], v[212:213], v[228:229], v[26:27] op_sel_hi:[1,0,1]
	v_pk_fma_f32 v[28:29], v[210:211], v[228:229], v[28:29] op_sel:[0,1,0]
	v_pk_fma_f32 v[30:31], v[212:213], v[228:229], v[30:31] op_sel:[0,1,0]
	ds_read_b128 v[222:225], v32 offset:1792
	ds_read_b128 v[226:229], v32 offset:1808
	s_waitcnt lgkmcnt(2)
	v_pk_mul_f32 v[242:243], v[230:231], v[102:103] op_sel_hi:[0,1]
	v_pk_mul_f32 v[244:245], v[230:231], v[110:111] op_sel_hi:[0,1]
	v_pk_fma_f32 v[242:243], v[86:87], v[210:211], v[242:243]
	v_pk_fma_f32 v[244:245], v[86:87], v[212:213], v[244:245]
	v_pk_fma_f32 v[242:243], v[234:235], v[118:119], v[242:243] op_sel_hi:[0,1,1]
	v_pk_fma_f32 v[244:245], v[234:235], v[126:127], v[244:245] op_sel_hi:[0,1,1]
	v_pk_fma_f32 v[242:243], v[230:231], v[104:105], v[242:243] op_sel:[1,0,0]
	v_pk_fma_f32 v[244:245], v[230:231], v[112:113], v[244:245] op_sel:[1,0,0]
	v_pk_fma_f32 v[242:243], v[234:235], v[120:121], v[242:243] op_sel:[1,0,0]
	v_pk_fma_f32 v[244:245], v[234:235], v[128:129], v[244:245] op_sel:[1,0,0]
	v_pk_fma_f32 v[242:243], v[232:233], v[106:107], v[242:243] op_sel_hi:[0,1,1]
	v_pk_fma_f32 v[244:245], v[232:233], v[114:115], v[244:245] op_sel_hi:[0,1,1]
	v_pk_fma_f32 v[242:243], v[236:237], v[122:123], v[242:243] op_sel_hi:[0,1,1]
	v_pk_fma_f32 v[244:245], v[236:237], v[130:131], v[244:245] op_sel_hi:[0,1,1]
	v_pk_fma_f32 v[242:243], v[232:233], v[108:109], v[242:243] op_sel:[1,0,0]
	v_pk_fma_f32 v[244:245], v[232:233], v[116:117], v[244:245] op_sel:[1,0,0]
	v_pk_fma_f32 v[242:243], v[236:237], v[124:125], v[242:243] op_sel:[1,0,0]
	v_pk_fma_f32 v[244:245], v[236:237], v[132:133], v[244:245] op_sel:[1,0,0]
	ds_read_b128 v[230:233], v32 offset:18176
	ds_read_b128 v[234:237], v32 offset:18192
	global_store_dwordx4 v246, v[242:245], s[100:101] nt
	global_load_dwordx4 v[210:213], v246, s[98:99] nt
	s_add_u32 s100, s100, 0x2000
	s_addc_u32 s101, s101, 0
	s_add_u32 s98, s98, 0x2000
	s_addc_u32 s99, s99, 0
	s_waitcnt vmcnt(30)
	s_waitcnt lgkmcnt(2)
	v_pk_fma_f32 v[0:1], v[214:215], v[222:223], v[0:1] op_sel_hi:[1,0,1]
	v_pk_fma_f32 v[2:3], v[216:217], v[222:223], v[2:3] op_sel_hi:[1,0,1]
	v_pk_fma_f32 v[4:5], v[214:215], v[222:223], v[4:5] op_sel:[0,1,0]
	v_pk_fma_f32 v[6:7], v[216:217], v[222:223], v[6:7] op_sel:[0,1,0]
	v_pk_fma_f32 v[8:9], v[214:215], v[224:225], v[8:9] op_sel_hi:[1,0,1]
	v_pk_fma_f32 v[10:11], v[216:217], v[224:225], v[10:11] op_sel_hi:[1,0,1]
	v_pk_fma_f32 v[12:13], v[214:215], v[224:225], v[12:13] op_sel:[0,1,0]
	v_pk_fma_f32 v[14:15], v[216:217], v[224:225], v[14:15] op_sel:[0,1,0]
	v_pk_fma_f32 v[16:17], v[214:215], v[226:227], v[16:17] op_sel_hi:[1,0,1]
	v_pk_fma_f32 v[18:19], v[216:217], v[226:227], v[18:19] op_sel_hi:[1,0,1]
	v_pk_fma_f32 v[20:21], v[214:215], v[226:227], v[20:21] op_sel:[0,1,0]
	v_pk_fma_f32 v[22:23], v[216:217], v[226:227], v[22:23] op_sel:[0,1,0]
	v_pk_fma_f32 v[24:25], v[214:215], v[228:229], v[24:25] op_sel_hi:[1,0,1]
	v_pk_fma_f32 v[26:27], v[216:217], v[228:229], v[26:27] op_sel_hi:[1,0,1]
	v_pk_fma_f32 v[28:29], v[214:215], v[228:229], v[28:29] op_sel:[0,1,0]
	v_pk_fma_f32 v[30:31], v[216:217], v[228:229], v[30:31] op_sel:[0,1,0]
	ds_read_b128 v[222:225], v32 offset:1920
	ds_read_b128 v[226:229], v32 offset:1936
	s_waitcnt lgkmcnt(2)
	v_pk_mul_f32 v[238:239], v[230:231], v[102:103] op_sel_hi:[0,1]
	v_pk_mul_f32 v[240:241], v[230:231], v[110:111] op_sel_hi:[0,1]
	v_pk_fma_f32 v[238:239], v[86:87], v[214:215], v[238:239]
	v_pk_fma_f32 v[240:241], v[86:87], v[216:217], v[240:241]
	v_pk_fma_f32 v[238:239], v[234:235], v[118:119], v[238:239] op_sel_hi:[0,1,1]
	v_pk_fma_f32 v[240:241], v[234:235], v[126:127], v[240:241] op_sel_hi:[0,1,1]
	v_pk_fma_f32 v[238:239], v[230:231], v[104:105], v[238:239] op_sel:[1,0,0]
	v_pk_fma_f32 v[240:241], v[230:231], v[112:113], v[240:241] op_sel:[1,0,0]
	v_pk_fma_f32 v[238:239], v[234:235], v[120:121], v[238:239] op_sel:[1,0,0]
	v_pk_fma_f32 v[240:241], v[234:235], v[128:129], v[240:241] op_sel:[1,0,0]
	v_pk_fma_f32 v[238:239], v[232:233], v[106:107], v[238:239] op_sel_hi:[0,1,1]
	v_pk_fma_f32 v[240:241], v[232:233], v[114:115], v[240:241] op_sel_hi:[0,1,1]
	v_pk_fma_f32 v[238:239], v[236:237], v[122:123], v[238:239] op_sel_hi:[0,1,1]
	v_pk_fma_f32 v[240:241], v[236:237], v[130:131], v[240:241] op_sel_hi:[0,1,1]
	v_pk_fma_f32 v[238:239], v[232:233], v[108:109], v[238:239] op_sel:[1,0,0]
	v_pk_fma_f32 v[240:241], v[232:233], v[116:117], v[240:241] op_sel:[1,0,0]
	v_pk_fma_f32 v[238:239], v[236:237], v[124:125], v[238:239] op_sel:[1,0,0]
	v_pk_fma_f32 v[240:241], v[236:237], v[132:133], v[240:241] op_sel:[1,0,0]
	ds_read_b128 v[230:233], v32 offset:18304
	ds_read_b128 v[234:237], v32 offset:18320
	global_store_dwordx4 v246, v[238:241], s[100:101] nt
	global_load_dwordx4 v[214:217], v246, s[98:99] nt
	s_add_u32 s100, s100, 0x2000
	s_addc_u32 s101, s101, 0
	s_add_u32 s98, s98, 0x2000
	s_addc_u32 s99, s99, 0
	s_waitcnt vmcnt(30)
	s_waitcnt lgkmcnt(2)
	v_pk_fma_f32 v[0:1], v[218:219], v[222:223], v[0:1] op_sel_hi:[1,0,1]
	v_pk_fma_f32 v[2:3], v[220:221], v[222:223], v[2:3] op_sel_hi:[1,0,1]
	v_pk_fma_f32 v[4:5], v[218:219], v[222:223], v[4:5] op_sel:[0,1,0]
	v_pk_fma_f32 v[6:7], v[220:221], v[222:223], v[6:7] op_sel:[0,1,0]
	v_pk_fma_f32 v[8:9], v[218:219], v[224:225], v[8:9] op_sel_hi:[1,0,1]
	v_pk_fma_f32 v[10:11], v[220:221], v[224:225], v[10:11] op_sel_hi:[1,0,1]
	v_pk_fma_f32 v[12:13], v[218:219], v[224:225], v[12:13] op_sel:[0,1,0]
	v_pk_fma_f32 v[14:15], v[220:221], v[224:225], v[14:15] op_sel:[0,1,0]
	v_pk_fma_f32 v[16:17], v[218:219], v[226:227], v[16:17] op_sel_hi:[1,0,1]
	v_pk_fma_f32 v[18:19], v[220:221], v[226:227], v[18:19] op_sel_hi:[1,0,1]
	v_pk_fma_f32 v[20:21], v[218:219], v[226:227], v[20:21] op_sel:[0,1,0]
	v_pk_fma_f32 v[22:23], v[220:221], v[226:227], v[22:23] op_sel:[0,1,0]
	v_pk_fma_f32 v[24:25], v[218:219], v[228:229], v[24:25] op_sel_hi:[1,0,1]
	v_pk_fma_f32 v[26:27], v[220:221], v[228:229], v[26:27] op_sel_hi:[1,0,1]
	v_pk_fma_f32 v[28:29], v[218:219], v[228:229], v[28:29] op_sel:[0,1,0]
	v_pk_fma_f32 v[30:31], v[220:221], v[228:229], v[30:31] op_sel:[0,1,0]
	ds_read_b128 v[222:225], v32 offset:2048
	ds_read_b128 v[226:229], v32 offset:2064
	s_waitcnt lgkmcnt(2)
	v_pk_mul_f32 v[242:243], v[230:231], v[102:103] op_sel_hi:[0,1]
	v_pk_mul_f32 v[244:245], v[230:231], v[110:111] op_sel_hi:[0,1]
	v_pk_fma_f32 v[242:243], v[86:87], v[218:219], v[242:243]
	v_pk_fma_f32 v[244:245], v[86:87], v[220:221], v[244:245]
	v_pk_fma_f32 v[242:243], v[234:235], v[118:119], v[242:243] op_sel_hi:[0,1,1]
	v_pk_fma_f32 v[244:245], v[234:235], v[126:127], v[244:245] op_sel_hi:[0,1,1]
	v_pk_fma_f32 v[242:243], v[230:231], v[104:105], v[242:243] op_sel:[1,0,0]
	v_pk_fma_f32 v[244:245], v[230:231], v[112:113], v[244:245] op_sel:[1,0,0]
	v_pk_fma_f32 v[242:243], v[234:235], v[120:121], v[242:243] op_sel:[1,0,0]
	v_pk_fma_f32 v[244:245], v[234:235], v[128:129], v[244:245] op_sel:[1,0,0]
	v_pk_fma_f32 v[242:243], v[232:233], v[106:107], v[242:243] op_sel_hi:[0,1,1]
	v_pk_fma_f32 v[244:245], v[232:233], v[114:115], v[244:245] op_sel_hi:[0,1,1]
	v_pk_fma_f32 v[242:243], v[236:237], v[122:123], v[242:243] op_sel_hi:[0,1,1]
	v_pk_fma_f32 v[244:245], v[236:237], v[130:131], v[244:245] op_sel_hi:[0,1,1]
	v_pk_fma_f32 v[242:243], v[232:233], v[108:109], v[242:243] op_sel:[1,0,0]
	v_pk_fma_f32 v[244:245], v[232:233], v[116:117], v[244:245] op_sel:[1,0,0]
	v_pk_fma_f32 v[242:243], v[236:237], v[124:125], v[242:243] op_sel:[1,0,0]
	v_pk_fma_f32 v[244:245], v[236:237], v[132:133], v[244:245] op_sel:[1,0,0]
	ds_read_b128 v[230:233], v32 offset:18432
	ds_read_b128 v[234:237], v32 offset:18448
	global_store_dwordx4 v246, v[242:245], s[100:101] nt
	global_load_dwordx4 v[218:221], v246, s[98:99] nt
	s_add_u32 s100, s100, 0x2000
	s_addc_u32 s101, s101, 0
	s_add_u32 s98, s98, 0x2000
	s_addc_u32 s99, s99, 0
	v_add_u32_e32 v32, 0x800, v32
	s_add_u32 vcc_lo, vcc_lo, 1
	s_cmp_lt_u32 vcc_lo, 6
	s_cbranch_scc1 .Lsstream_b_loop
	s_waitcnt vmcnt(30)
	s_waitcnt lgkmcnt(2)
	v_pk_fma_f32 v[0:1], v[134:135], v[222:223], v[0:1] op_sel_hi:[1,0,1]
	v_pk_fma_f32 v[2:3], v[136:137], v[222:223], v[2:3] op_sel_hi:[1,0,1]
	v_pk_fma_f32 v[4:5], v[134:135], v[222:223], v[4:5] op_sel:[0,1,0]
	v_pk_fma_f32 v[6:7], v[136:137], v[222:223], v[6:7] op_sel:[0,1,0]
	v_pk_fma_f32 v[8:9], v[134:135], v[224:225], v[8:9] op_sel_hi:[1,0,1]
	v_pk_fma_f32 v[10:11], v[136:137], v[224:225], v[10:11] op_sel_hi:[1,0,1]
	v_pk_fma_f32 v[12:13], v[134:135], v[224:225], v[12:13] op_sel:[0,1,0]
	v_pk_fma_f32 v[14:15], v[136:137], v[224:225], v[14:15] op_sel:[0,1,0]
	v_pk_fma_f32 v[16:17], v[134:135], v[226:227], v[16:17] op_sel_hi:[1,0,1]
	v_pk_fma_f32 v[18:19], v[136:137], v[226:227], v[18:19] op_sel_hi:[1,0,1]
	v_pk_fma_f32 v[20:21], v[134:135], v[226:227], v[20:21] op_sel:[0,1,0]
	v_pk_fma_f32 v[22:23], v[136:137], v[226:227], v[22:23] op_sel:[0,1,0]
	v_pk_fma_f32 v[24:25], v[134:135], v[228:229], v[24:25] op_sel_hi:[1,0,1]
	v_pk_fma_f32 v[26:27], v[136:137], v[228:229], v[26:27] op_sel_hi:[1,0,1]
	v_pk_fma_f32 v[28:29], v[134:135], v[228:229], v[28:29] op_sel:[0,1,0]
	v_pk_fma_f32 v[30:31], v[136:137], v[228:229], v[30:31] op_sel:[0,1,0]
	ds_read_b128 v[222:225], v32 offset:128
	ds_read_b128 v[226:229], v32 offset:144
	s_waitcnt lgkmcnt(2)
	v_pk_mul_f32 v[238:239], v[230:231], v[102:103] op_sel_hi:[0,1]
	v_pk_mul_f32 v[240:241], v[230:231], v[110:111] op_sel_hi:[0,1]
	v_pk_fma_f32 v[238:239], v[86:87], v[134:135], v[238:239]
	v_pk_fma_f32 v[240:241], v[86:87], v[136:137], v[240:241]
	v_pk_fma_f32 v[238:239], v[234:235], v[118:119], v[238:239] op_sel_hi:[0,1,1]
	v_pk_fma_f32 v[240:241], v[234:235], v[126:127], v[240:241] op_sel_hi:[0,1,1]
	v_pk_fma_f32 v[238:239], v[230:231], v[104:105], v[238:239] op_sel:[1,0,0]
	v_pk_fma_f32 v[240:241], v[230:231], v[112:113], v[240:241] op_sel:[1,0,0]
	v_pk_fma_f32 v[238:239], v[234:235], v[120:121], v[238:239] op_sel:[1,0,0]
	v_pk_fma_f32 v[240:241], v[234:235], v[128:129], v[240:241] op_sel:[1,0,0]
	v_pk_fma_f32 v[238:239], v[232:233], v[106:107], v[238:239] op_sel_hi:[0,1,1]
	v_pk_fma_f32 v[240:241], v[232:233], v[114:115], v[240:241] op_sel_hi:[0,1,1]
	v_pk_fma_f32 v[238:239], v[236:237], v[122:123], v[238:239] op_sel_hi:[0,1,1]
	v_pk_fma_f32 v[240:241], v[236:237], v[130:131], v[240:241] op_sel_hi:[0,1,1]
	v_pk_fma_f32 v[238:239], v[232:233], v[108:109], v[238:239] op_sel:[1,0,0]
	v_pk_fma_f32 v[240:241], v[232:233], v[116:117], v[240:241] op_sel:[1,0,0]
	v_pk_fma_f32 v[238:239], v[236:237], v[124:125], v[238:239] op_sel:[1,0,0]
	v_pk_fma_f32 v[240:241], v[236:237], v[132:133], v[240:241] op_sel:[1,0,0]
	ds_read_b128 v[230:233], v32 offset:16512
	ds_read_b128 v[234:237], v32 offset:16528
	global_store_dwordx4 v246, v[238:241], s[100:101] nt
	s_add_u32 s100, s100, 0x2000
	s_addc_u32 s101, s101, 0
	s_waitcnt vmcnt(29)
	s_waitcnt lgkmcnt(2)
	v_pk_fma_f32 v[0:1], v[138:139], v[222:223], v[0:1] op_sel_hi:[1,0,1]
	v_pk_fma_f32 v[2:3], v[140:141], v[222:223], v[2:3] op_sel_hi:[1,0,1]
	v_pk_fma_f32 v[4:5], v[138:139], v[222:223], v[4:5] op_sel:[0,1,0]
	v_pk_fma_f32 v[6:7], v[140:141], v[222:223], v[6:7] op_sel:[0,1,0]
	v_pk_fma_f32 v[8:9], v[138:139], v[224:225], v[8:9] op_sel_hi:[1,0,1]
	v_pk_fma_f32 v[10:11], v[140:141], v[224:225], v[10:11] op_sel_hi:[1,0,1]
	v_pk_fma_f32 v[12:13], v[138:139], v[224:225], v[12:13] op_sel:[0,1,0]
	v_pk_fma_f32 v[14:15], v[140:141], v[224:225], v[14:15] op_sel:[0,1,0]
	v_pk_fma_f32 v[16:17], v[138:139], v[226:227], v[16:17] op_sel_hi:[1,0,1]
	v_pk_fma_f32 v[18:19], v[140:141], v[226:227], v[18:19] op_sel_hi:[1,0,1]
	v_pk_fma_f32 v[20:21], v[138:139], v[226:227], v[20:21] op_sel:[0,1,0]
	v_pk_fma_f32 v[22:23], v[140:141], v[226:227], v[22:23] op_sel:[0,1,0]
	v_pk_fma_f32 v[24:25], v[138:139], v[228:229], v[24:25] op_sel_hi:[1,0,1]
	v_pk_fma_f32 v[26:27], v[140:141], v[228:229], v[26:27] op_sel_hi:[1,0,1]
	v_pk_fma_f32 v[28:29], v[138:139], v[228:229], v[28:29] op_sel:[0,1,0]
	v_pk_fma_f32 v[30:31], v[140:141], v[228:229], v[30:31] op_sel:[0,1,0]
	ds_read_b128 v[222:225], v32 offset:256
	ds_read_b128 v[226:229], v32 offset:272
	s_waitcnt lgkmcnt(2)
	v_pk_mul_f32 v[242:243], v[230:231], v[102:103] op_sel_hi:[0,1]
	v_pk_mul_f32 v[244:245], v[230:231], v[110:111] op_sel_hi:[0,1]
	v_pk_fma_f32 v[242:243], v[86:87], v[138:139], v[242:243]
	v_pk_fma_f32 v[244:245], v[86:87], v[140:141], v[244:245]
	v_pk_fma_f32 v[242:243], v[234:235], v[118:119], v[242:243] op_sel_hi:[0,1,1]
	v_pk_fma_f32 v[244:245], v[234:235], v[126:127], v[244:245] op_sel_hi:[0,1,1]
	v_pk_fma_f32 v[242:243], v[230:231], v[104:105], v[242:243] op_sel:[1,0,0]
	v_pk_fma_f32 v[244:245], v[230:231], v[112:113], v[244:245] op_sel:[1,0,0]
	v_pk_fma_f32 v[242:243], v[234:235], v[120:121], v[242:243] op_sel:[1,0,0]
	v_pk_fma_f32 v[244:245], v[234:235], v[128:129], v[244:245] op_sel:[1,0,0]
	v_pk_fma_f32 v[242:243], v[232:233], v[106:107], v[242:243] op_sel_hi:[0,1,1]
	v_pk_fma_f32 v[244:245], v[232:233], v[114:115], v[244:245] op_sel_hi:[0,1,1]
	v_pk_fma_f32 v[242:243], v[236:237], v[122:123], v[242:243] op_sel_hi:[0,1,1]
	v_pk_fma_f32 v[244:245], v[236:237], v[130:131], v[244:245] op_sel_hi:[0,1,1]
	v_pk_fma_f32 v[242:243], v[232:233], v[108:109], v[242:243] op_sel:[1,0,0]
	v_pk_fma_f32 v[244:245], v[232:233], v[116:117], v[244:245] op_sel:[1,0,0]
	v_pk_fma_f32 v[242:243], v[236:237], v[124:125], v[242:243] op_sel:[1,0,0]
	v_pk_fma_f32 v[244:245], v[236:237], v[132:133], v[244:245] op_sel:[1,0,0]
	ds_read_b128 v[230:233], v32 offset:16640
	ds_read_b128 v[234:237], v32 offset:16656
	global_store_dwordx4 v246, v[242:245], s[100:101] nt
	s_add_u32 s100, s100, 0x2000
	s_addc_u32 s101, s101, 0
	s_waitcnt vmcnt(28)
	s_waitcnt lgkmcnt(2)
	v_pk_fma_f32 v[0:1], v[142:143], v[222:223], v[0:1] op_sel_hi:[1,0,1]
	v_pk_fma_f32 v[2:3], v[144:145], v[222:223], v[2:3] op_sel_hi:[1,0,1]
	v_pk_fma_f32 v[4:5], v[142:143], v[222:223], v[4:5] op_sel:[0,1,0]
	v_pk_fma_f32 v[6:7], v[144:145], v[222:223], v[6:7] op_sel:[0,1,0]
	v_pk_fma_f32 v[8:9], v[142:143], v[224:225], v[8:9] op_sel_hi:[1,0,1]
	v_pk_fma_f32 v[10:11], v[144:145], v[224:225], v[10:11] op_sel_hi:[1,0,1]
	v_pk_fma_f32 v[12:13], v[142:143], v[224:225], v[12:13] op_sel:[0,1,0]
	v_pk_fma_f32 v[14:15], v[144:145], v[224:225], v[14:15] op_sel:[0,1,0]
	v_pk_fma_f32 v[16:17], v[142:143], v[226:227], v[16:17] op_sel_hi:[1,0,1]
	v_pk_fma_f32 v[18:19], v[144:145], v[226:227], v[18:19] op_sel_hi:[1,0,1]
	v_pk_fma_f32 v[20:21], v[142:143], v[226:227], v[20:21] op_sel:[0,1,0]
	v_pk_fma_f32 v[22:23], v[144:145], v[226:227], v[22:23] op_sel:[0,1,0]
	v_pk_fma_f32 v[24:25], v[142:143], v[228:229], v[24:25] op_sel_hi:[1,0,1]
	v_pk_fma_f32 v[26:27], v[144:145], v[228:229], v[26:27] op_sel_hi:[1,0,1]
	v_pk_fma_f32 v[28:29], v[142:143], v[228:229], v[28:29] op_sel:[0,1,0]
	v_pk_fma_f32 v[30:31], v[144:145], v[228:229], v[30:31] op_sel:[0,1,0]
	ds_read_b128 v[222:225], v32 offset:384
	ds_read_b128 v[226:229], v32 offset:400
	s_waitcnt lgkmcnt(2)
	v_pk_mul_f32 v[238:239], v[230:231], v[102:103] op_sel_hi:[0,1]
	v_pk_mul_f32 v[240:241], v[230:231], v[110:111] op_sel_hi:[0,1]
	v_pk_fma_f32 v[238:239], v[86:87], v[142:143], v[238:239]
	v_pk_fma_f32 v[240:241], v[86:87], v[144:145], v[240:241]
	v_pk_fma_f32 v[238:239], v[234:235], v[118:119], v[238:239] op_sel_hi:[0,1,1]
	v_pk_fma_f32 v[240:241], v[234:235], v[126:127], v[240:241] op_sel_hi:[0,1,1]
	v_pk_fma_f32 v[238:239], v[230:231], v[104:105], v[238:239] op_sel:[1,0,0]
	v_pk_fma_f32 v[240:241], v[230:231], v[112:113], v[240:241] op_sel:[1,0,0]
	v_pk_fma_f32 v[238:239], v[234:235], v[120:121], v[238:239] op_sel:[1,0,0]
	v_pk_fma_f32 v[240:241], v[234:235], v[128:129], v[240:241] op_sel:[1,0,0]
	v_pk_fma_f32 v[238:239], v[232:233], v[106:107], v[238:239] op_sel_hi:[0,1,1]
	v_pk_fma_f32 v[240:241], v[232:233], v[114:115], v[240:241] op_sel_hi:[0,1,1]
	v_pk_fma_f32 v[238:239], v[236:237], v[122:123], v[238:239] op_sel_hi:[0,1,1]
	v_pk_fma_f32 v[240:241], v[236:237], v[130:131], v[240:241] op_sel_hi:[0,1,1]
	v_pk_fma_f32 v[238:239], v[232:233], v[108:109], v[238:239] op_sel:[1,0,0]
	v_pk_fma_f32 v[240:241], v[232:233], v[116:117], v[240:241] op_sel:[1,0,0]
	v_pk_fma_f32 v[238:239], v[236:237], v[124:125], v[238:239] op_sel:[1,0,0]
	v_pk_fma_f32 v[240:241], v[236:237], v[132:133], v[240:241] op_sel:[1,0,0]
	ds_read_b128 v[230:233], v32 offset:16768
	ds_read_b128 v[234:237], v32 offset:16784
	global_store_dwordx4 v246, v[238:241], s[100:101] nt
	s_add_u32 s100, s100, 0x2000
	s_addc_u32 s101, s101, 0
	s_waitcnt vmcnt(27)
	s_waitcnt lgkmcnt(2)
	v_pk_fma_f32 v[0:1], v[158:159], v[222:223], v[0:1] op_sel_hi:[1,0,1]
	v_pk_fma_f32 v[2:3], v[160:161], v[222:223], v[2:3] op_sel_hi:[1,0,1]
	v_pk_fma_f32 v[4:5], v[158:159], v[222:223], v[4:5] op_sel:[0,1,0]
	v_pk_fma_f32 v[6:7], v[160:161], v[222:223], v[6:7] op_sel:[0,1,0]
	v_pk_fma_f32 v[8:9], v[158:159], v[224:225], v[8:9] op_sel_hi:[1,0,1]
	v_pk_fma_f32 v[10:11], v[160:161], v[224:225], v[10:11] op_sel_hi:[1,0,1]
	v_pk_fma_f32 v[12:13], v[158:159], v[224:225], v[12:13] op_sel:[0,1,0]
	v_pk_fma_f32 v[14:15], v[160:161], v[224:225], v[14:15] op_sel:[0,1,0]
	v_pk_fma_f32 v[16:17], v[158:159], v[226:227], v[16:17] op_sel_hi:[1,0,1]
	v_pk_fma_f32 v[18:19], v[160:161], v[226:227], v[18:19] op_sel_hi:[1,0,1]
	v_pk_fma_f32 v[20:21], v[158:159], v[226:227], v[20:21] op_sel:[0,1,0]
	v_pk_fma_f32 v[22:23], v[160:161], v[226:227], v[22:23] op_sel:[0,1,0]
	v_pk_fma_f32 v[24:25], v[158:159], v[228:229], v[24:25] op_sel_hi:[1,0,1]
	v_pk_fma_f32 v[26:27], v[160:161], v[228:229], v[26:27] op_sel_hi:[1,0,1]
	v_pk_fma_f32 v[28:29], v[158:159], v[228:229], v[28:29] op_sel:[0,1,0]
	v_pk_fma_f32 v[30:31], v[160:161], v[228:229], v[30:31] op_sel:[0,1,0]
	ds_read_b128 v[222:225], v32 offset:512
	ds_read_b128 v[226:229], v32 offset:528
	s_waitcnt lgkmcnt(2)
	v_pk_mul_f32 v[242:243], v[230:231], v[102:103] op_sel_hi:[0,1]
	v_pk_mul_f32 v[244:245], v[230:231], v[110:111] op_sel_hi:[0,1]
	v_pk_fma_f32 v[242:243], v[86:87], v[158:159], v[242:243]
	v_pk_fma_f32 v[244:245], v[86:87], v[160:161], v[244:245]
	v_pk_fma_f32 v[242:243], v[234:235], v[118:119], v[242:243] op_sel_hi:[0,1,1]
	v_pk_fma_f32 v[244:245], v[234:235], v[126:127], v[244:245] op_sel_hi:[0,1,1]
	v_pk_fma_f32 v[242:243], v[230:231], v[104:105], v[242:243] op_sel:[1,0,0]
	v_pk_fma_f32 v[244:245], v[230:231], v[112:113], v[244:245] op_sel:[1,0,0]
	v_pk_fma_f32 v[242:243], v[234:235], v[120:121], v[242:243] op_sel:[1,0,0]
	v_pk_fma_f32 v[244:245], v[234:235], v[128:129], v[244:245] op_sel:[1,0,0]
	v_pk_fma_f32 v[242:243], v[232:233], v[106:107], v[242:243] op_sel_hi:[0,1,1]
	v_pk_fma_f32 v[244:245], v[232:233], v[114:115], v[244:245] op_sel_hi:[0,1,1]
	v_pk_fma_f32 v[242:243], v[236:237], v[122:123], v[242:243] op_sel_hi:[0,1,1]
	v_pk_fma_f32 v[244:245], v[236:237], v[130:131], v[244:245] op_sel_hi:[0,1,1]
	v_pk_fma_f32 v[242:243], v[232:233], v[108:109], v[242:243] op_sel:[1,0,0]
	v_pk_fma_f32 v[244:245], v[232:233], v[116:117], v[244:245] op_sel:[1,0,0]
	v_pk_fma_f32 v[242:243], v[236:237], v[124:125], v[242:243] op_sel:[1,0,0]
	v_pk_fma_f32 v[244:245], v[236:237], v[132:133], v[244:245] op_sel:[1,0,0]
	ds_read_b128 v[230:233], v32 offset:16896
	ds_read_b128 v[234:237], v32 offset:16912
	global_store_dwordx4 v246, v[242:245], s[100:101] nt
	s_add_u32 s100, s100, 0x2000
	s_addc_u32 s101, s101, 0
	s_waitcnt vmcnt(26)
	s_waitcnt lgkmcnt(2)
	v_pk_fma_f32 v[0:1], v[162:163], v[222:223], v[0:1] op_sel_hi:[1,0,1]
	v_pk_fma_f32 v[2:3], v[164:165], v[222:223], v[2:3] op_sel_hi:[1,0,1]
	v_pk_fma_f32 v[4:5], v[162:163], v[222:223], v[4:5] op_sel:[0,1,0]
	v_pk_fma_f32 v[6:7], v[164:165], v[222:223], v[6:7] op_sel:[0,1,0]
	v_pk_fma_f32 v[8:9], v[162:163], v[224:225], v[8:9] op_sel_hi:[1,0,1]
	v_pk_fma_f32 v[10:11], v[164:165], v[224:225], v[10:11] op_sel_hi:[1,0,1]
	v_pk_fma_f32 v[12:13], v[162:163], v[224:225], v[12:13] op_sel:[0,1,0]
	v_pk_fma_f32 v[14:15], v[164:165], v[224:225], v[14:15] op_sel:[0,1,0]
	v_pk_fma_f32 v[16:17], v[162:163], v[226:227], v[16:17] op_sel_hi:[1,0,1]
	v_pk_fma_f32 v[18:19], v[164:165], v[226:227], v[18:19] op_sel_hi:[1,0,1]
	v_pk_fma_f32 v[20:21], v[162:163], v[226:227], v[20:21] op_sel:[0,1,0]
	v_pk_fma_f32 v[22:23], v[164:165], v[226:227], v[22:23] op_sel:[0,1,0]
	v_pk_fma_f32 v[24:25], v[162:163], v[228:229], v[24:25] op_sel_hi:[1,0,1]
	v_pk_fma_f32 v[26:27], v[164:165], v[228:229], v[26:27] op_sel_hi:[1,0,1]
	v_pk_fma_f32 v[28:29], v[162:163], v[228:229], v[28:29] op_sel:[0,1,0]
	v_pk_fma_f32 v[30:31], v[164:165], v[228:229], v[30:31] op_sel:[0,1,0]
	ds_read_b128 v[222:225], v32 offset:640
	ds_read_b128 v[226:229], v32 offset:656
	s_waitcnt lgkmcnt(2)
	v_pk_mul_f32 v[238:239], v[230:231], v[102:103] op_sel_hi:[0,1]
	v_pk_mul_f32 v[240:241], v[230:231], v[110:111] op_sel_hi:[0,1]
	v_pk_fma_f32 v[238:239], v[86:87], v[162:163], v[238:239]
	v_pk_fma_f32 v[240:241], v[86:87], v[164:165], v[240:241]
	v_pk_fma_f32 v[238:239], v[234:235], v[118:119], v[238:239] op_sel_hi:[0,1,1]
	v_pk_fma_f32 v[240:241], v[234:235], v[126:127], v[240:241] op_sel_hi:[0,1,1]
	v_pk_fma_f32 v[238:239], v[230:231], v[104:105], v[238:239] op_sel:[1,0,0]
	v_pk_fma_f32 v[240:241], v[230:231], v[112:113], v[240:241] op_sel:[1,0,0]
	v_pk_fma_f32 v[238:239], v[234:235], v[120:121], v[238:239] op_sel:[1,0,0]
	v_pk_fma_f32 v[240:241], v[234:235], v[128:129], v[240:241] op_sel:[1,0,0]
	v_pk_fma_f32 v[238:239], v[232:233], v[106:107], v[238:239] op_sel_hi:[0,1,1]
	v_pk_fma_f32 v[240:241], v[232:233], v[114:115], v[240:241] op_sel_hi:[0,1,1]
	v_pk_fma_f32 v[238:239], v[236:237], v[122:123], v[238:239] op_sel_hi:[0,1,1]
	v_pk_fma_f32 v[240:241], v[236:237], v[130:131], v[240:241] op_sel_hi:[0,1,1]
	v_pk_fma_f32 v[238:239], v[232:233], v[108:109], v[238:239] op_sel:[1,0,0]
	v_pk_fma_f32 v[240:241], v[232:233], v[116:117], v[240:241] op_sel:[1,0,0]
	v_pk_fma_f32 v[238:239], v[236:237], v[124:125], v[238:239] op_sel:[1,0,0]
	v_pk_fma_f32 v[240:241], v[236:237], v[132:133], v[240:241] op_sel:[1,0,0]
	ds_read_b128 v[230:233], v32 offset:17024
	ds_read_b128 v[234:237], v32 offset:17040
	global_store_dwordx4 v246, v[238:241], s[100:101] nt
	s_add_u32 s100, s100, 0x2000
	s_addc_u32 s101, s101, 0
	s_waitcnt vmcnt(25)
	s_waitcnt lgkmcnt(2)
	v_pk_fma_f32 v[0:1], v[166:167], v[222:223], v[0:1] op_sel_hi:[1,0,1]
	v_pk_fma_f32 v[2:3], v[168:169], v[222:223], v[2:3] op_sel_hi:[1,0,1]
	v_pk_fma_f32 v[4:5], v[166:167], v[222:223], v[4:5] op_sel:[0,1,0]
	v_pk_fma_f32 v[6:7], v[168:169], v[222:223], v[6:7] op_sel:[0,1,0]
	v_pk_fma_f32 v[8:9], v[166:167], v[224:225], v[8:9] op_sel_hi:[1,0,1]
	v_pk_fma_f32 v[10:11], v[168:169], v[224:225], v[10:11] op_sel_hi:[1,0,1]
	v_pk_fma_f32 v[12:13], v[166:167], v[224:225], v[12:13] op_sel:[0,1,0]
	v_pk_fma_f32 v[14:15], v[168:169], v[224:225], v[14:15] op_sel:[0,1,0]
	v_pk_fma_f32 v[16:17], v[166:167], v[226:227], v[16:17] op_sel_hi:[1,0,1]
	v_pk_fma_f32 v[18:19], v[168:169], v[226:227], v[18:19] op_sel_hi:[1,0,1]
	v_pk_fma_f32 v[20:21], v[166:167], v[226:227], v[20:21] op_sel:[0,1,0]
	v_pk_fma_f32 v[22:23], v[168:169], v[226:227], v[22:23] op_sel:[0,1,0]
	v_pk_fma_f32 v[24:25], v[166:167], v[228:229], v[24:25] op_sel_hi:[1,0,1]
	v_pk_fma_f32 v[26:27], v[168:169], v[228:229], v[26:27] op_sel_hi:[1,0,1]
	v_pk_fma_f32 v[28:29], v[166:167], v[228:229], v[28:29] op_sel:[0,1,0]
	v_pk_fma_f32 v[30:31], v[168:169], v[228:229], v[30:31] op_sel:[0,1,0]
	ds_read_b128 v[222:225], v32 offset:768
	ds_read_b128 v[226:229], v32 offset:784
	s_waitcnt lgkmcnt(2)
	v_pk_mul_f32 v[242:243], v[230:231], v[102:103] op_sel_hi:[0,1]
	v_pk_mul_f32 v[244:245], v[230:231], v[110:111] op_sel_hi:[0,1]
	v_pk_fma_f32 v[242:243], v[86:87], v[166:167], v[242:243]
	v_pk_fma_f32 v[244:245], v[86:87], v[168:169], v[244:245]
	v_pk_fma_f32 v[242:243], v[234:235], v[118:119], v[242:243] op_sel_hi:[0,1,1]
	v_pk_fma_f32 v[244:245], v[234:235], v[126:127], v[244:245] op_sel_hi:[0,1,1]
	v_pk_fma_f32 v[242:243], v[230:231], v[104:105], v[242:243] op_sel:[1,0,0]
	v_pk_fma_f32 v[244:245], v[230:231], v[112:113], v[244:245] op_sel:[1,0,0]
	v_pk_fma_f32 v[242:243], v[234:235], v[120:121], v[242:243] op_sel:[1,0,0]
	v_pk_fma_f32 v[244:245], v[234:235], v[128:129], v[244:245] op_sel:[1,0,0]
	v_pk_fma_f32 v[242:243], v[232:233], v[106:107], v[242:243] op_sel_hi:[0,1,1]
	v_pk_fma_f32 v[244:245], v[232:233], v[114:115], v[244:245] op_sel_hi:[0,1,1]
	v_pk_fma_f32 v[242:243], v[236:237], v[122:123], v[242:243] op_sel_hi:[0,1,1]
	v_pk_fma_f32 v[244:245], v[236:237], v[130:131], v[244:245] op_sel_hi:[0,1,1]
	v_pk_fma_f32 v[242:243], v[232:233], v[108:109], v[242:243] op_sel:[1,0,0]
	v_pk_fma_f32 v[244:245], v[232:233], v[116:117], v[244:245] op_sel:[1,0,0]
	v_pk_fma_f32 v[242:243], v[236:237], v[124:125], v[242:243] op_sel:[1,0,0]
	v_pk_fma_f32 v[244:245], v[236:237], v[132:133], v[244:245] op_sel:[1,0,0]
	ds_read_b128 v[230:233], v32 offset:17152
	ds_read_b128 v[234:237], v32 offset:17168
	global_store_dwordx4 v246, v[242:245], s[100:101] nt
	s_add_u32 s100, s100, 0x2000
	s_addc_u32 s101, s101, 0
	s_waitcnt vmcnt(24)
	s_waitcnt lgkmcnt(2)
	v_pk_fma_f32 v[0:1], v[170:171], v[222:223], v[0:1] op_sel_hi:[1,0,1]
	v_pk_fma_f32 v[2:3], v[172:173], v[222:223], v[2:3] op_sel_hi:[1,0,1]
	v_pk_fma_f32 v[4:5], v[170:171], v[222:223], v[4:5] op_sel:[0,1,0]
	v_pk_fma_f32 v[6:7], v[172:173], v[222:223], v[6:7] op_sel:[0,1,0]
	v_pk_fma_f32 v[8:9], v[170:171], v[224:225], v[8:9] op_sel_hi:[1,0,1]
	v_pk_fma_f32 v[10:11], v[172:173], v[224:225], v[10:11] op_sel_hi:[1,0,1]
	v_pk_fma_f32 v[12:13], v[170:171], v[224:225], v[12:13] op_sel:[0,1,0]
	v_pk_fma_f32 v[14:15], v[172:173], v[224:225], v[14:15] op_sel:[0,1,0]
	v_pk_fma_f32 v[16:17], v[170:171], v[226:227], v[16:17] op_sel_hi:[1,0,1]
	v_pk_fma_f32 v[18:19], v[172:173], v[226:227], v[18:19] op_sel_hi:[1,0,1]
	v_pk_fma_f32 v[20:21], v[170:171], v[226:227], v[20:21] op_sel:[0,1,0]
	v_pk_fma_f32 v[22:23], v[172:173], v[226:227], v[22:23] op_sel:[0,1,0]
	v_pk_fma_f32 v[24:25], v[170:171], v[228:229], v[24:25] op_sel_hi:[1,0,1]
	v_pk_fma_f32 v[26:27], v[172:173], v[228:229], v[26:27] op_sel_hi:[1,0,1]
	v_pk_fma_f32 v[28:29], v[170:171], v[228:229], v[28:29] op_sel:[0,1,0]
	v_pk_fma_f32 v[30:31], v[172:173], v[228:229], v[30:31] op_sel:[0,1,0]
	ds_read_b128 v[222:225], v32 offset:896
	ds_read_b128 v[226:229], v32 offset:912
	s_waitcnt lgkmcnt(2)
	v_pk_mul_f32 v[238:239], v[230:231], v[102:103] op_sel_hi:[0,1]
	v_pk_mul_f32 v[240:241], v[230:231], v[110:111] op_sel_hi:[0,1]
	v_pk_fma_f32 v[238:239], v[86:87], v[170:171], v[238:239]
	v_pk_fma_f32 v[240:241], v[86:87], v[172:173], v[240:241]
	v_pk_fma_f32 v[238:239], v[234:235], v[118:119], v[238:239] op_sel_hi:[0,1,1]
	v_pk_fma_f32 v[240:241], v[234:235], v[126:127], v[240:241] op_sel_hi:[0,1,1]
	v_pk_fma_f32 v[238:239], v[230:231], v[104:105], v[238:239] op_sel:[1,0,0]
	v_pk_fma_f32 v[240:241], v[230:231], v[112:113], v[240:241] op_sel:[1,0,0]
	v_pk_fma_f32 v[238:239], v[234:235], v[120:121], v[238:239] op_sel:[1,0,0]
	v_pk_fma_f32 v[240:241], v[234:235], v[128:129], v[240:241] op_sel:[1,0,0]
	v_pk_fma_f32 v[238:239], v[232:233], v[106:107], v[238:239] op_sel_hi:[0,1,1]
	v_pk_fma_f32 v[240:241], v[232:233], v[114:115], v[240:241] op_sel_hi:[0,1,1]
	v_pk_fma_f32 v[238:239], v[236:237], v[122:123], v[238:239] op_sel_hi:[0,1,1]
	v_pk_fma_f32 v[240:241], v[236:237], v[130:131], v[240:241] op_sel_hi:[0,1,1]
	v_pk_fma_f32 v[238:239], v[232:233], v[108:109], v[238:239] op_sel:[1,0,0]
	v_pk_fma_f32 v[240:241], v[232:233], v[116:117], v[240:241] op_sel:[1,0,0]
	v_pk_fma_f32 v[238:239], v[236:237], v[124:125], v[238:239] op_sel:[1,0,0]
	v_pk_fma_f32 v[240:241], v[236:237], v[132:133], v[240:241] op_sel:[1,0,0]
	ds_read_b128 v[230:233], v32 offset:17280
	ds_read_b128 v[234:237], v32 offset:17296
	global_store_dwordx4 v246, v[238:241], s[100:101] nt
	s_add_u32 s100, s100, 0x2000
	s_addc_u32 s101, s101, 0
	s_waitcnt vmcnt(23)
	s_waitcnt lgkmcnt(2)
	v_pk_fma_f32 v[0:1], v[174:175], v[222:223], v[0:1] op_sel_hi:[1,0,1]
	v_pk_fma_f32 v[2:3], v[176:177], v[222:223], v[2:3] op_sel_hi:[1,0,1]
	v_pk_fma_f32 v[4:5], v[174:175], v[222:223], v[4:5] op_sel:[0,1,0]
	v_pk_fma_f32 v[6:7], v[176:177], v[222:223], v[6:7] op_sel:[0,1,0]
	v_pk_fma_f32 v[8:9], v[174:175], v[224:225], v[8:9] op_sel_hi:[1,0,1]
	v_pk_fma_f32 v[10:11], v[176:177], v[224:225], v[10:11] op_sel_hi:[1,0,1]
	v_pk_fma_f32 v[12:13], v[174:175], v[224:225], v[12:13] op_sel:[0,1,0]
	v_pk_fma_f32 v[14:15], v[176:177], v[224:225], v[14:15] op_sel:[0,1,0]
	v_pk_fma_f32 v[16:17], v[174:175], v[226:227], v[16:17] op_sel_hi:[1,0,1]
	v_pk_fma_f32 v[18:19], v[176:177], v[226:227], v[18:19] op_sel_hi:[1,0,1]
	v_pk_fma_f32 v[20:21], v[174:175], v[226:227], v[20:21] op_sel:[0,1,0]
	v_pk_fma_f32 v[22:23], v[176:177], v[226:227], v[22:23] op_sel:[0,1,0]
	v_pk_fma_f32 v[24:25], v[174:175], v[228:229], v[24:25] op_sel_hi:[1,0,1]
	v_pk_fma_f32 v[26:27], v[176:177], v[228:229], v[26:27] op_sel_hi:[1,0,1]
	v_pk_fma_f32 v[28:29], v[174:175], v[228:229], v[28:29] op_sel:[0,1,0]
	v_pk_fma_f32 v[30:31], v[176:177], v[228:229], v[30:31] op_sel:[0,1,0]
	ds_read_b128 v[222:225], v32 offset:1024
	ds_read_b128 v[226:229], v32 offset:1040
	s_waitcnt lgkmcnt(2)
	v_pk_mul_f32 v[242:243], v[230:231], v[102:103] op_sel_hi:[0,1]
	v_pk_mul_f32 v[244:245], v[230:231], v[110:111] op_sel_hi:[0,1]
	v_pk_fma_f32 v[242:243], v[86:87], v[174:175], v[242:243]
	v_pk_fma_f32 v[244:245], v[86:87], v[176:177], v[244:245]
	v_pk_fma_f32 v[242:243], v[234:235], v[118:119], v[242:243] op_sel_hi:[0,1,1]
	v_pk_fma_f32 v[244:245], v[234:235], v[126:127], v[244:245] op_sel_hi:[0,1,1]
	v_pk_fma_f32 v[242:243], v[230:231], v[104:105], v[242:243] op_sel:[1,0,0]
	v_pk_fma_f32 v[244:245], v[230:231], v[112:113], v[244:245] op_sel:[1,0,0]
	v_pk_fma_f32 v[242:243], v[234:235], v[120:121], v[242:243] op_sel:[1,0,0]
	v_pk_fma_f32 v[244:245], v[234:235], v[128:129], v[244:245] op_sel:[1,0,0]
	v_pk_fma_f32 v[242:243], v[232:233], v[106:107], v[242:243] op_sel_hi:[0,1,1]
	v_pk_fma_f32 v[244:245], v[232:233], v[114:115], v[244:245] op_sel_hi:[0,1,1]
	v_pk_fma_f32 v[242:243], v[236:237], v[122:123], v[242:243] op_sel_hi:[0,1,1]
	v_pk_fma_f32 v[244:245], v[236:237], v[130:131], v[244:245] op_sel_hi:[0,1,1]
	v_pk_fma_f32 v[242:243], v[232:233], v[108:109], v[242:243] op_sel:[1,0,0]
	v_pk_fma_f32 v[244:245], v[232:233], v[116:117], v[244:245] op_sel:[1,0,0]
	v_pk_fma_f32 v[242:243], v[236:237], v[124:125], v[242:243] op_sel:[1,0,0]
	v_pk_fma_f32 v[244:245], v[236:237], v[132:133], v[244:245] op_sel:[1,0,0]
	ds_read_b128 v[230:233], v32 offset:17408
	ds_read_b128 v[234:237], v32 offset:17424
	global_store_dwordx4 v246, v[242:245], s[100:101] nt
	s_add_u32 s100, s100, 0x2000
	s_addc_u32 s101, s101, 0
	s_waitcnt vmcnt(22)
	s_waitcnt lgkmcnt(2)
	v_pk_fma_f32 v[0:1], v[178:179], v[222:223], v[0:1] op_sel_hi:[1,0,1]
	v_pk_fma_f32 v[2:3], v[180:181], v[222:223], v[2:3] op_sel_hi:[1,0,1]
	v_pk_fma_f32 v[4:5], v[178:179], v[222:223], v[4:5] op_sel:[0,1,0]
	v_pk_fma_f32 v[6:7], v[180:181], v[222:223], v[6:7] op_sel:[0,1,0]
	v_pk_fma_f32 v[8:9], v[178:179], v[224:225], v[8:9] op_sel_hi:[1,0,1]
	v_pk_fma_f32 v[10:11], v[180:181], v[224:225], v[10:11] op_sel_hi:[1,0,1]
	v_pk_fma_f32 v[12:13], v[178:179], v[224:225], v[12:13] op_sel:[0,1,0]
	v_pk_fma_f32 v[14:15], v[180:181], v[224:225], v[14:15] op_sel:[0,1,0]
	v_pk_fma_f32 v[16:17], v[178:179], v[226:227], v[16:17] op_sel_hi:[1,0,1]
	v_pk_fma_f32 v[18:19], v[180:181], v[226:227], v[18:19] op_sel_hi:[1,0,1]
	v_pk_fma_f32 v[20:21], v[178:179], v[226:227], v[20:21] op_sel:[0,1,0]
	v_pk_fma_f32 v[22:23], v[180:181], v[226:227], v[22:23] op_sel:[0,1,0]
	v_pk_fma_f32 v[24:25], v[178:179], v[228:229], v[24:25] op_sel_hi:[1,0,1]
	v_pk_fma_f32 v[26:27], v[180:181], v[228:229], v[26:27] op_sel_hi:[1,0,1]
	v_pk_fma_f32 v[28:29], v[178:179], v[228:229], v[28:29] op_sel:[0,1,0]
	v_pk_fma_f32 v[30:31], v[180:181], v[228:229], v[30:31] op_sel:[0,1,0]
	ds_read_b128 v[222:225], v32 offset:1152
	ds_read_b128 v[226:229], v32 offset:1168
	s_waitcnt lgkmcnt(2)
	v_pk_mul_f32 v[238:239], v[230:231], v[102:103] op_sel_hi:[0,1]
	v_pk_mul_f32 v[240:241], v[230:231], v[110:111] op_sel_hi:[0,1]
	v_pk_fma_f32 v[238:239], v[86:87], v[178:179], v[238:239]
	v_pk_fma_f32 v[240:241], v[86:87], v[180:181], v[240:241]
	v_pk_fma_f32 v[238:239], v[234:235], v[118:119], v[238:239] op_sel_hi:[0,1,1]
	v_pk_fma_f32 v[240:241], v[234:235], v[126:127], v[240:241] op_sel_hi:[0,1,1]
	v_pk_fma_f32 v[238:239], v[230:231], v[104:105], v[238:239] op_sel:[1,0,0]
	v_pk_fma_f32 v[240:241], v[230:231], v[112:113], v[240:241] op_sel:[1,0,0]
	v_pk_fma_f32 v[238:239], v[234:235], v[120:121], v[238:239] op_sel:[1,0,0]
	v_pk_fma_f32 v[240:241], v[234:235], v[128:129], v[240:241] op_sel:[1,0,0]
	v_pk_fma_f32 v[238:239], v[232:233], v[106:107], v[238:239] op_sel_hi:[0,1,1]
	v_pk_fma_f32 v[240:241], v[232:233], v[114:115], v[240:241] op_sel_hi:[0,1,1]
	v_pk_fma_f32 v[238:239], v[236:237], v[122:123], v[238:239] op_sel_hi:[0,1,1]
	v_pk_fma_f32 v[240:241], v[236:237], v[130:131], v[240:241] op_sel_hi:[0,1,1]
	v_pk_fma_f32 v[238:239], v[232:233], v[108:109], v[238:239] op_sel:[1,0,0]
	v_pk_fma_f32 v[240:241], v[232:233], v[116:117], v[240:241] op_sel:[1,0,0]
	v_pk_fma_f32 v[238:239], v[236:237], v[124:125], v[238:239] op_sel:[1,0,0]
	v_pk_fma_f32 v[240:241], v[236:237], v[132:133], v[240:241] op_sel:[1,0,0]
	ds_read_b128 v[230:233], v32 offset:17536
	ds_read_b128 v[234:237], v32 offset:17552
	global_store_dwordx4 v246, v[238:241], s[100:101] nt
	s_add_u32 s100, s100, 0x2000
	s_addc_u32 s101, s101, 0
	s_waitcnt vmcnt(21)
	s_waitcnt lgkmcnt(2)
	v_pk_fma_f32 v[0:1], v[182:183], v[222:223], v[0:1] op_sel_hi:[1,0,1]
	v_pk_fma_f32 v[2:3], v[184:185], v[222:223], v[2:3] op_sel_hi:[1,0,1]
	v_pk_fma_f32 v[4:5], v[182:183], v[222:223], v[4:5] op_sel:[0,1,0]
	v_pk_fma_f32 v[6:7], v[184:185], v[222:223], v[6:7] op_sel:[0,1,0]
	v_pk_fma_f32 v[8:9], v[182:183], v[224:225], v[8:9] op_sel_hi:[1,0,1]
	v_pk_fma_f32 v[10:11], v[184:185], v[224:225], v[10:11] op_sel_hi:[1,0,1]
	v_pk_fma_f32 v[12:13], v[182:183], v[224:225], v[12:13] op_sel:[0,1,0]
	v_pk_fma_f32 v[14:15], v[184:185], v[224:225], v[14:15] op_sel:[0,1,0]
	v_pk_fma_f32 v[16:17], v[182:183], v[226:227], v[16:17] op_sel_hi:[1,0,1]
	v_pk_fma_f32 v[18:19], v[184:185], v[226:227], v[18:19] op_sel_hi:[1,0,1]
	v_pk_fma_f32 v[20:21], v[182:183], v[226:227], v[20:21] op_sel:[0,1,0]
	v_pk_fma_f32 v[22:23], v[184:185], v[226:227], v[22:23] op_sel:[0,1,0]
	v_pk_fma_f32 v[24:25], v[182:183], v[228:229], v[24:25] op_sel_hi:[1,0,1]
	v_pk_fma_f32 v[26:27], v[184:185], v[228:229], v[26:27] op_sel_hi:[1,0,1]
	v_pk_fma_f32 v[28:29], v[182:183], v[228:229], v[28:29] op_sel:[0,1,0]
	v_pk_fma_f32 v[30:31], v[184:185], v[228:229], v[30:31] op_sel:[0,1,0]
	ds_read_b128 v[222:225], v32 offset:1280
	ds_read_b128 v[226:229], v32 offset:1296
	s_waitcnt lgkmcnt(2)
	v_pk_mul_f32 v[242:243], v[230:231], v[102:103] op_sel_hi:[0,1]
	v_pk_mul_f32 v[244:245], v[230:231], v[110:111] op_sel_hi:[0,1]
	v_pk_fma_f32 v[242:243], v[86:87], v[182:183], v[242:243]
	v_pk_fma_f32 v[244:245], v[86:87], v[184:185], v[244:245]
	v_pk_fma_f32 v[242:243], v[234:235], v[118:119], v[242:243] op_sel_hi:[0,1,1]
	v_pk_fma_f32 v[244:245], v[234:235], v[126:127], v[244:245] op_sel_hi:[0,1,1]
	v_pk_fma_f32 v[242:243], v[230:231], v[104:105], v[242:243] op_sel:[1,0,0]
	v_pk_fma_f32 v[244:245], v[230:231], v[112:113], v[244:245] op_sel:[1,0,0]
	v_pk_fma_f32 v[242:243], v[234:235], v[120:121], v[242:243] op_sel:[1,0,0]
	v_pk_fma_f32 v[244:245], v[234:235], v[128:129], v[244:245] op_sel:[1,0,0]
	v_pk_fma_f32 v[242:243], v[232:233], v[106:107], v[242:243] op_sel_hi:[0,1,1]
	v_pk_fma_f32 v[244:245], v[232:233], v[114:115], v[244:245] op_sel_hi:[0,1,1]
	v_pk_fma_f32 v[242:243], v[236:237], v[122:123], v[242:243] op_sel_hi:[0,1,1]
	v_pk_fma_f32 v[244:245], v[236:237], v[130:131], v[244:245] op_sel_hi:[0,1,1]
	v_pk_fma_f32 v[242:243], v[232:233], v[108:109], v[242:243] op_sel:[1,0,0]
	v_pk_fma_f32 v[244:245], v[232:233], v[116:117], v[244:245] op_sel:[1,0,0]
	v_pk_fma_f32 v[242:243], v[236:237], v[124:125], v[242:243] op_sel:[1,0,0]
	v_pk_fma_f32 v[244:245], v[236:237], v[132:133], v[244:245] op_sel:[1,0,0]
	ds_read_b128 v[230:233], v32 offset:17664
	ds_read_b128 v[234:237], v32 offset:17680
	global_store_dwordx4 v246, v[242:245], s[100:101] nt
	s_add_u32 s100, s100, 0x2000
	s_addc_u32 s101, s101, 0
	s_waitcnt vmcnt(20)
	s_waitcnt lgkmcnt(2)
	v_pk_fma_f32 v[0:1], v[186:187], v[222:223], v[0:1] op_sel_hi:[1,0,1]
	v_pk_fma_f32 v[2:3], v[188:189], v[222:223], v[2:3] op_sel_hi:[1,0,1]
	v_pk_fma_f32 v[4:5], v[186:187], v[222:223], v[4:5] op_sel:[0,1,0]
	v_pk_fma_f32 v[6:7], v[188:189], v[222:223], v[6:7] op_sel:[0,1,0]
	v_pk_fma_f32 v[8:9], v[186:187], v[224:225], v[8:9] op_sel_hi:[1,0,1]
	v_pk_fma_f32 v[10:11], v[188:189], v[224:225], v[10:11] op_sel_hi:[1,0,1]
	v_pk_fma_f32 v[12:13], v[186:187], v[224:225], v[12:13] op_sel:[0,1,0]
	v_pk_fma_f32 v[14:15], v[188:189], v[224:225], v[14:15] op_sel:[0,1,0]
	v_pk_fma_f32 v[16:17], v[186:187], v[226:227], v[16:17] op_sel_hi:[1,0,1]
	v_pk_fma_f32 v[18:19], v[188:189], v[226:227], v[18:19] op_sel_hi:[1,0,1]
	v_pk_fma_f32 v[20:21], v[186:187], v[226:227], v[20:21] op_sel:[0,1,0]
	v_pk_fma_f32 v[22:23], v[188:189], v[226:227], v[22:23] op_sel:[0,1,0]
	v_pk_fma_f32 v[24:25], v[186:187], v[228:229], v[24:25] op_sel_hi:[1,0,1]
	v_pk_fma_f32 v[26:27], v[188:189], v[228:229], v[26:27] op_sel_hi:[1,0,1]
	v_pk_fma_f32 v[28:29], v[186:187], v[228:229], v[28:29] op_sel:[0,1,0]
	v_pk_fma_f32 v[30:31], v[188:189], v[228:229], v[30:31] op_sel:[0,1,0]
	ds_read_b128 v[222:225], v32 offset:1408
	ds_read_b128 v[226:229], v32 offset:1424
	s_waitcnt lgkmcnt(2)
	v_pk_mul_f32 v[238:239], v[230:231], v[102:103] op_sel_hi:[0,1]
	v_pk_mul_f32 v[240:241], v[230:231], v[110:111] op_sel_hi:[0,1]
	v_pk_fma_f32 v[238:239], v[86:87], v[186:187], v[238:239]
	v_pk_fma_f32 v[240:241], v[86:87], v[188:189], v[240:241]
	v_pk_fma_f32 v[238:239], v[234:235], v[118:119], v[238:239] op_sel_hi:[0,1,1]
	v_pk_fma_f32 v[240:241], v[234:235], v[126:127], v[240:241] op_sel_hi:[0,1,1]
	v_pk_fma_f32 v[238:239], v[230:231], v[104:105], v[238:239] op_sel:[1,0,0]
	v_pk_fma_f32 v[240:241], v[230:231], v[112:113], v[240:241] op_sel:[1,0,0]
	v_pk_fma_f32 v[238:239], v[234:235], v[120:121], v[238:239] op_sel:[1,0,0]
	v_pk_fma_f32 v[240:241], v[234:235], v[128:129], v[240:241] op_sel:[1,0,0]
	v_pk_fma_f32 v[238:239], v[232:233], v[106:107], v[238:239] op_sel_hi:[0,1,1]
	v_pk_fma_f32 v[240:241], v[232:233], v[114:115], v[240:241] op_sel_hi:[0,1,1]
	v_pk_fma_f32 v[238:239], v[236:237], v[122:123], v[238:239] op_sel_hi:[0,1,1]
	v_pk_fma_f32 v[240:241], v[236:237], v[130:131], v[240:241] op_sel_hi:[0,1,1]
	v_pk_fma_f32 v[238:239], v[232:233], v[108:109], v[238:239] op_sel:[1,0,0]
	v_pk_fma_f32 v[240:241], v[232:233], v[116:117], v[240:241] op_sel:[1,0,0]
	v_pk_fma_f32 v[238:239], v[236:237], v[124:125], v[238:239] op_sel:[1,0,0]
	v_pk_fma_f32 v[240:241], v[236:237], v[132:133], v[240:241] op_sel:[1,0,0]
	ds_read_b128 v[230:233], v32 offset:17792
	ds_read_b128 v[234:237], v32 offset:17808
	global_store_dwordx4 v246, v[238:241], s[100:101] nt
	s_add_u32 s100, s100, 0x2000
	s_addc_u32 s101, s101, 0
	s_waitcnt vmcnt(19)
	s_waitcnt lgkmcnt(2)
	v_pk_fma_f32 v[0:1], v[190:191], v[222:223], v[0:1] op_sel_hi:[1,0,1]
	v_pk_fma_f32 v[2:3], v[192:193], v[222:223], v[2:3] op_sel_hi:[1,0,1]
	v_pk_fma_f32 v[4:5], v[190:191], v[222:223], v[4:5] op_sel:[0,1,0]
	v_pk_fma_f32 v[6:7], v[192:193], v[222:223], v[6:7] op_sel:[0,1,0]
	v_pk_fma_f32 v[8:9], v[190:191], v[224:225], v[8:9] op_sel_hi:[1,0,1]
	v_pk_fma_f32 v[10:11], v[192:193], v[224:225], v[10:11] op_sel_hi:[1,0,1]
	v_pk_fma_f32 v[12:13], v[190:191], v[224:225], v[12:13] op_sel:[0,1,0]
	v_pk_fma_f32 v[14:15], v[192:193], v[224:225], v[14:15] op_sel:[0,1,0]
	v_pk_fma_f32 v[16:17], v[190:191], v[226:227], v[16:17] op_sel_hi:[1,0,1]
	v_pk_fma_f32 v[18:19], v[192:193], v[226:227], v[18:19] op_sel_hi:[1,0,1]
	v_pk_fma_f32 v[20:21], v[190:191], v[226:227], v[20:21] op_sel:[0,1,0]
	v_pk_fma_f32 v[22:23], v[192:193], v[226:227], v[22:23] op_sel:[0,1,0]
	v_pk_fma_f32 v[24:25], v[190:191], v[228:229], v[24:25] op_sel_hi:[1,0,1]
	v_pk_fma_f32 v[26:27], v[192:193], v[228:229], v[26:27] op_sel_hi:[1,0,1]
	v_pk_fma_f32 v[28:29], v[190:191], v[228:229], v[28:29] op_sel:[0,1,0]
	v_pk_fma_f32 v[30:31], v[192:193], v[228:229], v[30:31] op_sel:[0,1,0]
	ds_read_b128 v[222:225], v32 offset:1536
	ds_read_b128 v[226:229], v32 offset:1552
	s_waitcnt lgkmcnt(2)
	v_pk_mul_f32 v[242:243], v[230:231], v[102:103] op_sel_hi:[0,1]
	v_pk_mul_f32 v[244:245], v[230:231], v[110:111] op_sel_hi:[0,1]
	v_pk_fma_f32 v[242:243], v[86:87], v[190:191], v[242:243]
	v_pk_fma_f32 v[244:245], v[86:87], v[192:193], v[244:245]
	v_pk_fma_f32 v[242:243], v[234:235], v[118:119], v[242:243] op_sel_hi:[0,1,1]
	v_pk_fma_f32 v[244:245], v[234:235], v[126:127], v[244:245] op_sel_hi:[0,1,1]
	v_pk_fma_f32 v[242:243], v[230:231], v[104:105], v[242:243] op_sel:[1,0,0]
	v_pk_fma_f32 v[244:245], v[230:231], v[112:113], v[244:245] op_sel:[1,0,0]
	v_pk_fma_f32 v[242:243], v[234:235], v[120:121], v[242:243] op_sel:[1,0,0]
	v_pk_fma_f32 v[244:245], v[234:235], v[128:129], v[244:245] op_sel:[1,0,0]
	v_pk_fma_f32 v[242:243], v[232:233], v[106:107], v[242:243] op_sel_hi:[0,1,1]
	v_pk_fma_f32 v[244:245], v[232:233], v[114:115], v[244:245] op_sel_hi:[0,1,1]
	v_pk_fma_f32 v[242:243], v[236:237], v[122:123], v[242:243] op_sel_hi:[0,1,1]
	v_pk_fma_f32 v[244:245], v[236:237], v[130:131], v[244:245] op_sel_hi:[0,1,1]
	v_pk_fma_f32 v[242:243], v[232:233], v[108:109], v[242:243] op_sel:[1,0,0]
	v_pk_fma_f32 v[244:245], v[232:233], v[116:117], v[244:245] op_sel:[1,0,0]
	v_pk_fma_f32 v[242:243], v[236:237], v[124:125], v[242:243] op_sel:[1,0,0]
	v_pk_fma_f32 v[244:245], v[236:237], v[132:133], v[244:245] op_sel:[1,0,0]
	ds_read_b128 v[230:233], v32 offset:17920
	ds_read_b128 v[234:237], v32 offset:17936
	global_store_dwordx4 v246, v[242:245], s[100:101] nt
	s_add_u32 s100, s100, 0x2000
	s_addc_u32 s101, s101, 0
	s_waitcnt vmcnt(18)
	s_waitcnt lgkmcnt(2)
	v_pk_fma_f32 v[0:1], v[194:195], v[222:223], v[0:1] op_sel_hi:[1,0,1]
	v_pk_fma_f32 v[2:3], v[196:197], v[222:223], v[2:3] op_sel_hi:[1,0,1]
	v_pk_fma_f32 v[4:5], v[194:195], v[222:223], v[4:5] op_sel:[0,1,0]
	v_pk_fma_f32 v[6:7], v[196:197], v[222:223], v[6:7] op_sel:[0,1,0]
	v_pk_fma_f32 v[8:9], v[194:195], v[224:225], v[8:9] op_sel_hi:[1,0,1]
	v_pk_fma_f32 v[10:11], v[196:197], v[224:225], v[10:11] op_sel_hi:[1,0,1]
	v_pk_fma_f32 v[12:13], v[194:195], v[224:225], v[12:13] op_sel:[0,1,0]
	v_pk_fma_f32 v[14:15], v[196:197], v[224:225], v[14:15] op_sel:[0,1,0]
	v_pk_fma_f32 v[16:17], v[194:195], v[226:227], v[16:17] op_sel_hi:[1,0,1]
	v_pk_fma_f32 v[18:19], v[196:197], v[226:227], v[18:19] op_sel_hi:[1,0,1]
	v_pk_fma_f32 v[20:21], v[194:195], v[226:227], v[20:21] op_sel:[0,1,0]
	v_pk_fma_f32 v[22:23], v[196:197], v[226:227], v[22:23] op_sel:[0,1,0]
	v_pk_fma_f32 v[24:25], v[194:195], v[228:229], v[24:25] op_sel_hi:[1,0,1]
	v_pk_fma_f32 v[26:27], v[196:197], v[228:229], v[26:27] op_sel_hi:[1,0,1]
	v_pk_fma_f32 v[28:29], v[194:195], v[228:229], v[28:29] op_sel:[0,1,0]
	v_pk_fma_f32 v[30:31], v[196:197], v[228:229], v[30:31] op_sel:[0,1,0]
	ds_read_b128 v[222:225], v32 offset:1664
	ds_read_b128 v[226:229], v32 offset:1680
	s_waitcnt lgkmcnt(2)
	v_pk_mul_f32 v[238:239], v[230:231], v[102:103] op_sel_hi:[0,1]
	v_pk_mul_f32 v[240:241], v[230:231], v[110:111] op_sel_hi:[0,1]
	v_pk_fma_f32 v[238:239], v[86:87], v[194:195], v[238:239]
	v_pk_fma_f32 v[240:241], v[86:87], v[196:197], v[240:241]
	v_pk_fma_f32 v[238:239], v[234:235], v[118:119], v[238:239] op_sel_hi:[0,1,1]
	v_pk_fma_f32 v[240:241], v[234:235], v[126:127], v[240:241] op_sel_hi:[0,1,1]
	v_pk_fma_f32 v[238:239], v[230:231], v[104:105], v[238:239] op_sel:[1,0,0]
	v_pk_fma_f32 v[240:241], v[230:231], v[112:113], v[240:241] op_sel:[1,0,0]
	v_pk_fma_f32 v[238:239], v[234:235], v[120:121], v[238:239] op_sel:[1,0,0]
	v_pk_fma_f32 v[240:241], v[234:235], v[128:129], v[240:241] op_sel:[1,0,0]
	v_pk_fma_f32 v[238:239], v[232:233], v[106:107], v[238:239] op_sel_hi:[0,1,1]
	v_pk_fma_f32 v[240:241], v[232:233], v[114:115], v[240:241] op_sel_hi:[0,1,1]
	v_pk_fma_f32 v[238:239], v[236:237], v[122:123], v[238:239] op_sel_hi:[0,1,1]
	v_pk_fma_f32 v[240:241], v[236:237], v[130:131], v[240:241] op_sel_hi:[0,1,1]
	v_pk_fma_f32 v[238:239], v[232:233], v[108:109], v[238:239] op_sel:[1,0,0]
	v_pk_fma_f32 v[240:241], v[232:233], v[116:117], v[240:241] op_sel:[1,0,0]
	v_pk_fma_f32 v[238:239], v[236:237], v[124:125], v[238:239] op_sel:[1,0,0]
	v_pk_fma_f32 v[240:241], v[236:237], v[132:133], v[240:241] op_sel:[1,0,0]
	ds_read_b128 v[230:233], v32 offset:18048
	ds_read_b128 v[234:237], v32 offset:18064
	global_store_dwordx4 v246, v[238:241], s[100:101] nt
	s_add_u32 s100, s100, 0x2000
	s_addc_u32 s101, s101, 0
	s_waitcnt vmcnt(17)
	s_waitcnt lgkmcnt(2)
	v_pk_fma_f32 v[0:1], v[210:211], v[222:223], v[0:1] op_sel_hi:[1,0,1]
	v_pk_fma_f32 v[2:3], v[212:213], v[222:223], v[2:3] op_sel_hi:[1,0,1]
	v_pk_fma_f32 v[4:5], v[210:211], v[222:223], v[4:5] op_sel:[0,1,0]
	v_pk_fma_f32 v[6:7], v[212:213], v[222:223], v[6:7] op_sel:[0,1,0]
	v_pk_fma_f32 v[8:9], v[210:211], v[224:225], v[8:9] op_sel_hi:[1,0,1]
	v_pk_fma_f32 v[10:11], v[212:213], v[224:225], v[10:11] op_sel_hi:[1,0,1]
	v_pk_fma_f32 v[12:13], v[210:211], v[224:225], v[12:13] op_sel:[0,1,0]
	v_pk_fma_f32 v[14:15], v[212:213], v[224:225], v[14:15] op_sel:[0,1,0]
	v_pk_fma_f32 v[16:17], v[210:211], v[226:227], v[16:17] op_sel_hi:[1,0,1]
	v_pk_fma_f32 v[18:19], v[212:213], v[226:227], v[18:19] op_sel_hi:[1,0,1]
	v_pk_fma_f32 v[20:21], v[210:211], v[226:227], v[20:21] op_sel:[0,1,0]
	v_pk_fma_f32 v[22:23], v[212:213], v[226:227], v[22:23] op_sel:[0,1,0]
	v_pk_fma_f32 v[24:25], v[210:211], v[228:229], v[24:25] op_sel_hi:[1,0,1]
	v_pk_fma_f32 v[26:27], v[212:213], v[228:229], v[26:27] op_sel_hi:[1,0,1]
	v_pk_fma_f32 v[28:29], v[210:211], v[228:229], v[28:29] op_sel:[0,1,0]
	v_pk_fma_f32 v[30:31], v[212:213], v[228:229], v[30:31] op_sel:[0,1,0]
	ds_read_b128 v[222:225], v32 offset:1792
	ds_read_b128 v[226:229], v32 offset:1808
	s_waitcnt lgkmcnt(2)
	v_pk_mul_f32 v[242:243], v[230:231], v[102:103] op_sel_hi:[0,1]
	v_pk_mul_f32 v[244:245], v[230:231], v[110:111] op_sel_hi:[0,1]
	v_pk_fma_f32 v[242:243], v[86:87], v[210:211], v[242:243]
	v_pk_fma_f32 v[244:245], v[86:87], v[212:213], v[244:245]
	v_pk_fma_f32 v[242:243], v[234:235], v[118:119], v[242:243] op_sel_hi:[0,1,1]
	v_pk_fma_f32 v[244:245], v[234:235], v[126:127], v[244:245] op_sel_hi:[0,1,1]
	v_pk_fma_f32 v[242:243], v[230:231], v[104:105], v[242:243] op_sel:[1,0,0]
	v_pk_fma_f32 v[244:245], v[230:231], v[112:113], v[244:245] op_sel:[1,0,0]
	v_pk_fma_f32 v[242:243], v[234:235], v[120:121], v[242:243] op_sel:[1,0,0]
	v_pk_fma_f32 v[244:245], v[234:235], v[128:129], v[244:245] op_sel:[1,0,0]
	v_pk_fma_f32 v[242:243], v[232:233], v[106:107], v[242:243] op_sel_hi:[0,1,1]
	v_pk_fma_f32 v[244:245], v[232:233], v[114:115], v[244:245] op_sel_hi:[0,1,1]
	v_pk_fma_f32 v[242:243], v[236:237], v[122:123], v[242:243] op_sel_hi:[0,1,1]
	v_pk_fma_f32 v[244:245], v[236:237], v[130:131], v[244:245] op_sel_hi:[0,1,1]
	v_pk_fma_f32 v[242:243], v[232:233], v[108:109], v[242:243] op_sel:[1,0,0]
	v_pk_fma_f32 v[244:245], v[232:233], v[116:117], v[244:245] op_sel:[1,0,0]
	v_pk_fma_f32 v[242:243], v[236:237], v[124:125], v[242:243] op_sel:[1,0,0]
	v_pk_fma_f32 v[244:245], v[236:237], v[132:133], v[244:245] op_sel:[1,0,0]
	ds_read_b128 v[230:233], v32 offset:18176
	ds_read_b128 v[234:237], v32 offset:18192
	global_store_dwordx4 v246, v[242:245], s[100:101] nt
	s_add_u32 s100, s100, 0x2000
	s_addc_u32 s101, s101, 0
	s_waitcnt vmcnt(16)
	s_waitcnt lgkmcnt(2)
	v_pk_fma_f32 v[0:1], v[214:215], v[222:223], v[0:1] op_sel_hi:[1,0,1]
	v_pk_fma_f32 v[2:3], v[216:217], v[222:223], v[2:3] op_sel_hi:[1,0,1]
	v_pk_fma_f32 v[4:5], v[214:215], v[222:223], v[4:5] op_sel:[0,1,0]
	v_pk_fma_f32 v[6:7], v[216:217], v[222:223], v[6:7] op_sel:[0,1,0]
	v_pk_fma_f32 v[8:9], v[214:215], v[224:225], v[8:9] op_sel_hi:[1,0,1]
	v_pk_fma_f32 v[10:11], v[216:217], v[224:225], v[10:11] op_sel_hi:[1,0,1]
	v_pk_fma_f32 v[12:13], v[214:215], v[224:225], v[12:13] op_sel:[0,1,0]
	v_pk_fma_f32 v[14:15], v[216:217], v[224:225], v[14:15] op_sel:[0,1,0]
	v_pk_fma_f32 v[16:17], v[214:215], v[226:227], v[16:17] op_sel_hi:[1,0,1]
	v_pk_fma_f32 v[18:19], v[216:217], v[226:227], v[18:19] op_sel_hi:[1,0,1]
	v_pk_fma_f32 v[20:21], v[214:215], v[226:227], v[20:21] op_sel:[0,1,0]
	v_pk_fma_f32 v[22:23], v[216:217], v[226:227], v[22:23] op_sel:[0,1,0]
	v_pk_fma_f32 v[24:25], v[214:215], v[228:229], v[24:25] op_sel_hi:[1,0,1]
	v_pk_fma_f32 v[26:27], v[216:217], v[228:229], v[26:27] op_sel_hi:[1,0,1]
	v_pk_fma_f32 v[28:29], v[214:215], v[228:229], v[28:29] op_sel:[0,1,0]
	v_pk_fma_f32 v[30:31], v[216:217], v[228:229], v[30:31] op_sel:[0,1,0]
	ds_read_b128 v[222:225], v32 offset:1920
	ds_read_b128 v[226:229], v32 offset:1936
	s_waitcnt lgkmcnt(2)
	v_pk_mul_f32 v[238:239], v[230:231], v[102:103] op_sel_hi:[0,1]
	v_pk_mul_f32 v[240:241], v[230:231], v[110:111] op_sel_hi:[0,1]
	v_pk_fma_f32 v[238:239], v[86:87], v[214:215], v[238:239]
	v_pk_fma_f32 v[240:241], v[86:87], v[216:217], v[240:241]
	v_pk_fma_f32 v[238:239], v[234:235], v[118:119], v[238:239] op_sel_hi:[0,1,1]
	v_pk_fma_f32 v[240:241], v[234:235], v[126:127], v[240:241] op_sel_hi:[0,1,1]
	v_pk_fma_f32 v[238:239], v[230:231], v[104:105], v[238:239] op_sel:[1,0,0]
	v_pk_fma_f32 v[240:241], v[230:231], v[112:113], v[240:241] op_sel:[1,0,0]
	v_pk_fma_f32 v[238:239], v[234:235], v[120:121], v[238:239] op_sel:[1,0,0]
	v_pk_fma_f32 v[240:241], v[234:235], v[128:129], v[240:241] op_sel:[1,0,0]
	v_pk_fma_f32 v[238:239], v[232:233], v[106:107], v[238:239] op_sel_hi:[0,1,1]
	v_pk_fma_f32 v[240:241], v[232:233], v[114:115], v[240:241] op_sel_hi:[0,1,1]
	v_pk_fma_f32 v[238:239], v[236:237], v[122:123], v[238:239] op_sel_hi:[0,1,1]
	v_pk_fma_f32 v[240:241], v[236:237], v[130:131], v[240:241] op_sel_hi:[0,1,1]
	v_pk_fma_f32 v[238:239], v[232:233], v[108:109], v[238:239] op_sel:[1,0,0]
	v_pk_fma_f32 v[240:241], v[232:233], v[116:117], v[240:241] op_sel:[1,0,0]
	v_pk_fma_f32 v[238:239], v[236:237], v[124:125], v[238:239] op_sel:[1,0,0]
	v_pk_fma_f32 v[240:241], v[236:237], v[132:133], v[240:241] op_sel:[1,0,0]
	ds_read_b128 v[230:233], v32 offset:18304
	ds_read_b128 v[234:237], v32 offset:18320
	global_store_dwordx4 v246, v[238:241], s[100:101] nt
	s_add_u32 s100, s100, 0x2000
	s_addc_u32 s101, s101, 0
	s_waitcnt vmcnt(15)
	s_waitcnt lgkmcnt(2)
	v_pk_fma_f32 v[0:1], v[218:219], v[222:223], v[0:1] op_sel_hi:[1,0,1]
	v_pk_fma_f32 v[2:3], v[220:221], v[222:223], v[2:3] op_sel_hi:[1,0,1]
	v_pk_fma_f32 v[4:5], v[218:219], v[222:223], v[4:5] op_sel:[0,1,0]
	v_pk_fma_f32 v[6:7], v[220:221], v[222:223], v[6:7] op_sel:[0,1,0]
	v_pk_fma_f32 v[8:9], v[218:219], v[224:225], v[8:9] op_sel_hi:[1,0,1]
	v_pk_fma_f32 v[10:11], v[220:221], v[224:225], v[10:11] op_sel_hi:[1,0,1]
	v_pk_fma_f32 v[12:13], v[218:219], v[224:225], v[12:13] op_sel:[0,1,0]
	v_pk_fma_f32 v[14:15], v[220:221], v[224:225], v[14:15] op_sel:[0,1,0]
	v_pk_fma_f32 v[16:17], v[218:219], v[226:227], v[16:17] op_sel_hi:[1,0,1]
	v_pk_fma_f32 v[18:19], v[220:221], v[226:227], v[18:19] op_sel_hi:[1,0,1]
	v_pk_fma_f32 v[20:21], v[218:219], v[226:227], v[20:21] op_sel:[0,1,0]
	v_pk_fma_f32 v[22:23], v[220:221], v[226:227], v[22:23] op_sel:[0,1,0]
	v_pk_fma_f32 v[24:25], v[218:219], v[228:229], v[24:25] op_sel_hi:[1,0,1]
	v_pk_fma_f32 v[26:27], v[220:221], v[228:229], v[26:27] op_sel_hi:[1,0,1]
	v_pk_fma_f32 v[28:29], v[218:219], v[228:229], v[28:29] op_sel:[0,1,0]
	v_pk_fma_f32 v[30:31], v[220:221], v[228:229], v[30:31] op_sel:[0,1,0]
	s_waitcnt lgkmcnt(0)
	v_pk_mul_f32 v[242:243], v[230:231], v[102:103] op_sel_hi:[0,1]
	v_pk_mul_f32 v[244:245], v[230:231], v[110:111] op_sel_hi:[0,1]
	v_pk_fma_f32 v[242:243], v[86:87], v[218:219], v[242:243]
	v_pk_fma_f32 v[244:245], v[86:87], v[220:221], v[244:245]
	v_pk_fma_f32 v[242:243], v[234:235], v[118:119], v[242:243] op_sel_hi:[0,1,1]
	v_pk_fma_f32 v[244:245], v[234:235], v[126:127], v[244:245] op_sel_hi:[0,1,1]
	v_pk_fma_f32 v[242:243], v[230:231], v[104:105], v[242:243] op_sel:[1,0,0]
	v_pk_fma_f32 v[244:245], v[230:231], v[112:113], v[244:245] op_sel:[1,0,0]
	v_pk_fma_f32 v[242:243], v[234:235], v[120:121], v[242:243] op_sel:[1,0,0]
	v_pk_fma_f32 v[244:245], v[234:235], v[128:129], v[244:245] op_sel:[1,0,0]
	v_pk_fma_f32 v[242:243], v[232:233], v[106:107], v[242:243] op_sel_hi:[0,1,1]
	v_pk_fma_f32 v[244:245], v[232:233], v[114:115], v[244:245] op_sel_hi:[0,1,1]
	v_pk_fma_f32 v[242:243], v[236:237], v[122:123], v[242:243] op_sel_hi:[0,1,1]
	v_pk_fma_f32 v[244:245], v[236:237], v[130:131], v[244:245] op_sel_hi:[0,1,1]
	v_pk_fma_f32 v[242:243], v[232:233], v[108:109], v[242:243] op_sel:[1,0,0]
	v_pk_fma_f32 v[244:245], v[232:233], v[116:117], v[244:245] op_sel:[1,0,0]
	v_pk_fma_f32 v[242:243], v[236:237], v[124:125], v[242:243] op_sel:[1,0,0]
	v_pk_fma_f32 v[244:245], v[236:237], v[132:133], v[244:245] op_sel:[1,0,0]
	global_store_dwordx4 v246, v[242:245], s[100:101] nt
	s_add_u32 s100, s100, 0x2000
	s_addc_u32 s101, s101, 0
	s_mov_b32 s36, 0x100000
	s_mov_b32 s37, 0
	s_mov_b32 s39, 0x696e000
	v_add_f32_e32 v32, v53, v52
	v_lshlrev_b32_e32 v52, 14, v94
	v_lshlrev_b32_e32 v53, 2, v156
	v_add3_u32 v52, 0, v52, v53
	ds_write_b128 v52, v[0:3] offset:32768
	ds_write_b128 v52, v[4:7] offset:34816
	ds_write_b128 v52, v[8:11] offset:36864
	ds_write_b128 v52, v[12:15] offset:38912
	ds_write_b128 v52, v[16:19] offset:40960
	ds_write_b128 v52, v[20:23] offset:43008
	ds_write_b128 v52, v[24:27] offset:45056
	ds_write_b128 v52, v[28:31] offset:47104
	v_lshlrev_b64 v[0:1], 3, v[88:89]
	v_lshl_add_u64 v[2:3], v[90:91], 0, v[0:1]
	v_lshl_add_u64 v[0:1], v[92:93], 0, v[0:1]
	s_waitcnt lgkmcnt(0)
	s_barrier
	flat_load_dwordx2 v[2:3], v[2:3]
	s_lshl_b32 s28, s28, 1
	flat_load_dwordx2 v[0:1], v[0:1]
	v_readlane_b32 s36, v255, 16
	s_add_u32 s36, s36, s28
	v_readlane_b32 s28, v255, 17
	s_addc_u32 s37, s28, 0
	v_lshl_add_u64 v[4:5], v[36:37], 1, s[36:37]
	s_lshl_b32 s28, s38, 3
	v_readlane_b32 s36, v255, 18
	s_add_u32 s36, s36, s28
	v_readlane_b32 s28, v255, 19
	s_addc_u32 s37, s28, 0
	s_add_i32 s28, 0, 0x18800
	v_mul_f32_e32 v32, 0xbfb8aa3b, v32
	v_exp_f32_e32 v32, v32
	s_waitcnt vmcnt(0) lgkmcnt(0)
	v_lshlrev_b32_e32 v19, 16, v2
	v_and_b32_e32 v18, 0xffff0000, v2
	v_lshlrev_b32_e32 v8, 16, v0
	v_and_b32_e32 v9, 0xffff0000, v0
	v_lshlrev_b32_e32 v10, 16, v1
	v_and_b32_e32 v11, 0xffff0000, v1
	ds_read2st64_b32 v[0:1], v84 offset0:128 offset1:192
	v_add_u32_e32 v2, 0x14000, v84
	ds_read_b32 v2, v2
	v_lshlrev_b32_e32 v6, 16, v3
	v_and_b32_e32 v7, 0xffff0000, v3
	s_waitcnt lgkmcnt(1)
	v_add_f32_e32 v0, v0, v1
	v_add_u32_e32 v1, 0x10000, v84
	ds_read_b32 v1, v1
	s_waitcnt lgkmcnt(0)
	v_add_f32_e32 v1, v1, v2
	v_add_f32_e32 v24, v0, v1
	v_mov_b32_e32 v0, s28
	v_readlane_b32 s28, v255, 20
	ds_read_b128 v[0:3], v0
	s_nop 0
	v_mov_b32_e32 v14, s28
	s_add_i32 s28, 0, 0x18900
	v_mov_b32_e32 v25, s28
	v_readlane_b32 s28, v255, 21
	ds_read_b32 v25, v25
	ds_read_b128 v[20:23], v14
	v_mov_b32_e32 v26, s28
	ds_read_b32 v26, v26
	v_readlane_b32 s28, v255, 22
	s_waitcnt lgkmcnt(2)
	v_add_f32_e32 v25, v0, v25
	v_add_f32_e32 v25, 0, v25
	v_pk_mul_f32 v[12:13], v[2:3], v[6:7]
	s_waitcnt lgkmcnt(0)
	v_add_f32_e32 v26, v1, v26
	v_add_f32_e32 v25, v25, v26
	v_mov_b32_e32 v26, s28
	ds_read_b32 v26, v26
	v_readlane_b32 s28, v255, 23
	v_pk_mul_f32 v[16:17], v[20:21], v[8:9]
	v_fmac_f32_e32 v24, v0, v19
	v_fmac_f32_e32 v24, v1, v18
	s_waitcnt lgkmcnt(0)
	v_add_f32_e32 v2, v2, v26
	v_add_f32_e32 v2, v25, v2
	v_mov_b32_e32 v25, s28
	ds_read_b32 v25, v25
	v_readlane_b32 s28, v255, 24
	v_add_f32_e32 v0, v24, v12
	v_add_f32_e32 v0, v0, v13
	v_add_f32_e32 v0, v0, v16
	s_waitcnt lgkmcnt(0)
	v_add_f32_e32 v3, v3, v25
	v_add_f32_e32 v25, v2, v3
	v_mov_b32_e32 v2, s28
	v_readlane_b32 s28, v255, 25
	ds_read_b32 v2, v2
	v_pk_mul_f32 v[14:15], v[22:23], v[10:11]
	v_mov_b32_e32 v3, s28
	ds_read_b32 v3, v3
	v_readlane_b32 s28, v255, 26
	v_add_f32_e32 v0, v0, v17
	v_add_f32_e32 v0, v0, v14
	v_add_f32_e32 v0, v0, v15
	s_waitcnt lgkmcnt(0)
	v_pk_add_f32 v[2:3], v[20:21], v[2:3]
	s_nop 0
	v_add_f32_e32 v2, v25, v2
	v_add_f32_e32 v20, v2, v3
	v_mov_b32_e32 v2, s28
	v_readlane_b32 s28, v255, 27
	ds_read_b32 v2, v2
	s_nop 0
	v_mov_b32_e32 v3, s28
	ds_read_b32 v3, v3
	s_waitcnt lgkmcnt(0)
	v_pk_add_f32 v[2:3], v[22:23], v[2:3]
	s_nop 0
	v_add_f32_e32 v2, v20, v2
	v_add_f32_e32 v2, v2, v3
	v_max_f32_e64 v1, |v2|, v32
	v_div_scale_f32 v2, s[38:39], v1, v1, v0
	v_rcp_f32_e32 v3, v2
	s_nop 0
	v_fma_f32 v12, -v2, v3, 1.0
	v_fmac_f32_e32 v3, v12, v3
	v_div_scale_f32 v12, vcc, v0, v1, v0
	v_mul_f32_e32 v13, v12, v3
	v_fma_f32 v14, -v2, v13, v12
	v_fmac_f32_e32 v13, v14, v3
	v_fma_f32 v2, -v2, v13, v12
	v_div_fmas_f32 v2, v2, v3, v13
	v_div_fixup_f32 v2, v2, v1, v0
	v_bfe_u32 v0, v2, 16, 1
	v_add3_u32 v3, v2, v0, s60
	v_lshlrev_b64 v[0:1], 12, v[40:41]
	v_lshl_add_u64 v[0:1], v[4:5], 0, v[0:1]
	flat_store_short_d16_hi v[0:1], v3
	v_mul_f32_e32 v3, v2, v2
	ds_bpermute_b32 v0, v146, v2
	ds_bpermute_b32 v3, v146, v3
	s_waitcnt lgkmcnt(0)
	v_add_f32_e32 v0, v2, v0
	v_fmac_f32_e32 v3, v2, v2
	ds_bpermute_b32 v1, v147, v0
	ds_bpermute_b32 v2, v147, v3
	s_waitcnt lgkmcnt(0)
	v_add_f32_e32 v0, v0, v1
	v_add_f32_e32 v2, v3, v2
	ds_bpermute_b32 v1, v148, v0
	ds_bpermute_b32 v3, v148, v2
	s_waitcnt lgkmcnt(0)
	v_add_f32_e32 v0, v0, v1
	v_add_f32_e32 v2, v2, v3
	ds_bpermute_b32 v1, v149, v0
	ds_bpermute_b32 v3, v149, v2
	s_waitcnt lgkmcnt(0)
	v_add_f32_e32 v0, v0, v1
	v_add_f32_e32 v2, v2, v3
	ds_bpermute_b32 v1, v150, v0
	ds_bpermute_b32 v3, v150, v2
	s_waitcnt lgkmcnt(0)
	v_add_f32_e32 v0, v0, v1
	v_add_f32_e32 v2, v2, v3
	ds_bpermute_b32 v1, v151, v0
	ds_bpermute_b32 v3, v151, v2
	s_and_saveexec_b64 s[38:39], s[6:7]
	s_cbranch_execz .LBB0_943
	s_waitcnt lgkmcnt(0)
	v_add_f32_e32 v12, v0, v1
	v_lshl_add_u64 v[0:1], s[36:37], 0, v[38:39]
	v_add_f32_e32 v2, v2, v3
	flat_atomic_add_f32 v[0:1], v12
	flat_atomic_add_f32 v[0:1], v2 offset:4

	.amdhsa_kernel _Z14fwd_megakernel6Params
		.amdhsa_group_segment_fixed_size 0
		.amdhsa_private_segment_fixed_size 0
		.amdhsa_kernarg_size 456
		.amdhsa_user_sgpr_count 2
		.amdhsa_user_sgpr_dispatch_ptr 0
		.amdhsa_user_sgpr_queue_ptr 0
		.amdhsa_user_sgpr_kernarg_segment_ptr 1
		.amdhsa_user_sgpr_dispatch_id 0
		.amdhsa_user_sgpr_kernarg_preload_length 0
		.amdhsa_user_sgpr_kernarg_preload_offset 0
		.amdhsa_user_sgpr_private_segment_size 0
		.amdhsa_uses_dynamic_stack 0
		.amdhsa_enable_private_segment 0
		.amdhsa_system_sgpr_workgroup_id_x 1
		.amdhsa_system_sgpr_workgroup_id_y 0
		.amdhsa_system_sgpr_workgroup_id_z 0
		.amdhsa_system_sgpr_workgroup_info 0
		.amdhsa_system_vgpr_workitem_id 2
		.amdhsa_next_free_vgpr 256
		.amdhsa_next_free_sgpr 102
		.amdhsa_accum_offset 256
		.amdhsa_reserve_vcc 1
		.amdhsa_float_round_mode_32 0
		.amdhsa_float_round_mode_16_64 0
		.amdhsa_float_denorm_mode_32 3
		.amdhsa_float_denorm_mode_16_64 3
		.amdhsa_dx10_clamp 1
		.amdhsa_ieee_mode 1
		.amdhsa_fp16_overflow 0
		.amdhsa_tg_split 0
		.amdhsa_exception_fp_ieee_invalid_op 0
		.amdhsa_exception_fp_denorm_src 0
		.amdhsa_exception_fp_ieee_div_zero 0
		.amdhsa_exception_fp_ieee_overflow 0
		.amdhsa_exception_fp_ieee_underflow 0
		.amdhsa_exception_fp_ieee_inexact 0
		.amdhsa_exception_int_div_zero 0
	.end_amdhsa_kernel

amdhsa.kernels:
  - .agpr_count:     0
    .args:
      - .offset:         0
        .size:           200
        .value_kind:     by_value
      - .offset:         200
        .size:           4
        .value_kind:     hidden_block_count_x
      - .offset:         204
        .size:           4
        .value_kind:     hidden_block_count_y
      - .offset:         208
        .size:           4
        .value_kind:     hidden_block_count_z
      - .offset:         212
        .size:           2
        .value_kind:     hidden_group_size_x
      - .offset:         214
        .size:           2
        .value_kind:     hidden_group_size_y
      - .offset:         216
        .size:           2
        .value_kind:     hidden_group_size_z
      - .offset:         218
        .size:           2
        .value_kind:     hidden_remainder_x
      - .offset:         220
        .size:           2
        .value_kind:     hidden_remainder_y
      - .offset:         222
        .size:           2
        .value_kind:     hidden_remainder_z
      - .offset:         240
        .size:           8
        .value_kind:     hidden_global_offset_x
      - .offset:         248
        .size:           8
        .value_kind:     hidden_global_offset_y
      - .offset:         256
        .size:           8
        .value_kind:     hidden_global_offset_z
      - .offset:         264
        .size:           2
        .value_kind:     hidden_grid_dims
      - .offset:         288
        .size:           8
        .value_kind:     hidden_multigrid_sync_arg
      - .offset:         320
        .size:           4
        .value_kind:     hidden_dynamic_lds_size
    .group_segment_fixed_size: 0
    .kernarg_segment_align: 8
    .kernarg_segment_size: 456
    .language:       OpenCL C
    .language_version:
      - 2
      - 0
    .max_flat_workgroup_size: 512
    .name:           _Z14fwd_megakernel6Params
    .private_segment_fixed_size: 0
    .sgpr_count:     108
    .sgpr_spill_count: 71
    .symbol:         _Z14fwd_megakernel6Params.kd
    .uniform_work_group_size: 1
    .uses_dynamic_stack: false
    .vgpr_count:     256
    .vgpr_spill_count: 0
    .wavefront_size: 64
